# speedup vs baseline: 1.1223x; 1.0038x over previous
; DEV int bidx() { int b = __builtin_amdgcn_readfirstlane(blockIdx.x); asm volatile("" : "+s"(b)); return b; }
; DEV int gdim() { int g = __builtin_amdgcn_readfirstlane(gridDim.x); asm volatile("" : "+s"(g)); return g; }
; template <int EPI, bool AF32>
; DEV void gemm_tile(const void* Ap, int lda, const u16* Bt, int ldb, int K, int m0, int n0, const Epi& ea, char* smem) {
;     ...
;   f32x4 acc[4][4];
; #pragma unroll
;   for (int m = 0; m < 4; m++)
; #pragma unroll
;     for (int n = 0; n < 4; n++) acc[m][n] = (f32x4){0.f, 0.f, 0.f, 0.f};
;   u32x4 ra[4], rb[4];
;   f32x4 rfa[8];
;   const int nk = K >> 6;
;   auto gload = [&](int kt) {
;     const int k0 = kt << 6;
; #pragma unroll
;     for (int i = 0; i < 4; i++) {
;       const int c = tid + i * 256, row = c >> 3, kc = c & 7;
;       if (AF32) {
;         const float* pa = (const float*)Ap + (size_t)(m0 + row) * lda + k0 + kc * 8;
;         rfa[2 * i] = *(const f32x4*)pa;
;         rfa[2 * i + 1] = *(const f32x4*)(pa + 4);
;       } else {
;         ra[i] = *(const u32x4*)((const u16*)Ap + (size_t)(m0 + row) * lda + k0 + kc * 8);
;       }
;       rb[i] = *(const u32x4*)(Bt + (size_t)(n0 + row) * ldb + k0 + kc * 8);
;     }
;   };
;   auto swrite = [&](int buf) {
; #pragma unroll
;     for (int i = 0; i < 4; i++) {
;       const int c = tid + i * 256, row = c >> 3, kc = c & 7;
;       u32x4 va;
;       if (AF32) {
;         va = (u32x4){pack2(rfa[2 * i][0], rfa[2 * i][1]), pack2(rfa[2 * i][2], rfa[2 * i][3]),
;                      pack2(rfa[2 * i + 1][0], rfa[2 * i + 1][1]), pack2(rfa[2 * i + 1][2], rfa[2 * i + 1][3])};
;       } else {
;         va = ra[i];
;       }
;       *(u32x4*)(sA + buf * 9216 + row * 72 + kc * 8) = va;
;       *(u32x4*)(sB + buf * 9216 + row * 72 + kc * 8) = rb[i];
;     }
;   };
;   gload(0);
;   swrite(0);
;   if (nk > 1) gload(1);
;   __syncthreads();
; template <int EPI, bool AF32>
; DEV void gemm_phase(const void* A, int lda, const u16* Bt, int ldb, int M, int N, int K, const Epi& ea, char* smem) {
;   const int ntm = M >> 7, ntn = N >> 7;
;   for (int tile = bidx(); tile < ntm * ntn; tile += gdim()) {
;     int m, n;
;     tile_mn(tile, ntm, ntn, m, n);
;     gemm_tile<EPI, AF32>(A, lda, Bt, ldb, K, m << 7, n << 7, ea, smem);
.LBB0_164:
	s_mul_hi_i32 s6, s8, 0x2aaaaaab
	s_lshr_b32 s7, s6, 31
	s_ashr_i32 s6, s6, 5
	s_add_i32 s6, s6, s7
	s_lshl_b32 s10, s6, 5
	s_mul_i32 s7, s6, 0xc0
	s_sub_i32 s6, 0x104, s10
	s_min_u32 s11, s6, 32
	s_sub_i32 s9, s8, s7
	v_cvt_f32_ubyte0_e32 v2, s11
	v_cvt_f32_i32_e32 v0, s9
	v_rcp_iflag_f32_e32 v3, v2
	s_ashr_i32 s6, s9, 30
	s_or_b32 s12, s6, 1
	s_waitcnt vmcnt(12)
	v_mov_b32_e32 v114, v157
	v_mul_f32_e32 v3, v0, v3
	v_trunc_f32_e32 v3, v3
	v_fma_f32 v0, -v3, v2, v0
	v_cvt_i32_f32_e32 v3, v3
	v_cmp_ge_f32_e64 s[6:7], |v0|, v2
	s_and_b64 s[6:7], s[6:7], exec
	s_cselect_b32 s6, s12, 0
	v_readfirstlane_b32 s7, v3
	s_add_i32 s6, s7, s6
	s_sext_i32_i16 s7, s6
	s_mul_i32 s6, s6, s11
	s_sub_i32 s6, s9, s6
	s_sext_i32_i16 s6, s6
	s_add_i32 s10, s10, s6
	s_lshl_b32 s9, s10, 7
	s_lshl_b32 s10, s7, 7
	v_ashrrev_i32_e32 v8, 3, v114
	v_add_u32_e32 v2, s9, v8
	v_ashrrev_i32_e32 v3, 31, v2
	v_lshlrev_b32_e32 v0, 3, v114
	v_add_u32_e32 v4, 0x100, v114
	v_lshlrev_b64 v[58:59], 11, v[2:3]
	v_and_b32_e32 v0, 56, v0
	v_ashrrev_i32_e32 v9, 3, v4
	v_lshl_add_u64 v[2:3], s[60:61], 0, v[58:59]
	v_lshlrev_b32_e32 v0, 1, v0
	v_add_u32_e32 v4, s9, v9
	v_add_u32_e32 v6, 0x200, v114
	v_lshl_add_u64 v[14:15], v[2:3], 0, v[0:1]
	v_add_u32_e32 v2, s10, v8
	v_ashrrev_i32_e32 v5, 31, v4
	v_ashrrev_i32_e32 v10, 3, v6
	v_ashrrev_i32_e32 v3, 31, v2
	v_lshlrev_b64 v[62:63], 11, v[4:5]
	v_add_u32_e32 v6, s9, v10
	v_lshlrev_b64 v[60:61], 11, v[2:3]
	v_lshl_add_u64 v[4:5], s[60:61], 0, v[62:63]
	v_ashrrev_i32_e32 v7, 31, v6
	v_lshl_add_u64 v[2:3], s[2:3], 0, v[60:61]
	v_lshl_add_u64 v[16:17], v[4:5], 0, v[0:1]
	v_add_u32_e32 v4, s10, v9
	v_lshlrev_b64 v[66:67], 11, v[6:7]
	v_lshl_add_u64 v[2:3], v[2:3], 0, v[0:1]
	v_ashrrev_i32_e32 v5, 31, v4
	v_lshl_add_u64 v[6:7], s[60:61], 0, v[66:67]
	global_load_dwordx4 v[30:33], v[2:3], off
	v_lshlrev_b64 v[64:65], 11, v[4:5]
	v_lshl_add_u64 v[68:69], v[6:7], 0, v[0:1]
	v_add_u32_e32 v6, s10, v10
	global_load_dwordx4 v[26:29], v[14:15], off
	global_load_dwordx4 v[34:37], v[16:17], off
	v_lshl_add_u64 v[4:5], s[2:3], 0, v[64:65]
	v_ashrrev_i32_e32 v7, 31, v6
	v_lshl_add_u64 v[4:5], v[4:5], 0, v[0:1]
	v_lshlrev_b64 v[70:71], 11, v[6:7]
	global_load_dwordx4 v[38:41], v[4:5], off
	v_lshl_add_u64 v[6:7], s[2:3], 0, v[70:71]
	global_load_dwordx4 v[42:45], v[68:69], off
	v_lshl_add_u64 v[18:19], v[6:7], 0, v[0:1]
	global_load_dwordx4 v[46:49], v[18:19], off
	v_add_u32_e32 v6, 0x300, v114
	v_ashrrev_i32_e32 v80, 3, v6
	v_add_u32_e32 v6, s9, v80
	v_ashrrev_i32_e32 v7, 31, v6
	v_lshlrev_b64 v[72:73], 11, v[6:7]
	v_lshl_add_u64 v[6:7], s[60:61], 0, v[72:73]
	v_lshl_add_u64 v[74:75], v[6:7], 0, v[0:1]
	v_add_u32_e32 v6, s10, v80
	v_ashrrev_i32_e32 v7, 31, v6
	v_lshlrev_b64 v[76:77], 11, v[6:7]
	v_lshl_add_u64 v[6:7], s[2:3], 0, v[76:77]
	v_lshl_add_u64 v[78:79], v[6:7], 0, v[0:1]
	global_load_dwordx4 v[50:53], v[74:75], off
	global_load_dwordx4 v[54:57], v[78:79], off
	s_waitcnt vmcnt(19)
	v_mul_lo_u32 v118, v8, s71
	v_mul_lo_u32 v119, v9, s71
	s_waitcnt vmcnt(18)
	v_mul_lo_u32 v123, v10, s71
	global_load_dwordx4 v[6:9], v[2:3], off offset:128
	global_load_dwordx4 v[10:13], v[4:5], off offset:128
	s_nop 0
	global_load_dwordx4 v[2:5], v[18:19], off offset:128
	global_load_dwordx4 v[22:25], v[14:15], off offset:128
	s_nop 0
	global_load_dwordx4 v[18:21], v[16:17], off offset:128
	s_nop 0
	global_load_dwordx4 v[14:17], v[68:69], off offset:128
	v_bfe_u32 v161, v157, 3, 4
	v_add_u32_e32 v161, 4, v161
	v_lshlrev_b32_e32 v161, 1, v161
	v_and_b32_e32 v161, 16, v161
	v_xor_b32_e32 v129, v0, v161
	v_lshl_add_u32 v122, v118, 1, v129
	v_lshl_add_u32 v121, v119, 1, v129
	v_lshl_add_u32 v120, v123, 1, v129
	v_and_b32_e32 v115, 15, v114
	s_waitcnt vmcnt(23)
	v_mul_lo_u32 v126, v80, s71
	v_bfe_u32 v116, v114, 4, 2
	v_lshl_add_u32 v124, v126, 1, v129
	s_mov_b32 s11, 0
	v_lshlrev_b32_e32 v125, 4, v116
	v_and_b32_e32 v161, 15, v157
	v_add_u32_e32 v161, 4, v161
	v_lshlrev_b32_e32 v161, 1, v161
	v_and_b32_e32 v161, 16, v161
	v_xor_b32_e32 v125, v125, v161
	s_mov_b64 s[6:7], 0
	s_waitcnt vmcnt(13)
	ds_write_b128 v122, v[30:33] offset:36864
	s_waitcnt vmcnt(12)
	ds_write_b128 v122, v[26:29]
	s_waitcnt vmcnt(11)
	ds_write_b128 v121, v[34:37]
	s_waitcnt vmcnt(10)
	ds_write_b128 v121, v[38:41] offset:36864
	s_waitcnt vmcnt(9)
	ds_write_b128 v120, v[42:45]
	s_waitcnt vmcnt(8)
	ds_write_b128 v120, v[46:49] offset:36864
	global_load_dwordx4 v[26:29], v[74:75], off offset:128
	global_load_dwordx4 v[30:33], v[78:79], off offset:128
	v_ashrrev_i32_e32 v34, 1, v114
	v_and_b32_e32 v117, 0xffffffc0, v34
	v_or_b32_e32 v34, v117, v115
	v_mul_lo_u32 v128, v34, s71
	v_lshlrev_b32_e32 v34, 4, v114
	v_and_b32_e32 v34, 0x70, v34
	v_and_b32_e32 v35, 0x4f, v114
	v_or_b32_e32 v76, v76, v34
	v_or_b32_e32 v72, v72, v34
	v_or_b32_e32 v70, v70, v34
	v_or_b32_e32 v66, v66, v34
	v_or_b32_e32 v64, v64, v34
	v_or_b32_e32 v62, v62, v34
	v_or_b32_e32 v60, v60, v34
	v_or_b32_e32 v58, v58, v34
	v_mov_b32_e32 v34, 0
	s_waitcnt vmcnt(9)
	ds_write_b128 v124, v[50:53]
	s_waitcnt vmcnt(8)
	ds_write_b128 v124, v[54:57] offset:36864
	v_mul_u32_u24_e32 v127, 0x48, v35
	v_mov_b32_e32 v98, v76
	v_mov_b32_e32 v100, v72
	v_mov_b32_e32 v102, v70
	v_mov_b32_e32 v104, v66
	v_mov_b32_e32 v106, v64
	v_mov_b32_e32 v108, v62
	v_mov_b32_e32 v110, v60
	v_mov_b32_e32 v112, v58
	v_mov_b32_e32 v35, v34
	v_mov_b32_e32 v36, v34
	v_mov_b32_e32 v37, v34
	v_mov_b32_e32 v38, v34
	v_mov_b32_e32 v39, v34
	v_mov_b32_e32 v40, v34
	v_mov_b32_e32 v41, v34
	v_mov_b32_e32 v42, v34
	v_mov_b32_e32 v43, v34
	v_mov_b32_e32 v44, v34
	v_mov_b32_e32 v45, v34
	v_mov_b32_e32 v46, v34
	v_mov_b32_e32 v47, v34
	v_mov_b32_e32 v48, v34
	v_mov_b32_e32 v49, v34
	v_mov_b32_e32 v50, v34
	v_mov_b32_e32 v51, v34
	v_mov_b32_e32 v52, v34
	v_mov_b32_e32 v53, v34
	v_mov_b32_e32 v54, v34
	v_mov_b32_e32 v55, v34
	v_mov_b32_e32 v56, v34
	v_mov_b32_e32 v57, v34
	v_mov_b32_e32 v58, v34
	v_mov_b32_e32 v59, v34
	v_mov_b32_e32 v60, v34
	v_mov_b32_e32 v61, v34
	v_mov_b32_e32 v62, v34
	v_mov_b32_e32 v63, v34
	v_mov_b32_e32 v64, v34
	v_mov_b32_e32 v65, v34
	v_mov_b32_e32 v66, v34
	v_mov_b32_e32 v67, v34
	v_mov_b32_e32 v68, v34
	v_mov_b32_e32 v69, v34
	v_mov_b32_e32 v70, v34
	v_mov_b32_e32 v71, v34
	v_mov_b32_e32 v72, v34
	v_mov_b32_e32 v73, v34
	v_mov_b32_e32 v74, v34
	v_mov_b32_e32 v75, v34
	v_mov_b32_e32 v76, v34
	v_mov_b32_e32 v77, v34
	v_mov_b32_e32 v78, v34
	v_mov_b32_e32 v79, v34
	v_mov_b32_e32 v80, v34
	v_mov_b32_e32 v81, v34
	v_mov_b32_e32 v82, v34
	v_mov_b32_e32 v83, v34
	v_mov_b32_e32 v84, v34
	v_mov_b32_e32 v85, v34
	v_mov_b32_e32 v86, v34
	v_mov_b32_e32 v87, v34
	v_mov_b32_e32 v88, v34
	v_mov_b32_e32 v89, v34
	v_mov_b32_e32 v90, v34
	v_mov_b32_e32 v91, v34
	v_mov_b32_e32 v92, v34
	v_mov_b32_e32 v93, v34
	v_mov_b32_e32 v94, v34
	v_mov_b32_e32 v95, v34
	v_mov_b32_e32 v96, v34
	v_mov_b32_e32 v97, v34
	s_waitcnt lgkmcnt(0)
	s_barrier
; DEV f32x4 mfma16(bf16x8 a, bf16x8 b, f32x4 c) { return __builtin_amdgcn_mfma_f32_16x16x32_bf16(a, b, c, 0, 0, 0); }
; template <int EPI, bool AF32>
; DEV void gemm_tile(const void* Ap, int lda, const u16* Bt, int ldb, int K, int m0, int n0, const Epi& ea, char* smem) {
;     ...
;   auto gload = [&](int kt) {
;     const int k0 = kt << 6;
; #pragma unroll
;     for (int i = 0; i < 4; i++) {
;       const int c = tid + i * 256, row = c >> 3, kc = c & 7;
;       if (AF32) {
;         const float* pa = (const float*)Ap + (size_t)(m0 + row) * lda + k0 + kc * 8;
;         rfa[2 * i] = *(const f32x4*)pa;
;         rfa[2 * i + 1] = *(const f32x4*)(pa + 4);
;       } else {
;         ra[i] = *(const u32x4*)((const u16*)Ap + (size_t)(m0 + row) * lda + k0 + kc * 8);
;       }
;       rb[i] = *(const u32x4*)(Bt + (size_t)(n0 + row) * ldb + k0 + kc * 8);
;     }
;   };
;   auto swrite = [&](int buf) {
; #pragma unroll
;     for (int i = 0; i < 4; i++) {
;       const int c = tid + i * 256, row = c >> 3, kc = c & 7;
;       u32x4 va;
;       if (AF32) {
;         va = (u32x4){pack2(rfa[2 * i][0], rfa[2 * i][1]), pack2(rfa[2 * i][2], rfa[2 * i][3]),
;                      pack2(rfa[2 * i + 1][0], rfa[2 * i + 1][1]), pack2(rfa[2 * i + 1][2], rfa[2 * i + 1][3])};
;       } else {
;         va = ra[i];
;       }
;       *(u32x4*)(sA + buf * 9216 + row * 72 + kc * 8) = va;
;       *(u32x4*)(sB + buf * 9216 + row * 72 + kc * 8) = rb[i];
;     }
;   };
;   gload(0);
;   swrite(0);
;   if (nk > 1) gload(1);
;   __syncthreads();
;   for (int kt = 0; kt < nk; kt++) {
;     const int buf = kt & 1;
;     if (kt + 1 < nk) swrite(buf ^ 1);
;     if (kt + 2 < nk) gload(kt + 2);
; #pragma unroll
;     for (int ks = 0; ks < 2; ks++) {
;       bf16x8 a[4], b[4];
; #pragma unroll
;       for (int m = 0; m < 4; m++) a[m] = *(const bf16x8*)(sA + buf * 9216 + (wr * 64 + m * 16 + fr) * 72 + ks * 32 + fq * 8);
; #pragma unroll
;       for (int n = 0; n < 4; n++) b[n] = *(const bf16x8*)(sB + buf * 9216 + (wc * 64 + n * 16 + fr) * 72 + ks * 32 + fq * 8);
;       __builtin_amdgcn_s_setprio(1);
; #pragma unroll
;       for (int m = 0; m < 4; m++)
; #pragma unroll
;         for (int n = 0; n < 4; n++) acc[m][n] = mfma16(a[m], b[n], acc[m][n]);
;       __builtin_amdgcn_s_setprio(0);
;     }
;     __syncthreads();
	v_lshl_add_u32 v161, v128, 1, v125
	v_lshl_add_u32 v129, v127, 1, v125
	s_mov_b32 s11, 0
	s_mov_b64 s[6:7], 0x100
	ds_read_b128 v[130:133], v161
	ds_read_b128 v[134:137], v161 offset:2304
	ds_read_b128 v[138:141], v161 offset:4608
	ds_read_b128 v[142:145], v161 offset:6912
	ds_read_b128 v[146:149], v129 offset:36864
	ds_read_b128 v[150:153], v129 offset:39168
	ds_read_b128 v[162:165], v129 offset:41472
	ds_read_b128 v[166:169], v129 offset:43776
.Lgk0_loop:
	s_waitcnt lgkmcnt(0)
	ds_read_b128 v[222:225], v161 offset:64
	ds_read_b128 v[226:229], v161 offset:2368
	ds_read_b128 v[230:233], v161 offset:4672
	ds_read_b128 v[234:237], v161 offset:6976
	ds_read_b128 v[238:241], v129 offset:36928
	ds_read_b128 v[242:245], v129 offset:39232
	ds_read_b128 v[246:249], v129 offset:41536
	ds_read_b128 v[250:253], v129 offset:43840
	v_mfma_f32_16x16x32_bf16 v[94:97], v[130:133], v[146:149], v[94:97]
	v_mfma_f32_16x16x32_bf16 v[90:93], v[130:133], v[150:153], v[90:93]
	v_mfma_f32_16x16x32_bf16 v[86:89], v[130:133], v[162:165], v[86:89]
	v_mfma_f32_16x16x32_bf16 v[82:85], v[130:133], v[166:169], v[82:85]
	s_waitcnt vmcnt(0)
	ds_write_b128 v122, v[22:25] offset:18432
	ds_write_b128 v122, v[6:9] offset:55296
	v_mfma_f32_16x16x32_bf16 v[78:81], v[134:137], v[146:149], v[78:81]
	ds_write_b128 v121, v[18:21] offset:18432
	ds_write_b128 v121, v[10:13] offset:55296
	v_mfma_f32_16x16x32_bf16 v[74:77], v[134:137], v[150:153], v[74:77]
	ds_write_b128 v120, v[14:17] offset:18432
	ds_write_b128 v120, v[2:5] offset:55296
	v_mfma_f32_16x16x32_bf16 v[70:73], v[134:137], v[162:165], v[70:73]
	ds_write_b128 v124, v[26:29] offset:18432
	ds_write_b128 v124, v[30:33] offset:55296
	v_mfma_f32_16x16x32_bf16 v[66:69], v[134:137], v[166:169], v[66:69]
	global_load_dwordx4 v[22:25], v112, s[66:67]
	v_mfma_f32_16x16x32_bf16 v[62:65], v[138:141], v[146:149], v[62:65]
	global_load_dwordx4 v[6:9], v110, s[4:5]
	v_mfma_f32_16x16x32_bf16 v[58:61], v[138:141], v[150:153], v[58:61]
	global_load_dwordx4 v[18:21], v108, s[66:67]
	v_mfma_f32_16x16x32_bf16 v[54:57], v[138:141], v[162:165], v[54:57]
	global_load_dwordx4 v[10:13], v106, s[4:5]
	v_mfma_f32_16x16x32_bf16 v[50:53], v[138:141], v[166:169], v[50:53]
	global_load_dwordx4 v[14:17], v104, s[66:67]
	v_mfma_f32_16x16x32_bf16 v[46:49], v[142:145], v[146:149], v[46:49]
	global_load_dwordx4 v[2:5], v102, s[4:5]
	v_mfma_f32_16x16x32_bf16 v[42:45], v[142:145], v[150:153], v[42:45]
	global_load_dwordx4 v[26:29], v100, s[66:67]
	v_mfma_f32_16x16x32_bf16 v[38:41], v[142:145], v[162:165], v[38:41]
	global_load_dwordx4 v[30:33], v98, s[4:5]
	v_mfma_f32_16x16x32_bf16 v[34:37], v[142:145], v[166:169], v[34:37]
	s_waitcnt lgkmcnt(0)
	s_barrier
	ds_read_b128 v[130:133], v161 offset:18432
	v_mfma_f32_16x16x32_bf16 v[94:97], v[222:225], v[238:241], v[94:97]
	ds_read_b128 v[134:137], v161 offset:20736
	v_mfma_f32_16x16x32_bf16 v[90:93], v[222:225], v[242:245], v[90:93]
	ds_read_b128 v[138:141], v161 offset:23040
	v_mfma_f32_16x16x32_bf16 v[86:89], v[222:225], v[246:249], v[86:89]
	ds_read_b128 v[142:145], v161 offset:25344
	v_mfma_f32_16x16x32_bf16 v[82:85], v[222:225], v[250:253], v[82:85]
	ds_read_b128 v[146:149], v129 offset:55296
	v_mfma_f32_16x16x32_bf16 v[78:81], v[226:229], v[238:241], v[78:81]
	ds_read_b128 v[150:153], v129 offset:57600
	v_mfma_f32_16x16x32_bf16 v[74:77], v[226:229], v[242:245], v[74:77]
	ds_read_b128 v[162:165], v129 offset:59904
	v_mfma_f32_16x16x32_bf16 v[70:73], v[226:229], v[246:249], v[70:73]
	ds_read_b128 v[166:169], v129 offset:62208
	v_mfma_f32_16x16x32_bf16 v[66:69], v[226:229], v[250:253], v[66:69]
	v_mfma_f32_16x16x32_bf16 v[62:65], v[230:233], v[238:241], v[62:65]
	v_mfma_f32_16x16x32_bf16 v[58:61], v[230:233], v[242:245], v[58:61]
	v_mfma_f32_16x16x32_bf16 v[54:57], v[230:233], v[246:249], v[54:57]
	v_mfma_f32_16x16x32_bf16 v[50:53], v[230:233], v[250:253], v[50:53]
	v_mfma_f32_16x16x32_bf16 v[46:49], v[234:237], v[238:241], v[46:49]
	v_mfma_f32_16x16x32_bf16 v[42:45], v[234:237], v[242:245], v[42:45]
	v_mfma_f32_16x16x32_bf16 v[38:41], v[234:237], v[246:249], v[38:41]
	v_mfma_f32_16x16x32_bf16 v[34:37], v[234:237], v[250:253], v[34:37]
	s_waitcnt lgkmcnt(0)
	ds_read_b128 v[222:225], v161 offset:18496
	ds_read_b128 v[226:229], v161 offset:20800
	ds_read_b128 v[230:233], v161 offset:23104
	ds_read_b128 v[234:237], v161 offset:25408
	ds_read_b128 v[238:241], v129 offset:55360
	ds_read_b128 v[242:245], v129 offset:57664
	ds_read_b128 v[246:249], v129 offset:59968
	ds_read_b128 v[250:253], v129 offset:62272
	v_mfma_f32_16x16x32_bf16 v[94:97], v[130:133], v[146:149], v[94:97]
	v_mfma_f32_16x16x32_bf16 v[90:93], v[130:133], v[150:153], v[90:93]
	v_mfma_f32_16x16x32_bf16 v[86:89], v[130:133], v[162:165], v[86:89]
	v_mfma_f32_16x16x32_bf16 v[82:85], v[130:133], v[166:169], v[82:85]
	s_waitcnt vmcnt(0)
	ds_write_b128 v122, v[22:25]
	ds_write_b128 v122, v[6:9] offset:36864
	v_mfma_f32_16x16x32_bf16 v[78:81], v[134:137], v[146:149], v[78:81]
	ds_write_b128 v121, v[18:21]
	ds_write_b128 v121, v[10:13] offset:36864
	v_mfma_f32_16x16x32_bf16 v[74:77], v[134:137], v[150:153], v[74:77]
	ds_write_b128 v120, v[14:17]
	ds_write_b128 v120, v[2:5] offset:36864
	v_mfma_f32_16x16x32_bf16 v[70:73], v[134:137], v[162:165], v[70:73]
	ds_write_b128 v124, v[26:29]
	ds_write_b128 v124, v[30:33] offset:36864
	v_mfma_f32_16x16x32_bf16 v[66:69], v[134:137], v[166:169], v[66:69]
	global_load_dwordx4 v[22:25], v112, s[66:67] offset:128
	v_mfma_f32_16x16x32_bf16 v[62:65], v[138:141], v[146:149], v[62:65]
	global_load_dwordx4 v[6:9], v110, s[4:5] offset:128
	v_mfma_f32_16x16x32_bf16 v[58:61], v[138:141], v[150:153], v[58:61]
	global_load_dwordx4 v[18:21], v108, s[66:67] offset:128
	v_mfma_f32_16x16x32_bf16 v[54:57], v[138:141], v[162:165], v[54:57]
	global_load_dwordx4 v[10:13], v106, s[4:5] offset:128
	v_mfma_f32_16x16x32_bf16 v[50:53], v[138:141], v[166:169], v[50:53]
	global_load_dwordx4 v[14:17], v104, s[66:67] offset:128
	v_mfma_f32_16x16x32_bf16 v[46:49], v[142:145], v[146:149], v[46:49]
	global_load_dwordx4 v[2:5], v102, s[4:5] offset:128
	v_mfma_f32_16x16x32_bf16 v[42:45], v[142:145], v[150:153], v[42:45]
	global_load_dwordx4 v[26:29], v100, s[66:67] offset:128
	v_mfma_f32_16x16x32_bf16 v[38:41], v[142:145], v[162:165], v[38:41]
	global_load_dwordx4 v[30:33], v98, s[4:5] offset:128
	v_mfma_f32_16x16x32_bf16 v[34:37], v[142:145], v[166:169], v[34:37]
	s_waitcnt lgkmcnt(0)
	s_barrier
; DEV f32x4 mfma16(bf16x8 a, bf16x8 b, f32x4 c) { return __builtin_amdgcn_mfma_f32_16x16x32_bf16(a, b, c, 0, 0, 0); }
; template <int EPI, bool AF32>
; DEV void gemm_tile(const void* Ap, int lda, const u16* Bt, int ldb, int K, int m0, int n0, const Epi& ea, char* smem) {
;     ...
;   for (int kt = 0; kt < nk; kt++) {
;     const int buf = kt & 1;
;     if (kt + 1 < nk) swrite(buf ^ 1);
;     if (kt + 2 < nk) gload(kt + 2);
; #pragma unroll
;     for (int ks = 0; ks < 2; ks++) {
;       bf16x8 a[4], b[4];
; #pragma unroll
;       for (int m = 0; m < 4; m++) a[m] = *(const bf16x8*)(sA + buf * 9216 + (wr * 64 + m * 16 + fr) * 72 + ks * 32 + fq * 8);
; #pragma unroll
;       for (int n = 0; n < 4; n++) b[n] = *(const bf16x8*)(sB + buf * 9216 + (wc * 64 + n * 16 + fr) * 72 + ks * 32 + fq * 8);
;       __builtin_amdgcn_s_setprio(1);
; #pragma unroll
;       for (int m = 0; m < 4; m++)
; #pragma unroll
;         for (int n = 0; n < 4; n++) acc[m][n] = mfma16(a[m], b[n], acc[m][n]);
;       __builtin_amdgcn_s_setprio(0);
;     }
;     __syncthreads();
	ds_read_b128 v[130:133], v161
	v_mfma_f32_16x16x32_bf16 v[94:97], v[222:225], v[238:241], v[94:97]
	ds_read_b128 v[134:137], v161 offset:2304
	v_mfma_f32_16x16x32_bf16 v[90:93], v[222:225], v[242:245], v[90:93]
	ds_read_b128 v[138:141], v161 offset:4608
	v_mfma_f32_16x16x32_bf16 v[86:89], v[222:225], v[246:249], v[86:89]
	ds_read_b128 v[142:145], v161 offset:6912
	v_mfma_f32_16x16x32_bf16 v[82:85], v[222:225], v[250:253], v[82:85]
	ds_read_b128 v[146:149], v129 offset:36864
	v_mfma_f32_16x16x32_bf16 v[78:81], v[226:229], v[238:241], v[78:81]
	ds_read_b128 v[150:153], v129 offset:39168
	v_mfma_f32_16x16x32_bf16 v[74:77], v[226:229], v[242:245], v[74:77]
	ds_read_b128 v[162:165], v129 offset:41472
	v_mfma_f32_16x16x32_bf16 v[70:73], v[226:229], v[246:249], v[70:73]
	ds_read_b128 v[166:169], v129 offset:43776
	v_mfma_f32_16x16x32_bf16 v[66:69], v[226:229], v[250:253], v[66:69]
	v_mfma_f32_16x16x32_bf16 v[62:65], v[230:233], v[238:241], v[62:65]
	v_add_u32_e32 v112, 0x100, v112
	v_mfma_f32_16x16x32_bf16 v[58:61], v[230:233], v[242:245], v[58:61]
	v_add_u32_e32 v110, 0x100, v110
	v_mfma_f32_16x16x32_bf16 v[54:57], v[230:233], v[246:249], v[54:57]
	v_add_u32_e32 v108, 0x100, v108
	v_mfma_f32_16x16x32_bf16 v[50:53], v[230:233], v[250:253], v[50:53]
	v_add_u32_e32 v106, 0x100, v106
	v_mfma_f32_16x16x32_bf16 v[46:49], v[234:237], v[238:241], v[46:49]
	v_add_u32_e32 v104, 0x100, v104
	v_mfma_f32_16x16x32_bf16 v[42:45], v[234:237], v[242:245], v[42:45]
	v_add_u32_e32 v102, 0x100, v102
	v_mfma_f32_16x16x32_bf16 v[38:41], v[234:237], v[246:249], v[38:41]
	v_add_u32_e32 v100, 0x100, v100
	v_mfma_f32_16x16x32_bf16 v[34:37], v[234:237], v[250:253], v[34:37]
	v_add_u32_e32 v98, 0x100, v98
	s_add_i32 s11, s11, 1
	s_cmp_lg_u32 s11, 7
	s_cbranch_scc1 .Lgk0_loop
	s_waitcnt lgkmcnt(0)
	ds_read_b128 v[222:225], v161 offset:64
	ds_read_b128 v[226:229], v161 offset:2368
	ds_read_b128 v[230:233], v161 offset:4672
	ds_read_b128 v[234:237], v161 offset:6976
	ds_read_b128 v[238:241], v129 offset:36928
	ds_read_b128 v[242:245], v129 offset:39232
	ds_read_b128 v[246:249], v129 offset:41536
	ds_read_b128 v[250:253], v129 offset:43840
	v_mfma_f32_16x16x32_bf16 v[94:97], v[130:133], v[146:149], v[94:97]
	v_mfma_f32_16x16x32_bf16 v[90:93], v[130:133], v[150:153], v[90:93]
	v_mfma_f32_16x16x32_bf16 v[86:89], v[130:133], v[162:165], v[86:89]
	v_mfma_f32_16x16x32_bf16 v[82:85], v[130:133], v[166:169], v[82:85]
	s_waitcnt vmcnt(0)
	ds_write_b128 v122, v[22:25] offset:18432
	ds_write_b128 v122, v[6:9] offset:55296
	v_mfma_f32_16x16x32_bf16 v[78:81], v[134:137], v[146:149], v[78:81]
	ds_write_b128 v121, v[18:21] offset:18432
	ds_write_b128 v121, v[10:13] offset:55296
	v_mfma_f32_16x16x32_bf16 v[74:77], v[134:137], v[150:153], v[74:77]
	ds_write_b128 v120, v[14:17] offset:18432
	ds_write_b128 v120, v[2:5] offset:55296
	v_mfma_f32_16x16x32_bf16 v[70:73], v[134:137], v[162:165], v[70:73]
	ds_write_b128 v124, v[26:29] offset:18432
	ds_write_b128 v124, v[30:33] offset:55296
	v_mfma_f32_16x16x32_bf16 v[66:69], v[134:137], v[166:169], v[66:69]
	v_mfma_f32_16x16x32_bf16 v[62:65], v[138:141], v[146:149], v[62:65]
	v_mfma_f32_16x16x32_bf16 v[58:61], v[138:141], v[150:153], v[58:61]
	v_mfma_f32_16x16x32_bf16 v[54:57], v[138:141], v[162:165], v[54:57]
	v_mfma_f32_16x16x32_bf16 v[50:53], v[138:141], v[166:169], v[50:53]
	v_mfma_f32_16x16x32_bf16 v[46:49], v[142:145], v[146:149], v[46:49]
	v_mfma_f32_16x16x32_bf16 v[42:45], v[142:145], v[150:153], v[42:45]
	v_mfma_f32_16x16x32_bf16 v[38:41], v[142:145], v[162:165], v[38:41]
	v_mfma_f32_16x16x32_bf16 v[34:37], v[142:145], v[166:169], v[34:37]
	s_waitcnt lgkmcnt(0)
	s_barrier
	ds_read_b128 v[130:133], v161 offset:18432
	v_mfma_f32_16x16x32_bf16 v[94:97], v[222:225], v[238:241], v[94:97]
	ds_read_b128 v[134:137], v161 offset:20736
	v_mfma_f32_16x16x32_bf16 v[90:93], v[222:225], v[242:245], v[90:93]
	ds_read_b128 v[138:141], v161 offset:23040
	v_mfma_f32_16x16x32_bf16 v[86:89], v[222:225], v[246:249], v[86:89]
	ds_read_b128 v[142:145], v161 offset:25344
	v_mfma_f32_16x16x32_bf16 v[82:85], v[222:225], v[250:253], v[82:85]
	ds_read_b128 v[146:149], v129 offset:55296
	v_mfma_f32_16x16x32_bf16 v[78:81], v[226:229], v[238:241], v[78:81]
	ds_read_b128 v[150:153], v129 offset:57600
	v_mfma_f32_16x16x32_bf16 v[74:77], v[226:229], v[242:245], v[74:77]
	ds_read_b128 v[162:165], v129 offset:59904
	v_mfma_f32_16x16x32_bf16 v[70:73], v[226:229], v[246:249], v[70:73]
	ds_read_b128 v[166:169], v129 offset:62208
	v_mfma_f32_16x16x32_bf16 v[66:69], v[226:229], v[250:253], v[66:69]
	v_mfma_f32_16x16x32_bf16 v[62:65], v[230:233], v[238:241], v[62:65]
	v_mfma_f32_16x16x32_bf16 v[58:61], v[230:233], v[242:245], v[58:61]
	v_mfma_f32_16x16x32_bf16 v[54:57], v[230:233], v[246:249], v[54:57]
	v_mfma_f32_16x16x32_bf16 v[50:53], v[230:233], v[250:253], v[50:53]
	v_mfma_f32_16x16x32_bf16 v[46:49], v[234:237], v[238:241], v[46:49]
	v_mfma_f32_16x16x32_bf16 v[42:45], v[234:237], v[242:245], v[42:45]
	v_mfma_f32_16x16x32_bf16 v[38:41], v[234:237], v[246:249], v[38:41]
	v_mfma_f32_16x16x32_bf16 v[34:37], v[234:237], v[250:253], v[34:37]
	s_waitcnt lgkmcnt(0)
; template <int EPI, bool AF32>
; DEV void gemm_tile(const void* Ap, int lda, const u16* Bt, int ldb, int K, int m0, int n0, const Epi& ea, char* smem) {
;     ...
; #pragma unroll
;   for (int m = 0; m < 4; m++) {
; #pragma unroll
;     for (int j = 0; j < 4; j++) {
;       const int row = m0 + wr * 64 + m * 16 + fq * 4 + j;
;       if (EPI == EP_F32) {
;         float* C = (float*)ea.p0;
; #pragma unroll
;         for (int n = 0; n < 4; n++) C[(size_t)row * ea.ld + cb + n * 16 + fr] = acc[m][n][j];
	ds_read_b128 v[222:225], v161 offset:18496
	ds_read_b128 v[226:229], v161 offset:20800
	ds_read_b128 v[230:233], v161 offset:23104
	ds_read_b128 v[234:237], v161 offset:25408
	ds_read_b128 v[238:241], v129 offset:55360
	ds_read_b128 v[242:245], v129 offset:57664
	ds_read_b128 v[246:249], v129 offset:59968
	ds_read_b128 v[250:253], v129 offset:62272
	v_mfma_f32_16x16x32_bf16 v[94:97], v[130:133], v[146:149], v[94:97]
	v_mfma_f32_16x16x32_bf16 v[90:93], v[130:133], v[150:153], v[90:93]
	v_mfma_f32_16x16x32_bf16 v[86:89], v[130:133], v[162:165], v[86:89]
	v_mfma_f32_16x16x32_bf16 v[82:85], v[130:133], v[166:169], v[82:85]
	v_mfma_f32_16x16x32_bf16 v[78:81], v[134:137], v[146:149], v[78:81]
	v_mfma_f32_16x16x32_bf16 v[74:77], v[134:137], v[150:153], v[74:77]
	v_mfma_f32_16x16x32_bf16 v[70:73], v[134:137], v[162:165], v[70:73]
	v_mfma_f32_16x16x32_bf16 v[66:69], v[134:137], v[166:169], v[66:69]
	v_mfma_f32_16x16x32_bf16 v[62:65], v[138:141], v[146:149], v[62:65]
	v_mfma_f32_16x16x32_bf16 v[58:61], v[138:141], v[150:153], v[58:61]
	v_mfma_f32_16x16x32_bf16 v[54:57], v[138:141], v[162:165], v[54:57]
	v_mfma_f32_16x16x32_bf16 v[50:53], v[138:141], v[166:169], v[50:53]
	v_mfma_f32_16x16x32_bf16 v[46:49], v[142:145], v[146:149], v[46:49]
	v_mfma_f32_16x16x32_bf16 v[42:45], v[142:145], v[150:153], v[42:45]
	v_mfma_f32_16x16x32_bf16 v[38:41], v[142:145], v[162:165], v[38:41]
	v_mfma_f32_16x16x32_bf16 v[34:37], v[142:145], v[166:169], v[34:37]
	s_waitcnt lgkmcnt(0)
	v_mfma_f32_16x16x32_bf16 v[94:97], v[222:225], v[238:241], v[94:97]
	v_mfma_f32_16x16x32_bf16 v[90:93], v[222:225], v[242:245], v[90:93]
	v_mfma_f32_16x16x32_bf16 v[86:89], v[222:225], v[246:249], v[86:89]
	v_mfma_f32_16x16x32_bf16 v[2:5], v[222:225], v[250:253], v[82:85]
	v_mfma_f32_16x16x32_bf16 v[30:33], v[226:229], v[238:241], v[78:81]
	v_mfma_f32_16x16x32_bf16 v[6:9], v[226:229], v[250:253], v[66:69]
	v_mfma_f32_16x16x32_bf16 v[10:13], v[230:233], v[250:253], v[50:53]
	v_mfma_f32_16x16x32_bf16 v[18:21], v[234:237], v[238:241], v[46:49]
	v_mfma_f32_16x16x32_bf16 v[22:25], v[234:237], v[242:245], v[42:45]
	v_mfma_f32_16x16x32_bf16 v[26:29], v[234:237], v[246:249], v[38:41]
	v_mfma_f32_16x16x32_bf16 v[14:17], v[234:237], v[250:253], v[34:37]
	v_mfma_f32_16x16x32_bf16 v[38:41], v[226:229], v[242:245], v[74:77]
	v_mfma_f32_16x16x32_bf16 v[46:49], v[226:229], v[246:249], v[70:73]
	v_mfma_f32_16x16x32_bf16 v[34:37], v[230:233], v[238:241], v[62:65]
	v_mfma_f32_16x16x32_bf16 v[42:45], v[230:233], v[242:245], v[58:61]
	v_mfma_f32_16x16x32_bf16 v[50:53], v[230:233], v[246:249], v[54:57]
	s_nop 7
	v_and_or_b32 v54, v114, 64, s10
	v_add_u32_e32 v0, s9, v117
	v_ashrrev_i32_e32 v55, 31, v54
	v_lshl_or_b32 v58, v116, 2, v0
	v_lshl_add_u64 v[54:55], v[54:55], 2, s[0:1]
	v_lshlrev_b32_e32 v0, 2, v115
	v_lshl_add_u64 v[54:55], v[54:55], 0, v[0:1]
	v_mad_i64_i32 v[56:57], s[6:7], v58, s68, v[54:55]
	v_or_b32_e32 v0, 1, v58
	s_barrier
	global_store_dword v[56:57], v94, off
	global_store_dword v[56:57], v90, off offset:64
	global_store_dword v[56:57], v86, off offset:128
	global_store_dword v[56:57], v2, off offset:192
	v_mad_i64_i32 v[56:57], s[6:7], v0, s68, v[54:55]
	v_or_b32_e32 v0, 2, v58
	global_store_dword v[56:57], v95, off
	global_store_dword v[56:57], v91, off offset:64
	global_store_dword v[56:57], v87, off offset:128
	global_store_dword v[56:57], v3, off offset:192
	v_mad_i64_i32 v[2:3], s[6:7], v0, s68, v[54:55]
	v_or_b32_e32 v0, 3, v58
	global_store_dword v[2:3], v96, off
	global_store_dword v[2:3], v92, off offset:64
	global_store_dword v[2:3], v88, off offset:128
	global_store_dword v[2:3], v4, off offset:192
	v_mad_i64_i32 v[2:3], s[6:7], v0, s68, v[54:55]
	v_or_b32_e32 v0, 16, v58
	global_store_dword v[2:3], v97, off
	global_store_dword v[2:3], v93, off offset:64
	global_store_dword v[2:3], v89, off offset:128
	global_store_dword v[2:3], v5, off offset:192
	v_mad_i64_i32 v[2:3], s[6:7], v0, s68, v[54:55]
	v_or_b32_e32 v0, 17, v58
	global_store_dword v[2:3], v30, off
	global_store_dword v[2:3], v38, off offset:64
	global_store_dword v[2:3], v46, off offset:128
	global_store_dword v[2:3], v6, off offset:192
	v_mad_i64_i32 v[2:3], s[6:7], v0, s68, v[54:55]
	v_or_b32_e32 v0, 18, v58
	global_store_dword v[2:3], v31, off
	global_store_dword v[2:3], v39, off offset:64
	global_store_dword v[2:3], v47, off offset:128
	global_store_dword v[2:3], v7, off offset:192
	v_mad_i64_i32 v[2:3], s[6:7], v0, s68, v[54:55]
	v_or_b32_e32 v0, 19, v58
	global_store_dword v[2:3], v32, off
	global_store_dword v[2:3], v40, off offset:64
	global_store_dword v[2:3], v48, off offset:128
	global_store_dword v[2:3], v8, off offset:192
	v_mad_i64_i32 v[2:3], s[6:7], v0, s68, v[54:55]
	v_or_b32_e32 v0, 32, v58
	global_store_dword v[2:3], v33, off
	global_store_dword v[2:3], v41, off offset:64
	global_store_dword v[2:3], v49, off offset:128
	global_store_dword v[2:3], v9, off offset:192
	v_mad_i64_i32 v[2:3], s[6:7], v0, s68, v[54:55]
	v_or_b32_e32 v0, 33, v58
	global_store_dword v[2:3], v34, off
	global_store_dword v[2:3], v42, off offset:64
	global_store_dword v[2:3], v50, off offset:128
	global_store_dword v[2:3], v10, off offset:192
	v_mad_i64_i32 v[2:3], s[6:7], v0, s68, v[54:55]
	v_or_b32_e32 v0, 34, v58
	global_store_dword v[2:3], v35, off
	global_store_dword v[2:3], v43, off offset:64
	global_store_dword v[2:3], v51, off offset:128
	global_store_dword v[2:3], v11, off offset:192
	v_mad_i64_i32 v[2:3], s[6:7], v0, s68, v[54:55]
	v_or_b32_e32 v0, 35, v58
	global_store_dword v[2:3], v36, off
	global_store_dword v[2:3], v44, off offset:64
	global_store_dword v[2:3], v52, off offset:128
	global_store_dword v[2:3], v12, off offset:192
	v_mad_i64_i32 v[2:3], s[6:7], v0, s68, v[54:55]
	v_or_b32_e32 v0, 48, v58
	global_store_dword v[2:3], v37, off
	global_store_dword v[2:3], v45, off offset:64
	global_store_dword v[2:3], v53, off offset:128
	global_store_dword v[2:3], v13, off offset:192
	v_mad_i64_i32 v[2:3], s[6:7], v0, s68, v[54:55]
	v_or_b32_e32 v0, 49, v58
	global_store_dword v[2:3], v18, off
	global_store_dword v[2:3], v22, off offset:64
	global_store_dword v[2:3], v26, off offset:128
	global_store_dword v[2:3], v14, off offset:192
	v_mad_i64_i32 v[2:3], s[6:7], v0, s68, v[54:55]
	v_or_b32_e32 v0, 50, v58
	global_store_dword v[2:3], v19, off
	global_store_dword v[2:3], v23, off offset:64
	global_store_dword v[2:3], v27, off offset:128
	global_store_dword v[2:3], v15, off offset:192
	v_mad_i64_i32 v[2:3], s[6:7], v0, s68, v[54:55]
	v_or_b32_e32 v0, 51, v58
	global_store_dword v[2:3], v20, off
	global_store_dword v[2:3], v24, off offset:64
	global_store_dword v[2:3], v28, off offset:128
	global_store_dword v[2:3], v16, off offset:192
	v_mad_i64_i32 v[2:3], s[6:7], v0, s68, v[54:55]
	v_readfirstlane_b32 s6, v198
	global_store_dword v[2:3], v21, off
	global_store_dword v[2:3], v25, off offset:64
	global_store_dword v[2:3], v29, off offset:128
	global_store_dword v[2:3], v17, off offset:192
	s_add_i32 s8, s6, s8
	s_cmpk_lt_i32 s8, 0x618
	s_cbranch_scc1 .LBB0_164

; DEV int bidx() { int b = __builtin_amdgcn_readfirstlane(blockIdx.x); asm volatile("" : "+s"(b)); return b; }
; DEV int gdim() { int g = __builtin_amdgcn_readfirstlane(gridDim.x); asm volatile("" : "+s"(g)); return g; }
; template <int EPI, bool AF32>
; DEV void gemm_tile(const void* Ap, int lda, const u16* Bt, int ldb, int K, int m0, int n0, const Epi& ea, char* smem) {
;     ...
;   f32x4 acc[4][4];
; #pragma unroll
;   for (int m = 0; m < 4; m++)
; #pragma unroll
;     for (int n = 0; n < 4; n++) acc[m][n] = (f32x4){0.f, 0.f, 0.f, 0.f};
;   u32x4 ra[4], rb[4];
;   f32x4 rfa[8];
;   const int nk = K >> 6;
;   auto gload = [&](int kt) {
;     const int k0 = kt << 6;
; #pragma unroll
;     for (int i = 0; i < 4; i++) {
;       const int c = tid + i * 256, row = c >> 3, kc = c & 7;
;       if (AF32) {
;         const float* pa = (const float*)Ap + (size_t)(m0 + row) * lda + k0 + kc * 8;
;         rfa[2 * i] = *(const f32x4*)pa;
;         rfa[2 * i + 1] = *(const f32x4*)(pa + 4);
;       } else {
;         ra[i] = *(const u32x4*)((const u16*)Ap + (size_t)(m0 + row) * lda + k0 + kc * 8);
;       }
;       rb[i] = *(const u32x4*)(Bt + (size_t)(n0 + row) * ldb + k0 + kc * 8);
;     }
;   };
;   auto swrite = [&](int buf) {
; #pragma unroll
;     for (int i = 0; i < 4; i++) {
;       const int c = tid + i * 256, row = c >> 3, kc = c & 7;
;       u32x4 va;
;       if (AF32) {
;         va = (u32x4){pack2(rfa[2 * i][0], rfa[2 * i][1]), pack2(rfa[2 * i][2], rfa[2 * i][3]),
;                      pack2(rfa[2 * i + 1][0], rfa[2 * i + 1][1]), pack2(rfa[2 * i + 1][2], rfa[2 * i + 1][3])};
;       } else {
;         va = ra[i];
;       }
;       *(u32x4*)(sA + buf * 9216 + row * 72 + kc * 8) = va;
;       *(u32x4*)(sB + buf * 9216 + row * 72 + kc * 8) = rb[i];
;     }
;   };
;   gload(0);
;   swrite(0);
;   if (nk > 1) gload(1);
;   __syncthreads();
; template <int EPI, bool AF32>
; DEV void gemm_phase(const void* A, int lda, const u16* Bt, int ldb, int M, int N, int K, const Epi& ea, char* smem) {
;   const int ntm = M >> 7, ntn = N >> 7;
;   for (int tile = bidx(); tile < ntm * ntn; tile += gdim()) {
;     int m, n;
;     tile_mn(tile, ntm, ntn, m, n);
;     gemm_tile<EPI, AF32>(A, lda, Bt, ldb, K, m << 7, n << 7, ea, smem);
.LBB0_547:
	s_ashr_i32 s0, s26, 31
	s_lshr_b32 s0, s0, 22
	s_add_i32 s0, s26, s0
	s_ashr_i32 s1, s0, 10
	s_and_b32 s0, s0, 0xfffffc00
	s_lshl_b32 s3, s1, 5
	s_sub_i32 s2, s26, s0
	s_sub_i32 s0, 0x104, s3
	s_min_u32 s4, s0, 32
	v_cvt_f32_ubyte0_e32 v2, s4
	v_cvt_f32_i32_e32 v0, s2
	v_rcp_iflag_f32_e32 v3, v2
	s_ashr_i32 s0, s2, 30
	s_or_b32 s5, s0, 1
	s_waitcnt vmcnt(12)
	v_mov_b32_e32 v114, v157
	v_mul_f32_e32 v3, v0, v3
	v_trunc_f32_e32 v3, v3
	v_fma_f32 v0, -v3, v2, v0
	v_cvt_i32_f32_e32 v3, v3
	v_cmp_ge_f32_e64 s[0:1], |v0|, v2
	s_and_b64 s[0:1], s[0:1], exec
	s_cselect_b32 s0, s5, 0
	v_readfirstlane_b32 s1, v3
	s_add_i32 s0, s1, s0
	s_sext_i32_i16 s29, s0
	s_mul_i32 s0, s0, s4
	s_sub_i32 s0, s2, s0
	s_sext_i32_i16 s0, s0
	s_add_i32 s3, s3, s0
	s_lshl_b32 s2, s3, 7
	s_lshl_b32 s3, s29, 7
	v_ashrrev_i32_e32 v8, 3, v114
	v_add_u32_e32 v2, s2, v8
	v_ashrrev_i32_e32 v3, 31, v2
	v_lshlrev_b32_e32 v0, 3, v114
	v_add_u32_e32 v4, 0x100, v114
	v_lshlrev_b64 v[58:59], 11, v[2:3]
	v_and_b32_e32 v0, 56, v0
	v_ashrrev_i32_e32 v9, 3, v4
	v_lshl_add_u64 v[2:3], s[60:61], 0, v[58:59]
	v_lshlrev_b32_e32 v0, 1, v0
	v_add_u32_e32 v4, s2, v9
	v_add_u32_e32 v6, 0x200, v114
	v_lshl_add_u64 v[14:15], v[2:3], 0, v[0:1]
	v_add_u32_e32 v2, s3, v8
	v_ashrrev_i32_e32 v5, 31, v4
	v_ashrrev_i32_e32 v10, 3, v6
	v_ashrrev_i32_e32 v3, 31, v2
	v_lshlrev_b64 v[62:63], 11, v[4:5]
	v_add_u32_e32 v6, s2, v10
	v_lshlrev_b64 v[60:61], 11, v[2:3]
	v_lshl_add_u64 v[4:5], s[60:61], 0, v[62:63]
	v_ashrrev_i32_e32 v7, 31, v6
	v_lshl_add_u64 v[2:3], s[12:13], 0, v[60:61]
	v_lshl_add_u64 v[16:17], v[4:5], 0, v[0:1]
	v_add_u32_e32 v4, s3, v9
	v_lshlrev_b64 v[66:67], 11, v[6:7]
	v_lshl_add_u64 v[2:3], v[2:3], 0, v[0:1]
	v_ashrrev_i32_e32 v5, 31, v4
	v_lshl_add_u64 v[6:7], s[60:61], 0, v[66:67]
	global_load_dwordx4 v[30:33], v[2:3], off
	v_lshlrev_b64 v[64:65], 11, v[4:5]
	v_lshl_add_u64 v[68:69], v[6:7], 0, v[0:1]
	v_add_u32_e32 v6, s3, v10
	global_load_dwordx4 v[26:29], v[14:15], off
	global_load_dwordx4 v[34:37], v[16:17], off
	v_lshl_add_u64 v[4:5], s[12:13], 0, v[64:65]
	v_ashrrev_i32_e32 v7, 31, v6
	v_lshl_add_u64 v[4:5], v[4:5], 0, v[0:1]
	v_lshlrev_b64 v[70:71], 11, v[6:7]
	global_load_dwordx4 v[38:41], v[4:5], off
	v_lshl_add_u64 v[6:7], s[12:13], 0, v[70:71]
	global_load_dwordx4 v[42:45], v[68:69], off
	v_lshl_add_u64 v[18:19], v[6:7], 0, v[0:1]
	global_load_dwordx4 v[46:49], v[18:19], off
	v_add_u32_e32 v6, 0x300, v114
	v_ashrrev_i32_e32 v80, 3, v6
	v_add_u32_e32 v6, s2, v80
	v_ashrrev_i32_e32 v7, 31, v6
	v_lshlrev_b64 v[72:73], 11, v[6:7]
	v_lshl_add_u64 v[6:7], s[60:61], 0, v[72:73]
	v_lshl_add_u64 v[74:75], v[6:7], 0, v[0:1]
	v_add_u32_e32 v6, s3, v80
	v_ashrrev_i32_e32 v7, 31, v6
	v_lshlrev_b64 v[76:77], 11, v[6:7]
	v_lshl_add_u64 v[6:7], s[12:13], 0, v[76:77]
	v_lshl_add_u64 v[78:79], v[6:7], 0, v[0:1]
	global_load_dwordx4 v[50:53], v[74:75], off
	global_load_dwordx4 v[54:57], v[78:79], off
	s_waitcnt vmcnt(19)
	v_mul_lo_u32 v118, v8, s71
	v_mul_lo_u32 v119, v9, s71
	s_waitcnt vmcnt(18)
	v_mul_lo_u32 v123, v10, s71
	global_load_dwordx4 v[6:9], v[2:3], off offset:128
	global_load_dwordx4 v[10:13], v[4:5], off offset:128
	s_nop 0
	global_load_dwordx4 v[2:5], v[18:19], off offset:128
	global_load_dwordx4 v[22:25], v[14:15], off offset:128
	s_nop 0
	global_load_dwordx4 v[18:21], v[16:17], off offset:128
	s_nop 0
	global_load_dwordx4 v[14:17], v[68:69], off offset:128
	v_bfe_u32 v161, v157, 3, 4
	v_add_u32_e32 v161, 4, v161
	v_lshlrev_b32_e32 v161, 1, v161
	v_and_b32_e32 v161, 16, v161
	v_xor_b32_e32 v129, v0, v161
	v_lshl_add_u32 v122, v118, 1, v129
	v_lshl_add_u32 v121, v119, 1, v129
	v_lshl_add_u32 v120, v123, 1, v129
	v_and_b32_e32 v116, 15, v114
	s_waitcnt vmcnt(23)
	v_mul_lo_u32 v126, v80, s71
	v_bfe_u32 v115, v114, 4, 2
	v_lshl_add_u32 v124, v126, 1, v129
	s_mov_b32 s4, 0
	v_lshlrev_b32_e32 v125, 4, v115
	v_and_b32_e32 v161, 15, v157
	v_add_u32_e32 v161, 4, v161
	v_lshlrev_b32_e32 v161, 1, v161
	v_and_b32_e32 v161, 16, v161
	v_xor_b32_e32 v125, v125, v161
	s_mov_b64 s[0:1], 0
	s_waitcnt vmcnt(13)
	ds_write_b128 v122, v[30:33] offset:36864
	s_waitcnt vmcnt(12)
	ds_write_b128 v122, v[26:29]
	s_waitcnt vmcnt(11)
	ds_write_b128 v121, v[34:37]
	s_waitcnt vmcnt(10)
	ds_write_b128 v121, v[38:41] offset:36864
	s_waitcnt vmcnt(9)
	ds_write_b128 v120, v[42:45]
	s_waitcnt vmcnt(8)
	ds_write_b128 v120, v[46:49] offset:36864
	global_load_dwordx4 v[26:29], v[74:75], off offset:128
	global_load_dwordx4 v[30:33], v[78:79], off offset:128
	v_ashrrev_i32_e32 v34, 1, v114
	v_and_b32_e32 v117, 0xffffffc0, v34
	v_or_b32_e32 v34, v117, v116
	v_mul_lo_u32 v128, v34, s71
	v_lshlrev_b32_e32 v34, 4, v114
	v_and_b32_e32 v34, 0x70, v34
	v_and_b32_e32 v35, 0x4f, v114
	v_or_b32_e32 v76, v76, v34
	v_or_b32_e32 v72, v72, v34
	v_or_b32_e32 v70, v70, v34
	v_or_b32_e32 v66, v66, v34
	v_or_b32_e32 v64, v64, v34
	v_or_b32_e32 v62, v62, v34
	v_or_b32_e32 v60, v60, v34
	v_or_b32_e32 v58, v58, v34
	v_mov_b32_e32 v34, 0
	s_waitcnt vmcnt(9)
	ds_write_b128 v124, v[50:53]
	s_waitcnt vmcnt(8)
	ds_write_b128 v124, v[54:57] offset:36864
	v_mul_u32_u24_e32 v127, 0x48, v35
	v_mov_b32_e32 v98, v76
	v_mov_b32_e32 v100, v72
	v_mov_b32_e32 v102, v70
	v_mov_b32_e32 v104, v66
	v_mov_b32_e32 v106, v64
	v_mov_b32_e32 v108, v62
	v_mov_b32_e32 v110, v60
	v_mov_b32_e32 v112, v58
	v_mov_b32_e32 v35, v34
	v_mov_b32_e32 v36, v34
	v_mov_b32_e32 v37, v34
	v_mov_b32_e32 v38, v34
	v_mov_b32_e32 v39, v34
	v_mov_b32_e32 v40, v34
	v_mov_b32_e32 v41, v34
	v_mov_b32_e32 v42, v34
	v_mov_b32_e32 v43, v34
	v_mov_b32_e32 v44, v34
	v_mov_b32_e32 v45, v34
	v_mov_b32_e32 v46, v34
	v_mov_b32_e32 v47, v34
	v_mov_b32_e32 v48, v34
	v_mov_b32_e32 v49, v34
	v_mov_b32_e32 v50, v34
	v_mov_b32_e32 v51, v34
	v_mov_b32_e32 v52, v34
	v_mov_b32_e32 v53, v34
	v_mov_b32_e32 v54, v34
	v_mov_b32_e32 v55, v34
	v_mov_b32_e32 v56, v34
	v_mov_b32_e32 v57, v34
	v_mov_b32_e32 v58, v34
	v_mov_b32_e32 v59, v34
	v_mov_b32_e32 v60, v34
	v_mov_b32_e32 v61, v34
	v_mov_b32_e32 v62, v34
	v_mov_b32_e32 v63, v34
	v_mov_b32_e32 v64, v34
	v_mov_b32_e32 v65, v34
	v_mov_b32_e32 v66, v34
	v_mov_b32_e32 v67, v34
	v_mov_b32_e32 v68, v34
	v_mov_b32_e32 v69, v34
	v_mov_b32_e32 v70, v34
	v_mov_b32_e32 v71, v34
	v_mov_b32_e32 v72, v34
	v_mov_b32_e32 v73, v34
	v_mov_b32_e32 v74, v34
	v_mov_b32_e32 v75, v34
	v_mov_b32_e32 v76, v34
	v_mov_b32_e32 v77, v34
	v_mov_b32_e32 v78, v34
	v_mov_b32_e32 v79, v34
	v_mov_b32_e32 v80, v34
	v_mov_b32_e32 v81, v34
	v_mov_b32_e32 v82, v34
	v_mov_b32_e32 v83, v34
	v_mov_b32_e32 v84, v34
	v_mov_b32_e32 v85, v34
	v_mov_b32_e32 v86, v34
	v_mov_b32_e32 v87, v34
	v_mov_b32_e32 v88, v34
	v_mov_b32_e32 v89, v34
	v_mov_b32_e32 v90, v34
	v_mov_b32_e32 v91, v34
	v_mov_b32_e32 v92, v34
	v_mov_b32_e32 v93, v34
	v_mov_b32_e32 v94, v34
	v_mov_b32_e32 v95, v34
	v_mov_b32_e32 v96, v34
	v_mov_b32_e32 v97, v34
	s_waitcnt lgkmcnt(0)
	s_barrier
; DEV f32x4 mfma16(bf16x8 a, bf16x8 b, f32x4 c) { return __builtin_amdgcn_mfma_f32_16x16x32_bf16(a, b, c, 0, 0, 0); }
; template <int EPI, bool AF32>
; DEV void gemm_tile(const void* Ap, int lda, const u16* Bt, int ldb, int K, int m0, int n0, const Epi& ea, char* smem) {
;     ...
;   auto gload = [&](int kt) {
;     const int k0 = kt << 6;
; #pragma unroll
;     for (int i = 0; i < 4; i++) {
;       const int c = tid + i * 256, row = c >> 3, kc = c & 7;
;       if (AF32) {
;         const float* pa = (const float*)Ap + (size_t)(m0 + row) * lda + k0 + kc * 8;
;         rfa[2 * i] = *(const f32x4*)pa;
;         rfa[2 * i + 1] = *(const f32x4*)(pa + 4);
;       } else {
;         ra[i] = *(const u32x4*)((const u16*)Ap + (size_t)(m0 + row) * lda + k0 + kc * 8);
;       }
;       rb[i] = *(const u32x4*)(Bt + (size_t)(n0 + row) * ldb + k0 + kc * 8);
;     }
;   };
;   auto swrite = [&](int buf) {
; #pragma unroll
;     for (int i = 0; i < 4; i++) {
;       const int c = tid + i * 256, row = c >> 3, kc = c & 7;
;       u32x4 va;
;       if (AF32) {
;         va = (u32x4){pack2(rfa[2 * i][0], rfa[2 * i][1]), pack2(rfa[2 * i][2], rfa[2 * i][3]),
;                      pack2(rfa[2 * i + 1][0], rfa[2 * i + 1][1]), pack2(rfa[2 * i + 1][2], rfa[2 * i + 1][3])};
;       } else {
;         va = ra[i];
;       }
;       *(u32x4*)(sA + buf * 9216 + row * 72 + kc * 8) = va;
;       *(u32x4*)(sB + buf * 9216 + row * 72 + kc * 8) = rb[i];
;     }
;   };
;   gload(0);
;   swrite(0);
;   if (nk > 1) gload(1);
;   __syncthreads();
;   for (int kt = 0; kt < nk; kt++) {
;     const int buf = kt & 1;
;     if (kt + 1 < nk) swrite(buf ^ 1);
;     if (kt + 2 < nk) gload(kt + 2);
; #pragma unroll
;     for (int ks = 0; ks < 2; ks++) {
;       bf16x8 a[4], b[4];
; #pragma unroll
;       for (int m = 0; m < 4; m++) a[m] = *(const bf16x8*)(sA + buf * 9216 + (wr * 64 + m * 16 + fr) * 72 + ks * 32 + fq * 8);
; #pragma unroll
;       for (int n = 0; n < 4; n++) b[n] = *(const bf16x8*)(sB + buf * 9216 + (wc * 64 + n * 16 + fr) * 72 + ks * 32 + fq * 8);
;       __builtin_amdgcn_s_setprio(1);
; #pragma unroll
;       for (int m = 0; m < 4; m++)
; #pragma unroll
;         for (int n = 0; n < 4; n++) acc[m][n] = mfma16(a[m], b[n], acc[m][n]);
;       __builtin_amdgcn_s_setprio(0);
;     }
;     __syncthreads();
	v_lshl_add_u32 v161, v128, 1, v125
	v_lshl_add_u32 v129, v127, 1, v125
	s_mov_b32 s4, 0
	s_mov_b64 s[0:1], 0x100
	ds_read_b128 v[130:133], v161
	ds_read_b128 v[134:137], v161 offset:2304
	ds_read_b128 v[138:141], v161 offset:4608
	ds_read_b128 v[142:145], v161 offset:6912
	ds_read_b128 v[146:149], v129 offset:36864
	ds_read_b128 v[150:153], v129 offset:39168
	ds_read_b128 v[162:165], v129 offset:41472
	ds_read_b128 v[166:169], v129 offset:43776
.Lgk1_loop:
	s_waitcnt lgkmcnt(0)
	ds_read_b128 v[222:225], v161 offset:64
	ds_read_b128 v[226:229], v161 offset:2368
	ds_read_b128 v[230:233], v161 offset:4672
	ds_read_b128 v[234:237], v161 offset:6976
	ds_read_b128 v[238:241], v129 offset:36928
	ds_read_b128 v[242:245], v129 offset:39232
	ds_read_b128 v[246:249], v129 offset:41536
	ds_read_b128 v[250:253], v129 offset:43840
	v_mfma_f32_16x16x32_bf16 v[94:97], v[130:133], v[146:149], v[94:97]
	v_mfma_f32_16x16x32_bf16 v[90:93], v[130:133], v[150:153], v[90:93]
	v_mfma_f32_16x16x32_bf16 v[86:89], v[130:133], v[162:165], v[86:89]
	v_mfma_f32_16x16x32_bf16 v[82:85], v[130:133], v[166:169], v[82:85]
	s_waitcnt vmcnt(0)
	ds_write_b128 v122, v[22:25] offset:18432
	ds_write_b128 v122, v[6:9] offset:55296
	v_mfma_f32_16x16x32_bf16 v[78:81], v[134:137], v[146:149], v[78:81]
	ds_write_b128 v121, v[18:21] offset:18432
	ds_write_b128 v121, v[10:13] offset:55296
	v_mfma_f32_16x16x32_bf16 v[74:77], v[134:137], v[150:153], v[74:77]
	ds_write_b128 v120, v[14:17] offset:18432
	ds_write_b128 v120, v[2:5] offset:55296
	v_mfma_f32_16x16x32_bf16 v[70:73], v[134:137], v[162:165], v[70:73]
	ds_write_b128 v124, v[26:29] offset:18432
	ds_write_b128 v124, v[30:33] offset:55296
	v_mfma_f32_16x16x32_bf16 v[66:69], v[134:137], v[166:169], v[66:69]
	global_load_dwordx4 v[22:25], v112, s[66:67]
	v_mfma_f32_16x16x32_bf16 v[62:65], v[138:141], v[146:149], v[62:65]
	global_load_dwordx4 v[6:9], v110, s[20:21]
	v_mfma_f32_16x16x32_bf16 v[58:61], v[138:141], v[150:153], v[58:61]
	global_load_dwordx4 v[18:21], v108, s[66:67]
	v_mfma_f32_16x16x32_bf16 v[54:57], v[138:141], v[162:165], v[54:57]
	global_load_dwordx4 v[10:13], v106, s[20:21]
	v_mfma_f32_16x16x32_bf16 v[50:53], v[138:141], v[166:169], v[50:53]
	global_load_dwordx4 v[14:17], v104, s[66:67]
	v_mfma_f32_16x16x32_bf16 v[46:49], v[142:145], v[146:149], v[46:49]
	global_load_dwordx4 v[2:5], v102, s[20:21]
	v_mfma_f32_16x16x32_bf16 v[42:45], v[142:145], v[150:153], v[42:45]
	global_load_dwordx4 v[26:29], v100, s[66:67]
	v_mfma_f32_16x16x32_bf16 v[38:41], v[142:145], v[162:165], v[38:41]
	global_load_dwordx4 v[30:33], v98, s[20:21]
	v_mfma_f32_16x16x32_bf16 v[34:37], v[142:145], v[166:169], v[34:37]
	s_waitcnt lgkmcnt(0)
	s_barrier
	ds_read_b128 v[130:133], v161 offset:18432
	v_mfma_f32_16x16x32_bf16 v[94:97], v[222:225], v[238:241], v[94:97]
	ds_read_b128 v[134:137], v161 offset:20736
	v_mfma_f32_16x16x32_bf16 v[90:93], v[222:225], v[242:245], v[90:93]
	ds_read_b128 v[138:141], v161 offset:23040
	v_mfma_f32_16x16x32_bf16 v[86:89], v[222:225], v[246:249], v[86:89]
	ds_read_b128 v[142:145], v161 offset:25344
	v_mfma_f32_16x16x32_bf16 v[82:85], v[222:225], v[250:253], v[82:85]
	ds_read_b128 v[146:149], v129 offset:55296
	v_mfma_f32_16x16x32_bf16 v[78:81], v[226:229], v[238:241], v[78:81]
	ds_read_b128 v[150:153], v129 offset:57600
	v_mfma_f32_16x16x32_bf16 v[74:77], v[226:229], v[242:245], v[74:77]
	ds_read_b128 v[162:165], v129 offset:59904
	v_mfma_f32_16x16x32_bf16 v[70:73], v[226:229], v[246:249], v[70:73]
	ds_read_b128 v[166:169], v129 offset:62208
	v_mfma_f32_16x16x32_bf16 v[66:69], v[226:229], v[250:253], v[66:69]
	v_mfma_f32_16x16x32_bf16 v[62:65], v[230:233], v[238:241], v[62:65]
	v_mfma_f32_16x16x32_bf16 v[58:61], v[230:233], v[242:245], v[58:61]
	v_mfma_f32_16x16x32_bf16 v[54:57], v[230:233], v[246:249], v[54:57]
	v_mfma_f32_16x16x32_bf16 v[50:53], v[230:233], v[250:253], v[50:53]
	v_mfma_f32_16x16x32_bf16 v[46:49], v[234:237], v[238:241], v[46:49]
	v_mfma_f32_16x16x32_bf16 v[42:45], v[234:237], v[242:245], v[42:45]
	v_mfma_f32_16x16x32_bf16 v[38:41], v[234:237], v[246:249], v[38:41]
	v_mfma_f32_16x16x32_bf16 v[34:37], v[234:237], v[250:253], v[34:37]
	s_waitcnt lgkmcnt(0)
	ds_read_b128 v[222:225], v161 offset:18496
	ds_read_b128 v[226:229], v161 offset:20800
	ds_read_b128 v[230:233], v161 offset:23104
	ds_read_b128 v[234:237], v161 offset:25408
	ds_read_b128 v[238:241], v129 offset:55360
	ds_read_b128 v[242:245], v129 offset:57664
	ds_read_b128 v[246:249], v129 offset:59968
	ds_read_b128 v[250:253], v129 offset:62272
	v_mfma_f32_16x16x32_bf16 v[94:97], v[130:133], v[146:149], v[94:97]
	v_mfma_f32_16x16x32_bf16 v[90:93], v[130:133], v[150:153], v[90:93]
	v_mfma_f32_16x16x32_bf16 v[86:89], v[130:133], v[162:165], v[86:89]
	v_mfma_f32_16x16x32_bf16 v[82:85], v[130:133], v[166:169], v[82:85]
	s_waitcnt vmcnt(0)
	ds_write_b128 v122, v[22:25]
	ds_write_b128 v122, v[6:9] offset:36864
	v_mfma_f32_16x16x32_bf16 v[78:81], v[134:137], v[146:149], v[78:81]
	ds_write_b128 v121, v[18:21]
	ds_write_b128 v121, v[10:13] offset:36864
	v_mfma_f32_16x16x32_bf16 v[74:77], v[134:137], v[150:153], v[74:77]
	ds_write_b128 v120, v[14:17]
	ds_write_b128 v120, v[2:5] offset:36864
	v_mfma_f32_16x16x32_bf16 v[70:73], v[134:137], v[162:165], v[70:73]
	ds_write_b128 v124, v[26:29]
	ds_write_b128 v124, v[30:33] offset:36864
	v_mfma_f32_16x16x32_bf16 v[66:69], v[134:137], v[166:169], v[66:69]
	global_load_dwordx4 v[22:25], v112, s[66:67] offset:128
	v_mfma_f32_16x16x32_bf16 v[62:65], v[138:141], v[146:149], v[62:65]
	global_load_dwordx4 v[6:9], v110, s[20:21] offset:128
	v_mfma_f32_16x16x32_bf16 v[58:61], v[138:141], v[150:153], v[58:61]
	global_load_dwordx4 v[18:21], v108, s[66:67] offset:128
	v_mfma_f32_16x16x32_bf16 v[54:57], v[138:141], v[162:165], v[54:57]
	global_load_dwordx4 v[10:13], v106, s[20:21] offset:128
	v_mfma_f32_16x16x32_bf16 v[50:53], v[138:141], v[166:169], v[50:53]
	global_load_dwordx4 v[14:17], v104, s[66:67] offset:128
	v_mfma_f32_16x16x32_bf16 v[46:49], v[142:145], v[146:149], v[46:49]
	global_load_dwordx4 v[2:5], v102, s[20:21] offset:128
	v_mfma_f32_16x16x32_bf16 v[42:45], v[142:145], v[150:153], v[42:45]
	global_load_dwordx4 v[26:29], v100, s[66:67] offset:128
	v_mfma_f32_16x16x32_bf16 v[38:41], v[142:145], v[162:165], v[38:41]
	global_load_dwordx4 v[30:33], v98, s[20:21] offset:128
	v_mfma_f32_16x16x32_bf16 v[34:37], v[142:145], v[166:169], v[34:37]
	s_waitcnt lgkmcnt(0)
	s_barrier
; DEV f32x4 mfma16(bf16x8 a, bf16x8 b, f32x4 c) { return __builtin_amdgcn_mfma_f32_16x16x32_bf16(a, b, c, 0, 0, 0); }
; template <int EPI, bool AF32>
; DEV void gemm_tile(const void* Ap, int lda, const u16* Bt, int ldb, int K, int m0, int n0, const Epi& ea, char* smem) {
;     ...
;   auto gload = [&](int kt) {
;     const int k0 = kt << 6;
; #pragma unroll
;     for (int i = 0; i < 4; i++) {
;       const int c = tid + i * 256, row = c >> 3, kc = c & 7;
;       if (AF32) {
;         const float* pa = (const float*)Ap + (size_t)(m0 + row) * lda + k0 + kc * 8;
;         rfa[2 * i] = *(const f32x4*)pa;
;         rfa[2 * i + 1] = *(const f32x4*)(pa + 4);
;       } else {
;         ra[i] = *(const u32x4*)((const u16*)Ap + (size_t)(m0 + row) * lda + k0 + kc * 8);
;       }
;       rb[i] = *(const u32x4*)(Bt + (size_t)(n0 + row) * ldb + k0 + kc * 8);
;     }
;   };
;   auto swrite = [&](int buf) {
; #pragma unroll
;     for (int i = 0; i < 4; i++) {
;       const int c = tid + i * 256, row = c >> 3, kc = c & 7;
;       u32x4 va;
;       if (AF32) {
;         va = (u32x4){pack2(rfa[2 * i][0], rfa[2 * i][1]), pack2(rfa[2 * i][2], rfa[2 * i][3]),
;                      pack2(rfa[2 * i + 1][0], rfa[2 * i + 1][1]), pack2(rfa[2 * i + 1][2], rfa[2 * i + 1][3])};
;       } else {
;         va = ra[i];
;       }
;       *(u32x4*)(sA + buf * 9216 + row * 72 + kc * 8) = va;
;       *(u32x4*)(sB + buf * 9216 + row * 72 + kc * 8) = rb[i];
;     }
;   };
;   gload(0);
;   swrite(0);
;   if (nk > 1) gload(1);
;   __syncthreads();
;   for (int kt = 0; kt < nk; kt++) {
;     const int buf = kt & 1;
;     if (kt + 1 < nk) swrite(buf ^ 1);
;     if (kt + 2 < nk) gload(kt + 2);
; #pragma unroll
;     for (int ks = 0; ks < 2; ks++) {
;       bf16x8 a[4], b[4];
; #pragma unroll
;       for (int m = 0; m < 4; m++) a[m] = *(const bf16x8*)(sA + buf * 9216 + (wr * 64 + m * 16 + fr) * 72 + ks * 32 + fq * 8);
; #pragma unroll
;       for (int n = 0; n < 4; n++) b[n] = *(const bf16x8*)(sB + buf * 9216 + (wc * 64 + n * 16 + fr) * 72 + ks * 32 + fq * 8);
;       __builtin_amdgcn_s_setprio(1);
; #pragma unroll
;       for (int m = 0; m < 4; m++)
; #pragma unroll
;         for (int n = 0; n < 4; n++) acc[m][n] = mfma16(a[m], b[n], acc[m][n]);
;       __builtin_amdgcn_s_setprio(0);
;     }
;     __syncthreads();
;   }
	ds_read_b128 v[130:133], v161
	v_mfma_f32_16x16x32_bf16 v[94:97], v[222:225], v[238:241], v[94:97]
	ds_read_b128 v[134:137], v161 offset:2304
	v_mfma_f32_16x16x32_bf16 v[90:93], v[222:225], v[242:245], v[90:93]
	ds_read_b128 v[138:141], v161 offset:4608
	v_mfma_f32_16x16x32_bf16 v[86:89], v[222:225], v[246:249], v[86:89]
	ds_read_b128 v[142:145], v161 offset:6912
	v_mfma_f32_16x16x32_bf16 v[82:85], v[222:225], v[250:253], v[82:85]
	ds_read_b128 v[146:149], v129 offset:36864
	v_mfma_f32_16x16x32_bf16 v[78:81], v[226:229], v[238:241], v[78:81]
	ds_read_b128 v[150:153], v129 offset:39168
	v_mfma_f32_16x16x32_bf16 v[74:77], v[226:229], v[242:245], v[74:77]
	ds_read_b128 v[162:165], v129 offset:41472
	v_mfma_f32_16x16x32_bf16 v[70:73], v[226:229], v[246:249], v[70:73]
	ds_read_b128 v[166:169], v129 offset:43776
	v_mfma_f32_16x16x32_bf16 v[66:69], v[226:229], v[250:253], v[66:69]
	v_mfma_f32_16x16x32_bf16 v[62:65], v[230:233], v[238:241], v[62:65]
	v_add_u32_e32 v112, 0x100, v112
	v_mfma_f32_16x16x32_bf16 v[58:61], v[230:233], v[242:245], v[58:61]
	v_add_u32_e32 v110, 0x100, v110
	v_mfma_f32_16x16x32_bf16 v[54:57], v[230:233], v[246:249], v[54:57]
	v_add_u32_e32 v108, 0x100, v108
	v_mfma_f32_16x16x32_bf16 v[50:53], v[230:233], v[250:253], v[50:53]
	v_add_u32_e32 v106, 0x100, v106
	v_mfma_f32_16x16x32_bf16 v[46:49], v[234:237], v[238:241], v[46:49]
	v_add_u32_e32 v104, 0x100, v104
	v_mfma_f32_16x16x32_bf16 v[42:45], v[234:237], v[242:245], v[42:45]
	v_add_u32_e32 v102, 0x100, v102
	v_mfma_f32_16x16x32_bf16 v[38:41], v[234:237], v[246:249], v[38:41]
	v_add_u32_e32 v100, 0x100, v100
	v_mfma_f32_16x16x32_bf16 v[34:37], v[234:237], v[250:253], v[34:37]
	v_add_u32_e32 v98, 0x100, v98
	s_add_i32 s4, s4, 1
	s_cmp_lg_u32 s4, 7
	s_cbranch_scc1 .Lgk1_loop
	s_waitcnt lgkmcnt(0)
	ds_read_b128 v[222:225], v161 offset:64
	ds_read_b128 v[226:229], v161 offset:2368
	ds_read_b128 v[230:233], v161 offset:4672
	ds_read_b128 v[234:237], v161 offset:6976
	ds_read_b128 v[238:241], v129 offset:36928
	ds_read_b128 v[242:245], v129 offset:39232
	ds_read_b128 v[246:249], v129 offset:41536
	ds_read_b128 v[250:253], v129 offset:43840
	v_mfma_f32_16x16x32_bf16 v[94:97], v[130:133], v[146:149], v[94:97]
	v_mfma_f32_16x16x32_bf16 v[90:93], v[130:133], v[150:153], v[90:93]
	v_mfma_f32_16x16x32_bf16 v[86:89], v[130:133], v[162:165], v[86:89]
	v_mfma_f32_16x16x32_bf16 v[82:85], v[130:133], v[166:169], v[82:85]
	s_waitcnt vmcnt(0)
	ds_write_b128 v122, v[22:25] offset:18432
	ds_write_b128 v122, v[6:9] offset:55296
	v_mfma_f32_16x16x32_bf16 v[78:81], v[134:137], v[146:149], v[78:81]
	ds_write_b128 v121, v[18:21] offset:18432
	ds_write_b128 v121, v[10:13] offset:55296
	v_mfma_f32_16x16x32_bf16 v[74:77], v[134:137], v[150:153], v[74:77]
	ds_write_b128 v120, v[14:17] offset:18432
	ds_write_b128 v120, v[2:5] offset:55296
	v_mfma_f32_16x16x32_bf16 v[70:73], v[134:137], v[162:165], v[70:73]
	ds_write_b128 v124, v[26:29] offset:18432
	ds_write_b128 v124, v[30:33] offset:55296
	v_mfma_f32_16x16x32_bf16 v[66:69], v[134:137], v[166:169], v[66:69]
	v_mfma_f32_16x16x32_bf16 v[62:65], v[138:141], v[146:149], v[62:65]
	v_mfma_f32_16x16x32_bf16 v[58:61], v[138:141], v[150:153], v[58:61]
	v_mfma_f32_16x16x32_bf16 v[54:57], v[138:141], v[162:165], v[54:57]
	v_mfma_f32_16x16x32_bf16 v[50:53], v[138:141], v[166:169], v[50:53]
	v_mfma_f32_16x16x32_bf16 v[46:49], v[142:145], v[146:149], v[46:49]
	v_mfma_f32_16x16x32_bf16 v[42:45], v[142:145], v[150:153], v[42:45]
	v_mfma_f32_16x16x32_bf16 v[38:41], v[142:145], v[162:165], v[38:41]
	v_mfma_f32_16x16x32_bf16 v[34:37], v[142:145], v[166:169], v[34:37]
	s_waitcnt lgkmcnt(0)
	s_barrier
	ds_read_b128 v[130:133], v161 offset:18432
	v_mfma_f32_16x16x32_bf16 v[94:97], v[222:225], v[238:241], v[94:97]
	ds_read_b128 v[134:137], v161 offset:20736
	v_mfma_f32_16x16x32_bf16 v[90:93], v[222:225], v[242:245], v[90:93]
	ds_read_b128 v[138:141], v161 offset:23040
	v_mfma_f32_16x16x32_bf16 v[86:89], v[222:225], v[246:249], v[86:89]
	ds_read_b128 v[142:145], v161 offset:25344
	v_mfma_f32_16x16x32_bf16 v[82:85], v[222:225], v[250:253], v[82:85]
	ds_read_b128 v[146:149], v129 offset:55296
	v_mfma_f32_16x16x32_bf16 v[78:81], v[226:229], v[238:241], v[78:81]
	ds_read_b128 v[150:153], v129 offset:57600
	v_mfma_f32_16x16x32_bf16 v[74:77], v[226:229], v[242:245], v[74:77]
	ds_read_b128 v[162:165], v129 offset:59904
	v_mfma_f32_16x16x32_bf16 v[70:73], v[226:229], v[246:249], v[70:73]
	ds_read_b128 v[166:169], v129 offset:62208
	v_mfma_f32_16x16x32_bf16 v[66:69], v[226:229], v[250:253], v[66:69]
	v_mfma_f32_16x16x32_bf16 v[62:65], v[230:233], v[238:241], v[62:65]
	v_mfma_f32_16x16x32_bf16 v[58:61], v[230:233], v[242:245], v[58:61]
	v_mfma_f32_16x16x32_bf16 v[54:57], v[230:233], v[246:249], v[54:57]
	v_mfma_f32_16x16x32_bf16 v[50:53], v[230:233], v[250:253], v[50:53]
	v_mfma_f32_16x16x32_bf16 v[46:49], v[234:237], v[238:241], v[46:49]
	v_mfma_f32_16x16x32_bf16 v[42:45], v[234:237], v[242:245], v[42:45]
	v_mfma_f32_16x16x32_bf16 v[38:41], v[234:237], v[246:249], v[38:41]
	v_mfma_f32_16x16x32_bf16 v[34:37], v[234:237], v[250:253], v[34:37]
	s_waitcnt lgkmcnt(0)
; template <int EPI, bool AF32>
; DEV void gemm_tile(const void* Ap, int lda, const u16* Bt, int ldb, int K, int m0, int n0, const Epi& ea, char* smem) {
;     ...
;       } else if (EPI == EP_GDNA) {
;         if (cb < 3072) {
;           u16* C = (u16*)ea.p0;
;           u16* H = (u16*)ea.p2;
;           float* O = (float*)ea.p3;
;           const int l = ea.layer;
; #pragma unroll
;           for (int n = 0; n < 4; n++) {
;             const int col = cb + n * 16 + fr;
;             const float v = acc[m][n][j];
;             const u16 hv = f2bf(v);
;             if (row < T_P) {
;               __builtin_nontemporal_store(hv, &C[((size_t)((row >> 6) * 8 + ((col >> 7) & 7)) * 3 + (col >> 10)) * 8192 + (row & 63) * 128 + (col & 127)]);
;               const int r = row & 63, ci = row >> 6;
;               if (r >= 61 && ((ci + 1) & 127) != 0) H[((size_t)(ci + 1) * 3 + (r - 61)) * 3072 + col] = hv;
	ds_read_b128 v[222:225], v161 offset:18496
	ds_read_b128 v[226:229], v161 offset:20800
	ds_read_b128 v[230:233], v161 offset:23104
	ds_read_b128 v[234:237], v161 offset:25408
	ds_read_b128 v[238:241], v129 offset:55360
	ds_read_b128 v[242:245], v129 offset:57664
	ds_read_b128 v[246:249], v129 offset:59968
	ds_read_b128 v[250:253], v129 offset:62272
	v_mfma_f32_16x16x32_bf16 v[94:97], v[130:133], v[146:149], v[94:97]
	v_mfma_f32_16x16x32_bf16 v[90:93], v[130:133], v[150:153], v[90:93]
	v_mfma_f32_16x16x32_bf16 v[86:89], v[130:133], v[162:165], v[86:89]
	v_mfma_f32_16x16x32_bf16 v[82:85], v[130:133], v[166:169], v[82:85]
	v_mfma_f32_16x16x32_bf16 v[78:81], v[134:137], v[146:149], v[78:81]
	v_mfma_f32_16x16x32_bf16 v[74:77], v[134:137], v[150:153], v[74:77]
	v_mfma_f32_16x16x32_bf16 v[70:73], v[134:137], v[162:165], v[70:73]
	v_mfma_f32_16x16x32_bf16 v[66:69], v[134:137], v[166:169], v[66:69]
	v_mfma_f32_16x16x32_bf16 v[62:65], v[138:141], v[146:149], v[62:65]
	v_mfma_f32_16x16x32_bf16 v[58:61], v[138:141], v[150:153], v[58:61]
	v_mfma_f32_16x16x32_bf16 v[54:57], v[138:141], v[162:165], v[54:57]
	v_mfma_f32_16x16x32_bf16 v[50:53], v[138:141], v[166:169], v[50:53]
	v_mfma_f32_16x16x32_bf16 v[46:49], v[142:145], v[146:149], v[46:49]
	v_mfma_f32_16x16x32_bf16 v[42:45], v[142:145], v[150:153], v[42:45]
	v_mfma_f32_16x16x32_bf16 v[38:41], v[142:145], v[162:165], v[38:41]
	v_mfma_f32_16x16x32_bf16 v[34:37], v[142:145], v[166:169], v[34:37]
	s_waitcnt lgkmcnt(0)
	v_mfma_f32_16x16x32_bf16 v[30:33], v[230:233], v[238:241], v[62:65]
	v_mfma_f32_16x16x32_bf16 v[26:29], v[230:233], v[242:245], v[58:61]
	v_mfma_f32_16x16x32_bf16 v[22:25], v[230:233], v[246:249], v[54:57]
	v_mfma_f32_16x16x32_bf16 v[18:21], v[230:233], v[250:253], v[50:53]
	v_mfma_f32_16x16x32_bf16 v[14:17], v[234:237], v[238:241], v[46:49]
	v_mfma_f32_16x16x32_bf16 v[10:13], v[234:237], v[242:245], v[42:45]
	v_mfma_f32_16x16x32_bf16 v[6:9], v[234:237], v[246:249], v[38:41]
	v_mfma_f32_16x16x32_bf16 v[2:5], v[234:237], v[250:253], v[34:37]
	v_mfma_f32_16x16x32_bf16 v[62:65], v[222:225], v[238:241], v[94:97]
	v_mfma_f32_16x16x32_bf16 v[58:61], v[222:225], v[242:245], v[90:93]
	v_mfma_f32_16x16x32_bf16 v[54:57], v[222:225], v[246:249], v[86:89]
	v_mfma_f32_16x16x32_bf16 v[50:53], v[222:225], v[250:253], v[82:85]
	v_mfma_f32_16x16x32_bf16 v[46:49], v[226:229], v[238:241], v[78:81]
	v_mfma_f32_16x16x32_bf16 v[42:45], v[226:229], v[242:245], v[74:77]
	v_mfma_f32_16x16x32_bf16 v[38:41], v[226:229], v[246:249], v[70:73]
	v_mfma_f32_16x16x32_bf16 v[34:37], v[226:229], v[250:253], v[66:69]
	s_nop 7
	s_cmp_lt_u32 s2, 0x8000
	s_cbranch_scc0 .Lgd_orig
	s_cmpk_lt_u32 s3, 0xc00
	s_cbranch_scc0 .Lgd_orig
	v_and_b32_e32 v66, 15, v157
	v_bfe_u32 v67, v157, 4, 2
	v_bfe_u32 v68, v157, 6, 1
	v_lshrrev_b32_e32 v69, 7, v157
	s_nop 0
	v_readfirstlane_b32 s4, v69
	s_lshr_b32 s5, s2, 6
	s_add_i32 s5, s5, s4
	s_and_b32 s6, s29, 7
	s_lshr_b32 s7, s29, 3
	s_lshl_b32 s8, s5, 3
	s_add_i32 s8, s8, s6
	s_mul_i32 s8, s8, 3
	s_add_i32 s8, s8, s7
	s_lshl_b32 s8, s8, 14
	s_add_u32 s10, s62, s8
	s_addc_u32 s11, s63, 0
	s_add_u32 s10, s10, 0x2800000
	s_addc_u32 s11, s11, 0
	v_lshlrev_b32_e32 v70, 10, v67
	v_lshl_add_u32 v70, v68, 7, v70
	v_lshl_add_u32 v70, v66, 1, v70
	v_mov_b32_e32 v71, 0
	v_lshl_add_u64 v[70:71], s[10:11], 0, v[70:71]
	s_mov_b64 s[8:9], 0x1000
	s_barrier
	v_cvt_pk_bf16_f32 v72, v62, v62
	global_store_short v[70:71], v72, off nt
	v_cvt_pk_bf16_f32 v73, v58, v58
	global_store_short v[70:71], v73, off offset:32 nt
	v_cvt_pk_bf16_f32 v74, v54, v54
	global_store_short v[70:71], v74, off offset:64 nt
	v_cvt_pk_bf16_f32 v75, v50, v50
	global_store_short v[70:71], v75, off offset:96 nt
	v_cvt_pk_bf16_f32 v72, v63, v63
	global_store_short v[70:71], v72, off offset:256 nt
	v_cvt_pk_bf16_f32 v73, v59, v59
	global_store_short v[70:71], v73, off offset:288 nt
	v_cvt_pk_bf16_f32 v74, v55, v55
	global_store_short v[70:71], v74, off offset:320 nt
	v_cvt_pk_bf16_f32 v75, v51, v51
	global_store_short v[70:71], v75, off offset:352 nt
	v_cvt_pk_bf16_f32 v72, v64, v64
	global_store_short v[70:71], v72, off offset:512 nt
	v_cvt_pk_bf16_f32 v73, v60, v60
	global_store_short v[70:71], v73, off offset:544 nt
	v_cvt_pk_bf16_f32 v74, v56, v56
	global_store_short v[70:71], v74, off offset:576 nt
	v_cvt_pk_bf16_f32 v75, v52, v52
	global_store_short v[70:71], v75, off offset:608 nt
	v_cvt_pk_bf16_f32 v72, v65, v65
	global_store_short v[70:71], v72, off offset:768 nt
	v_cvt_pk_bf16_f32 v73, v61, v61
	global_store_short v[70:71], v73, off offset:800 nt
	v_cvt_pk_bf16_f32 v74, v57, v57
	global_store_short v[70:71], v74, off offset:832 nt
	v_cvt_pk_bf16_f32 v75, v53, v53
	global_store_short v[70:71], v75, off offset:864 nt
	v_lshl_add_u64 v[70:71], v[70:71], 0, s[8:9]
	v_cvt_pk_bf16_f32 v72, v46, v46
	global_store_short v[70:71], v72, off nt
	v_cvt_pk_bf16_f32 v73, v42, v42
	global_store_short v[70:71], v73, off offset:32 nt
	v_cvt_pk_bf16_f32 v74, v38, v38
	global_store_short v[70:71], v74, off offset:64 nt
	v_cvt_pk_bf16_f32 v75, v34, v34
	global_store_short v[70:71], v75, off offset:96 nt
	v_cvt_pk_bf16_f32 v72, v47, v47
	global_store_short v[70:71], v72, off offset:256 nt
	v_cvt_pk_bf16_f32 v73, v43, v43
	global_store_short v[70:71], v73, off offset:288 nt
; template <int EPI, bool AF32>
; DEV void gemm_tile(const void* Ap, int lda, const u16* Bt, int ldb, int K, int m0, int n0, const Epi& ea, char* smem) {
;     ...
; #pragma unroll
;           for (int n = 0; n < 4; n++) {
;             const int col = cb + n * 16 + fr;
;             const float v = acc[m][n][j];
;             const u16 hv = f2bf(v);
;             if (row < T_P) {
;               __builtin_nontemporal_store(hv, &C[((size_t)((row >> 6) * 8 + ((col >> 7) & 7)) * 3 + (col >> 10)) * 8192 + (row & 63) * 128 + (col & 127)]);
;               const int r = row & 63, ci = row >> 6;
;               if (r >= 61 && ((ci + 1) & 127) != 0) H[((size_t)(ci + 1) * 3 + (r - 61)) * 3072 + col] = hv;
;               const int pos = row & 8191;
;               if (pos >= 8189) O[O_PCONV + ((size_t)(l * 4 + (row >> 13)) * 3 + (pos - 8189)) * 3072 + col] = v;
	v_cvt_pk_bf16_f32 v74, v39, v39
	global_store_short v[70:71], v74, off offset:320 nt
	v_cvt_pk_bf16_f32 v75, v35, v35
	global_store_short v[70:71], v75, off offset:352 nt
	v_cvt_pk_bf16_f32 v72, v48, v48
	global_store_short v[70:71], v72, off offset:512 nt
	v_cvt_pk_bf16_f32 v73, v44, v44
	global_store_short v[70:71], v73, off offset:544 nt
	v_cvt_pk_bf16_f32 v74, v40, v40
	global_store_short v[70:71], v74, off offset:576 nt
	v_cvt_pk_bf16_f32 v75, v36, v36
	global_store_short v[70:71], v75, off offset:608 nt
	v_cvt_pk_bf16_f32 v72, v49, v49
	global_store_short v[70:71], v72, off offset:768 nt
	v_cvt_pk_bf16_f32 v73, v45, v45
	global_store_short v[70:71], v73, off offset:800 nt
	v_cvt_pk_bf16_f32 v74, v41, v41
	global_store_short v[70:71], v74, off offset:832 nt
	v_cvt_pk_bf16_f32 v75, v37, v37
	global_store_short v[70:71], v75, off offset:864 nt
	v_lshl_add_u64 v[70:71], v[70:71], 0, s[8:9]
	v_cvt_pk_bf16_f32 v72, v30, v30
	global_store_short v[70:71], v72, off nt
	v_cvt_pk_bf16_f32 v73, v26, v26
	global_store_short v[70:71], v73, off offset:32 nt
	v_cvt_pk_bf16_f32 v74, v22, v22
	global_store_short v[70:71], v74, off offset:64 nt
	v_cvt_pk_bf16_f32 v75, v18, v18
	global_store_short v[70:71], v75, off offset:96 nt
	v_cvt_pk_bf16_f32 v72, v31, v31
	global_store_short v[70:71], v72, off offset:256 nt
	v_cvt_pk_bf16_f32 v73, v27, v27
	global_store_short v[70:71], v73, off offset:288 nt
	v_cvt_pk_bf16_f32 v74, v23, v23
	global_store_short v[70:71], v74, off offset:320 nt
	v_cvt_pk_bf16_f32 v75, v19, v19
	global_store_short v[70:71], v75, off offset:352 nt
	v_cvt_pk_bf16_f32 v72, v32, v32
	global_store_short v[70:71], v72, off offset:512 nt
	v_cvt_pk_bf16_f32 v73, v28, v28
	global_store_short v[70:71], v73, off offset:544 nt
	v_cvt_pk_bf16_f32 v74, v24, v24
	global_store_short v[70:71], v74, off offset:576 nt
	v_cvt_pk_bf16_f32 v75, v20, v20
	global_store_short v[70:71], v75, off offset:608 nt
	v_cvt_pk_bf16_f32 v72, v33, v33
	global_store_short v[70:71], v72, off offset:768 nt
	v_cvt_pk_bf16_f32 v73, v29, v29
	global_store_short v[70:71], v73, off offset:800 nt
	v_cvt_pk_bf16_f32 v74, v25, v25
	global_store_short v[70:71], v74, off offset:832 nt
	v_cvt_pk_bf16_f32 v75, v21, v21
	global_store_short v[70:71], v75, off offset:864 nt
	v_lshl_add_u64 v[70:71], v[70:71], 0, s[8:9]
	v_cvt_pk_bf16_f32 v72, v14, v14
	global_store_short v[70:71], v72, off nt
	v_cvt_pk_bf16_f32 v73, v10, v10
	global_store_short v[70:71], v73, off offset:32 nt
	v_cvt_pk_bf16_f32 v74, v6, v6
	global_store_short v[70:71], v74, off offset:64 nt
	v_cvt_pk_bf16_f32 v75, v2, v2
	global_store_short v[70:71], v75, off offset:96 nt
	v_cvt_pk_bf16_f32 v72, v15, v15
	global_store_short v[70:71], v72, off offset:256 nt
	v_cvt_pk_bf16_f32 v73, v11, v11
	global_store_short v[70:71], v73, off offset:288 nt
	v_cvt_pk_bf16_f32 v74, v7, v7
	global_store_short v[70:71], v74, off offset:320 nt
	v_cvt_pk_bf16_f32 v75, v3, v3
	global_store_short v[70:71], v75, off offset:352 nt
	v_cvt_pk_bf16_f32 v72, v16, v16
	global_store_short v[70:71], v72, off offset:512 nt
	v_cvt_pk_bf16_f32 v73, v12, v12
	global_store_short v[70:71], v73, off offset:544 nt
	v_cvt_pk_bf16_f32 v74, v8, v8
	global_store_short v[70:71], v74, off offset:576 nt
	v_cvt_pk_bf16_f32 v75, v4, v4
	global_store_short v[70:71], v75, off offset:608 nt
	v_cvt_pk_bf16_f32 v72, v17, v17
	global_store_short v[70:71], v72, off offset:768 nt
	v_cvt_pk_bf16_f32 v73, v13, v13
	global_store_short v[70:71], v73, off offset:800 nt
	v_cvt_pk_bf16_f32 v74, v9, v9
	global_store_short v[70:71], v74, off offset:832 nt
	v_cvt_pk_bf16_f32 v75, v5, v5
	global_store_short v[70:71], v75, off offset:864 nt
	v_cmp_eq_u32_e32 vcc, 3, v67
	s_and_saveexec_b64 s[6:7], vcc
	s_cbranch_execz .Lgd_done
	v_lshl_add_u32 v72, v68, 6, v66
	v_add_u32_e32 v72, s3, v72
	v_mov_b32_e32 v73, 0
	s_and_b32 s8, s5, 0x7f
	s_cmp_eq_u32 s8, 0x7f
	s_cbranch_scc1 .Lgd_pconv
	s_add_i32 s8, s5, 1
	s_mul_i32 s8, s8, 0x4800
	s_add_u32 s10, s62, s8
	s_addc_u32 s11, s63, 0
	s_add_u32 s10, s10, 0x1b008000
	s_addc_u32 s11, s11, 0
	v_lshlrev_b32_e32 v72, 1, v72
	v_lshl_add_u64 v[72:73], s[10:11], 0, v[72:73]
	s_mov_b64 s[8:9], 0x1800
	v_cvt_pk_bf16_f32 v74, v15, v15
	global_store_short v[72:73], v74, off
	v_cvt_pk_bf16_f32 v75, v11, v11
	global_store_short v[72:73], v75, off offset:32
	v_cvt_pk_bf16_f32 v74, v7, v7
	global_store_short v[72:73], v74, off offset:64
	v_cvt_pk_bf16_f32 v75, v3, v3
	global_store_short v[72:73], v75, off offset:96
	v_lshl_add_u64 v[72:73], v[72:73], 0, s[8:9]
	v_cvt_pk_bf16_f32 v74, v16, v16
	global_store_short v[72:73], v74, off
	v_cvt_pk_bf16_f32 v75, v12, v12
	global_store_short v[72:73], v75, off offset:32
	v_cvt_pk_bf16_f32 v74, v8, v8
	global_store_short v[72:73], v74, off offset:64
	v_cvt_pk_bf16_f32 v75, v4, v4
	global_store_short v[72:73], v75, off offset:96
	v_lshl_add_u64 v[72:73], v[72:73], 0, s[8:9]
	v_cvt_pk_bf16_f32 v74, v17, v17
	global_store_short v[72:73], v74, off
	v_cvt_pk_bf16_f32 v75, v13, v13
	global_store_short v[72:73], v75, off offset:32
	v_cvt_pk_bf16_f32 v74, v9, v9
	global_store_short v[72:73], v74, off offset:64
	v_cvt_pk_bf16_f32 v75, v5, v5
	global_store_short v[72:73], v75, off offset:96
	s_branch .Lgd_done

; DEV int tidx() { int t = threadIdx.x; asm volatile("" : "+v"(t)); return t; }
; template <int EPI, bool AF32>
; DEV void gemm_tile(const void* Ap, int lda, const u16* Bt, int ldb, int K, int m0, int n0, const Epi& ea, char* smem) {
;   u16* sA = (u16*)smem;
;   u16* sB = sA + 2 * 128 * 72;
;   const int tid = tidx(), lane = tid & 63, wv = tid >> 6;
;   const int wr = wv >> 1, wc = wv & 1, fr = lane & 15, fq = lane >> 4;
;   f32x4 acc[4][4];
; #pragma unroll
;   for (int m = 0; m < 4; m++)
; #pragma unroll
;     for (int n = 0; n < 4; n++) acc[m][n] = (f32x4){0.f, 0.f, 0.f, 0.f};
;   u32x4 ra[4], rb[4];
;   f32x4 rfa[8];
;   const int nk = K >> 6;
;   auto gload = [&](int kt) {
;     const int k0 = kt << 6;
; #pragma unroll
;     for (int i = 0; i < 4; i++) {
;       const int c = tid + i * 256, row = c >> 3, kc = c & 7;
;       if (AF32) {
;         const float* pa = (const float*)Ap + (size_t)(m0 + row) * lda + k0 + kc * 8;
;         rfa[2 * i] = *(const f32x4*)pa;
;         rfa[2 * i + 1] = *(const f32x4*)(pa + 4);
;       } else {
;         ra[i] = *(const u32x4*)((const u16*)Ap + (size_t)(m0 + row) * lda + k0 + kc * 8);
;       }
;       rb[i] = *(const u32x4*)(Bt + (size_t)(n0 + row) * ldb + k0 + kc * 8);
;     }
;   };
;   auto swrite = [&](int buf) {
; #pragma unroll
;     for (int i = 0; i < 4; i++) {
;       const int c = tid + i * 256, row = c >> 3, kc = c & 7;
;       u32x4 va;
;       if (AF32) {
;         va = (u32x4){pack2(rfa[2 * i][0], rfa[2 * i][1]), pack2(rfa[2 * i][2], rfa[2 * i][3]),
;                      pack2(rfa[2 * i + 1][0], rfa[2 * i + 1][1]), pack2(rfa[2 * i + 1][2], rfa[2 * i + 1][3])};
;       } else {
;         va = ra[i];
;       }
;       *(u32x4*)(sA + buf * 9216 + row * 72 + kc * 8) = va;
;       *(u32x4*)(sB + buf * 9216 + row * 72 + kc * 8) = rb[i];
;     }
;   };
;   gload(0);
;   swrite(0);
;   if (nk > 1) gload(1);
;   __syncthreads();
.LBB0_1262:
	s_ashr_i32 s0, s8, 31
	s_lshr_b32 s0, s0, 23
	s_add_i32 s0, s8, s0
	s_ashr_i32 s1, s0, 9
	s_and_b32 s0, s0, 0xfffffe00
	s_lshl_b32 s10, s1, 5
	s_sub_i32 s9, s8, s0
	s_sub_i32 s0, 0x104, s10
	s_min_u32 s11, s0, 32
	v_cvt_f32_ubyte0_e32 v2, s11
	v_cvt_f32_i32_e32 v0, s9
	v_rcp_iflag_f32_e32 v3, v2
	s_ashr_i32 s0, s9, 30
	s_or_b32 s12, s0, 1
	s_waitcnt vmcnt(12)
	v_mov_b32_e32 v114, v157
	v_mul_f32_e32 v3, v0, v3
	v_trunc_f32_e32 v3, v3
	v_fma_f32 v0, -v3, v2, v0
	v_cvt_i32_f32_e32 v3, v3
	v_cmp_ge_f32_e64 s[0:1], |v0|, v2
	s_and_b64 s[0:1], s[0:1], exec
	s_cselect_b32 s0, s12, 0
	v_readfirstlane_b32 s1, v3
	s_add_i32 s0, s1, s0
	s_sext_i32_i16 s1, s0
	s_mul_i32 s0, s0, s11
	s_sub_i32 s0, s9, s0
	s_sext_i32_i16 s0, s0
	s_add_i32 s10, s10, s0
	s_lshl_b32 s9, s10, 7
	s_lshl_b32 s10, s1, 7
	v_ashrrev_i32_e32 v8, 3, v114
	v_add_u32_e32 v2, s9, v8
	v_ashrrev_i32_e32 v3, 31, v2
	v_lshlrev_b32_e32 v0, 3, v114
	v_add_u32_e32 v4, 0x100, v114
	v_lshlrev_b64 v[58:59], 11, v[2:3]
	v_and_b32_e32 v0, 56, v0
	v_ashrrev_i32_e32 v9, 3, v4
	v_lshl_add_u64 v[2:3], s[60:61], 0, v[58:59]
	v_lshlrev_b32_e32 v0, 1, v0
	v_add_u32_e32 v4, s9, v9
	v_add_u32_e32 v6, 0x200, v114
	v_lshl_add_u64 v[14:15], v[2:3], 0, v[0:1]
	v_add_u32_e32 v2, s10, v8
	v_ashrrev_i32_e32 v5, 31, v4
	v_ashrrev_i32_e32 v10, 3, v6
	v_ashrrev_i32_e32 v3, 31, v2
	v_lshlrev_b64 v[62:63], 11, v[4:5]
	v_add_u32_e32 v6, s9, v10
	v_lshlrev_b64 v[60:61], 11, v[2:3]
	v_lshl_add_u64 v[4:5], s[60:61], 0, v[62:63]
	v_ashrrev_i32_e32 v7, 31, v6
	v_lshl_add_u64 v[2:3], s[4:5], 0, v[60:61]
	v_lshl_add_u64 v[16:17], v[4:5], 0, v[0:1]
	v_add_u32_e32 v4, s10, v9
	v_lshlrev_b64 v[66:67], 11, v[6:7]
	v_lshl_add_u64 v[2:3], v[2:3], 0, v[0:1]
	v_ashrrev_i32_e32 v5, 31, v4
	v_lshl_add_u64 v[6:7], s[60:61], 0, v[66:67]
	global_load_dwordx4 v[30:33], v[2:3], off
	v_lshlrev_b64 v[64:65], 11, v[4:5]
	v_lshl_add_u64 v[68:69], v[6:7], 0, v[0:1]
	v_add_u32_e32 v6, s10, v10
	global_load_dwordx4 v[26:29], v[14:15], off
	global_load_dwordx4 v[34:37], v[16:17], off
	v_lshl_add_u64 v[4:5], s[4:5], 0, v[64:65]
	v_ashrrev_i32_e32 v7, 31, v6
	v_lshl_add_u64 v[4:5], v[4:5], 0, v[0:1]
	v_lshlrev_b64 v[70:71], 11, v[6:7]
	global_load_dwordx4 v[38:41], v[4:5], off
	v_lshl_add_u64 v[6:7], s[4:5], 0, v[70:71]
	global_load_dwordx4 v[42:45], v[68:69], off
	v_lshl_add_u64 v[18:19], v[6:7], 0, v[0:1]
	global_load_dwordx4 v[46:49], v[18:19], off
	v_add_u32_e32 v6, 0x300, v114
	v_ashrrev_i32_e32 v80, 3, v6
	v_add_u32_e32 v6, s9, v80
	v_ashrrev_i32_e32 v7, 31, v6
	v_lshlrev_b64 v[72:73], 11, v[6:7]
	v_lshl_add_u64 v[6:7], s[60:61], 0, v[72:73]
	v_lshl_add_u64 v[74:75], v[6:7], 0, v[0:1]
	v_add_u32_e32 v6, s10, v80
	v_ashrrev_i32_e32 v7, 31, v6
	v_lshlrev_b64 v[76:77], 11, v[6:7]
	v_lshl_add_u64 v[6:7], s[4:5], 0, v[76:77]
	v_lshl_add_u64 v[78:79], v[6:7], 0, v[0:1]
	global_load_dwordx4 v[50:53], v[74:75], off
	global_load_dwordx4 v[54:57], v[78:79], off
	s_waitcnt vmcnt(19)
	v_mul_lo_u32 v118, v8, s71
	v_mul_lo_u32 v119, v9, s71
	s_waitcnt vmcnt(18)
	v_mul_lo_u32 v123, v10, s71
	global_load_dwordx4 v[6:9], v[2:3], off offset:128
	global_load_dwordx4 v[10:13], v[4:5], off offset:128
	s_nop 0
	global_load_dwordx4 v[2:5], v[18:19], off offset:128
	global_load_dwordx4 v[22:25], v[14:15], off offset:128
	s_nop 0
	global_load_dwordx4 v[18:21], v[16:17], off offset:128
	s_nop 0
	global_load_dwordx4 v[14:17], v[68:69], off offset:128
	v_bfe_u32 v161, v157, 3, 4
	v_add_u32_e32 v161, 4, v161
	v_lshlrev_b32_e32 v161, 1, v161
	v_and_b32_e32 v161, 16, v161
	v_xor_b32_e32 v129, v0, v161
	v_lshl_add_u32 v122, v118, 1, v129
	v_lshl_add_u32 v121, v119, 1, v129
	v_lshl_add_u32 v120, v123, 1, v129
	v_and_b32_e32 v115, 15, v114
	s_waitcnt vmcnt(23)
	v_mul_lo_u32 v126, v80, s71
	v_bfe_u32 v116, v114, 4, 2
	v_lshl_add_u32 v124, v126, 1, v129
	s_mov_b32 s11, 0
	v_lshlrev_b32_e32 v125, 4, v116
	v_and_b32_e32 v161, 15, v157
	v_add_u32_e32 v161, 4, v161
	v_lshlrev_b32_e32 v161, 1, v161
	v_and_b32_e32 v161, 16, v161
	v_xor_b32_e32 v125, v125, v161
	s_mov_b64 s[0:1], 0
	s_waitcnt vmcnt(13)
	ds_write_b128 v122, v[30:33] offset:36864
	s_waitcnt vmcnt(12)
	ds_write_b128 v122, v[26:29]
	s_waitcnt vmcnt(11)
	ds_write_b128 v121, v[34:37]
	s_waitcnt vmcnt(10)
	ds_write_b128 v121, v[38:41] offset:36864
	s_waitcnt vmcnt(9)
	ds_write_b128 v120, v[42:45]
	s_waitcnt vmcnt(8)
	ds_write_b128 v120, v[46:49] offset:36864
	global_load_dwordx4 v[26:29], v[74:75], off offset:128
	global_load_dwordx4 v[30:33], v[78:79], off offset:128
	v_ashrrev_i32_e32 v34, 1, v114
	v_and_b32_e32 v117, 0xffffffc0, v34
	v_or_b32_e32 v34, v117, v115
	v_mul_lo_u32 v128, v34, s71
	v_lshlrev_b32_e32 v34, 4, v114
	v_and_b32_e32 v34, 0x70, v34
	v_and_b32_e32 v35, 0x4f, v114
	v_or_b32_e32 v76, v76, v34
	v_or_b32_e32 v72, v72, v34
	v_or_b32_e32 v70, v70, v34
	v_or_b32_e32 v66, v66, v34
	v_or_b32_e32 v64, v64, v34
	v_or_b32_e32 v62, v62, v34
	v_or_b32_e32 v60, v60, v34
	v_or_b32_e32 v58, v58, v34
	v_mov_b32_e32 v34, 0
	s_waitcnt vmcnt(9)
	ds_write_b128 v124, v[50:53]
	s_waitcnt vmcnt(8)
	ds_write_b128 v124, v[54:57] offset:36864
	v_mul_u32_u24_e32 v127, 0x48, v35
	v_mov_b32_e32 v98, v76
	v_mov_b32_e32 v100, v72
	v_mov_b32_e32 v102, v70
	v_mov_b32_e32 v104, v66
	v_mov_b32_e32 v106, v64
	v_mov_b32_e32 v108, v62
	v_mov_b32_e32 v110, v60
	v_mov_b32_e32 v112, v58
	v_mov_b32_e32 v35, v34
	v_mov_b32_e32 v36, v34
	v_mov_b32_e32 v37, v34
	v_mov_b32_e32 v38, v34
	v_mov_b32_e32 v39, v34
	v_mov_b32_e32 v40, v34
	v_mov_b32_e32 v41, v34
	v_mov_b32_e32 v42, v34
	v_mov_b32_e32 v43, v34
	v_mov_b32_e32 v44, v34
	v_mov_b32_e32 v45, v34
	v_mov_b32_e32 v46, v34
	v_mov_b32_e32 v47, v34
	v_mov_b32_e32 v48, v34
	v_mov_b32_e32 v49, v34
	v_mov_b32_e32 v50, v34
	v_mov_b32_e32 v51, v34
	v_mov_b32_e32 v52, v34
	v_mov_b32_e32 v53, v34
	v_mov_b32_e32 v54, v34
	v_mov_b32_e32 v55, v34
	v_mov_b32_e32 v56, v34
	v_mov_b32_e32 v57, v34
	v_mov_b32_e32 v58, v34
	v_mov_b32_e32 v59, v34
	v_mov_b32_e32 v60, v34
	v_mov_b32_e32 v61, v34
	v_mov_b32_e32 v62, v34
	v_mov_b32_e32 v63, v34
	v_mov_b32_e32 v64, v34
	v_mov_b32_e32 v65, v34
	v_mov_b32_e32 v66, v34
	v_mov_b32_e32 v67, v34
	v_mov_b32_e32 v68, v34
	v_mov_b32_e32 v69, v34
	v_mov_b32_e32 v70, v34
	v_mov_b32_e32 v71, v34
	v_mov_b32_e32 v72, v34
	v_mov_b32_e32 v73, v34
	v_mov_b32_e32 v74, v34
	v_mov_b32_e32 v75, v34
	v_mov_b32_e32 v76, v34
	v_mov_b32_e32 v77, v34
	v_mov_b32_e32 v78, v34
	v_mov_b32_e32 v79, v34
	v_mov_b32_e32 v80, v34
	v_mov_b32_e32 v81, v34
	v_mov_b32_e32 v82, v34
	v_mov_b32_e32 v83, v34
	v_mov_b32_e32 v84, v34
	v_mov_b32_e32 v85, v34
	v_mov_b32_e32 v86, v34
	v_mov_b32_e32 v87, v34
	v_mov_b32_e32 v88, v34
	v_mov_b32_e32 v89, v34
	v_mov_b32_e32 v90, v34
	v_mov_b32_e32 v91, v34
	v_mov_b32_e32 v92, v34
	v_mov_b32_e32 v93, v34
	v_mov_b32_e32 v94, v34
	v_mov_b32_e32 v95, v34
	v_mov_b32_e32 v96, v34
	v_mov_b32_e32 v97, v34
	s_waitcnt lgkmcnt(0)
	s_barrier
; DEV f32x4 mfma16(bf16x8 a, bf16x8 b, f32x4 c) { return __builtin_amdgcn_mfma_f32_16x16x32_bf16(a, b, c, 0, 0, 0); }
; template <int EPI, bool AF32>
; DEV void gemm_tile(const void* Ap, int lda, const u16* Bt, int ldb, int K, int m0, int n0, const Epi& ea, char* smem) {
;     ...
;   auto gload = [&](int kt) {
;     const int k0 = kt << 6;
; #pragma unroll
;     for (int i = 0; i < 4; i++) {
;       const int c = tid + i * 256, row = c >> 3, kc = c & 7;
;       if (AF32) {
;         const float* pa = (const float*)Ap + (size_t)(m0 + row) * lda + k0 + kc * 8;
;         rfa[2 * i] = *(const f32x4*)pa;
;         rfa[2 * i + 1] = *(const f32x4*)(pa + 4);
;       } else {
;         ra[i] = *(const u32x4*)((const u16*)Ap + (size_t)(m0 + row) * lda + k0 + kc * 8);
;       }
;       rb[i] = *(const u32x4*)(Bt + (size_t)(n0 + row) * ldb + k0 + kc * 8);
;     }
;   };
;   auto swrite = [&](int buf) {
; #pragma unroll
;     for (int i = 0; i < 4; i++) {
;       const int c = tid + i * 256, row = c >> 3, kc = c & 7;
;       u32x4 va;
;       if (AF32) {
;         va = (u32x4){pack2(rfa[2 * i][0], rfa[2 * i][1]), pack2(rfa[2 * i][2], rfa[2 * i][3]),
;                      pack2(rfa[2 * i + 1][0], rfa[2 * i + 1][1]), pack2(rfa[2 * i + 1][2], rfa[2 * i + 1][3])};
;       } else {
;         va = ra[i];
;       }
;       *(u32x4*)(sA + buf * 9216 + row * 72 + kc * 8) = va;
;       *(u32x4*)(sB + buf * 9216 + row * 72 + kc * 8) = rb[i];
;     }
;   };
;   gload(0);
;   swrite(0);
;   if (nk > 1) gload(1);
;   __syncthreads();
;   for (int kt = 0; kt < nk; kt++) {
;     const int buf = kt & 1;
;     if (kt + 1 < nk) swrite(buf ^ 1);
;     if (kt + 2 < nk) gload(kt + 2);
; #pragma unroll
;     for (int ks = 0; ks < 2; ks++) {
;       bf16x8 a[4], b[4];
; #pragma unroll
;       for (int m = 0; m < 4; m++) a[m] = *(const bf16x8*)(sA + buf * 9216 + (wr * 64 + m * 16 + fr) * 72 + ks * 32 + fq * 8);
; #pragma unroll
;       for (int n = 0; n < 4; n++) b[n] = *(const bf16x8*)(sB + buf * 9216 + (wc * 64 + n * 16 + fr) * 72 + ks * 32 + fq * 8);
;       __builtin_amdgcn_s_setprio(1);
; #pragma unroll
;       for (int m = 0; m < 4; m++)
; #pragma unroll
;         for (int n = 0; n < 4; n++) acc[m][n] = mfma16(a[m], b[n], acc[m][n]);
;       __builtin_amdgcn_s_setprio(0);
;     }
;     __syncthreads();
;   }
	v_lshl_add_u32 v161, v128, 1, v125
	v_lshl_add_u32 v129, v127, 1, v125
	s_mov_b32 s11, 0
	s_mov_b64 s[0:1], 0x100
	ds_read_b128 v[130:133], v161
	ds_read_b128 v[134:137], v161 offset:2304
	ds_read_b128 v[138:141], v161 offset:4608
	ds_read_b128 v[142:145], v161 offset:6912
	ds_read_b128 v[146:149], v129 offset:36864
	ds_read_b128 v[150:153], v129 offset:39168
	ds_read_b128 v[162:165], v129 offset:41472
	ds_read_b128 v[166:169], v129 offset:43776
.Lgk2_loop:
	s_waitcnt lgkmcnt(0)
	ds_read_b128 v[222:225], v161 offset:64
	ds_read_b128 v[226:229], v161 offset:2368
	ds_read_b128 v[230:233], v161 offset:4672
	ds_read_b128 v[234:237], v161 offset:6976
	ds_read_b128 v[238:241], v129 offset:36928
	ds_read_b128 v[242:245], v129 offset:39232
	ds_read_b128 v[246:249], v129 offset:41536
	ds_read_b128 v[250:253], v129 offset:43840
	v_mfma_f32_16x16x32_bf16 v[94:97], v[130:133], v[146:149], v[94:97]
	v_mfma_f32_16x16x32_bf16 v[90:93], v[130:133], v[150:153], v[90:93]
	v_mfma_f32_16x16x32_bf16 v[86:89], v[130:133], v[162:165], v[86:89]
	v_mfma_f32_16x16x32_bf16 v[82:85], v[130:133], v[166:169], v[82:85]
	s_waitcnt vmcnt(0)
	ds_write_b128 v122, v[22:25] offset:18432
	ds_write_b128 v122, v[6:9] offset:55296
	v_mfma_f32_16x16x32_bf16 v[78:81], v[134:137], v[146:149], v[78:81]
	ds_write_b128 v121, v[18:21] offset:18432
	ds_write_b128 v121, v[10:13] offset:55296
	v_mfma_f32_16x16x32_bf16 v[74:77], v[134:137], v[150:153], v[74:77]
	ds_write_b128 v120, v[14:17] offset:18432
	ds_write_b128 v120, v[2:5] offset:55296
	v_mfma_f32_16x16x32_bf16 v[70:73], v[134:137], v[162:165], v[70:73]
	ds_write_b128 v124, v[26:29] offset:18432
	ds_write_b128 v124, v[30:33] offset:55296
	v_mfma_f32_16x16x32_bf16 v[66:69], v[134:137], v[166:169], v[66:69]
	global_load_dwordx4 v[22:25], v112, s[66:67]
	v_mfma_f32_16x16x32_bf16 v[62:65], v[138:141], v[146:149], v[62:65]
	global_load_dwordx4 v[6:9], v110, s[6:7]
	v_mfma_f32_16x16x32_bf16 v[58:61], v[138:141], v[150:153], v[58:61]
	global_load_dwordx4 v[18:21], v108, s[66:67]
	v_mfma_f32_16x16x32_bf16 v[54:57], v[138:141], v[162:165], v[54:57]
	global_load_dwordx4 v[10:13], v106, s[6:7]
	v_mfma_f32_16x16x32_bf16 v[50:53], v[138:141], v[166:169], v[50:53]
	global_load_dwordx4 v[14:17], v104, s[66:67]
	v_mfma_f32_16x16x32_bf16 v[46:49], v[142:145], v[146:149], v[46:49]
	global_load_dwordx4 v[2:5], v102, s[6:7]
	v_mfma_f32_16x16x32_bf16 v[42:45], v[142:145], v[150:153], v[42:45]
	global_load_dwordx4 v[26:29], v100, s[66:67]
	v_mfma_f32_16x16x32_bf16 v[38:41], v[142:145], v[162:165], v[38:41]
	global_load_dwordx4 v[30:33], v98, s[6:7]
	v_mfma_f32_16x16x32_bf16 v[34:37], v[142:145], v[166:169], v[34:37]
	s_waitcnt lgkmcnt(0)
	s_barrier
	ds_read_b128 v[130:133], v161 offset:18432
	v_mfma_f32_16x16x32_bf16 v[94:97], v[222:225], v[238:241], v[94:97]
	ds_read_b128 v[134:137], v161 offset:20736
	v_mfma_f32_16x16x32_bf16 v[90:93], v[222:225], v[242:245], v[90:93]
	ds_read_b128 v[138:141], v161 offset:23040
	v_mfma_f32_16x16x32_bf16 v[86:89], v[222:225], v[246:249], v[86:89]
	ds_read_b128 v[142:145], v161 offset:25344
	v_mfma_f32_16x16x32_bf16 v[82:85], v[222:225], v[250:253], v[82:85]
	ds_read_b128 v[146:149], v129 offset:55296
	v_mfma_f32_16x16x32_bf16 v[78:81], v[226:229], v[238:241], v[78:81]
	ds_read_b128 v[150:153], v129 offset:57600
	v_mfma_f32_16x16x32_bf16 v[74:77], v[226:229], v[242:245], v[74:77]
	ds_read_b128 v[162:165], v129 offset:59904
	v_mfma_f32_16x16x32_bf16 v[70:73], v[226:229], v[246:249], v[70:73]
	ds_read_b128 v[166:169], v129 offset:62208
	v_mfma_f32_16x16x32_bf16 v[66:69], v[226:229], v[250:253], v[66:69]
	v_mfma_f32_16x16x32_bf16 v[62:65], v[230:233], v[238:241], v[62:65]
	v_mfma_f32_16x16x32_bf16 v[58:61], v[230:233], v[242:245], v[58:61]
	v_mfma_f32_16x16x32_bf16 v[54:57], v[230:233], v[246:249], v[54:57]
	v_mfma_f32_16x16x32_bf16 v[50:53], v[230:233], v[250:253], v[50:53]
	v_mfma_f32_16x16x32_bf16 v[46:49], v[234:237], v[238:241], v[46:49]
	v_mfma_f32_16x16x32_bf16 v[42:45], v[234:237], v[242:245], v[42:45]
	v_mfma_f32_16x16x32_bf16 v[38:41], v[234:237], v[246:249], v[38:41]
	v_mfma_f32_16x16x32_bf16 v[34:37], v[234:237], v[250:253], v[34:37]
	s_waitcnt lgkmcnt(0)
	ds_read_b128 v[222:225], v161 offset:18496
	ds_read_b128 v[226:229], v161 offset:20800
	ds_read_b128 v[230:233], v161 offset:23104
	ds_read_b128 v[234:237], v161 offset:25408
	ds_read_b128 v[238:241], v129 offset:55360
	ds_read_b128 v[242:245], v129 offset:57664
	ds_read_b128 v[246:249], v129 offset:59968
	ds_read_b128 v[250:253], v129 offset:62272
	v_mfma_f32_16x16x32_bf16 v[94:97], v[130:133], v[146:149], v[94:97]
	v_mfma_f32_16x16x32_bf16 v[90:93], v[130:133], v[150:153], v[90:93]
	v_mfma_f32_16x16x32_bf16 v[86:89], v[130:133], v[162:165], v[86:89]
	v_mfma_f32_16x16x32_bf16 v[82:85], v[130:133], v[166:169], v[82:85]
	s_waitcnt vmcnt(0)
	ds_write_b128 v122, v[22:25]
	ds_write_b128 v122, v[6:9] offset:36864
	v_mfma_f32_16x16x32_bf16 v[78:81], v[134:137], v[146:149], v[78:81]
	ds_write_b128 v121, v[18:21]
	ds_write_b128 v121, v[10:13] offset:36864
	v_mfma_f32_16x16x32_bf16 v[74:77], v[134:137], v[150:153], v[74:77]
	ds_write_b128 v120, v[14:17]
	ds_write_b128 v120, v[2:5] offset:36864
	v_mfma_f32_16x16x32_bf16 v[70:73], v[134:137], v[162:165], v[70:73]
	ds_write_b128 v124, v[26:29]
	ds_write_b128 v124, v[30:33] offset:36864
	v_mfma_f32_16x16x32_bf16 v[66:69], v[134:137], v[166:169], v[66:69]
	global_load_dwordx4 v[22:25], v112, s[66:67] offset:128
	v_mfma_f32_16x16x32_bf16 v[62:65], v[138:141], v[146:149], v[62:65]
	global_load_dwordx4 v[6:9], v110, s[6:7] offset:128
	v_mfma_f32_16x16x32_bf16 v[58:61], v[138:141], v[150:153], v[58:61]
	global_load_dwordx4 v[18:21], v108, s[66:67] offset:128
	v_mfma_f32_16x16x32_bf16 v[54:57], v[138:141], v[162:165], v[54:57]
	global_load_dwordx4 v[10:13], v106, s[6:7] offset:128
	v_mfma_f32_16x16x32_bf16 v[50:53], v[138:141], v[166:169], v[50:53]
	global_load_dwordx4 v[14:17], v104, s[66:67] offset:128
	v_mfma_f32_16x16x32_bf16 v[46:49], v[142:145], v[146:149], v[46:49]
	global_load_dwordx4 v[2:5], v102, s[6:7] offset:128
	v_mfma_f32_16x16x32_bf16 v[42:45], v[142:145], v[150:153], v[42:45]
	global_load_dwordx4 v[26:29], v100, s[66:67] offset:128
	v_mfma_f32_16x16x32_bf16 v[38:41], v[142:145], v[162:165], v[38:41]
	global_load_dwordx4 v[30:33], v98, s[6:7] offset:128
	v_mfma_f32_16x16x32_bf16 v[34:37], v[142:145], v[166:169], v[34:37]
	s_waitcnt lgkmcnt(0)
	s_barrier
; DEV f32x4 mfma16(bf16x8 a, bf16x8 b, f32x4 c) { return __builtin_amdgcn_mfma_f32_16x16x32_bf16(a, b, c, 0, 0, 0); }
; template <int EPI, bool AF32>
; DEV void gemm_tile(const void* Ap, int lda, const u16* Bt, int ldb, int K, int m0, int n0, const Epi& ea, char* smem) {
;     ...
;   auto gload = [&](int kt) {
;     const int k0 = kt << 6;
; #pragma unroll
;     for (int i = 0; i < 4; i++) {
;       const int c = tid + i * 256, row = c >> 3, kc = c & 7;
;       if (AF32) {
;         const float* pa = (const float*)Ap + (size_t)(m0 + row) * lda + k0 + kc * 8;
;         rfa[2 * i] = *(const f32x4*)pa;
;         rfa[2 * i + 1] = *(const f32x4*)(pa + 4);
;       } else {
;         ra[i] = *(const u32x4*)((const u16*)Ap + (size_t)(m0 + row) * lda + k0 + kc * 8);
;       }
;       rb[i] = *(const u32x4*)(Bt + (size_t)(n0 + row) * ldb + k0 + kc * 8);
;     }
;   };
;   auto swrite = [&](int buf) {
; #pragma unroll
;     for (int i = 0; i < 4; i++) {
;       const int c = tid + i * 256, row = c >> 3, kc = c & 7;
;       u32x4 va;
;       if (AF32) {
;         va = (u32x4){pack2(rfa[2 * i][0], rfa[2 * i][1]), pack2(rfa[2 * i][2], rfa[2 * i][3]),
;                      pack2(rfa[2 * i + 1][0], rfa[2 * i + 1][1]), pack2(rfa[2 * i + 1][2], rfa[2 * i + 1][3])};
;       } else {
;         va = ra[i];
;       }
;       *(u32x4*)(sA + buf * 9216 + row * 72 + kc * 8) = va;
;       *(u32x4*)(sB + buf * 9216 + row * 72 + kc * 8) = rb[i];
;     }
;   };
;   gload(0);
;   swrite(0);
;   if (nk > 1) gload(1);
;   __syncthreads();
;   for (int kt = 0; kt < nk; kt++) {
;     const int buf = kt & 1;
;     if (kt + 1 < nk) swrite(buf ^ 1);
;     if (kt + 2 < nk) gload(kt + 2);
; #pragma unroll
;     for (int ks = 0; ks < 2; ks++) {
;       bf16x8 a[4], b[4];
; #pragma unroll
;       for (int m = 0; m < 4; m++) a[m] = *(const bf16x8*)(sA + buf * 9216 + (wr * 64 + m * 16 + fr) * 72 + ks * 32 + fq * 8);
; #pragma unroll
;       for (int n = 0; n < 4; n++) b[n] = *(const bf16x8*)(sB + buf * 9216 + (wc * 64 + n * 16 + fr) * 72 + ks * 32 + fq * 8);
;       __builtin_amdgcn_s_setprio(1);
; #pragma unroll
;       for (int m = 0; m < 4; m++)
; #pragma unroll
;         for (int n = 0; n < 4; n++) acc[m][n] = mfma16(a[m], b[n], acc[m][n]);
;       __builtin_amdgcn_s_setprio(0);
;     }
;     __syncthreads();
;   }
	ds_read_b128 v[130:133], v161
	v_mfma_f32_16x16x32_bf16 v[94:97], v[222:225], v[238:241], v[94:97]
	ds_read_b128 v[134:137], v161 offset:2304
	v_mfma_f32_16x16x32_bf16 v[90:93], v[222:225], v[242:245], v[90:93]
	ds_read_b128 v[138:141], v161 offset:4608
	v_mfma_f32_16x16x32_bf16 v[86:89], v[222:225], v[246:249], v[86:89]
	ds_read_b128 v[142:145], v161 offset:6912
	v_mfma_f32_16x16x32_bf16 v[82:85], v[222:225], v[250:253], v[82:85]
	ds_read_b128 v[146:149], v129 offset:36864
	v_mfma_f32_16x16x32_bf16 v[78:81], v[226:229], v[238:241], v[78:81]
	ds_read_b128 v[150:153], v129 offset:39168
	v_mfma_f32_16x16x32_bf16 v[74:77], v[226:229], v[242:245], v[74:77]
	ds_read_b128 v[162:165], v129 offset:41472
	v_mfma_f32_16x16x32_bf16 v[70:73], v[226:229], v[246:249], v[70:73]
	ds_read_b128 v[166:169], v129 offset:43776
	v_mfma_f32_16x16x32_bf16 v[66:69], v[226:229], v[250:253], v[66:69]
	v_mfma_f32_16x16x32_bf16 v[62:65], v[230:233], v[238:241], v[62:65]
	v_add_u32_e32 v112, 0x100, v112
	v_mfma_f32_16x16x32_bf16 v[58:61], v[230:233], v[242:245], v[58:61]
	v_add_u32_e32 v110, 0x100, v110
	v_mfma_f32_16x16x32_bf16 v[54:57], v[230:233], v[246:249], v[54:57]
	v_add_u32_e32 v108, 0x100, v108
	v_mfma_f32_16x16x32_bf16 v[50:53], v[230:233], v[250:253], v[50:53]
	v_add_u32_e32 v106, 0x100, v106
	v_mfma_f32_16x16x32_bf16 v[46:49], v[234:237], v[238:241], v[46:49]
	v_add_u32_e32 v104, 0x100, v104
	v_mfma_f32_16x16x32_bf16 v[42:45], v[234:237], v[242:245], v[42:45]
	v_add_u32_e32 v102, 0x100, v102
	v_mfma_f32_16x16x32_bf16 v[38:41], v[234:237], v[246:249], v[38:41]
	v_add_u32_e32 v100, 0x100, v100
	v_mfma_f32_16x16x32_bf16 v[34:37], v[234:237], v[250:253], v[34:37]
	v_add_u32_e32 v98, 0x100, v98
	s_add_i32 s11, s11, 1
	s_cmp_lg_u32 s11, 7
	s_cbranch_scc1 .Lgk2_loop
	s_waitcnt lgkmcnt(0)
	ds_read_b128 v[222:225], v161 offset:64
	ds_read_b128 v[226:229], v161 offset:2368
	ds_read_b128 v[230:233], v161 offset:4672
	ds_read_b128 v[234:237], v161 offset:6976
	ds_read_b128 v[238:241], v129 offset:36928
	ds_read_b128 v[242:245], v129 offset:39232
	ds_read_b128 v[246:249], v129 offset:41536
	ds_read_b128 v[250:253], v129 offset:43840
	v_mfma_f32_16x16x32_bf16 v[94:97], v[130:133], v[146:149], v[94:97]
	v_mfma_f32_16x16x32_bf16 v[90:93], v[130:133], v[150:153], v[90:93]
	v_mfma_f32_16x16x32_bf16 v[86:89], v[130:133], v[162:165], v[86:89]
	v_mfma_f32_16x16x32_bf16 v[82:85], v[130:133], v[166:169], v[82:85]
	s_waitcnt vmcnt(0)
	ds_write_b128 v122, v[22:25] offset:18432
	ds_write_b128 v122, v[6:9] offset:55296
	v_mfma_f32_16x16x32_bf16 v[78:81], v[134:137], v[146:149], v[78:81]
	ds_write_b128 v121, v[18:21] offset:18432
	ds_write_b128 v121, v[10:13] offset:55296
	v_mfma_f32_16x16x32_bf16 v[74:77], v[134:137], v[150:153], v[74:77]
	ds_write_b128 v120, v[14:17] offset:18432
	ds_write_b128 v120, v[2:5] offset:55296
	v_mfma_f32_16x16x32_bf16 v[70:73], v[134:137], v[162:165], v[70:73]
	ds_write_b128 v124, v[26:29] offset:18432
	ds_write_b128 v124, v[30:33] offset:55296
	v_mfma_f32_16x16x32_bf16 v[66:69], v[134:137], v[166:169], v[66:69]
	v_mfma_f32_16x16x32_bf16 v[62:65], v[138:141], v[146:149], v[62:65]
	v_mfma_f32_16x16x32_bf16 v[58:61], v[138:141], v[150:153], v[58:61]
	v_mfma_f32_16x16x32_bf16 v[54:57], v[138:141], v[162:165], v[54:57]
	v_mfma_f32_16x16x32_bf16 v[50:53], v[138:141], v[166:169], v[50:53]
	v_mfma_f32_16x16x32_bf16 v[46:49], v[142:145], v[146:149], v[46:49]
	v_mfma_f32_16x16x32_bf16 v[42:45], v[142:145], v[150:153], v[42:45]
	v_mfma_f32_16x16x32_bf16 v[38:41], v[142:145], v[162:165], v[38:41]
	v_mfma_f32_16x16x32_bf16 v[34:37], v[142:145], v[166:169], v[34:37]
	s_waitcnt lgkmcnt(0)
	s_barrier
	ds_read_b128 v[130:133], v161 offset:18432
	v_mfma_f32_16x16x32_bf16 v[94:97], v[222:225], v[238:241], v[94:97]
	ds_read_b128 v[134:137], v161 offset:20736
	v_mfma_f32_16x16x32_bf16 v[90:93], v[222:225], v[242:245], v[90:93]
	ds_read_b128 v[138:141], v161 offset:23040
	v_mfma_f32_16x16x32_bf16 v[86:89], v[222:225], v[246:249], v[86:89]
	ds_read_b128 v[142:145], v161 offset:25344
	v_mfma_f32_16x16x32_bf16 v[82:85], v[222:225], v[250:253], v[82:85]
	ds_read_b128 v[146:149], v129 offset:55296
	v_mfma_f32_16x16x32_bf16 v[78:81], v[226:229], v[238:241], v[78:81]
	ds_read_b128 v[150:153], v129 offset:57600
	v_mfma_f32_16x16x32_bf16 v[74:77], v[226:229], v[242:245], v[74:77]
	ds_read_b128 v[162:165], v129 offset:59904
	v_mfma_f32_16x16x32_bf16 v[70:73], v[226:229], v[246:249], v[70:73]
	ds_read_b128 v[166:169], v129 offset:62208
	v_mfma_f32_16x16x32_bf16 v[66:69], v[226:229], v[250:253], v[66:69]
	v_mfma_f32_16x16x32_bf16 v[62:65], v[230:233], v[238:241], v[62:65]
	v_mfma_f32_16x16x32_bf16 v[58:61], v[230:233], v[242:245], v[58:61]
	v_mfma_f32_16x16x32_bf16 v[54:57], v[230:233], v[246:249], v[54:57]
	v_mfma_f32_16x16x32_bf16 v[50:53], v[230:233], v[250:253], v[50:53]
	v_mfma_f32_16x16x32_bf16 v[46:49], v[234:237], v[238:241], v[46:49]
	v_mfma_f32_16x16x32_bf16 v[42:45], v[234:237], v[242:245], v[42:45]
	v_mfma_f32_16x16x32_bf16 v[38:41], v[234:237], v[246:249], v[38:41]
	v_mfma_f32_16x16x32_bf16 v[34:37], v[234:237], v[250:253], v[34:37]
	s_waitcnt lgkmcnt(0)
; DEV float sigmf(float x) { return __builtin_amdgcn_rcpf(1.f + __expf(-x)); }
; template <int EPI, bool AF32>
; DEV void gemm_tile(const void* Ap, int lda, const u16* Bt, int ldb, int K, int m0, int n0, const Epi& ea, char* smem) {
;     ...
; #pragma unroll
;   for (int m = 0; m < 4; m++) {
; #pragma unroll
;     for (int j = 0; j < 4; j++) {
;       const int row = m0 + wr * 64 + m * 16 + fq * 4 + j;
;       if (EPI == EP_F32) {
;         float* C = (float*)ea.p0;
; #pragma unroll
;         for (int n = 0; n < 4; n++) C[(size_t)row * ea.ld + cb + n * 16 + fr] = acc[m][n][j];
;       } else if (EPI == EP_BF16) {
;         u16* C = (u16*)ea.p0;
; #pragma unroll
;         for (int n = 0; n < 4; n++) C[(size_t)row * ea.ld + cb + n * 16 + fr] = f2bf(acc[m][n][j]);
;       } else if (EPI == EP_SIG) {
;         u16* C = (u16*)ea.p0;
; #pragma unroll
;         for (int n = 0; n < 4; n++) C[(size_t)row * ea.ld + cb + n * 16 + fr] = f2bf(sigmf(acc[m][n][j]));
	ds_read_b128 v[222:225], v161 offset:18496
	ds_read_b128 v[226:229], v161 offset:20800
	ds_read_b128 v[230:233], v161 offset:23104
	ds_read_b128 v[234:237], v161 offset:25408
	ds_read_b128 v[238:241], v129 offset:55360
	ds_read_b128 v[242:245], v129 offset:57664
	ds_read_b128 v[246:249], v129 offset:59968
	ds_read_b128 v[250:253], v129 offset:62272
	v_mfma_f32_16x16x32_bf16 v[94:97], v[130:133], v[146:149], v[94:97]
	v_mfma_f32_16x16x32_bf16 v[90:93], v[130:133], v[150:153], v[90:93]
	v_mfma_f32_16x16x32_bf16 v[86:89], v[130:133], v[162:165], v[86:89]
	v_mfma_f32_16x16x32_bf16 v[82:85], v[130:133], v[166:169], v[82:85]
	v_mfma_f32_16x16x32_bf16 v[78:81], v[134:137], v[146:149], v[78:81]
	v_mfma_f32_16x16x32_bf16 v[74:77], v[134:137], v[150:153], v[74:77]
	v_mfma_f32_16x16x32_bf16 v[70:73], v[134:137], v[162:165], v[70:73]
	v_mfma_f32_16x16x32_bf16 v[66:69], v[134:137], v[166:169], v[66:69]
	v_mfma_f32_16x16x32_bf16 v[62:65], v[138:141], v[146:149], v[62:65]
	v_mfma_f32_16x16x32_bf16 v[58:61], v[138:141], v[150:153], v[58:61]
	v_mfma_f32_16x16x32_bf16 v[54:57], v[138:141], v[162:165], v[54:57]
	v_mfma_f32_16x16x32_bf16 v[50:53], v[138:141], v[166:169], v[50:53]
	v_mfma_f32_16x16x32_bf16 v[46:49], v[142:145], v[146:149], v[46:49]
	v_mfma_f32_16x16x32_bf16 v[42:45], v[142:145], v[150:153], v[42:45]
	v_mfma_f32_16x16x32_bf16 v[38:41], v[142:145], v[162:165], v[38:41]
	v_mfma_f32_16x16x32_bf16 v[34:37], v[142:145], v[166:169], v[34:37]
	s_waitcnt lgkmcnt(0)
	v_mfma_f32_16x16x32_bf16 v[94:97], v[222:225], v[238:241], v[94:97]
	v_mfma_f32_16x16x32_bf16 v[90:93], v[222:225], v[242:245], v[90:93]
	v_mfma_f32_16x16x32_bf16 v[86:89], v[222:225], v[246:249], v[86:89]
	v_mfma_f32_16x16x32_bf16 v[122:125], v[222:225], v[250:253], v[82:85]
	v_mfma_f32_16x16x32_bf16 v[30:33], v[230:233], v[238:241], v[62:65]
	v_mfma_f32_16x16x32_bf16 v[26:29], v[230:233], v[242:245], v[58:61]
	v_mfma_f32_16x16x32_bf16 v[22:25], v[230:233], v[246:249], v[54:57]
	v_mfma_f32_16x16x32_bf16 v[18:21], v[230:233], v[250:253], v[50:53]
	v_mfma_f32_16x16x32_bf16 v[14:17], v[234:237], v[238:241], v[46:49]
	v_mfma_f32_16x16x32_bf16 v[10:13], v[234:237], v[242:245], v[42:45]
	v_mfma_f32_16x16x32_bf16 v[6:9], v[234:237], v[246:249], v[38:41]
	v_mfma_f32_16x16x32_bf16 v[2:5], v[234:237], v[250:253], v[34:37]
	v_mfma_f32_16x16x32_bf16 v[46:49], v[226:229], v[238:241], v[78:81]
	v_mfma_f32_16x16x32_bf16 v[42:45], v[226:229], v[242:245], v[74:77]
	v_mfma_f32_16x16x32_bf16 v[38:41], v[226:229], v[246:249], v[70:73]
	v_mfma_f32_16x16x32_bf16 v[34:37], v[226:229], v[250:253], v[66:69]
	s_nop 7
	s_nop 1
	v_mul_f32_e32 v51, 0xbfb8aa3b, v94
	v_exp_f32_e32 v56, v51
	v_and_or_b32 v52, v114, 64, s10
	v_add_u32_e32 v0, s9, v117
	v_ashrrev_i32_e32 v53, 31, v52
	v_lshl_or_b32 v50, v116, 2, v0
	v_lshl_add_u64 v[52:53], v[52:53], 1, s[2:3]
	v_lshlrev_b32_e32 v0, 1, v115
	v_lshl_add_u64 v[52:53], v[52:53], 0, v[0:1]
	v_ashrrev_i32_e32 v51, 31, v50
	v_add_f32_e32 v0, 1.0, v56
	v_lshlrev_b64 v[54:55], 12, v[50:51]
	v_rcp_f32_e32 v0, v0
	v_mul_f32_e32 v51, 0xbfb8aa3b, v90
	v_exp_f32_e32 v51, v51
	v_lshl_add_u64 v[54:55], v[52:53], 0, v[54:55]
	v_cvt_pk_bf16_f32 v0, v0, s0
	s_barrier
	global_store_short v[54:55], v0, off
	v_add_f32_e32 v0, 1.0, v51
	v_mul_f32_e32 v51, 0xbfb8aa3b, v86
	v_exp_f32_e32 v51, v51
	v_mul_f32_e32 v56, 0xbfb8aa3b, v122
	v_exp_f32_e32 v56, v56
	v_rcp_f32_e32 v0, v0
	v_add_f32_e32 v51, 1.0, v51
	v_rcp_f32_e32 v51, v51
	v_add_f32_e32 v56, 1.0, v56
	v_rcp_f32_e32 v56, v56
	v_cvt_pk_bf16_f32 v0, v0, s0
	global_store_short v[54:55], v0, off offset:32
	v_cvt_pk_bf16_f32 v0, v51, s0
	global_store_short v[54:55], v0, off offset:64
	v_cvt_pk_bf16_f32 v0, v56, s0
	global_store_short v[54:55], v0, off offset:96
	v_mul_f32_e32 v0, 0xbfb8aa3b, v95
	v_exp_f32_e32 v0, v0
	v_mul_f32_e32 v51, 0xbfb8aa3b, v91
	v_or_b32_e32 v54, 1, v50
	v_exp_f32_e32 v51, v51
	v_add_f32_e32 v0, 1.0, v0
	v_rcp_f32_e32 v0, v0
	v_ashrrev_i32_e32 v55, 31, v54
	v_lshlrev_b64 v[54:55], 12, v[54:55]
	v_lshl_add_u64 v[54:55], v[52:53], 0, v[54:55]
	v_cvt_pk_bf16_f32 v0, v0, s0
	global_store_short v[54:55], v0, off
	v_add_f32_e32 v0, 1.0, v51
	v_mul_f32_e32 v51, 0xbfb8aa3b, v87
	v_exp_f32_e32 v51, v51
	v_mul_f32_e32 v56, 0xbfb8aa3b, v123
	v_exp_f32_e32 v56, v56
	v_rcp_f32_e32 v0, v0
	v_add_f32_e32 v51, 1.0, v51
	v_rcp_f32_e32 v51, v51
	v_add_f32_e32 v56, 1.0, v56
	v_rcp_f32_e32 v56, v56
	v_cvt_pk_bf16_f32 v0, v0, s0
	global_store_short v[54:55], v0, off offset:32
	v_cvt_pk_bf16_f32 v0, v51, s0
	global_store_short v[54:55], v0, off offset:64
	v_cvt_pk_bf16_f32 v0, v56, s0
	global_store_short v[54:55], v0, off offset:96
	v_mul_f32_e32 v0, 0xbfb8aa3b, v96
	v_exp_f32_e32 v0, v0
	v_mul_f32_e32 v51, 0xbfb8aa3b, v92
	v_or_b32_e32 v54, 2, v50
	v_exp_f32_e32 v51, v51
	v_add_f32_e32 v0, 1.0, v0
	v_rcp_f32_e32 v0, v0
	v_ashrrev_i32_e32 v55, 31, v54
	v_lshlrev_b64 v[54:55], 12, v[54:55]
	v_lshl_add_u64 v[54:55], v[52:53], 0, v[54:55]
	v_cvt_pk_bf16_f32 v0, v0, s0
	global_store_short v[54:55], v0, off
	v_add_f32_e32 v0, 1.0, v51
	v_mul_f32_e32 v51, 0xbfb8aa3b, v88
	v_exp_f32_e32 v51, v51
	v_mul_f32_e32 v56, 0xbfb8aa3b, v124
	v_exp_f32_e32 v56, v56
	v_rcp_f32_e32 v0, v0
	v_add_f32_e32 v51, 1.0, v51
	v_rcp_f32_e32 v51, v51
	v_add_f32_e32 v56, 1.0, v56
	v_rcp_f32_e32 v56, v56
	v_cvt_pk_bf16_f32 v0, v0, s0
	global_store_short v[54:55], v0, off offset:32
	v_cvt_pk_bf16_f32 v0, v51, s0
	global_store_short v[54:55], v0, off offset:64
	v_cvt_pk_bf16_f32 v0, v56, s0
	global_store_short v[54:55], v0, off offset:96
	v_mul_f32_e32 v0, 0xbfb8aa3b, v97
	v_exp_f32_e32 v0, v0
	v_mul_f32_e32 v51, 0xbfb8aa3b, v93
	v_or_b32_e32 v54, 3, v50
	v_exp_f32_e32 v51, v51
; DEV float sigmf(float x) { return __builtin_amdgcn_rcpf(1.f + __expf(-x)); }
; template <int EPI, bool AF32>
; DEV void gemm_tile(const void* Ap, int lda, const u16* Bt, int ldb, int K, int m0, int n0, const Epi& ea, char* smem) {
;     ...
; #pragma unroll
;   for (int m = 0; m < 4; m++) {
; #pragma unroll
;     for (int j = 0; j < 4; j++) {
;       const int row = m0 + wr * 64 + m * 16 + fq * 4 + j;
;       if (EPI == EP_F32) {
;         float* C = (float*)ea.p0;
; #pragma unroll
;         for (int n = 0; n < 4; n++) C[(size_t)row * ea.ld + cb + n * 16 + fr] = acc[m][n][j];
;       } else if (EPI == EP_BF16) {
;         u16* C = (u16*)ea.p0;
; #pragma unroll
;         for (int n = 0; n < 4; n++) C[(size_t)row * ea.ld + cb + n * 16 + fr] = f2bf(acc[m][n][j]);
;       } else if (EPI == EP_SIG) {
;         u16* C = (u16*)ea.p0;
; #pragma unroll
;         for (int n = 0; n < 4; n++) C[(size_t)row * ea.ld + cb + n * 16 + fr] = f2bf(sigmf(acc[m][n][j]));
	v_add_f32_e32 v0, 1.0, v0
	v_rcp_f32_e32 v0, v0
	v_ashrrev_i32_e32 v55, 31, v54
	v_lshlrev_b64 v[54:55], 12, v[54:55]
	v_lshl_add_u64 v[54:55], v[52:53], 0, v[54:55]
	v_cvt_pk_bf16_f32 v0, v0, s0
	global_store_short v[54:55], v0, off
	v_add_f32_e32 v0, 1.0, v51
	v_mul_f32_e32 v51, 0xbfb8aa3b, v89
	v_exp_f32_e32 v51, v51
	v_mul_f32_e32 v56, 0xbfb8aa3b, v125
	v_exp_f32_e32 v56, v56
	v_rcp_f32_e32 v0, v0
	v_add_f32_e32 v51, 1.0, v51
	v_rcp_f32_e32 v51, v51
	v_add_f32_e32 v56, 1.0, v56
	v_rcp_f32_e32 v56, v56
	v_cvt_pk_bf16_f32 v0, v0, s0
	global_store_short v[54:55], v0, off offset:32
	v_cvt_pk_bf16_f32 v0, v51, s0
	global_store_short v[54:55], v0, off offset:64
	v_cvt_pk_bf16_f32 v0, v56, s0
	global_store_short v[54:55], v0, off offset:96
	v_mul_f32_e32 v0, 0xbfb8aa3b, v46
	v_exp_f32_e32 v0, v0
	v_mul_f32_e32 v42, 0xbfb8aa3b, v42
	v_or_b32_e32 v54, 16, v50
	v_exp_f32_e32 v42, v42
	v_add_f32_e32 v0, 1.0, v0
	v_rcp_f32_e32 v0, v0
	v_mul_f32_e32 v38, 0xbfb8aa3b, v38
	v_ashrrev_i32_e32 v55, 31, v54
	v_exp_f32_e32 v38, v38
	v_mul_f32_e32 v34, 0xbfb8aa3b, v34
	v_lshlrev_b64 v[54:55], 12, v[54:55]
	v_exp_f32_e32 v34, v34
	v_lshl_add_u64 v[54:55], v[52:53], 0, v[54:55]
	v_cvt_pk_bf16_f32 v0, v0, s0
	global_store_short v[54:55], v0, off
	v_add_f32_e32 v0, 1.0, v42
	v_rcp_f32_e32 v0, v0
	v_add_f32_e32 v38, 1.0, v38
	v_rcp_f32_e32 v38, v38
	v_add_f32_e32 v34, 1.0, v34
	v_rcp_f32_e32 v34, v34
	v_cvt_pk_bf16_f32 v0, v0, s0
	global_store_short v[54:55], v0, off offset:32
	v_cvt_pk_bf16_f32 v0, v38, s0
	global_store_short v[54:55], v0, off offset:64
	v_cvt_pk_bf16_f32 v0, v34, s0
	global_store_short v[54:55], v0, off offset:96
	v_mul_f32_e32 v0, 0xbfb8aa3b, v47
	v_exp_f32_e32 v0, v0
	v_mul_f32_e32 v34, 0xbfb8aa3b, v43
	v_or_b32_e32 v46, 17, v50
	v_exp_f32_e32 v34, v34
	v_add_f32_e32 v0, 1.0, v0
	v_rcp_f32_e32 v0, v0
	v_ashrrev_i32_e32 v47, 31, v46
	v_lshlrev_b64 v[46:47], 12, v[46:47]
	v_lshl_add_u64 v[42:43], v[52:53], 0, v[46:47]
	v_cvt_pk_bf16_f32 v0, v0, s0
	global_store_short v[42:43], v0, off
	v_add_f32_e32 v0, 1.0, v34
	v_mul_f32_e32 v34, 0xbfb8aa3b, v39
	v_exp_f32_e32 v34, v34
	v_mul_f32_e32 v35, 0xbfb8aa3b, v35
	v_exp_f32_e32 v35, v35
	v_rcp_f32_e32 v0, v0
	v_add_f32_e32 v34, 1.0, v34
	v_rcp_f32_e32 v34, v34
	v_add_f32_e32 v35, 1.0, v35
	v_rcp_f32_e32 v35, v35
	v_cvt_pk_bf16_f32 v0, v0, s0
	global_store_short v[42:43], v0, off offset:32
	v_cvt_pk_bf16_f32 v0, v34, s0
	global_store_short v[42:43], v0, off offset:64
	v_cvt_pk_bf16_f32 v0, v35, s0
	global_store_short v[42:43], v0, off offset:96
	v_mul_f32_e32 v0, 0xbfb8aa3b, v48
	v_exp_f32_e32 v0, v0
	v_mul_f32_e32 v38, 0xbfb8aa3b, v44
	v_or_b32_e32 v34, 18, v50
	v_exp_f32_e32 v38, v38
	v_add_f32_e32 v0, 1.0, v0
	v_rcp_f32_e32 v0, v0
	v_ashrrev_i32_e32 v35, 31, v34
	v_lshlrev_b64 v[34:35], 12, v[34:35]
	v_lshl_add_u64 v[34:35], v[52:53], 0, v[34:35]
	v_cvt_pk_bf16_f32 v0, v0, s0
	global_store_short v[34:35], v0, off
	v_add_f32_e32 v0, 1.0, v38
	v_mul_f32_e32 v38, 0xbfb8aa3b, v40
	v_exp_f32_e32 v38, v38
	v_mul_f32_e32 v36, 0xbfb8aa3b, v36
	v_exp_f32_e32 v36, v36
	v_rcp_f32_e32 v0, v0
	v_add_f32_e32 v38, 1.0, v38
	v_rcp_f32_e32 v38, v38
	v_add_f32_e32 v36, 1.0, v36
	v_rcp_f32_e32 v36, v36
	v_cvt_pk_bf16_f32 v0, v0, s0
	global_store_short v[34:35], v0, off offset:32
	v_cvt_pk_bf16_f32 v0, v38, s0
	global_store_short v[34:35], v0, off offset:64
	v_cvt_pk_bf16_f32 v0, v36, s0
	global_store_short v[34:35], v0, off offset:96
	v_mul_f32_e32 v0, 0xbfb8aa3b, v49
	v_exp_f32_e32 v0, v0
	v_mul_f32_e32 v36, 0xbfb8aa3b, v45
	v_or_b32_e32 v34, 19, v50
	v_exp_f32_e32 v36, v36
	v_add_f32_e32 v0, 1.0, v0
	v_rcp_f32_e32 v0, v0
	v_ashrrev_i32_e32 v35, 31, v34
	v_lshlrev_b64 v[34:35], 12, v[34:35]
	v_lshl_add_u64 v[34:35], v[52:53], 0, v[34:35]
	v_cvt_pk_bf16_f32 v0, v0, s0
	global_store_short v[34:35], v0, off
	v_add_f32_e32 v0, 1.0, v36
	v_mul_f32_e32 v36, 0xbfb8aa3b, v41
	v_exp_f32_e32 v36, v36
	v_mul_f32_e32 v37, 0xbfb8aa3b, v37
	v_exp_f32_e32 v37, v37
	v_rcp_f32_e32 v0, v0
	v_add_f32_e32 v36, 1.0, v36
	v_rcp_f32_e32 v36, v36
	v_add_f32_e32 v37, 1.0, v37
	v_rcp_f32_e32 v37, v37
	v_cvt_pk_bf16_f32 v0, v0, s0
	global_store_short v[34:35], v0, off offset:32
	v_cvt_pk_bf16_f32 v0, v36, s0
	global_store_short v[34:35], v0, off offset:64
	v_cvt_pk_bf16_f32 v0, v37, s0
	global_store_short v[34:35], v0, off offset:96
	v_mul_f32_e32 v0, 0xbfb8aa3b, v30
	v_exp_f32_e32 v0, v0
	v_mul_f32_e32 v26, 0xbfb8aa3b, v26
	v_or_b32_e32 v34, 32, v50
	v_exp_f32_e32 v26, v26
	v_add_f32_e32 v0, 1.0, v0
	v_rcp_f32_e32 v0, v0
	v_mul_f32_e32 v22, 0xbfb8aa3b, v22
	v_ashrrev_i32_e32 v35, 31, v34
	v_exp_f32_e32 v22, v22
	v_mul_f32_e32 v18, 0xbfb8aa3b, v18
	v_lshlrev_b64 v[34:35], 12, v[34:35]
	v_exp_f32_e32 v18, v18
	v_lshl_add_u64 v[34:35], v[52:53], 0, v[34:35]
	v_cvt_pk_bf16_f32 v0, v0, s0
	global_store_short v[34:35], v0, off
	v_add_f32_e32 v0, 1.0, v26
	v_rcp_f32_e32 v0, v0
	v_add_f32_e32 v22, 1.0, v22
	v_rcp_f32_e32 v22, v22
	v_add_f32_e32 v18, 1.0, v18
	v_rcp_f32_e32 v18, v18
	v_cvt_pk_bf16_f32 v0, v0, s0
	global_store_short v[34:35], v0, off offset:32
	v_cvt_pk_bf16_f32 v0, v22, s0
	global_store_short v[34:35], v0, off offset:64
	v_cvt_pk_bf16_f32 v0, v18, s0
	global_store_short v[34:35], v0, off offset:96
	v_mul_f32_e32 v0, 0xbfb8aa3b, v31
	v_exp_f32_e32 v0, v0
	v_mul_f32_e32 v18, 0xbfb8aa3b, v27
	v_or_b32_e32 v30, 33, v50
	v_exp_f32_e32 v18, v18
	v_add_f32_e32 v0, 1.0, v0
	v_rcp_f32_e32 v0, v0
	v_ashrrev_i32_e32 v31, 31, v30
	v_lshlrev_b64 v[30:31], 12, v[30:31]
	v_lshl_add_u64 v[26:27], v[52:53], 0, v[30:31]
	v_cvt_pk_bf16_f32 v0, v0, s0
	global_store_short v[26:27], v0, off
	v_add_f32_e32 v0, 1.0, v18
	v_mul_f32_e32 v18, 0xbfb8aa3b, v23
; DEV float sigmf(float x) { return __builtin_amdgcn_rcpf(1.f + __expf(-x)); }
; template <int EPI, bool AF32>
; DEV void gemm_tile(const void* Ap, int lda, const u16* Bt, int ldb, int K, int m0, int n0, const Epi& ea, char* smem) {
;     ...
; #pragma unroll
;   for (int m = 0; m < 4; m++) {
; #pragma unroll
;     for (int j = 0; j < 4; j++) {
;       const int row = m0 + wr * 64 + m * 16 + fq * 4 + j;
;       if (EPI == EP_F32) {
;         float* C = (float*)ea.p0;
; #pragma unroll
;         for (int n = 0; n < 4; n++) C[(size_t)row * ea.ld + cb + n * 16 + fr] = acc[m][n][j];
;       } else if (EPI == EP_BF16) {
;         u16* C = (u16*)ea.p0;
; #pragma unroll
;         for (int n = 0; n < 4; n++) C[(size_t)row * ea.ld + cb + n * 16 + fr] = f2bf(acc[m][n][j]);
;       } else if (EPI == EP_SIG) {
;         u16* C = (u16*)ea.p0;
; #pragma unroll
;         for (int n = 0; n < 4; n++) C[(size_t)row * ea.ld + cb + n * 16 + fr] = f2bf(sigmf(acc[m][n][j]));
	v_exp_f32_e32 v18, v18
	v_mul_f32_e32 v19, 0xbfb8aa3b, v19
	v_exp_f32_e32 v19, v19
	v_rcp_f32_e32 v0, v0
	v_add_f32_e32 v18, 1.0, v18
	v_rcp_f32_e32 v18, v18
	v_add_f32_e32 v19, 1.0, v19
	v_rcp_f32_e32 v19, v19
	v_cvt_pk_bf16_f32 v0, v0, s0
	global_store_short v[26:27], v0, off offset:32
	v_cvt_pk_bf16_f32 v0, v18, s0
	global_store_short v[26:27], v0, off offset:64
	v_cvt_pk_bf16_f32 v0, v19, s0
	global_store_short v[26:27], v0, off offset:96
	v_mul_f32_e32 v0, 0xbfb8aa3b, v32
	v_exp_f32_e32 v0, v0
	v_mul_f32_e32 v22, 0xbfb8aa3b, v28
	v_or_b32_e32 v18, 34, v50
	v_exp_f32_e32 v22, v22
	v_add_f32_e32 v0, 1.0, v0
	v_rcp_f32_e32 v0, v0
	v_ashrrev_i32_e32 v19, 31, v18
	v_lshlrev_b64 v[18:19], 12, v[18:19]
	v_lshl_add_u64 v[18:19], v[52:53], 0, v[18:19]
	v_cvt_pk_bf16_f32 v0, v0, s0
	global_store_short v[18:19], v0, off
	v_add_f32_e32 v0, 1.0, v22
	v_mul_f32_e32 v22, 0xbfb8aa3b, v24
	v_exp_f32_e32 v22, v22
	v_mul_f32_e32 v20, 0xbfb8aa3b, v20
	v_exp_f32_e32 v20, v20
	v_rcp_f32_e32 v0, v0
	v_add_f32_e32 v22, 1.0, v22
	v_rcp_f32_e32 v22, v22
	v_add_f32_e32 v20, 1.0, v20
	v_rcp_f32_e32 v20, v20
	v_cvt_pk_bf16_f32 v0, v0, s0
	global_store_short v[18:19], v0, off offset:32
	v_cvt_pk_bf16_f32 v0, v22, s0
	global_store_short v[18:19], v0, off offset:64
	v_cvt_pk_bf16_f32 v0, v20, s0
	global_store_short v[18:19], v0, off offset:96
	v_mul_f32_e32 v0, 0xbfb8aa3b, v33
	v_exp_f32_e32 v0, v0
	v_mul_f32_e32 v20, 0xbfb8aa3b, v29
	v_or_b32_e32 v18, 35, v50
	v_exp_f32_e32 v20, v20
	v_add_f32_e32 v0, 1.0, v0
	v_rcp_f32_e32 v0, v0
	v_ashrrev_i32_e32 v19, 31, v18
	v_lshlrev_b64 v[18:19], 12, v[18:19]
	v_lshl_add_u64 v[18:19], v[52:53], 0, v[18:19]
	v_cvt_pk_bf16_f32 v0, v0, s0
	global_store_short v[18:19], v0, off
	v_add_f32_e32 v0, 1.0, v20
	v_mul_f32_e32 v20, 0xbfb8aa3b, v25
	v_exp_f32_e32 v20, v20
	v_mul_f32_e32 v21, 0xbfb8aa3b, v21
	v_exp_f32_e32 v21, v21
	v_rcp_f32_e32 v0, v0
	v_add_f32_e32 v20, 1.0, v20
	v_rcp_f32_e32 v20, v20
	v_add_f32_e32 v21, 1.0, v21
	v_rcp_f32_e32 v21, v21
	v_cvt_pk_bf16_f32 v0, v0, s0
	global_store_short v[18:19], v0, off offset:32
	v_cvt_pk_bf16_f32 v0, v20, s0
	global_store_short v[18:19], v0, off offset:64
	v_cvt_pk_bf16_f32 v0, v21, s0
	global_store_short v[18:19], v0, off offset:96
	v_mul_f32_e32 v0, 0xbfb8aa3b, v14
	v_exp_f32_e32 v0, v0
	v_mul_f32_e32 v10, 0xbfb8aa3b, v10
	v_or_b32_e32 v18, 48, v50
	v_exp_f32_e32 v10, v10
	v_add_f32_e32 v0, 1.0, v0
	v_rcp_f32_e32 v0, v0
	v_mul_f32_e32 v6, 0xbfb8aa3b, v6
	v_ashrrev_i32_e32 v19, 31, v18
	v_exp_f32_e32 v6, v6
	v_mul_f32_e32 v2, 0xbfb8aa3b, v2
	v_lshlrev_b64 v[18:19], 12, v[18:19]
	v_exp_f32_e32 v2, v2
	v_lshl_add_u64 v[18:19], v[52:53], 0, v[18:19]
	v_cvt_pk_bf16_f32 v0, v0, s0
	global_store_short v[18:19], v0, off
	v_add_f32_e32 v0, 1.0, v10
	v_rcp_f32_e32 v0, v0
	v_add_f32_e32 v6, 1.0, v6
	v_rcp_f32_e32 v6, v6
	v_add_f32_e32 v2, 1.0, v2
	v_rcp_f32_e32 v2, v2
	v_cvt_pk_bf16_f32 v0, v0, s0
	global_store_short v[18:19], v0, off offset:32
	v_cvt_pk_bf16_f32 v0, v6, s0
	global_store_short v[18:19], v0, off offset:64
	v_cvt_pk_bf16_f32 v0, v2, s0
	global_store_short v[18:19], v0, off offset:96
	v_mul_f32_e32 v0, 0xbfb8aa3b, v15
	v_exp_f32_e32 v0, v0
	v_mul_f32_e32 v2, 0xbfb8aa3b, v11
	v_or_b32_e32 v14, 49, v50
	v_exp_f32_e32 v2, v2
	v_add_f32_e32 v0, 1.0, v0
	v_rcp_f32_e32 v0, v0
	v_ashrrev_i32_e32 v15, 31, v14
	v_lshlrev_b64 v[14:15], 12, v[14:15]
	v_lshl_add_u64 v[10:11], v[52:53], 0, v[14:15]
	v_cvt_pk_bf16_f32 v0, v0, s0
	global_store_short v[10:11], v0, off
	v_add_f32_e32 v0, 1.0, v2
	v_mul_f32_e32 v2, 0xbfb8aa3b, v7
	v_exp_f32_e32 v2, v2
	v_mul_f32_e32 v3, 0xbfb8aa3b, v3
	v_exp_f32_e32 v3, v3
	v_rcp_f32_e32 v0, v0
	v_add_f32_e32 v2, 1.0, v2
	v_rcp_f32_e32 v2, v2
	v_add_f32_e32 v3, 1.0, v3
	v_rcp_f32_e32 v3, v3
	v_cvt_pk_bf16_f32 v0, v0, s0
	global_store_short v[10:11], v0, off offset:32
	v_cvt_pk_bf16_f32 v0, v2, s0
	global_store_short v[10:11], v0, off offset:64
	v_cvt_pk_bf16_f32 v0, v3, s0
	global_store_short v[10:11], v0, off offset:96
	v_mul_f32_e32 v0, 0xbfb8aa3b, v16
	v_exp_f32_e32 v0, v0
	v_mul_f32_e32 v6, 0xbfb8aa3b, v12
	v_or_b32_e32 v2, 50, v50
	v_exp_f32_e32 v6, v6
	v_add_f32_e32 v0, 1.0, v0
	v_rcp_f32_e32 v0, v0
	v_ashrrev_i32_e32 v3, 31, v2
	v_lshlrev_b64 v[2:3], 12, v[2:3]
	v_lshl_add_u64 v[2:3], v[52:53], 0, v[2:3]
	v_cvt_pk_bf16_f32 v0, v0, s0
	global_store_short v[2:3], v0, off
	v_add_f32_e32 v0, 1.0, v6
	v_mul_f32_e32 v6, 0xbfb8aa3b, v8
	v_exp_f32_e32 v6, v6
	v_mul_f32_e32 v4, 0xbfb8aa3b, v4
	v_exp_f32_e32 v4, v4
	v_rcp_f32_e32 v0, v0
	v_add_f32_e32 v6, 1.0, v6
	v_rcp_f32_e32 v6, v6
	v_add_f32_e32 v4, 1.0, v4
	v_rcp_f32_e32 v4, v4
	v_cvt_pk_bf16_f32 v0, v0, s0
	global_store_short v[2:3], v0, off offset:32
	v_cvt_pk_bf16_f32 v0, v6, s0
	global_store_short v[2:3], v0, off offset:64
	v_cvt_pk_bf16_f32 v0, v4, s0
	global_store_short v[2:3], v0, off offset:96
	v_mul_f32_e32 v0, 0xbfb8aa3b, v17
	v_exp_f32_e32 v0, v0
	v_mul_f32_e32 v4, 0xbfb8aa3b, v13
	v_or_b32_e32 v2, 51, v50
	v_exp_f32_e32 v4, v4
	v_add_f32_e32 v0, 1.0, v0
	v_rcp_f32_e32 v0, v0
	v_ashrrev_i32_e32 v3, 31, v2
	v_lshlrev_b64 v[2:3], 12, v[2:3]
	v_lshl_add_u64 v[2:3], v[52:53], 0, v[2:3]
	v_cvt_pk_bf16_f32 v0, v0, s0
	global_store_short v[2:3], v0, off
	v_add_f32_e32 v0, 1.0, v4
	v_mul_f32_e32 v4, 0xbfb8aa3b, v9
	v_exp_f32_e32 v4, v4
	v_mul_f32_e32 v5, 0xbfb8aa3b, v5
	v_exp_f32_e32 v5, v5
	v_rcp_f32_e32 v0, v0
	v_add_f32_e32 v4, 1.0, v4
	v_rcp_f32_e32 v4, v4
	v_add_f32_e32 v5, 1.0, v5
	v_rcp_f32_e32 v5, v5
	v_cvt_pk_bf16_f32 v0, v0, s0
	global_store_short v[2:3], v0, off offset:32
	v_cvt_pk_bf16_f32 v0, v4, s0
	global_store_short v[2:3], v0, off offset:64
	v_cvt_pk_bf16_f32 v0, v5, s0
	v_readfirstlane_b32 s0, v198
	global_store_short v[2:3], v0, off offset:96
	s_add_i32 s8, s0, s8
	s_cmpk_lt_i32 s8, 0x1040
	s_cbranch_scc1 .LBB0_1262

; DEV int tidx() { int t = threadIdx.x; asm volatile("" : "+v"(t)); return t; }
; template <int EPI, bool AF32>
; DEV void gemm_tile(const void* Ap, int lda, const u16* Bt, int ldb, int K, int m0, int n0, const Epi& ea, char* smem) {
;   u16* sA = (u16*)smem;
;   u16* sB = sA + 2 * 128 * 72;
;   const int tid = tidx(), lane = tid & 63, wv = tid >> 6;
;   const int wr = wv >> 1, wc = wv & 1, fr = lane & 15, fq = lane >> 4;
;   f32x4 acc[4][4];
; #pragma unroll
;   for (int m = 0; m < 4; m++)
; #pragma unroll
;     for (int n = 0; n < 4; n++) acc[m][n] = (f32x4){0.f, 0.f, 0.f, 0.f};
;   u32x4 ra[4], rb[4];
;   f32x4 rfa[8];
;   const int nk = K >> 6;
;   auto gload = [&](int kt) {
;     const int k0 = kt << 6;
; #pragma unroll
;     for (int i = 0; i < 4; i++) {
;       const int c = tid + i * 256, row = c >> 3, kc = c & 7;
;       if (AF32) {
;         const float* pa = (const float*)Ap + (size_t)(m0 + row) * lda + k0 + kc * 8;
;         rfa[2 * i] = *(const f32x4*)pa;
;         rfa[2 * i + 1] = *(const f32x4*)(pa + 4);
;       } else {
;         ra[i] = *(const u32x4*)((const u16*)Ap + (size_t)(m0 + row) * lda + k0 + kc * 8);
;       }
;       rb[i] = *(const u32x4*)(Bt + (size_t)(n0 + row) * ldb + k0 + kc * 8);
;     }
;   };
;   auto swrite = [&](int buf) {
; #pragma unroll
;     for (int i = 0; i < 4; i++) {
;       const int c = tid + i * 256, row = c >> 3, kc = c & 7;
;       u32x4 va;
;       if (AF32) {
;         va = (u32x4){pack2(rfa[2 * i][0], rfa[2 * i][1]), pack2(rfa[2 * i][2], rfa[2 * i][3]),
;                      pack2(rfa[2 * i + 1][0], rfa[2 * i + 1][1]), pack2(rfa[2 * i + 1][2], rfa[2 * i + 1][3])};
;       } else {
;         va = ra[i];
;       }
;       *(u32x4*)(sA + buf * 9216 + row * 72 + kc * 8) = va;
;       *(u32x4*)(sB + buf * 9216 + row * 72 + kc * 8) = rb[i];
;     }
;   };
;   gload(0);
;   swrite(0);
;   if (nk > 1) gload(1);
;   __syncthreads();
.LBB0_1304:
	s_ashr_i32 s0, s16, 31
	s_lshr_b32 s0, s0, 24
	s_add_i32 s0, s16, s0
	s_ashr_i32 s1, s0, 8
	s_and_b32 s0, s0, 0xffffff00
	s_lshl_b32 s18, s1, 5
	s_sub_i32 s17, s16, s0
	s_sub_i32 s0, 0x104, s18
	s_min_u32 s19, s0, 32
	v_cvt_f32_ubyte0_e32 v2, s19
	v_cvt_f32_i32_e32 v0, s17
	v_rcp_iflag_f32_e32 v3, v2
	s_ashr_i32 s0, s17, 30
	s_or_b32 s20, s0, 1
	s_waitcnt vmcnt(12)
	v_mov_b32_e32 v114, v157
	v_mul_f32_e32 v3, v0, v3
	v_trunc_f32_e32 v3, v3
	v_fma_f32 v0, -v3, v2, v0
	v_cvt_i32_f32_e32 v3, v3
	v_cmp_ge_f32_e64 s[0:1], |v0|, v2
	s_and_b64 s[0:1], s[0:1], exec
	s_cselect_b32 s0, s20, 0
	v_readfirstlane_b32 s1, v3
	s_add_i32 s0, s1, s0
	s_sext_i32_i16 s1, s0
	s_mul_i32 s0, s0, s19
	s_sub_i32 s0, s17, s0
	s_sext_i32_i16 s0, s0
	s_add_i32 s18, s18, s0
	s_lshl_b32 s18, s18, 7
	s_lshl_b32 s17, s1, 7
	v_ashrrev_i32_e32 v8, 3, v114
	v_add_u32_e32 v2, s18, v8
	v_ashrrev_i32_e32 v3, 31, v2
	v_lshlrev_b32_e32 v0, 3, v114
	v_add_u32_e32 v4, 0x100, v114
	v_lshlrev_b64 v[58:59], 11, v[2:3]
	v_and_b32_e32 v0, 56, v0
	v_ashrrev_i32_e32 v9, 3, v4
	v_lshl_add_u64 v[2:3], s[6:7], 0, v[58:59]
	v_lshlrev_b32_e32 v0, 1, v0
	v_add_u32_e32 v4, s18, v9
	v_add_u32_e32 v6, 0x200, v114
	v_lshl_add_u64 v[14:15], v[2:3], 0, v[0:1]
	v_add_u32_e32 v2, s17, v8
	v_ashrrev_i32_e32 v5, 31, v4
	v_ashrrev_i32_e32 v10, 3, v6
	v_ashrrev_i32_e32 v3, 31, v2
	v_lshlrev_b64 v[62:63], 11, v[4:5]
	v_add_u32_e32 v6, s18, v10
	v_lshlrev_b64 v[60:61], 11, v[2:3]
	v_lshl_add_u64 v[4:5], s[6:7], 0, v[62:63]
	v_ashrrev_i32_e32 v7, 31, v6
	v_lshl_add_u64 v[2:3], s[10:11], 0, v[60:61]
	v_lshl_add_u64 v[16:17], v[4:5], 0, v[0:1]
	v_add_u32_e32 v4, s17, v9
	v_lshlrev_b64 v[66:67], 11, v[6:7]
	v_lshl_add_u64 v[2:3], v[2:3], 0, v[0:1]
	v_ashrrev_i32_e32 v5, 31, v4
	v_lshl_add_u64 v[6:7], s[6:7], 0, v[66:67]
	global_load_dwordx4 v[30:33], v[2:3], off
	v_lshlrev_b64 v[64:65], 11, v[4:5]
	v_lshl_add_u64 v[68:69], v[6:7], 0, v[0:1]
	v_add_u32_e32 v6, s17, v10
	global_load_dwordx4 v[26:29], v[14:15], off
	global_load_dwordx4 v[34:37], v[16:17], off
	v_lshl_add_u64 v[4:5], s[10:11], 0, v[64:65]
	v_ashrrev_i32_e32 v7, 31, v6
	v_lshl_add_u64 v[4:5], v[4:5], 0, v[0:1]
	v_lshlrev_b64 v[70:71], 11, v[6:7]
	global_load_dwordx4 v[38:41], v[4:5], off
	v_lshl_add_u64 v[6:7], s[10:11], 0, v[70:71]
	global_load_dwordx4 v[42:45], v[68:69], off
	v_lshl_add_u64 v[18:19], v[6:7], 0, v[0:1]
	global_load_dwordx4 v[46:49], v[18:19], off
	v_add_u32_e32 v6, 0x300, v114
	v_ashrrev_i32_e32 v80, 3, v6
	v_add_u32_e32 v6, s18, v80
	v_ashrrev_i32_e32 v7, 31, v6
	v_lshlrev_b64 v[72:73], 11, v[6:7]
	v_lshl_add_u64 v[6:7], s[6:7], 0, v[72:73]
	v_lshl_add_u64 v[74:75], v[6:7], 0, v[0:1]
	v_add_u32_e32 v6, s17, v80
	v_ashrrev_i32_e32 v7, 31, v6
	v_lshlrev_b64 v[76:77], 11, v[6:7]
	v_lshl_add_u64 v[6:7], s[10:11], 0, v[76:77]
	v_lshl_add_u64 v[78:79], v[6:7], 0, v[0:1]
	global_load_dwordx4 v[50:53], v[74:75], off
	global_load_dwordx4 v[54:57], v[78:79], off
	s_waitcnt vmcnt(19)
	v_mul_lo_u32 v118, v8, s71
	v_mul_lo_u32 v119, v9, s71
	s_waitcnt vmcnt(18)
	v_mul_lo_u32 v123, v10, s71
	global_load_dwordx4 v[6:9], v[2:3], off offset:128
	global_load_dwordx4 v[10:13], v[4:5], off offset:128
	s_nop 0
	global_load_dwordx4 v[2:5], v[18:19], off offset:128
	global_load_dwordx4 v[22:25], v[14:15], off offset:128
	s_nop 0
	global_load_dwordx4 v[18:21], v[16:17], off offset:128
	s_nop 0
	global_load_dwordx4 v[14:17], v[68:69], off offset:128
	v_bfe_u32 v161, v157, 3, 4
	v_add_u32_e32 v161, 4, v161
	v_lshlrev_b32_e32 v161, 1, v161
	v_and_b32_e32 v161, 16, v161
	v_xor_b32_e32 v129, v0, v161
	v_lshl_add_u32 v122, v118, 1, v129
	v_lshl_add_u32 v121, v119, 1, v129
	v_lshl_add_u32 v120, v123, 1, v129
	v_and_b32_e32 v115, 15, v114
	s_waitcnt vmcnt(23)
	v_mul_lo_u32 v126, v80, s71
	v_bfe_u32 v116, v114, 4, 2
	v_lshl_add_u32 v124, v126, 1, v129
	s_mov_b32 s19, 0
	v_lshlrev_b32_e32 v125, 4, v116
	v_and_b32_e32 v161, 15, v157
	v_add_u32_e32 v161, 4, v161
	v_lshlrev_b32_e32 v161, 1, v161
	v_and_b32_e32 v161, 16, v161
	v_xor_b32_e32 v125, v125, v161
	s_mov_b64 s[0:1], 0
	s_waitcnt vmcnt(13)
	ds_write_b128 v122, v[30:33] offset:36864
	s_waitcnt vmcnt(12)
	ds_write_b128 v122, v[26:29]
	s_waitcnt vmcnt(11)
	ds_write_b128 v121, v[34:37]
	s_waitcnt vmcnt(10)
	ds_write_b128 v121, v[38:41] offset:36864
	s_waitcnt vmcnt(9)
	ds_write_b128 v120, v[42:45]
	s_waitcnt vmcnt(8)
	ds_write_b128 v120, v[46:49] offset:36864
	global_load_dwordx4 v[26:29], v[74:75], off offset:128
	global_load_dwordx4 v[30:33], v[78:79], off offset:128
	v_ashrrev_i32_e32 v34, 1, v114
	v_and_b32_e32 v117, 0xffffffc0, v34
	v_or_b32_e32 v34, v117, v115
	v_mul_lo_u32 v128, v34, s71
	v_lshlrev_b32_e32 v34, 4, v114
	v_and_b32_e32 v34, 0x70, v34
	v_and_b32_e32 v35, 0x4f, v114
	v_or_b32_e32 v76, v76, v34
	v_or_b32_e32 v72, v72, v34
	v_or_b32_e32 v70, v70, v34
	v_or_b32_e32 v66, v66, v34
	v_or_b32_e32 v64, v64, v34
	v_or_b32_e32 v62, v62, v34
	v_or_b32_e32 v60, v60, v34
	v_or_b32_e32 v58, v58, v34
	v_mov_b32_e32 v34, 0
	s_waitcnt vmcnt(9)
	ds_write_b128 v124, v[50:53]
	s_waitcnt vmcnt(8)
	ds_write_b128 v124, v[54:57] offset:36864
	v_mul_u32_u24_e32 v127, 0x48, v35
	v_mov_b32_e32 v98, v76
	v_mov_b32_e32 v100, v72
	v_mov_b32_e32 v102, v70
	v_mov_b32_e32 v104, v66
	v_mov_b32_e32 v106, v64
	v_mov_b32_e32 v108, v62
	v_mov_b32_e32 v110, v60
	v_mov_b32_e32 v112, v58
	v_mov_b32_e32 v35, v34
	v_mov_b32_e32 v36, v34
	v_mov_b32_e32 v37, v34
	v_mov_b32_e32 v38, v34
	v_mov_b32_e32 v39, v34
	v_mov_b32_e32 v40, v34
	v_mov_b32_e32 v41, v34
	v_mov_b32_e32 v42, v34
	v_mov_b32_e32 v43, v34
	v_mov_b32_e32 v44, v34
	v_mov_b32_e32 v45, v34
	v_mov_b32_e32 v46, v34
	v_mov_b32_e32 v47, v34
	v_mov_b32_e32 v48, v34
	v_mov_b32_e32 v49, v34
	v_mov_b32_e32 v50, v34
	v_mov_b32_e32 v51, v34
	v_mov_b32_e32 v52, v34
	v_mov_b32_e32 v53, v34
	v_mov_b32_e32 v54, v34
	v_mov_b32_e32 v55, v34
	v_mov_b32_e32 v56, v34
	v_mov_b32_e32 v57, v34
	v_mov_b32_e32 v58, v34
	v_mov_b32_e32 v59, v34
	v_mov_b32_e32 v60, v34
	v_mov_b32_e32 v61, v34
	v_mov_b32_e32 v62, v34
	v_mov_b32_e32 v63, v34
	v_mov_b32_e32 v64, v34
	v_mov_b32_e32 v65, v34
	v_mov_b32_e32 v66, v34
	v_mov_b32_e32 v67, v34
	v_mov_b32_e32 v68, v34
	v_mov_b32_e32 v69, v34
	v_mov_b32_e32 v70, v34
	v_mov_b32_e32 v71, v34
	v_mov_b32_e32 v72, v34
	v_mov_b32_e32 v73, v34
	v_mov_b32_e32 v74, v34
	v_mov_b32_e32 v75, v34
	v_mov_b32_e32 v76, v34
	v_mov_b32_e32 v77, v34
	v_mov_b32_e32 v78, v34
	v_mov_b32_e32 v79, v34
	v_mov_b32_e32 v80, v34
	v_mov_b32_e32 v81, v34
	v_mov_b32_e32 v82, v34
	v_mov_b32_e32 v83, v34
	v_mov_b32_e32 v84, v34
	v_mov_b32_e32 v85, v34
	v_mov_b32_e32 v86, v34
	v_mov_b32_e32 v87, v34
	v_mov_b32_e32 v88, v34
	v_mov_b32_e32 v89, v34
	v_mov_b32_e32 v90, v34
	v_mov_b32_e32 v91, v34
	v_mov_b32_e32 v92, v34
	v_mov_b32_e32 v93, v34
	v_mov_b32_e32 v94, v34
	v_mov_b32_e32 v95, v34
	v_mov_b32_e32 v96, v34
	v_mov_b32_e32 v97, v34
	s_waitcnt lgkmcnt(0)
	s_barrier
; DEV f32x4 mfma16(bf16x8 a, bf16x8 b, f32x4 c) { return __builtin_amdgcn_mfma_f32_16x16x32_bf16(a, b, c, 0, 0, 0); }
; template <int EPI, bool AF32>
; DEV void gemm_tile(const void* Ap, int lda, const u16* Bt, int ldb, int K, int m0, int n0, const Epi& ea, char* smem) {
;     ...
;   auto gload = [&](int kt) {
;     const int k0 = kt << 6;
; #pragma unroll
;     for (int i = 0; i < 4; i++) {
;       const int c = tid + i * 256, row = c >> 3, kc = c & 7;
;       if (AF32) {
;         const float* pa = (const float*)Ap + (size_t)(m0 + row) * lda + k0 + kc * 8;
;         rfa[2 * i] = *(const f32x4*)pa;
;         rfa[2 * i + 1] = *(const f32x4*)(pa + 4);
;       } else {
;         ra[i] = *(const u32x4*)((const u16*)Ap + (size_t)(m0 + row) * lda + k0 + kc * 8);
;       }
;       rb[i] = *(const u32x4*)(Bt + (size_t)(n0 + row) * ldb + k0 + kc * 8);
;     }
;   };
;   auto swrite = [&](int buf) {
; #pragma unroll
;     for (int i = 0; i < 4; i++) {
;       const int c = tid + i * 256, row = c >> 3, kc = c & 7;
;       u32x4 va;
;       if (AF32) {
;         va = (u32x4){pack2(rfa[2 * i][0], rfa[2 * i][1]), pack2(rfa[2 * i][2], rfa[2 * i][3]),
;                      pack2(rfa[2 * i + 1][0], rfa[2 * i + 1][1]), pack2(rfa[2 * i + 1][2], rfa[2 * i + 1][3])};
;       } else {
;         va = ra[i];
;       }
;       *(u32x4*)(sA + buf * 9216 + row * 72 + kc * 8) = va;
;       *(u32x4*)(sB + buf * 9216 + row * 72 + kc * 8) = rb[i];
;     }
;   };
;   gload(0);
;   swrite(0);
;   if (nk > 1) gload(1);
;   __syncthreads();
;   for (int kt = 0; kt < nk; kt++) {
;     const int buf = kt & 1;
;     if (kt + 1 < nk) swrite(buf ^ 1);
;     if (kt + 2 < nk) gload(kt + 2);
; #pragma unroll
;     for (int ks = 0; ks < 2; ks++) {
;       bf16x8 a[4], b[4];
; #pragma unroll
;       for (int m = 0; m < 4; m++) a[m] = *(const bf16x8*)(sA + buf * 9216 + (wr * 64 + m * 16 + fr) * 72 + ks * 32 + fq * 8);
; #pragma unroll
;       for (int n = 0; n < 4; n++) b[n] = *(const bf16x8*)(sB + buf * 9216 + (wc * 64 + n * 16 + fr) * 72 + ks * 32 + fq * 8);
;       __builtin_amdgcn_s_setprio(1);
; #pragma unroll
;       for (int m = 0; m < 4; m++)
; #pragma unroll
;         for (int n = 0; n < 4; n++) acc[m][n] = mfma16(a[m], b[n], acc[m][n]);
;       __builtin_amdgcn_s_setprio(0);
;     }
;     __syncthreads();
;   }
	v_lshl_add_u32 v161, v128, 1, v125
	v_lshl_add_u32 v129, v127, 1, v125
	s_mov_b32 s19, 0
	s_mov_b64 s[0:1], 0x100
	ds_read_b128 v[130:133], v161
	ds_read_b128 v[134:137], v161 offset:2304
	ds_read_b128 v[138:141], v161 offset:4608
	ds_read_b128 v[142:145], v161 offset:6912
	ds_read_b128 v[146:149], v129 offset:36864
	ds_read_b128 v[150:153], v129 offset:39168
	ds_read_b128 v[162:165], v129 offset:41472
	ds_read_b128 v[166:169], v129 offset:43776
.Lgk3_loop:
	s_waitcnt lgkmcnt(0)
	ds_read_b128 v[222:225], v161 offset:64
	ds_read_b128 v[226:229], v161 offset:2368
	ds_read_b128 v[230:233], v161 offset:4672
	ds_read_b128 v[234:237], v161 offset:6976
	ds_read_b128 v[238:241], v129 offset:36928
	ds_read_b128 v[242:245], v129 offset:39232
	ds_read_b128 v[246:249], v129 offset:41536
	ds_read_b128 v[250:253], v129 offset:43840
	v_mfma_f32_16x16x32_bf16 v[34:37], v[130:133], v[146:149], v[34:37]
	v_mfma_f32_16x16x32_bf16 v[38:41], v[130:133], v[150:153], v[38:41]
	v_mfma_f32_16x16x32_bf16 v[42:45], v[130:133], v[162:165], v[42:45]
	v_mfma_f32_16x16x32_bf16 v[46:49], v[130:133], v[166:169], v[46:49]
	s_waitcnt vmcnt(0)
	ds_write_b128 v122, v[22:25] offset:18432
	ds_write_b128 v122, v[6:9] offset:55296
	v_mfma_f32_16x16x32_bf16 v[50:53], v[134:137], v[146:149], v[50:53]
	ds_write_b128 v121, v[18:21] offset:18432
	ds_write_b128 v121, v[10:13] offset:55296
	v_mfma_f32_16x16x32_bf16 v[54:57], v[134:137], v[150:153], v[54:57]
	ds_write_b128 v120, v[14:17] offset:18432
	ds_write_b128 v120, v[2:5] offset:55296
	v_mfma_f32_16x16x32_bf16 v[58:61], v[134:137], v[162:165], v[58:61]
	ds_write_b128 v124, v[26:29] offset:18432
	ds_write_b128 v124, v[30:33] offset:55296
	v_mfma_f32_16x16x32_bf16 v[62:65], v[134:137], v[166:169], v[62:65]
	global_load_dwordx4 v[22:25], v112, s[14:15]
	v_mfma_f32_16x16x32_bf16 v[66:69], v[138:141], v[146:149], v[66:69]
	global_load_dwordx4 v[6:9], v110, s[12:13]
	v_mfma_f32_16x16x32_bf16 v[70:73], v[138:141], v[150:153], v[70:73]
	global_load_dwordx4 v[18:21], v108, s[14:15]
	v_mfma_f32_16x16x32_bf16 v[74:77], v[138:141], v[162:165], v[74:77]
	global_load_dwordx4 v[10:13], v106, s[12:13]
	v_mfma_f32_16x16x32_bf16 v[78:81], v[138:141], v[166:169], v[78:81]
	global_load_dwordx4 v[14:17], v104, s[14:15]
	v_mfma_f32_16x16x32_bf16 v[82:85], v[142:145], v[146:149], v[82:85]
	global_load_dwordx4 v[2:5], v102, s[12:13]
	v_mfma_f32_16x16x32_bf16 v[86:89], v[142:145], v[150:153], v[86:89]
	global_load_dwordx4 v[26:29], v100, s[14:15]
	v_mfma_f32_16x16x32_bf16 v[90:93], v[142:145], v[162:165], v[90:93]
	global_load_dwordx4 v[30:33], v98, s[12:13]
	v_mfma_f32_16x16x32_bf16 v[94:97], v[142:145], v[166:169], v[94:97]
	s_waitcnt lgkmcnt(0)
	s_barrier
	ds_read_b128 v[130:133], v161 offset:18432
	v_mfma_f32_16x16x32_bf16 v[34:37], v[222:225], v[238:241], v[34:37]
	ds_read_b128 v[134:137], v161 offset:20736
	v_mfma_f32_16x16x32_bf16 v[38:41], v[222:225], v[242:245], v[38:41]
	ds_read_b128 v[138:141], v161 offset:23040
	v_mfma_f32_16x16x32_bf16 v[42:45], v[222:225], v[246:249], v[42:45]
	ds_read_b128 v[142:145], v161 offset:25344
	v_mfma_f32_16x16x32_bf16 v[46:49], v[222:225], v[250:253], v[46:49]
	ds_read_b128 v[146:149], v129 offset:55296
	v_mfma_f32_16x16x32_bf16 v[50:53], v[226:229], v[238:241], v[50:53]
	ds_read_b128 v[150:153], v129 offset:57600
	v_mfma_f32_16x16x32_bf16 v[54:57], v[226:229], v[242:245], v[54:57]
	ds_read_b128 v[162:165], v129 offset:59904
	v_mfma_f32_16x16x32_bf16 v[58:61], v[226:229], v[246:249], v[58:61]
	ds_read_b128 v[166:169], v129 offset:62208
	v_mfma_f32_16x16x32_bf16 v[62:65], v[226:229], v[250:253], v[62:65]
	v_mfma_f32_16x16x32_bf16 v[66:69], v[230:233], v[238:241], v[66:69]
	v_mfma_f32_16x16x32_bf16 v[70:73], v[230:233], v[242:245], v[70:73]
	v_mfma_f32_16x16x32_bf16 v[74:77], v[230:233], v[246:249], v[74:77]
	v_mfma_f32_16x16x32_bf16 v[78:81], v[230:233], v[250:253], v[78:81]
	v_mfma_f32_16x16x32_bf16 v[82:85], v[234:237], v[238:241], v[82:85]
	v_mfma_f32_16x16x32_bf16 v[86:89], v[234:237], v[242:245], v[86:89]
	v_mfma_f32_16x16x32_bf16 v[90:93], v[234:237], v[246:249], v[90:93]
	v_mfma_f32_16x16x32_bf16 v[94:97], v[234:237], v[250:253], v[94:97]
	s_waitcnt lgkmcnt(0)
	ds_read_b128 v[222:225], v161 offset:18496
	ds_read_b128 v[226:229], v161 offset:20800
	ds_read_b128 v[230:233], v161 offset:23104
	ds_read_b128 v[234:237], v161 offset:25408
	ds_read_b128 v[238:241], v129 offset:55360
	ds_read_b128 v[242:245], v129 offset:57664
	ds_read_b128 v[246:249], v129 offset:59968
	ds_read_b128 v[250:253], v129 offset:62272
	v_mfma_f32_16x16x32_bf16 v[34:37], v[130:133], v[146:149], v[34:37]
	v_mfma_f32_16x16x32_bf16 v[38:41], v[130:133], v[150:153], v[38:41]
	v_mfma_f32_16x16x32_bf16 v[42:45], v[130:133], v[162:165], v[42:45]
	v_mfma_f32_16x16x32_bf16 v[46:49], v[130:133], v[166:169], v[46:49]
	s_waitcnt vmcnt(0)
	ds_write_b128 v122, v[22:25]
	ds_write_b128 v122, v[6:9] offset:36864
	v_mfma_f32_16x16x32_bf16 v[50:53], v[134:137], v[146:149], v[50:53]
	ds_write_b128 v121, v[18:21]
	ds_write_b128 v121, v[10:13] offset:36864
	v_mfma_f32_16x16x32_bf16 v[54:57], v[134:137], v[150:153], v[54:57]
	ds_write_b128 v120, v[14:17]
	ds_write_b128 v120, v[2:5] offset:36864
	v_mfma_f32_16x16x32_bf16 v[58:61], v[134:137], v[162:165], v[58:61]
	ds_write_b128 v124, v[26:29]
	ds_write_b128 v124, v[30:33] offset:36864
	v_mfma_f32_16x16x32_bf16 v[62:65], v[134:137], v[166:169], v[62:65]
	global_load_dwordx4 v[22:25], v112, s[14:15] offset:128
	v_mfma_f32_16x16x32_bf16 v[66:69], v[138:141], v[146:149], v[66:69]
	global_load_dwordx4 v[6:9], v110, s[12:13] offset:128
	v_mfma_f32_16x16x32_bf16 v[70:73], v[138:141], v[150:153], v[70:73]
	global_load_dwordx4 v[18:21], v108, s[14:15] offset:128
	v_mfma_f32_16x16x32_bf16 v[74:77], v[138:141], v[162:165], v[74:77]
	global_load_dwordx4 v[10:13], v106, s[12:13] offset:128
	v_mfma_f32_16x16x32_bf16 v[78:81], v[138:141], v[166:169], v[78:81]
	global_load_dwordx4 v[14:17], v104, s[14:15] offset:128
	v_mfma_f32_16x16x32_bf16 v[82:85], v[142:145], v[146:149], v[82:85]
	global_load_dwordx4 v[2:5], v102, s[12:13] offset:128
	v_mfma_f32_16x16x32_bf16 v[86:89], v[142:145], v[150:153], v[86:89]
	global_load_dwordx4 v[26:29], v100, s[14:15] offset:128
	v_mfma_f32_16x16x32_bf16 v[90:93], v[142:145], v[162:165], v[90:93]
	global_load_dwordx4 v[30:33], v98, s[12:13] offset:128
	v_mfma_f32_16x16x32_bf16 v[94:97], v[142:145], v[166:169], v[94:97]
	s_waitcnt lgkmcnt(0)
	s_barrier
; DEV f32x4 mfma16(bf16x8 a, bf16x8 b, f32x4 c) { return __builtin_amdgcn_mfma_f32_16x16x32_bf16(a, b, c, 0, 0, 0); }
; template <int EPI, bool AF32>
; DEV void gemm_tile(const void* Ap, int lda, const u16* Bt, int ldb, int K, int m0, int n0, const Epi& ea, char* smem) {
;     ...
;   auto gload = [&](int kt) {
;     const int k0 = kt << 6;
; #pragma unroll
;     for (int i = 0; i < 4; i++) {
;       const int c = tid + i * 256, row = c >> 3, kc = c & 7;
;       if (AF32) {
;         const float* pa = (const float*)Ap + (size_t)(m0 + row) * lda + k0 + kc * 8;
;         rfa[2 * i] = *(const f32x4*)pa;
;         rfa[2 * i + 1] = *(const f32x4*)(pa + 4);
;       } else {
;         ra[i] = *(const u32x4*)((const u16*)Ap + (size_t)(m0 + row) * lda + k0 + kc * 8);
;       }
;       rb[i] = *(const u32x4*)(Bt + (size_t)(n0 + row) * ldb + k0 + kc * 8);
;     }
;   };
;   auto swrite = [&](int buf) {
; #pragma unroll
;     for (int i = 0; i < 4; i++) {
;       const int c = tid + i * 256, row = c >> 3, kc = c & 7;
;       u32x4 va;
;       if (AF32) {
;         va = (u32x4){pack2(rfa[2 * i][0], rfa[2 * i][1]), pack2(rfa[2 * i][2], rfa[2 * i][3]),
;                      pack2(rfa[2 * i + 1][0], rfa[2 * i + 1][1]), pack2(rfa[2 * i + 1][2], rfa[2 * i + 1][3])};
;       } else {
;         va = ra[i];
;       }
;       *(u32x4*)(sA + buf * 9216 + row * 72 + kc * 8) = va;
;       *(u32x4*)(sB + buf * 9216 + row * 72 + kc * 8) = rb[i];
;     }
;   };
;   gload(0);
;   swrite(0);
;   if (nk > 1) gload(1);
;   __syncthreads();
;   for (int kt = 0; kt < nk; kt++) {
;     const int buf = kt & 1;
;     if (kt + 1 < nk) swrite(buf ^ 1);
;     if (kt + 2 < nk) gload(kt + 2);
; #pragma unroll
;     for (int ks = 0; ks < 2; ks++) {
;       bf16x8 a[4], b[4];
; #pragma unroll
;       for (int m = 0; m < 4; m++) a[m] = *(const bf16x8*)(sA + buf * 9216 + (wr * 64 + m * 16 + fr) * 72 + ks * 32 + fq * 8);
; #pragma unroll
;       for (int n = 0; n < 4; n++) b[n] = *(const bf16x8*)(sB + buf * 9216 + (wc * 64 + n * 16 + fr) * 72 + ks * 32 + fq * 8);
;       __builtin_amdgcn_s_setprio(1);
; #pragma unroll
;       for (int m = 0; m < 4; m++)
; #pragma unroll
;         for (int n = 0; n < 4; n++) acc[m][n] = mfma16(a[m], b[n], acc[m][n]);
;       __builtin_amdgcn_s_setprio(0);
;     }
;     __syncthreads();
;   }
	ds_read_b128 v[130:133], v161
	v_mfma_f32_16x16x32_bf16 v[34:37], v[222:225], v[238:241], v[34:37]
	ds_read_b128 v[134:137], v161 offset:2304
	v_mfma_f32_16x16x32_bf16 v[38:41], v[222:225], v[242:245], v[38:41]
	ds_read_b128 v[138:141], v161 offset:4608
	v_mfma_f32_16x16x32_bf16 v[42:45], v[222:225], v[246:249], v[42:45]
	ds_read_b128 v[142:145], v161 offset:6912
	v_mfma_f32_16x16x32_bf16 v[46:49], v[222:225], v[250:253], v[46:49]
	ds_read_b128 v[146:149], v129 offset:36864
	v_mfma_f32_16x16x32_bf16 v[50:53], v[226:229], v[238:241], v[50:53]
	ds_read_b128 v[150:153], v129 offset:39168
	v_mfma_f32_16x16x32_bf16 v[54:57], v[226:229], v[242:245], v[54:57]
	ds_read_b128 v[162:165], v129 offset:41472
	v_mfma_f32_16x16x32_bf16 v[58:61], v[226:229], v[246:249], v[58:61]
	ds_read_b128 v[166:169], v129 offset:43776
	v_mfma_f32_16x16x32_bf16 v[62:65], v[226:229], v[250:253], v[62:65]
	v_mfma_f32_16x16x32_bf16 v[66:69], v[230:233], v[238:241], v[66:69]
	v_add_u32_e32 v112, 0x100, v112
	v_mfma_f32_16x16x32_bf16 v[70:73], v[230:233], v[242:245], v[70:73]
	v_add_u32_e32 v110, 0x100, v110
	v_mfma_f32_16x16x32_bf16 v[74:77], v[230:233], v[246:249], v[74:77]
	v_add_u32_e32 v108, 0x100, v108
	v_mfma_f32_16x16x32_bf16 v[78:81], v[230:233], v[250:253], v[78:81]
	v_add_u32_e32 v106, 0x100, v106
	v_mfma_f32_16x16x32_bf16 v[82:85], v[234:237], v[238:241], v[82:85]
	v_add_u32_e32 v104, 0x100, v104
	v_mfma_f32_16x16x32_bf16 v[86:89], v[234:237], v[242:245], v[86:89]
	v_add_u32_e32 v102, 0x100, v102
	v_mfma_f32_16x16x32_bf16 v[90:93], v[234:237], v[246:249], v[90:93]
	v_add_u32_e32 v100, 0x100, v100
	v_mfma_f32_16x16x32_bf16 v[94:97], v[234:237], v[250:253], v[94:97]
	v_add_u32_e32 v98, 0x100, v98
	s_add_i32 s19, s19, 1
	s_cmp_lg_u32 s19, 7
	s_cbranch_scc1 .Lgk3_loop
	s_waitcnt lgkmcnt(0)
	ds_read_b128 v[222:225], v161 offset:64
	ds_read_b128 v[226:229], v161 offset:2368
	ds_read_b128 v[230:233], v161 offset:4672
	ds_read_b128 v[234:237], v161 offset:6976
	ds_read_b128 v[238:241], v129 offset:36928
	ds_read_b128 v[242:245], v129 offset:39232
	ds_read_b128 v[246:249], v129 offset:41536
	ds_read_b128 v[250:253], v129 offset:43840
	v_mfma_f32_16x16x32_bf16 v[34:37], v[130:133], v[146:149], v[34:37]
	v_mfma_f32_16x16x32_bf16 v[38:41], v[130:133], v[150:153], v[38:41]
	v_mfma_f32_16x16x32_bf16 v[42:45], v[130:133], v[162:165], v[42:45]
	v_mfma_f32_16x16x32_bf16 v[46:49], v[130:133], v[166:169], v[46:49]
	s_waitcnt vmcnt(0)
	ds_write_b128 v122, v[22:25] offset:18432
	ds_write_b128 v122, v[6:9] offset:55296
	v_mfma_f32_16x16x32_bf16 v[50:53], v[134:137], v[146:149], v[50:53]
	ds_write_b128 v121, v[18:21] offset:18432
	ds_write_b128 v121, v[10:13] offset:55296
	v_mfma_f32_16x16x32_bf16 v[54:57], v[134:137], v[150:153], v[54:57]
	ds_write_b128 v120, v[14:17] offset:18432
	ds_write_b128 v120, v[2:5] offset:55296
	v_mfma_f32_16x16x32_bf16 v[58:61], v[134:137], v[162:165], v[58:61]
	ds_write_b128 v124, v[26:29] offset:18432
	ds_write_b128 v124, v[30:33] offset:55296
	v_mfma_f32_16x16x32_bf16 v[62:65], v[134:137], v[166:169], v[62:65]
	v_mfma_f32_16x16x32_bf16 v[66:69], v[138:141], v[146:149], v[66:69]
	v_mfma_f32_16x16x32_bf16 v[70:73], v[138:141], v[150:153], v[70:73]
	v_mfma_f32_16x16x32_bf16 v[74:77], v[138:141], v[162:165], v[74:77]
	v_mfma_f32_16x16x32_bf16 v[78:81], v[138:141], v[166:169], v[78:81]
	v_mfma_f32_16x16x32_bf16 v[82:85], v[142:145], v[146:149], v[82:85]
	v_mfma_f32_16x16x32_bf16 v[86:89], v[142:145], v[150:153], v[86:89]
	v_mfma_f32_16x16x32_bf16 v[90:93], v[142:145], v[162:165], v[90:93]
	v_mfma_f32_16x16x32_bf16 v[94:97], v[142:145], v[166:169], v[94:97]
	s_waitcnt lgkmcnt(0)
	s_barrier
	ds_read_b128 v[130:133], v161 offset:18432
	v_mfma_f32_16x16x32_bf16 v[34:37], v[222:225], v[238:241], v[34:37]
	ds_read_b128 v[134:137], v161 offset:20736
	v_mfma_f32_16x16x32_bf16 v[38:41], v[222:225], v[242:245], v[38:41]
	ds_read_b128 v[138:141], v161 offset:23040
	v_mfma_f32_16x16x32_bf16 v[42:45], v[222:225], v[246:249], v[42:45]
	ds_read_b128 v[142:145], v161 offset:25344
	v_mfma_f32_16x16x32_bf16 v[46:49], v[222:225], v[250:253], v[46:49]
	ds_read_b128 v[146:149], v129 offset:55296
	v_mfma_f32_16x16x32_bf16 v[50:53], v[226:229], v[238:241], v[50:53]
	ds_read_b128 v[150:153], v129 offset:57600
	v_mfma_f32_16x16x32_bf16 v[54:57], v[226:229], v[242:245], v[54:57]
	ds_read_b128 v[162:165], v129 offset:59904
	v_mfma_f32_16x16x32_bf16 v[58:61], v[226:229], v[246:249], v[58:61]
	ds_read_b128 v[166:169], v129 offset:62208
	v_mfma_f32_16x16x32_bf16 v[62:65], v[226:229], v[250:253], v[62:65]
	v_mfma_f32_16x16x32_bf16 v[66:69], v[230:233], v[238:241], v[66:69]
	v_mfma_f32_16x16x32_bf16 v[70:73], v[230:233], v[242:245], v[70:73]
	v_mfma_f32_16x16x32_bf16 v[74:77], v[230:233], v[246:249], v[74:77]
	v_mfma_f32_16x16x32_bf16 v[78:81], v[230:233], v[250:253], v[78:81]
	v_mfma_f32_16x16x32_bf16 v[82:85], v[234:237], v[238:241], v[82:85]
	v_mfma_f32_16x16x32_bf16 v[86:89], v[234:237], v[242:245], v[86:89]
	v_mfma_f32_16x16x32_bf16 v[90:93], v[234:237], v[246:249], v[90:93]
	v_mfma_f32_16x16x32_bf16 v[94:97], v[234:237], v[250:253], v[94:97]
	s_waitcnt lgkmcnt(0)
; DEV f32x4 mfma16(bf16x8 a, bf16x8 b, f32x4 c) { return __builtin_amdgcn_mfma_f32_16x16x32_bf16(a, b, c, 0, 0, 0); }
; template <int EPI, bool AF32>
; DEV void gemm_tile(const void* Ap, int lda, const u16* Bt, int ldb, int K, int m0, int n0, const Epi& ea, char* smem) {
;     ...
;   for (int kt = 0; kt < nk; kt++) {
;     const int buf = kt & 1;
;     if (kt + 1 < nk) swrite(buf ^ 1);
;     if (kt + 2 < nk) gload(kt + 2);
; #pragma unroll
;     for (int ks = 0; ks < 2; ks++) {
;       bf16x8 a[4], b[4];
; #pragma unroll
;       for (int m = 0; m < 4; m++) a[m] = *(const bf16x8*)(sA + buf * 9216 + (wr * 64 + m * 16 + fr) * 72 + ks * 32 + fq * 8);
; #pragma unroll
;       for (int n = 0; n < 4; n++) b[n] = *(const bf16x8*)(sB + buf * 9216 + (wc * 64 + n * 16 + fr) * 72 + ks * 32 + fq * 8);
;       __builtin_amdgcn_s_setprio(1);
; #pragma unroll
;       for (int m = 0; m < 4; m++)
; #pragma unroll
;         for (int n = 0; n < 4; n++) acc[m][n] = mfma16(a[m], b[n], acc[m][n]);
;       __builtin_amdgcn_s_setprio(0);
;     }
;     __syncthreads();
;   }
;     ...
;       u16* C = (u16*)ea.p0;
;       const u16* G = (const u16*)ea.p1 + (EPI == EP_MERGE2 ? 1024 : 0);
;       u16 gv[4][4][4], cv[4][4][4];
; #pragma unroll
;       for (int m = 0; m < 4; m++)
; #pragma unroll
;         for (int j = 0; j < 4; j++)
; #pragma unroll
;           for (int n = 0; n < 4; n++) {
;             gv[m][j][n] = G[(size_t)(rbase + m * 16 + j) * 2048 + cbase + n * 16];
;             if (EPI == EP_MERGE2) cv[m][j][n] = C[(size_t)(rbase + m * 16 + j) * 1024 + cbase + n * 16];
;           }
	ds_read_b128 v[222:225], v161 offset:18496
	ds_read_b128 v[226:229], v161 offset:20800
	ds_read_b128 v[230:233], v161 offset:23104
	ds_read_b128 v[234:237], v161 offset:25408
	ds_read_b128 v[238:241], v129 offset:55360
	ds_read_b128 v[242:245], v129 offset:57664
	ds_read_b128 v[246:249], v129 offset:59968
	ds_read_b128 v[250:253], v129 offset:62272
	v_mfma_f32_16x16x32_bf16 v[34:37], v[130:133], v[146:149], v[34:37]
	v_mfma_f32_16x16x32_bf16 v[38:41], v[130:133], v[150:153], v[38:41]
	v_mfma_f32_16x16x32_bf16 v[42:45], v[130:133], v[162:165], v[42:45]
	v_mfma_f32_16x16x32_bf16 v[98:101], v[130:133], v[166:169], v[46:49]
	v_mfma_f32_16x16x32_bf16 v[50:53], v[134:137], v[146:149], v[50:53]
	v_mfma_f32_16x16x32_bf16 v[54:57], v[134:137], v[150:153], v[54:57]
	v_mfma_f32_16x16x32_bf16 v[58:61], v[134:137], v[162:165], v[58:61]
	v_mfma_f32_16x16x32_bf16 v[62:65], v[134:137], v[166:169], v[62:65]
	v_mfma_f32_16x16x32_bf16 v[66:69], v[138:141], v[146:149], v[66:69]
	v_mfma_f32_16x16x32_bf16 v[70:73], v[138:141], v[150:153], v[70:73]
	v_mfma_f32_16x16x32_bf16 v[74:77], v[138:141], v[162:165], v[74:77]
	v_mfma_f32_16x16x32_bf16 v[78:81], v[138:141], v[166:169], v[78:81]
	v_mfma_f32_16x16x32_bf16 v[82:85], v[142:145], v[146:149], v[82:85]
	v_mfma_f32_16x16x32_bf16 v[86:89], v[142:145], v[150:153], v[86:89]
	v_mfma_f32_16x16x32_bf16 v[90:93], v[142:145], v[162:165], v[90:93]
	v_mfma_f32_16x16x32_bf16 v[94:97], v[142:145], v[166:169], v[94:97]
	s_waitcnt lgkmcnt(0)
	v_mfma_f32_16x16x32_bf16 v[118:121], v[222:225], v[238:241], v[34:37]
	v_mfma_f32_16x16x32_bf16 v[122:125], v[222:225], v[242:245], v[38:41]
	v_mfma_f32_16x16x32_bf16 v[126:129], v[222:225], v[246:249], v[42:45]
	v_mfma_f32_16x16x32_bf16 v[42:45], v[226:229], v[242:245], v[54:57]
	v_mfma_f32_16x16x32_bf16 v[38:41], v[226:229], v[246:249], v[58:61]
	v_mfma_f32_16x16x32_bf16 v[34:37], v[226:229], v[250:253], v[62:65]
	v_mfma_f32_16x16x32_bf16 v[30:33], v[230:233], v[238:241], v[66:69]
	v_mfma_f32_16x16x32_bf16 v[26:29], v[230:233], v[242:245], v[70:73]
	v_mfma_f32_16x16x32_bf16 v[22:25], v[230:233], v[246:249], v[74:77]
	v_mfma_f32_16x16x32_bf16 v[18:21], v[230:233], v[250:253], v[78:81]
	v_mfma_f32_16x16x32_bf16 v[14:17], v[234:237], v[238:241], v[82:85]
	v_mfma_f32_16x16x32_bf16 v[10:13], v[234:237], v[242:245], v[86:89]
	v_mfma_f32_16x16x32_bf16 v[6:9], v[234:237], v[246:249], v[90:93]
	v_mfma_f32_16x16x32_bf16 v[2:5], v[234:237], v[250:253], v[94:97]
	v_mfma_f32_16x16x32_bf16 v[46:49], v[226:229], v[238:241], v[50:53]
	v_mfma_f32_16x16x32_bf16 v[50:53], v[222:225], v[250:253], v[98:101]
	s_nop 7
	v_and_b32_e32 v114, 64, v114
	v_add_u32_e32 v0, s18, v117
	v_or3_b32 v54, v114, s17, v115
	v_lshl_or_b32 v72, v116, 2, v0
	v_ashrrev_i32_e32 v55, 31, v54
	v_lshlrev_b64 v[66:67], 1, v[54:55]
	v_ashrrev_i32_e32 v73, 31, v72
	v_or_b32_e32 v78, 1, v72
	v_lshl_add_u64 v[74:75], s[4:5], 0, v[66:67]
	v_lshlrev_b64 v[54:55], 12, v[72:73]
	v_ashrrev_i32_e32 v79, 31, v78
	v_or_b32_e32 v82, 2, v72
	v_lshl_add_u64 v[76:77], v[74:75], 0, v[54:55]
	v_lshlrev_b64 v[54:55], 12, v[78:79]
	v_ashrrev_i32_e32 v83, 31, v82
	v_or_b32_e32 v86, 3, v72
	v_lshl_add_u64 v[80:81], v[74:75], 0, v[54:55]
	v_lshlrev_b64 v[54:55], 12, v[82:83]
	v_ashrrev_i32_e32 v87, 31, v86
	v_or_b32_e32 v90, 16, v72
	v_lshl_add_u64 v[84:85], v[74:75], 0, v[54:55]
	v_lshlrev_b64 v[54:55], 12, v[86:87]
	v_ashrrev_i32_e32 v91, 31, v90
	v_or_b32_e32 v94, 17, v72
	v_lshl_add_u64 v[88:89], v[74:75], 0, v[54:55]
	v_lshlrev_b64 v[54:55], 12, v[90:91]
	v_ashrrev_i32_e32 v95, 31, v94
	v_or_b32_e32 v98, 18, v72
	v_lshl_add_u64 v[92:93], v[74:75], 0, v[54:55]
	v_lshlrev_b64 v[54:55], 12, v[94:95]
	v_ashrrev_i32_e32 v99, 31, v98
	v_or_b32_e32 v102, 19, v72
	v_lshl_add_u64 v[96:97], v[74:75], 0, v[54:55]
	v_lshlrev_b64 v[54:55], 12, v[98:99]
	v_ashrrev_i32_e32 v103, 31, v102
	v_or_b32_e32 v70, 32, v72
	v_lshl_add_u64 v[100:101], v[74:75], 0, v[54:55]
	v_lshlrev_b64 v[54:55], 12, v[102:103]
	v_ashrrev_i32_e32 v71, 31, v70
	v_or_b32_e32 v68, 33, v72
	v_lshl_add_u64 v[104:105], v[74:75], 0, v[54:55]
	v_lshlrev_b64 v[54:55], 12, v[70:71]
	v_ashrrev_i32_e32 v69, 31, v68
	v_or_b32_e32 v64, 34, v72
	v_lshl_add_u64 v[106:107], v[74:75], 0, v[54:55]
	v_lshlrev_b64 v[54:55], 12, v[68:69]
	v_ashrrev_i32_e32 v65, 31, v64
	v_or_b32_e32 v62, 35, v72
	v_lshl_add_u64 v[108:109], v[74:75], 0, v[54:55]
	v_lshlrev_b64 v[54:55], 12, v[64:65]
	v_ashrrev_i32_e32 v63, 31, v62
	v_or_b32_e32 v60, 48, v72
	v_lshl_add_u64 v[110:111], v[74:75], 0, v[54:55]
	v_lshlrev_b64 v[54:55], 12, v[62:63]
	v_ashrrev_i32_e32 v61, 31, v60
	v_or_b32_e32 v58, 49, v72
	v_lshl_add_u64 v[112:113], v[74:75], 0, v[54:55]
	v_lshlrev_b64 v[54:55], 12, v[60:61]
	v_ashrrev_i32_e32 v59, 31, v58
	v_or_b32_e32 v56, 50, v72
	v_lshl_add_u64 v[114:115], v[74:75], 0, v[54:55]
	v_lshlrev_b64 v[54:55], 12, v[58:59]
	v_ashrrev_i32_e32 v57, 31, v56
	v_lshl_add_u64 v[116:117], v[74:75], 0, v[54:55]
	v_lshlrev_b64 v[54:55], 12, v[56:57]
	v_lshl_add_u64 v[130:131], v[74:75], 0, v[54:55]
	v_or_b32_e32 v54, 51, v72
	v_ashrrev_i32_e32 v55, 31, v54
	v_lshlrev_b64 v[132:133], 12, v[54:55]
	v_lshl_add_u64 v[74:75], v[74:75], 0, v[132:133]
	s_barrier
; DEV float bf2f(u16 h) { return __uint_as_float(((unsigned)h) << 16); }
; template <int EPI, bool AF32>
; DEV void gemm_tile(const void* Ap, int lda, const u16* Bt, int ldb, int K, int m0, int n0, const Epi& ea, char* smem) {
;     ...
;       u16* C = (u16*)ea.p0;
;       const u16* G = (const u16*)ea.p1 + (EPI == EP_MERGE2 ? 1024 : 0);
;       u16 gv[4][4][4], cv[4][4][4];
; #pragma unroll
;       for (int m = 0; m < 4; m++)
; #pragma unroll
;         for (int j = 0; j < 4; j++)
; #pragma unroll
;           for (int n = 0; n < 4; n++) {
;             gv[m][j][n] = G[(size_t)(rbase + m * 16 + j) * 2048 + cbase + n * 16];
;             if (EPI == EP_MERGE2) cv[m][j][n] = C[(size_t)(rbase + m * 16 + j) * 1024 + cbase + n * 16];
;           }
;       __builtin_amdgcn_sched_barrier(0);
; #pragma unroll
;       for (int m = 0; m < 4; m++)
; #pragma unroll
;         for (int j = 0; j < 4; j++)
; #pragma unroll
;           for (int n = 0; n < 4; n++) {
;             float v = bf2f(gv[m][j][n]) * acc[m][n][j];
;             if (EPI == EP_MERGE2) v += bf2f(cv[m][j][n]);
;             C[(size_t)(rbase + m * 16 + j) * 1024 + cbase + n * 16] = f2bf(v);
	global_load_ushort v0, v[76:77], off
	global_load_ushort v132, v[76:77], off offset:32
	global_load_ushort v133, v[76:77], off offset:64
	s_nop 0
	global_load_ushort v76, v[76:77], off offset:96
	s_nop 0
	global_load_ushort v77, v[80:81], off
	global_load_ushort v134, v[80:81], off offset:32
	global_load_ushort v135, v[80:81], off offset:64
	s_nop 0
	global_load_ushort v80, v[80:81], off offset:96
	s_nop 0
	global_load_ushort v81, v[84:85], off
	global_load_ushort v136, v[84:85], off offset:32
	global_load_ushort v137, v[84:85], off offset:64
	s_nop 0
	global_load_ushort v84, v[84:85], off offset:96
	s_nop 0
	global_load_ushort v85, v[88:89], off
	global_load_ushort v138, v[88:89], off offset:32
	global_load_ushort v139, v[88:89], off offset:64
	s_nop 0
	global_load_ushort v88, v[88:89], off offset:96
	s_nop 0
	global_load_ushort v89, v[92:93], off
	global_load_ushort v140, v[92:93], off offset:32
	global_load_ushort v141, v[92:93], off offset:64
	s_nop 0
	global_load_ushort v92, v[92:93], off offset:96
	s_nop 0
	global_load_ushort v93, v[96:97], off
	global_load_ushort v142, v[96:97], off offset:32
	global_load_ushort v143, v[96:97], off offset:64
	s_nop 0
	global_load_ushort v96, v[96:97], off offset:96
	s_nop 0
	global_load_ushort v97, v[100:101], off
	global_load_ushort v144, v[100:101], off offset:32
	global_load_ushort v145, v[100:101], off offset:64
	s_nop 0
	global_load_ushort v100, v[100:101], off offset:96
	s_nop 0
	global_load_ushort v101, v[104:105], off
	global_load_ushort v146, v[104:105], off offset:32
	global_load_ushort v147, v[104:105], off offset:64
	s_nop 0
	global_load_ushort v104, v[104:105], off offset:96
	s_nop 0
	global_load_ushort v105, v[106:107], off
	global_load_ushort v148, v[106:107], off offset:32
	global_load_ushort v149, v[106:107], off offset:64
	s_nop 0
	global_load_ushort v106, v[106:107], off offset:96
	s_nop 0
	global_load_ushort v107, v[108:109], off
	global_load_ushort v150, v[108:109], off offset:32
	global_load_ushort v151, v[108:109], off offset:64
	s_nop 0
	global_load_ushort v108, v[108:109], off offset:96
	s_nop 0
	global_load_ushort v109, v[110:111], off
	global_load_ushort v152, v[110:111], off offset:32
	global_load_ushort v153, v[110:111], off offset:64
	s_nop 0
	global_load_ushort v110, v[110:111], off offset:96
	s_nop 0
	global_load_ushort v111, v[112:113], off
	global_load_ushort v161, v[112:113], off offset:32
	global_load_ushort v162, v[112:113], off offset:64
	s_nop 0
	global_load_ushort v112, v[112:113], off offset:96
	s_nop 0
	global_load_ushort v113, v[114:115], off
	global_load_ushort v163, v[114:115], off offset:32
	global_load_ushort v164, v[114:115], off offset:64
	s_nop 0
	global_load_ushort v114, v[114:115], off offset:96
	s_nop 0
	global_load_ushort v115, v[116:117], off
	global_load_ushort v165, v[116:117], off offset:32
	global_load_ushort v166, v[116:117], off offset:64
	s_nop 0
	global_load_ushort v116, v[116:117], off offset:96
	s_nop 0
	global_load_ushort v117, v[130:131], off
	global_load_ushort v167, v[130:131], off offset:32
	global_load_ushort v168, v[130:131], off offset:64
	s_nop 0
	global_load_ushort v130, v[130:131], off offset:96
	s_nop 0
	global_load_ushort v131, v[74:75], off
	global_load_ushort v169, v[74:75], off offset:32
	global_load_ushort v170, v[74:75], off offset:64
	s_nop 0
	global_load_ushort v74, v[74:75], off offset:96
	s_waitcnt vmcnt(62)
	v_lshlrev_b32_e32 v0, 16, v0
	v_lshl_add_u64 v[66:67], s[2:3], 0, v[66:67]
	v_lshlrev_b64 v[72:73], 11, v[72:73]
	v_mul_f32_e32 v0, v118, v0
	v_lshl_add_u64 v[72:73], v[66:67], 0, v[72:73]
	v_cvt_pk_bf16_f32 v0, v0, s0
	global_store_short v[72:73], v0, off
	v_lshlrev_b32_e32 v0, 16, v132
	v_mul_f32_e32 v0, v122, v0
	v_cvt_pk_bf16_f32 v0, v0, s0
	global_store_short v[72:73], v0, off offset:32
	s_waitcnt vmcnt(62)
	v_lshlrev_b32_e32 v0, 16, v133
	v_mul_f32_e32 v0, v126, v0
	v_cvt_pk_bf16_f32 v0, v0, s0
	global_store_short v[72:73], v0, off offset:64
	v_lshlrev_b32_e32 v0, 16, v76
	v_mul_f32_e32 v0, v50, v0
	v_cvt_pk_bf16_f32 v0, v0, s0
	global_store_short v[72:73], v0, off offset:96
	s_waitcnt vmcnt(62)
	v_lshlrev_b32_e32 v0, 16, v77
	v_lshlrev_b64 v[72:73], 11, v[78:79]
	v_mul_f32_e32 v0, v119, v0
	v_lshl_add_u64 v[72:73], v[66:67], 0, v[72:73]
	v_cvt_pk_bf16_f32 v0, v0, s0
	global_store_short v[72:73], v0, off
	v_lshlrev_b32_e32 v0, 16, v134
	v_mul_f32_e32 v0, v123, v0
	v_cvt_pk_bf16_f32 v0, v0, s0
	global_store_short v[72:73], v0, off offset:32
	s_waitcnt vmcnt(62)
	v_lshlrev_b32_e32 v0, 16, v135
	v_mul_f32_e32 v0, v127, v0
	v_cvt_pk_bf16_f32 v0, v0, s0
	global_store_short v[72:73], v0, off offset:64
	v_lshlrev_b32_e32 v0, 16, v80
	v_mul_f32_e32 v0, v51, v0
	v_cvt_pk_bf16_f32 v0, v0, s0
	global_store_short v[72:73], v0, off offset:96
	s_waitcnt vmcnt(62)
	v_lshlrev_b32_e32 v0, 16, v81
	v_lshlrev_b64 v[50:51], 11, v[82:83]
	v_mul_f32_e32 v0, v120, v0
	v_lshl_add_u64 v[50:51], v[66:67], 0, v[50:51]
	v_cvt_pk_bf16_f32 v0, v0, s0
	global_store_short v[50:51], v0, off
	v_lshlrev_b32_e32 v0, 16, v136
	v_mul_f32_e32 v0, v124, v0
	v_cvt_pk_bf16_f32 v0, v0, s0
	global_store_short v[50:51], v0, off offset:32
	s_waitcnt vmcnt(62)
	v_lshlrev_b32_e32 v0, 16, v137
	v_mul_f32_e32 v0, v128, v0
	v_cvt_pk_bf16_f32 v0, v0, s0
	global_store_short v[50:51], v0, off offset:64
	v_lshlrev_b32_e32 v0, 16, v84
	v_mul_f32_e32 v0, v52, v0
	v_cvt_pk_bf16_f32 v0, v0, s0
	global_store_short v[50:51], v0, off offset:96
	s_waitcnt vmcnt(62)
	v_lshlrev_b32_e32 v0, 16, v85
	v_lshlrev_b64 v[50:51], 11, v[86:87]
	v_mul_f32_e32 v0, v121, v0
	v_lshl_add_u64 v[50:51], v[66:67], 0, v[50:51]
	v_cvt_pk_bf16_f32 v0, v0, s0
	global_store_short v[50:51], v0, off
	v_lshlrev_b32_e32 v0, 16, v138
	v_mul_f32_e32 v0, v125, v0
	v_cvt_pk_bf16_f32 v0, v0, s0
	global_store_short v[50:51], v0, off offset:32
	s_waitcnt vmcnt(62)
; DEV float bf2f(u16 h) { return __uint_as_float(((unsigned)h) << 16); }
; template <int EPI, bool AF32>
; DEV void gemm_tile(const void* Ap, int lda, const u16* Bt, int ldb, int K, int m0, int n0, const Epi& ea, char* smem) {
;     ...
; #pragma unroll
;       for (int m = 0; m < 4; m++)
; #pragma unroll
;         for (int j = 0; j < 4; j++)
; #pragma unroll
;           for (int n = 0; n < 4; n++) {
;             float v = bf2f(gv[m][j][n]) * acc[m][n][j];
;             if (EPI == EP_MERGE2) v += bf2f(cv[m][j][n]);
;             C[(size_t)(rbase + m * 16 + j) * 1024 + cbase + n * 16] = f2bf(v);
	v_lshlrev_b32_e32 v0, 16, v139
	v_mul_f32_e32 v0, v129, v0
	v_cvt_pk_bf16_f32 v0, v0, s0
	global_store_short v[50:51], v0, off offset:64
	v_lshlrev_b32_e32 v0, 16, v88
	v_mul_f32_e32 v0, v53, v0
	v_cvt_pk_bf16_f32 v0, v0, s0
	global_store_short v[50:51], v0, off offset:96
	s_waitcnt vmcnt(62)
	v_lshlrev_b32_e32 v0, 16, v89
	v_lshlrev_b64 v[50:51], 11, v[90:91]
	v_mul_f32_e32 v0, v46, v0
	v_lshl_add_u64 v[50:51], v[66:67], 0, v[50:51]
	v_cvt_pk_bf16_f32 v0, v0, s0
	global_store_short v[50:51], v0, off
	v_lshlrev_b32_e32 v0, 16, v140
	v_mul_f32_e32 v0, v42, v0
	v_cvt_pk_bf16_f32 v0, v0, s0
	global_store_short v[50:51], v0, off offset:32
	s_waitcnt vmcnt(62)
	v_lshlrev_b32_e32 v0, 16, v141
	v_mul_f32_e32 v0, v38, v0
	v_cvt_pk_bf16_f32 v0, v0, s0
	global_store_short v[50:51], v0, off offset:64
	v_lshlrev_b32_e32 v0, 16, v92
	v_mul_f32_e32 v0, v34, v0
	v_cvt_pk_bf16_f32 v0, v0, s0
	global_store_short v[50:51], v0, off offset:96
	s_waitcnt vmcnt(62)
	v_lshlrev_b32_e32 v0, 16, v93
	v_lshlrev_b64 v[50:51], 11, v[94:95]
	v_mul_f32_e32 v0, v47, v0
	v_lshl_add_u64 v[50:51], v[66:67], 0, v[50:51]
	v_cvt_pk_bf16_f32 v0, v0, s0
	global_store_short v[50:51], v0, off
	v_lshlrev_b32_e32 v0, 16, v142
	v_mul_f32_e32 v0, v43, v0
	v_cvt_pk_bf16_f32 v0, v0, s0
	global_store_short v[50:51], v0, off offset:32
	s_waitcnt vmcnt(62)
	v_lshlrev_b32_e32 v0, 16, v143
	v_mul_f32_e32 v0, v39, v0
	v_cvt_pk_bf16_f32 v0, v0, s0
	global_store_short v[50:51], v0, off offset:64
	v_lshlrev_b32_e32 v0, 16, v96
	v_mul_f32_e32 v0, v35, v0
	v_cvt_pk_bf16_f32 v0, v0, s0
	global_store_short v[50:51], v0, off offset:96
	s_waitcnt vmcnt(62)
	v_lshlrev_b32_e32 v0, 16, v97
	v_lshlrev_b64 v[34:35], 11, v[98:99]
	v_mul_f32_e32 v0, v48, v0
	v_lshl_add_u64 v[34:35], v[66:67], 0, v[34:35]
	v_cvt_pk_bf16_f32 v0, v0, s0
	global_store_short v[34:35], v0, off
	v_lshlrev_b32_e32 v0, 16, v144
	v_mul_f32_e32 v0, v44, v0
	v_cvt_pk_bf16_f32 v0, v0, s0
	global_store_short v[34:35], v0, off offset:32
	s_waitcnt vmcnt(62)
	v_lshlrev_b32_e32 v0, 16, v145
	v_mul_f32_e32 v0, v40, v0
	v_cvt_pk_bf16_f32 v0, v0, s0
	global_store_short v[34:35], v0, off offset:64
	v_lshlrev_b32_e32 v0, 16, v100
	v_mul_f32_e32 v0, v36, v0
	v_cvt_pk_bf16_f32 v0, v0, s0
	global_store_short v[34:35], v0, off offset:96
	s_waitcnt vmcnt(62)
	v_lshlrev_b32_e32 v0, 16, v101
	v_lshlrev_b64 v[34:35], 11, v[102:103]
	v_mul_f32_e32 v0, v49, v0
	v_lshl_add_u64 v[34:35], v[66:67], 0, v[34:35]
	v_cvt_pk_bf16_f32 v0, v0, s0
	global_store_short v[34:35], v0, off
	v_lshlrev_b32_e32 v0, 16, v146
	v_mul_f32_e32 v0, v45, v0
	v_cvt_pk_bf16_f32 v0, v0, s0
	global_store_short v[34:35], v0, off offset:32
	s_waitcnt vmcnt(62)
	v_lshlrev_b32_e32 v0, 16, v147
	v_mul_f32_e32 v0, v41, v0
	v_cvt_pk_bf16_f32 v0, v0, s0
	global_store_short v[34:35], v0, off offset:64
	v_lshlrev_b32_e32 v0, 16, v104
	v_mul_f32_e32 v0, v37, v0
	v_cvt_pk_bf16_f32 v0, v0, s0
	global_store_short v[34:35], v0, off offset:96
	s_waitcnt vmcnt(62)
	v_lshlrev_b32_e32 v0, 16, v105
	v_lshlrev_b64 v[34:35], 11, v[70:71]
	v_mul_f32_e32 v0, v30, v0
	v_lshl_add_u64 v[34:35], v[66:67], 0, v[34:35]
	v_cvt_pk_bf16_f32 v0, v0, s0
	global_store_short v[34:35], v0, off
	v_lshlrev_b32_e32 v0, 16, v148
	v_mul_f32_e32 v0, v26, v0
	v_cvt_pk_bf16_f32 v0, v0, s0
	global_store_short v[34:35], v0, off offset:32
	s_waitcnt vmcnt(62)
	v_lshlrev_b32_e32 v0, 16, v149
	v_mul_f32_e32 v0, v22, v0
	v_cvt_pk_bf16_f32 v0, v0, s0
	global_store_short v[34:35], v0, off offset:64
	v_lshlrev_b32_e32 v0, 16, v106
	v_mul_f32_e32 v0, v18, v0
	v_cvt_pk_bf16_f32 v0, v0, s0
	global_store_short v[34:35], v0, off offset:96
	s_waitcnt vmcnt(62)
	v_lshlrev_b32_e32 v0, 16, v107
	v_lshlrev_b64 v[34:35], 11, v[68:69]
	v_mul_f32_e32 v0, v31, v0
	v_lshl_add_u64 v[34:35], v[66:67], 0, v[34:35]
	v_cvt_pk_bf16_f32 v0, v0, s0
	global_store_short v[34:35], v0, off
	v_lshlrev_b32_e32 v0, 16, v150
	v_mul_f32_e32 v0, v27, v0
	v_cvt_pk_bf16_f32 v0, v0, s0
	global_store_short v[34:35], v0, off offset:32
	s_waitcnt vmcnt(62)
	v_lshlrev_b32_e32 v0, 16, v151
	v_mul_f32_e32 v0, v23, v0
	v_cvt_pk_bf16_f32 v0, v0, s0
	global_store_short v[34:35], v0, off offset:64
	v_lshlrev_b32_e32 v0, 16, v108
	v_mul_f32_e32 v0, v19, v0
	v_cvt_pk_bf16_f32 v0, v0, s0
	global_store_short v[34:35], v0, off offset:96
	s_waitcnt vmcnt(62)
; DEV float bf2f(u16 h) { return __uint_as_float(((unsigned)h) << 16); }
; template <int EPI, bool AF32>
; DEV void gemm_tile(const void* Ap, int lda, const u16* Bt, int ldb, int K, int m0, int n0, const Epi& ea, char* smem) {
;     ...
; #pragma unroll
;       for (int m = 0; m < 4; m++)
; #pragma unroll
;         for (int j = 0; j < 4; j++)
; #pragma unroll
;           for (int n = 0; n < 4; n++) {
;             float v = bf2f(gv[m][j][n]) * acc[m][n][j];
;             if (EPI == EP_MERGE2) v += bf2f(cv[m][j][n]);
;             C[(size_t)(rbase + m * 16 + j) * 1024 + cbase + n * 16] = f2bf(v);
	v_lshlrev_b32_e32 v0, 16, v109
	v_lshlrev_b64 v[18:19], 11, v[64:65]
	v_mul_f32_e32 v0, v32, v0
	v_lshl_add_u64 v[18:19], v[66:67], 0, v[18:19]
	v_cvt_pk_bf16_f32 v0, v0, s0
	global_store_short v[18:19], v0, off
	v_lshlrev_b32_e32 v0, 16, v152
	v_mul_f32_e32 v0, v28, v0
	v_cvt_pk_bf16_f32 v0, v0, s0
	global_store_short v[18:19], v0, off offset:32
	s_waitcnt vmcnt(62)
	v_lshlrev_b32_e32 v0, 16, v153
	v_mul_f32_e32 v0, v24, v0
	v_cvt_pk_bf16_f32 v0, v0, s0
	global_store_short v[18:19], v0, off offset:64
	v_lshlrev_b32_e32 v0, 16, v110
	v_mul_f32_e32 v0, v20, v0
	v_cvt_pk_bf16_f32 v0, v0, s0
	global_store_short v[18:19], v0, off offset:96
	s_waitcnt vmcnt(62)
	v_lshlrev_b32_e32 v0, 16, v111
	v_lshlrev_b64 v[18:19], 11, v[62:63]
	v_mul_f32_e32 v0, v33, v0
	v_lshl_add_u64 v[18:19], v[66:67], 0, v[18:19]
	v_cvt_pk_bf16_f32 v0, v0, s0
	global_store_short v[18:19], v0, off
	v_lshlrev_b32_e32 v0, 16, v161
	v_mul_f32_e32 v0, v29, v0
	v_cvt_pk_bf16_f32 v0, v0, s0
	global_store_short v[18:19], v0, off offset:32
	s_waitcnt vmcnt(62)
	v_lshlrev_b32_e32 v0, 16, v162
	v_mul_f32_e32 v0, v25, v0
	v_cvt_pk_bf16_f32 v0, v0, s0
	global_store_short v[18:19], v0, off offset:64
	v_lshlrev_b32_e32 v0, 16, v112
	v_mul_f32_e32 v0, v21, v0
	v_cvt_pk_bf16_f32 v0, v0, s0
	global_store_short v[18:19], v0, off offset:96
	s_waitcnt vmcnt(62)
	v_lshlrev_b32_e32 v0, 16, v113
	v_lshlrev_b64 v[18:19], 11, v[60:61]
	v_mul_f32_e32 v0, v14, v0
	v_lshl_add_u64 v[18:19], v[66:67], 0, v[18:19]
	v_cvt_pk_bf16_f32 v0, v0, s0
	global_store_short v[18:19], v0, off
	v_lshlrev_b32_e32 v0, 16, v163
	v_mul_f32_e32 v0, v10, v0
	v_cvt_pk_bf16_f32 v0, v0, s0
	global_store_short v[18:19], v0, off offset:32
	s_waitcnt vmcnt(62)
	v_lshlrev_b32_e32 v0, 16, v164
	v_mul_f32_e32 v0, v6, v0
	v_cvt_pk_bf16_f32 v0, v0, s0
	global_store_short v[18:19], v0, off offset:64
	v_lshlrev_b32_e32 v0, 16, v114
	v_mul_f32_e32 v0, v2, v0
	v_cvt_pk_bf16_f32 v0, v0, s0
	global_store_short v[18:19], v0, off offset:96
	s_waitcnt vmcnt(62)
	v_lshlrev_b32_e32 v0, 16, v115
	v_lshlrev_b64 v[18:19], 11, v[58:59]
	v_mul_f32_e32 v0, v15, v0
	v_lshl_add_u64 v[18:19], v[66:67], 0, v[18:19]
	v_cvt_pk_bf16_f32 v0, v0, s0
	global_store_short v[18:19], v0, off
	v_lshlrev_b32_e32 v0, 16, v165
	v_mul_f32_e32 v0, v11, v0
	v_cvt_pk_bf16_f32 v0, v0, s0
	global_store_short v[18:19], v0, off offset:32
	s_waitcnt vmcnt(62)
	v_lshlrev_b32_e32 v0, 16, v166
	v_mul_f32_e32 v0, v7, v0
	v_cvt_pk_bf16_f32 v0, v0, s0
	global_store_short v[18:19], v0, off offset:64
	v_lshlrev_b32_e32 v0, 16, v116
	v_mul_f32_e32 v0, v3, v0
	v_cvt_pk_bf16_f32 v0, v0, s0
	global_store_short v[18:19], v0, off offset:96
	s_waitcnt vmcnt(62)
	v_lshlrev_b32_e32 v0, 16, v117
	v_lshlrev_b64 v[2:3], 11, v[56:57]
	v_mul_f32_e32 v0, v16, v0
	v_lshl_add_u64 v[2:3], v[66:67], 0, v[2:3]
	v_cvt_pk_bf16_f32 v0, v0, s0
	global_store_short v[2:3], v0, off
	v_lshlrev_b32_e32 v0, 16, v167
	v_mul_f32_e32 v0, v12, v0
	v_cvt_pk_bf16_f32 v0, v0, s0
	global_store_short v[2:3], v0, off offset:32
	s_waitcnt vmcnt(62)
	v_lshlrev_b32_e32 v0, 16, v168
	v_mul_f32_e32 v0, v8, v0
	v_cvt_pk_bf16_f32 v0, v0, s0
	global_store_short v[2:3], v0, off offset:64
	v_lshlrev_b32_e32 v0, 16, v130
	v_mul_f32_e32 v0, v4, v0
	v_cvt_pk_bf16_f32 v0, v0, s0
	global_store_short v[2:3], v0, off offset:96
	s_waitcnt vmcnt(62)
	v_lshlrev_b32_e32 v0, 16, v131
	v_lshlrev_b64 v[2:3], 11, v[54:55]
	v_mul_f32_e32 v0, v17, v0
	v_lshl_add_u64 v[2:3], v[66:67], 0, v[2:3]
	v_cvt_pk_bf16_f32 v0, v0, s0
	global_store_short v[2:3], v0, off
	v_lshlrev_b32_e32 v0, 16, v169
	v_mul_f32_e32 v0, v13, v0
	v_cvt_pk_bf16_f32 v0, v0, s0
	global_store_short v[2:3], v0, off offset:32
	s_waitcnt vmcnt(62)
	v_lshlrev_b32_e32 v0, 16, v170
	v_mul_f32_e32 v0, v9, v0
	v_cvt_pk_bf16_f32 v0, v0, s0
	global_store_short v[2:3], v0, off offset:64
	v_lshlrev_b32_e32 v0, 16, v74
	v_mul_f32_e32 v0, v5, v0
	v_cvt_pk_bf16_f32 v0, v0, s0
	v_readfirstlane_b32 s0, v198
	global_store_short v[2:3], v0, off offset:96
	s_add_i32 s16, s0, s16
	s_cmpk_lt_i32 s16, 0x820
	s_cbranch_scc1 .LBB0_1304

; DEV int tidx() { int t = threadIdx.x; asm volatile("" : "+v"(t)); return t; }
; template <int EPI, bool AF32>
; DEV void gemm_tile(const void* Ap, int lda, const u16* Bt, int ldb, int K, int m0, int n0, const Epi& ea, char* smem) {
;   u16* sA = (u16*)smem;
;   u16* sB = sA + 2 * 128 * 72;
;   const int tid = tidx(), lane = tid & 63, wv = tid >> 6;
;   const int wr = wv >> 1, wc = wv & 1, fr = lane & 15, fq = lane >> 4;
;   f32x4 acc[4][4];
; #pragma unroll
;   for (int m = 0; m < 4; m++)
; #pragma unroll
;     for (int n = 0; n < 4; n++) acc[m][n] = (f32x4){0.f, 0.f, 0.f, 0.f};
;   u32x4 ra[4], rb[4];
;   f32x4 rfa[8];
;   const int nk = K >> 6;
;   auto gload = [&](int kt) {
;     const int k0 = kt << 6;
; #pragma unroll
;     for (int i = 0; i < 4; i++) {
;       const int c = tid + i * 256, row = c >> 3, kc = c & 7;
;       if (AF32) {
;         const float* pa = (const float*)Ap + (size_t)(m0 + row) * lda + k0 + kc * 8;
;         rfa[2 * i] = *(const f32x4*)pa;
;         rfa[2 * i + 1] = *(const f32x4*)(pa + 4);
;       } else {
;         ra[i] = *(const u32x4*)((const u16*)Ap + (size_t)(m0 + row) * lda + k0 + kc * 8);
;       }
;       rb[i] = *(const u32x4*)(Bt + (size_t)(n0 + row) * ldb + k0 + kc * 8);
;     }
;   };
;   auto swrite = [&](int buf) {
; #pragma unroll
;     for (int i = 0; i < 4; i++) {
;       const int c = tid + i * 256, row = c >> 3, kc = c & 7;
;       u32x4 va;
;       if (AF32) {
;         va = (u32x4){pack2(rfa[2 * i][0], rfa[2 * i][1]), pack2(rfa[2 * i][2], rfa[2 * i][3]),
;                      pack2(rfa[2 * i + 1][0], rfa[2 * i + 1][1]), pack2(rfa[2 * i + 1][2], rfa[2 * i + 1][3])};
;       } else {
;         va = ra[i];
;       }
;       *(u32x4*)(sA + buf * 9216 + row * 72 + kc * 8) = va;
;       *(u32x4*)(sB + buf * 9216 + row * 72 + kc * 8) = rb[i];
;     }
;   };
;   gload(0);
;   swrite(0);
;   if (nk > 1) gload(1);
;   __syncthreads();
.LBB0_1309:
	s_ashr_i32 s0, s14, 31
	s_lshr_b32 s0, s0, 24
	s_add_i32 s0, s14, s0
	s_ashr_i32 s1, s0, 8
	s_and_b32 s0, s0, 0xffffff00
	s_lshl_b32 s16, s1, 5
	s_sub_i32 s15, s14, s0
	s_sub_i32 s0, 0x104, s16
	s_min_u32 s17, s0, 32
	v_cvt_f32_ubyte0_e32 v2, s17
	v_cvt_f32_i32_e32 v0, s15
	v_rcp_iflag_f32_e32 v3, v2
	s_ashr_i32 s0, s15, 30
	s_or_b32 s18, s0, 1
	s_waitcnt vmcnt(12)
	v_mov_b32_e32 v114, v157
	v_mul_f32_e32 v3, v0, v3
	v_trunc_f32_e32 v3, v3
	v_fma_f32 v0, -v3, v2, v0
	v_cvt_i32_f32_e32 v3, v3
	v_cmp_ge_f32_e64 s[0:1], |v0|, v2
	s_and_b64 s[0:1], s[0:1], exec
	s_cselect_b32 s0, s18, 0
	v_readfirstlane_b32 s1, v3
	s_add_i32 s0, s1, s0
	s_sext_i32_i16 s1, s0
	s_mul_i32 s0, s0, s17
	s_sub_i32 s0, s15, s0
	s_sext_i32_i16 s0, s0
	s_add_i32 s16, s16, s0
	s_lshl_b32 s16, s16, 7
	s_lshl_b32 s15, s1, 7
	v_ashrrev_i32_e32 v8, 3, v114
	v_add_u32_e32 v2, s16, v8
	v_ashrrev_i32_e32 v3, 31, v2
	v_lshlrev_b32_e32 v0, 3, v114
	v_add_u32_e32 v4, 0x100, v114
	v_lshlrev_b64 v[58:59], 11, v[2:3]
	v_and_b32_e32 v0, 56, v0
	v_ashrrev_i32_e32 v9, 3, v4
	v_lshl_add_u64 v[2:3], s[4:5], 0, v[58:59]
	v_lshlrev_b32_e32 v0, 1, v0
	v_add_u32_e32 v4, s16, v9
	v_add_u32_e32 v6, 0x200, v114
	v_lshl_add_u64 v[14:15], v[2:3], 0, v[0:1]
	v_add_u32_e32 v2, s15, v8
	v_ashrrev_i32_e32 v5, 31, v4
	v_ashrrev_i32_e32 v10, 3, v6
	v_ashrrev_i32_e32 v3, 31, v2
	v_lshlrev_b64 v[62:63], 11, v[4:5]
	v_add_u32_e32 v6, s16, v10
	v_lshlrev_b64 v[60:61], 11, v[2:3]
	v_lshl_add_u64 v[4:5], s[4:5], 0, v[62:63]
	v_ashrrev_i32_e32 v7, 31, v6
	v_lshl_add_u64 v[2:3], s[6:7], 0, v[60:61]
	v_lshl_add_u64 v[16:17], v[4:5], 0, v[0:1]
	v_add_u32_e32 v4, s15, v9
	v_lshlrev_b64 v[66:67], 11, v[6:7]
	v_lshl_add_u64 v[2:3], v[2:3], 0, v[0:1]
	v_ashrrev_i32_e32 v5, 31, v4
	v_lshl_add_u64 v[6:7], s[4:5], 0, v[66:67]
	global_load_dwordx4 v[30:33], v[2:3], off
	v_lshlrev_b64 v[64:65], 11, v[4:5]
	v_lshl_add_u64 v[68:69], v[6:7], 0, v[0:1]
	v_add_u32_e32 v6, s15, v10
	global_load_dwordx4 v[26:29], v[14:15], off
	global_load_dwordx4 v[34:37], v[16:17], off
	v_lshl_add_u64 v[4:5], s[6:7], 0, v[64:65]
	v_ashrrev_i32_e32 v7, 31, v6
	v_lshl_add_u64 v[4:5], v[4:5], 0, v[0:1]
	v_lshlrev_b64 v[70:71], 11, v[6:7]
	global_load_dwordx4 v[38:41], v[4:5], off
	v_lshl_add_u64 v[6:7], s[6:7], 0, v[70:71]
	global_load_dwordx4 v[42:45], v[68:69], off
	v_lshl_add_u64 v[18:19], v[6:7], 0, v[0:1]
	global_load_dwordx4 v[46:49], v[18:19], off
	v_add_u32_e32 v6, 0x300, v114
	v_ashrrev_i32_e32 v80, 3, v6
	v_add_u32_e32 v6, s16, v80
	v_ashrrev_i32_e32 v7, 31, v6
	v_lshlrev_b64 v[72:73], 11, v[6:7]
	v_lshl_add_u64 v[6:7], s[4:5], 0, v[72:73]
	v_lshl_add_u64 v[74:75], v[6:7], 0, v[0:1]
	v_add_u32_e32 v6, s15, v80
	v_ashrrev_i32_e32 v7, 31, v6
	v_lshlrev_b64 v[76:77], 11, v[6:7]
	v_lshl_add_u64 v[6:7], s[6:7], 0, v[76:77]
	v_lshl_add_u64 v[78:79], v[6:7], 0, v[0:1]
	global_load_dwordx4 v[50:53], v[74:75], off
	global_load_dwordx4 v[54:57], v[78:79], off
	s_waitcnt vmcnt(19)
	v_mul_lo_u32 v118, v8, s71
	v_mul_lo_u32 v119, v9, s71
	s_waitcnt vmcnt(18)
	v_mul_lo_u32 v123, v10, s71
	global_load_dwordx4 v[6:9], v[2:3], off offset:128
	global_load_dwordx4 v[10:13], v[4:5], off offset:128
	s_nop 0
	global_load_dwordx4 v[2:5], v[18:19], off offset:128
	global_load_dwordx4 v[22:25], v[14:15], off offset:128
	s_nop 0
	global_load_dwordx4 v[18:21], v[16:17], off offset:128
	s_nop 0
	global_load_dwordx4 v[14:17], v[68:69], off offset:128
	v_bfe_u32 v161, v157, 3, 4
	v_add_u32_e32 v161, 4, v161
	v_lshlrev_b32_e32 v161, 1, v161
	v_and_b32_e32 v161, 16, v161
	v_xor_b32_e32 v129, v0, v161
	v_lshl_add_u32 v122, v118, 1, v129
	v_lshl_add_u32 v121, v119, 1, v129
	v_lshl_add_u32 v120, v123, 1, v129
	v_and_b32_e32 v115, 15, v114
	s_waitcnt vmcnt(23)
	v_mul_lo_u32 v126, v80, s71
	v_bfe_u32 v116, v114, 4, 2
	v_lshl_add_u32 v124, v126, 1, v129
	s_mov_b32 s17, 0
	v_lshlrev_b32_e32 v125, 4, v116
	v_and_b32_e32 v161, 15, v157
	v_add_u32_e32 v161, 4, v161
	v_lshlrev_b32_e32 v161, 1, v161
	v_and_b32_e32 v161, 16, v161
	v_xor_b32_e32 v125, v125, v161
	s_mov_b64 s[0:1], 0
	s_waitcnt vmcnt(13)
	ds_write_b128 v122, v[30:33] offset:36864
	s_waitcnt vmcnt(12)
	ds_write_b128 v122, v[26:29]
	s_waitcnt vmcnt(11)
	ds_write_b128 v121, v[34:37]
	s_waitcnt vmcnt(10)
	ds_write_b128 v121, v[38:41] offset:36864
	s_waitcnt vmcnt(9)
	ds_write_b128 v120, v[42:45]
	s_waitcnt vmcnt(8)
	ds_write_b128 v120, v[46:49] offset:36864
	global_load_dwordx4 v[26:29], v[74:75], off offset:128
	global_load_dwordx4 v[30:33], v[78:79], off offset:128
	v_ashrrev_i32_e32 v34, 1, v114
	v_and_b32_e32 v117, 0xffffffc0, v34
	v_or_b32_e32 v34, v117, v115
	v_mul_lo_u32 v128, v34, s71
	v_lshlrev_b32_e32 v34, 4, v114
	v_and_b32_e32 v34, 0x70, v34
	v_and_b32_e32 v35, 0x4f, v114
	v_or_b32_e32 v76, v76, v34
	v_or_b32_e32 v72, v72, v34
	v_or_b32_e32 v70, v70, v34
	v_or_b32_e32 v66, v66, v34
	v_or_b32_e32 v64, v64, v34
	v_or_b32_e32 v62, v62, v34
	v_or_b32_e32 v60, v60, v34
	v_or_b32_e32 v58, v58, v34
	v_mov_b32_e32 v34, 0
	s_waitcnt vmcnt(9)
	ds_write_b128 v124, v[50:53]
	s_waitcnt vmcnt(8)
	ds_write_b128 v124, v[54:57] offset:36864
	v_mul_u32_u24_e32 v127, 0x48, v35
	v_mov_b32_e32 v98, v76
	v_mov_b32_e32 v100, v72
	v_mov_b32_e32 v102, v70
	v_mov_b32_e32 v104, v66
	v_mov_b32_e32 v106, v64
	v_mov_b32_e32 v108, v62
	v_mov_b32_e32 v110, v60
	v_mov_b32_e32 v112, v58
	v_mov_b32_e32 v35, v34
	v_mov_b32_e32 v36, v34
	v_mov_b32_e32 v37, v34
	v_mov_b32_e32 v38, v34
	v_mov_b32_e32 v39, v34
	v_mov_b32_e32 v40, v34
	v_mov_b32_e32 v41, v34
	v_mov_b32_e32 v42, v34
	v_mov_b32_e32 v43, v34
	v_mov_b32_e32 v44, v34
	v_mov_b32_e32 v45, v34
	v_mov_b32_e32 v46, v34
	v_mov_b32_e32 v47, v34
	v_mov_b32_e32 v48, v34
	v_mov_b32_e32 v49, v34
	v_mov_b32_e32 v50, v34
	v_mov_b32_e32 v51, v34
	v_mov_b32_e32 v52, v34
	v_mov_b32_e32 v53, v34
	v_mov_b32_e32 v54, v34
	v_mov_b32_e32 v55, v34
	v_mov_b32_e32 v56, v34
	v_mov_b32_e32 v57, v34
	v_mov_b32_e32 v58, v34
	v_mov_b32_e32 v59, v34
	v_mov_b32_e32 v60, v34
	v_mov_b32_e32 v61, v34
	v_mov_b32_e32 v62, v34
	v_mov_b32_e32 v63, v34
	v_mov_b32_e32 v64, v34
	v_mov_b32_e32 v65, v34
	v_mov_b32_e32 v66, v34
	v_mov_b32_e32 v67, v34
	v_mov_b32_e32 v68, v34
	v_mov_b32_e32 v69, v34
	v_mov_b32_e32 v70, v34
	v_mov_b32_e32 v71, v34
	v_mov_b32_e32 v72, v34
	v_mov_b32_e32 v73, v34
	v_mov_b32_e32 v74, v34
	v_mov_b32_e32 v75, v34
	v_mov_b32_e32 v76, v34
	v_mov_b32_e32 v77, v34
	v_mov_b32_e32 v78, v34
	v_mov_b32_e32 v79, v34
	v_mov_b32_e32 v80, v34
	v_mov_b32_e32 v81, v34
	v_mov_b32_e32 v82, v34
	v_mov_b32_e32 v83, v34
	v_mov_b32_e32 v84, v34
	v_mov_b32_e32 v85, v34
	v_mov_b32_e32 v86, v34
	v_mov_b32_e32 v87, v34
	v_mov_b32_e32 v88, v34
	v_mov_b32_e32 v89, v34
	v_mov_b32_e32 v90, v34
	v_mov_b32_e32 v91, v34
	v_mov_b32_e32 v92, v34
	v_mov_b32_e32 v93, v34
	v_mov_b32_e32 v94, v34
	v_mov_b32_e32 v95, v34
	v_mov_b32_e32 v96, v34
	v_mov_b32_e32 v97, v34
	s_waitcnt lgkmcnt(0)
	s_barrier
; DEV f32x4 mfma16(bf16x8 a, bf16x8 b, f32x4 c) { return __builtin_amdgcn_mfma_f32_16x16x32_bf16(a, b, c, 0, 0, 0); }
; template <int EPI, bool AF32>
; DEV void gemm_tile(const void* Ap, int lda, const u16* Bt, int ldb, int K, int m0, int n0, const Epi& ea, char* smem) {
;     ...
;   auto gload = [&](int kt) {
;     const int k0 = kt << 6;
; #pragma unroll
;     for (int i = 0; i < 4; i++) {
;       const int c = tid + i * 256, row = c >> 3, kc = c & 7;
;       if (AF32) {
;         const float* pa = (const float*)Ap + (size_t)(m0 + row) * lda + k0 + kc * 8;
;         rfa[2 * i] = *(const f32x4*)pa;
;         rfa[2 * i + 1] = *(const f32x4*)(pa + 4);
;       } else {
;         ra[i] = *(const u32x4*)((const u16*)Ap + (size_t)(m0 + row) * lda + k0 + kc * 8);
;       }
;       rb[i] = *(const u32x4*)(Bt + (size_t)(n0 + row) * ldb + k0 + kc * 8);
;     }
;   };
;   auto swrite = [&](int buf) {
; #pragma unroll
;     for (int i = 0; i < 4; i++) {
;       const int c = tid + i * 256, row = c >> 3, kc = c & 7;
;       u32x4 va;
;       if (AF32) {
;         va = (u32x4){pack2(rfa[2 * i][0], rfa[2 * i][1]), pack2(rfa[2 * i][2], rfa[2 * i][3]),
;                      pack2(rfa[2 * i + 1][0], rfa[2 * i + 1][1]), pack2(rfa[2 * i + 1][2], rfa[2 * i + 1][3])};
;       } else {
;         va = ra[i];
;       }
;       *(u32x4*)(sA + buf * 9216 + row * 72 + kc * 8) = va;
;       *(u32x4*)(sB + buf * 9216 + row * 72 + kc * 8) = rb[i];
;     }
;   };
;   gload(0);
;   swrite(0);
;   if (nk > 1) gload(1);
;   __syncthreads();
;   for (int kt = 0; kt < nk; kt++) {
;     const int buf = kt & 1;
;     if (kt + 1 < nk) swrite(buf ^ 1);
;     if (kt + 2 < nk) gload(kt + 2);
; #pragma unroll
;     for (int ks = 0; ks < 2; ks++) {
;       bf16x8 a[4], b[4];
; #pragma unroll
;       for (int m = 0; m < 4; m++) a[m] = *(const bf16x8*)(sA + buf * 9216 + (wr * 64 + m * 16 + fr) * 72 + ks * 32 + fq * 8);
; #pragma unroll
;       for (int n = 0; n < 4; n++) b[n] = *(const bf16x8*)(sB + buf * 9216 + (wc * 64 + n * 16 + fr) * 72 + ks * 32 + fq * 8);
;       __builtin_amdgcn_s_setprio(1);
; #pragma unroll
;       for (int m = 0; m < 4; m++)
; #pragma unroll
;         for (int n = 0; n < 4; n++) acc[m][n] = mfma16(a[m], b[n], acc[m][n]);
;       __builtin_amdgcn_s_setprio(0);
;     }
;     __syncthreads();
;   }
	v_lshl_add_u32 v161, v128, 1, v125
	v_lshl_add_u32 v129, v127, 1, v125
	s_mov_b32 s17, 0
	s_mov_b64 s[0:1], 0x100
	ds_read_b128 v[130:133], v161
	ds_read_b128 v[134:137], v161 offset:2304
	ds_read_b128 v[138:141], v161 offset:4608
	ds_read_b128 v[142:145], v161 offset:6912
	ds_read_b128 v[146:149], v129 offset:36864
	ds_read_b128 v[150:153], v129 offset:39168
	ds_read_b128 v[162:165], v129 offset:41472
	ds_read_b128 v[166:169], v129 offset:43776
.Lgk4_loop:
	s_waitcnt lgkmcnt(0)
	ds_read_b128 v[222:225], v161 offset:64
	ds_read_b128 v[226:229], v161 offset:2368
	ds_read_b128 v[230:233], v161 offset:4672
	ds_read_b128 v[234:237], v161 offset:6976
	ds_read_b128 v[238:241], v129 offset:36928
	ds_read_b128 v[242:245], v129 offset:39232
	ds_read_b128 v[246:249], v129 offset:41536
	ds_read_b128 v[250:253], v129 offset:43840
	v_mfma_f32_16x16x32_bf16 v[34:37], v[130:133], v[146:149], v[34:37]
	v_mfma_f32_16x16x32_bf16 v[38:41], v[130:133], v[150:153], v[38:41]
	v_mfma_f32_16x16x32_bf16 v[42:45], v[130:133], v[162:165], v[42:45]
	v_mfma_f32_16x16x32_bf16 v[46:49], v[130:133], v[166:169], v[46:49]
	s_waitcnt vmcnt(0)
	ds_write_b128 v122, v[22:25] offset:18432
	ds_write_b128 v122, v[6:9] offset:55296
	v_mfma_f32_16x16x32_bf16 v[50:53], v[134:137], v[146:149], v[50:53]
	ds_write_b128 v121, v[18:21] offset:18432
	ds_write_b128 v121, v[10:13] offset:55296
	v_mfma_f32_16x16x32_bf16 v[54:57], v[134:137], v[150:153], v[54:57]
	ds_write_b128 v120, v[14:17] offset:18432
	ds_write_b128 v120, v[2:5] offset:55296
	v_mfma_f32_16x16x32_bf16 v[58:61], v[134:137], v[162:165], v[58:61]
	ds_write_b128 v124, v[26:29] offset:18432
	ds_write_b128 v124, v[30:33] offset:55296
	v_mfma_f32_16x16x32_bf16 v[62:65], v[134:137], v[166:169], v[62:65]
	global_load_dwordx4 v[22:25], v112, s[12:13]
	v_mfma_f32_16x16x32_bf16 v[66:69], v[138:141], v[146:149], v[66:69]
	global_load_dwordx4 v[6:9], v110, s[10:11]
	v_mfma_f32_16x16x32_bf16 v[70:73], v[138:141], v[150:153], v[70:73]
	global_load_dwordx4 v[18:21], v108, s[12:13]
	v_mfma_f32_16x16x32_bf16 v[74:77], v[138:141], v[162:165], v[74:77]
	global_load_dwordx4 v[10:13], v106, s[10:11]
	v_mfma_f32_16x16x32_bf16 v[78:81], v[138:141], v[166:169], v[78:81]
	global_load_dwordx4 v[14:17], v104, s[12:13]
	v_mfma_f32_16x16x32_bf16 v[82:85], v[142:145], v[146:149], v[82:85]
	global_load_dwordx4 v[2:5], v102, s[10:11]
	v_mfma_f32_16x16x32_bf16 v[86:89], v[142:145], v[150:153], v[86:89]
	global_load_dwordx4 v[26:29], v100, s[12:13]
	v_mfma_f32_16x16x32_bf16 v[90:93], v[142:145], v[162:165], v[90:93]
	global_load_dwordx4 v[30:33], v98, s[10:11]
	v_mfma_f32_16x16x32_bf16 v[94:97], v[142:145], v[166:169], v[94:97]
	s_waitcnt lgkmcnt(0)
	s_barrier
	ds_read_b128 v[130:133], v161 offset:18432
	v_mfma_f32_16x16x32_bf16 v[34:37], v[222:225], v[238:241], v[34:37]
	ds_read_b128 v[134:137], v161 offset:20736
	v_mfma_f32_16x16x32_bf16 v[38:41], v[222:225], v[242:245], v[38:41]
	ds_read_b128 v[138:141], v161 offset:23040
	v_mfma_f32_16x16x32_bf16 v[42:45], v[222:225], v[246:249], v[42:45]
	ds_read_b128 v[142:145], v161 offset:25344
	v_mfma_f32_16x16x32_bf16 v[46:49], v[222:225], v[250:253], v[46:49]
	ds_read_b128 v[146:149], v129 offset:55296
	v_mfma_f32_16x16x32_bf16 v[50:53], v[226:229], v[238:241], v[50:53]
	ds_read_b128 v[150:153], v129 offset:57600
	v_mfma_f32_16x16x32_bf16 v[54:57], v[226:229], v[242:245], v[54:57]
	ds_read_b128 v[162:165], v129 offset:59904
	v_mfma_f32_16x16x32_bf16 v[58:61], v[226:229], v[246:249], v[58:61]
	ds_read_b128 v[166:169], v129 offset:62208
	v_mfma_f32_16x16x32_bf16 v[62:65], v[226:229], v[250:253], v[62:65]
	v_mfma_f32_16x16x32_bf16 v[66:69], v[230:233], v[238:241], v[66:69]
	v_mfma_f32_16x16x32_bf16 v[70:73], v[230:233], v[242:245], v[70:73]
	v_mfma_f32_16x16x32_bf16 v[74:77], v[230:233], v[246:249], v[74:77]
	v_mfma_f32_16x16x32_bf16 v[78:81], v[230:233], v[250:253], v[78:81]
	v_mfma_f32_16x16x32_bf16 v[82:85], v[234:237], v[238:241], v[82:85]
	v_mfma_f32_16x16x32_bf16 v[86:89], v[234:237], v[242:245], v[86:89]
	v_mfma_f32_16x16x32_bf16 v[90:93], v[234:237], v[246:249], v[90:93]
	v_mfma_f32_16x16x32_bf16 v[94:97], v[234:237], v[250:253], v[94:97]
	s_waitcnt lgkmcnt(0)
	ds_read_b128 v[222:225], v161 offset:18496
	ds_read_b128 v[226:229], v161 offset:20800
	ds_read_b128 v[230:233], v161 offset:23104
	ds_read_b128 v[234:237], v161 offset:25408
	ds_read_b128 v[238:241], v129 offset:55360
	ds_read_b128 v[242:245], v129 offset:57664
	ds_read_b128 v[246:249], v129 offset:59968
	ds_read_b128 v[250:253], v129 offset:62272
	v_mfma_f32_16x16x32_bf16 v[34:37], v[130:133], v[146:149], v[34:37]
	v_mfma_f32_16x16x32_bf16 v[38:41], v[130:133], v[150:153], v[38:41]
	v_mfma_f32_16x16x32_bf16 v[42:45], v[130:133], v[162:165], v[42:45]
	v_mfma_f32_16x16x32_bf16 v[46:49], v[130:133], v[166:169], v[46:49]
	s_waitcnt vmcnt(0)
	ds_write_b128 v122, v[22:25]
	ds_write_b128 v122, v[6:9] offset:36864
	v_mfma_f32_16x16x32_bf16 v[50:53], v[134:137], v[146:149], v[50:53]
	ds_write_b128 v121, v[18:21]
	ds_write_b128 v121, v[10:13] offset:36864
	v_mfma_f32_16x16x32_bf16 v[54:57], v[134:137], v[150:153], v[54:57]
	ds_write_b128 v120, v[14:17]
	ds_write_b128 v120, v[2:5] offset:36864
	v_mfma_f32_16x16x32_bf16 v[58:61], v[134:137], v[162:165], v[58:61]
	ds_write_b128 v124, v[26:29]
	ds_write_b128 v124, v[30:33] offset:36864
	v_mfma_f32_16x16x32_bf16 v[62:65], v[134:137], v[166:169], v[62:65]
	global_load_dwordx4 v[22:25], v112, s[12:13] offset:128
	v_mfma_f32_16x16x32_bf16 v[66:69], v[138:141], v[146:149], v[66:69]
	global_load_dwordx4 v[6:9], v110, s[10:11] offset:128
	v_mfma_f32_16x16x32_bf16 v[70:73], v[138:141], v[150:153], v[70:73]
	global_load_dwordx4 v[18:21], v108, s[12:13] offset:128
	v_mfma_f32_16x16x32_bf16 v[74:77], v[138:141], v[162:165], v[74:77]
	global_load_dwordx4 v[10:13], v106, s[10:11] offset:128
	v_mfma_f32_16x16x32_bf16 v[78:81], v[138:141], v[166:169], v[78:81]
	global_load_dwordx4 v[14:17], v104, s[12:13] offset:128
	v_mfma_f32_16x16x32_bf16 v[82:85], v[142:145], v[146:149], v[82:85]
	global_load_dwordx4 v[2:5], v102, s[10:11] offset:128
	v_mfma_f32_16x16x32_bf16 v[86:89], v[142:145], v[150:153], v[86:89]
	global_load_dwordx4 v[26:29], v100, s[12:13] offset:128
	v_mfma_f32_16x16x32_bf16 v[90:93], v[142:145], v[162:165], v[90:93]
	global_load_dwordx4 v[30:33], v98, s[10:11] offset:128
	v_mfma_f32_16x16x32_bf16 v[94:97], v[142:145], v[166:169], v[94:97]
	s_waitcnt lgkmcnt(0)
	s_barrier
; DEV f32x4 mfma16(bf16x8 a, bf16x8 b, f32x4 c) { return __builtin_amdgcn_mfma_f32_16x16x32_bf16(a, b, c, 0, 0, 0); }
; template <int EPI, bool AF32>
; DEV void gemm_tile(const void* Ap, int lda, const u16* Bt, int ldb, int K, int m0, int n0, const Epi& ea, char* smem) {
;     ...
;   auto gload = [&](int kt) {
;     const int k0 = kt << 6;
; #pragma unroll
;     for (int i = 0; i < 4; i++) {
;       const int c = tid + i * 256, row = c >> 3, kc = c & 7;
;       if (AF32) {
;         const float* pa = (const float*)Ap + (size_t)(m0 + row) * lda + k0 + kc * 8;
;         rfa[2 * i] = *(const f32x4*)pa;
;         rfa[2 * i + 1] = *(const f32x4*)(pa + 4);
;       } else {
;         ra[i] = *(const u32x4*)((const u16*)Ap + (size_t)(m0 + row) * lda + k0 + kc * 8);
;       }
;       rb[i] = *(const u32x4*)(Bt + (size_t)(n0 + row) * ldb + k0 + kc * 8);
;     }
;   };
;   auto swrite = [&](int buf) {
; #pragma unroll
;     for (int i = 0; i < 4; i++) {
;       const int c = tid + i * 256, row = c >> 3, kc = c & 7;
;       u32x4 va;
;       if (AF32) {
;         va = (u32x4){pack2(rfa[2 * i][0], rfa[2 * i][1]), pack2(rfa[2 * i][2], rfa[2 * i][3]),
;                      pack2(rfa[2 * i + 1][0], rfa[2 * i + 1][1]), pack2(rfa[2 * i + 1][2], rfa[2 * i + 1][3])};
;       } else {
;         va = ra[i];
;       }
;       *(u32x4*)(sA + buf * 9216 + row * 72 + kc * 8) = va;
;       *(u32x4*)(sB + buf * 9216 + row * 72 + kc * 8) = rb[i];
;     }
;   };
;   gload(0);
;   swrite(0);
;   if (nk > 1) gload(1);
;   __syncthreads();
;   for (int kt = 0; kt < nk; kt++) {
;     const int buf = kt & 1;
;     if (kt + 1 < nk) swrite(buf ^ 1);
;     if (kt + 2 < nk) gload(kt + 2);
; #pragma unroll
;     for (int ks = 0; ks < 2; ks++) {
;       bf16x8 a[4], b[4];
; #pragma unroll
;       for (int m = 0; m < 4; m++) a[m] = *(const bf16x8*)(sA + buf * 9216 + (wr * 64 + m * 16 + fr) * 72 + ks * 32 + fq * 8);
; #pragma unroll
;       for (int n = 0; n < 4; n++) b[n] = *(const bf16x8*)(sB + buf * 9216 + (wc * 64 + n * 16 + fr) * 72 + ks * 32 + fq * 8);
;       __builtin_amdgcn_s_setprio(1);
; #pragma unroll
;       for (int m = 0; m < 4; m++)
; #pragma unroll
;         for (int n = 0; n < 4; n++) acc[m][n] = mfma16(a[m], b[n], acc[m][n]);
;       __builtin_amdgcn_s_setprio(0);
;     }
;     __syncthreads();
;   }
	ds_read_b128 v[130:133], v161
	v_mfma_f32_16x16x32_bf16 v[34:37], v[222:225], v[238:241], v[34:37]
	ds_read_b128 v[134:137], v161 offset:2304
	v_mfma_f32_16x16x32_bf16 v[38:41], v[222:225], v[242:245], v[38:41]
	ds_read_b128 v[138:141], v161 offset:4608
	v_mfma_f32_16x16x32_bf16 v[42:45], v[222:225], v[246:249], v[42:45]
	ds_read_b128 v[142:145], v161 offset:6912
	v_mfma_f32_16x16x32_bf16 v[46:49], v[222:225], v[250:253], v[46:49]
	ds_read_b128 v[146:149], v129 offset:36864
	v_mfma_f32_16x16x32_bf16 v[50:53], v[226:229], v[238:241], v[50:53]
	ds_read_b128 v[150:153], v129 offset:39168
	v_mfma_f32_16x16x32_bf16 v[54:57], v[226:229], v[242:245], v[54:57]
	ds_read_b128 v[162:165], v129 offset:41472
	v_mfma_f32_16x16x32_bf16 v[58:61], v[226:229], v[246:249], v[58:61]
	ds_read_b128 v[166:169], v129 offset:43776
	v_mfma_f32_16x16x32_bf16 v[62:65], v[226:229], v[250:253], v[62:65]
	v_mfma_f32_16x16x32_bf16 v[66:69], v[230:233], v[238:241], v[66:69]
	v_add_u32_e32 v112, 0x100, v112
	v_mfma_f32_16x16x32_bf16 v[70:73], v[230:233], v[242:245], v[70:73]
	v_add_u32_e32 v110, 0x100, v110
	v_mfma_f32_16x16x32_bf16 v[74:77], v[230:233], v[246:249], v[74:77]
	v_add_u32_e32 v108, 0x100, v108
	v_mfma_f32_16x16x32_bf16 v[78:81], v[230:233], v[250:253], v[78:81]
	v_add_u32_e32 v106, 0x100, v106
	v_mfma_f32_16x16x32_bf16 v[82:85], v[234:237], v[238:241], v[82:85]
	v_add_u32_e32 v104, 0x100, v104
	v_mfma_f32_16x16x32_bf16 v[86:89], v[234:237], v[242:245], v[86:89]
	v_add_u32_e32 v102, 0x100, v102
	v_mfma_f32_16x16x32_bf16 v[90:93], v[234:237], v[246:249], v[90:93]
	v_add_u32_e32 v100, 0x100, v100
	v_mfma_f32_16x16x32_bf16 v[94:97], v[234:237], v[250:253], v[94:97]
	v_add_u32_e32 v98, 0x100, v98
	s_add_i32 s17, s17, 1
	s_cmp_lg_u32 s17, 7
	s_cbranch_scc1 .Lgk4_loop
	s_waitcnt lgkmcnt(0)
	ds_read_b128 v[222:225], v161 offset:64
	ds_read_b128 v[226:229], v161 offset:2368
	ds_read_b128 v[230:233], v161 offset:4672
	ds_read_b128 v[234:237], v161 offset:6976
	ds_read_b128 v[238:241], v129 offset:36928
	ds_read_b128 v[242:245], v129 offset:39232
	ds_read_b128 v[246:249], v129 offset:41536
	ds_read_b128 v[250:253], v129 offset:43840
	v_mfma_f32_16x16x32_bf16 v[34:37], v[130:133], v[146:149], v[34:37]
	v_mfma_f32_16x16x32_bf16 v[38:41], v[130:133], v[150:153], v[38:41]
	v_mfma_f32_16x16x32_bf16 v[42:45], v[130:133], v[162:165], v[42:45]
	v_mfma_f32_16x16x32_bf16 v[46:49], v[130:133], v[166:169], v[46:49]
	s_waitcnt vmcnt(0)
	ds_write_b128 v122, v[22:25] offset:18432
	ds_write_b128 v122, v[6:9] offset:55296
	v_mfma_f32_16x16x32_bf16 v[50:53], v[134:137], v[146:149], v[50:53]
	ds_write_b128 v121, v[18:21] offset:18432
	ds_write_b128 v121, v[10:13] offset:55296
	v_mfma_f32_16x16x32_bf16 v[54:57], v[134:137], v[150:153], v[54:57]
	ds_write_b128 v120, v[14:17] offset:18432
	ds_write_b128 v120, v[2:5] offset:55296
	v_mfma_f32_16x16x32_bf16 v[58:61], v[134:137], v[162:165], v[58:61]
	ds_write_b128 v124, v[26:29] offset:18432
	ds_write_b128 v124, v[30:33] offset:55296
	v_mfma_f32_16x16x32_bf16 v[62:65], v[134:137], v[166:169], v[62:65]
	v_mfma_f32_16x16x32_bf16 v[66:69], v[138:141], v[146:149], v[66:69]
	v_mfma_f32_16x16x32_bf16 v[70:73], v[138:141], v[150:153], v[70:73]
	v_mfma_f32_16x16x32_bf16 v[74:77], v[138:141], v[162:165], v[74:77]
	v_mfma_f32_16x16x32_bf16 v[78:81], v[138:141], v[166:169], v[78:81]
	v_mfma_f32_16x16x32_bf16 v[82:85], v[142:145], v[146:149], v[82:85]
	v_mfma_f32_16x16x32_bf16 v[86:89], v[142:145], v[150:153], v[86:89]
	v_mfma_f32_16x16x32_bf16 v[90:93], v[142:145], v[162:165], v[90:93]
	v_mfma_f32_16x16x32_bf16 v[94:97], v[142:145], v[166:169], v[94:97]
	s_waitcnt lgkmcnt(0)
	s_barrier
	ds_read_b128 v[130:133], v161 offset:18432
	v_mfma_f32_16x16x32_bf16 v[34:37], v[222:225], v[238:241], v[34:37]
	ds_read_b128 v[134:137], v161 offset:20736
	v_mfma_f32_16x16x32_bf16 v[38:41], v[222:225], v[242:245], v[38:41]
	ds_read_b128 v[138:141], v161 offset:23040
	v_mfma_f32_16x16x32_bf16 v[42:45], v[222:225], v[246:249], v[42:45]
	ds_read_b128 v[142:145], v161 offset:25344
	v_mfma_f32_16x16x32_bf16 v[46:49], v[222:225], v[250:253], v[46:49]
	ds_read_b128 v[146:149], v129 offset:55296
	v_mfma_f32_16x16x32_bf16 v[50:53], v[226:229], v[238:241], v[50:53]
	ds_read_b128 v[150:153], v129 offset:57600
	v_mfma_f32_16x16x32_bf16 v[54:57], v[226:229], v[242:245], v[54:57]
	ds_read_b128 v[162:165], v129 offset:59904
	v_mfma_f32_16x16x32_bf16 v[58:61], v[226:229], v[246:249], v[58:61]
	ds_read_b128 v[166:169], v129 offset:62208
	v_mfma_f32_16x16x32_bf16 v[62:65], v[226:229], v[250:253], v[62:65]
	v_mfma_f32_16x16x32_bf16 v[66:69], v[230:233], v[238:241], v[66:69]
	v_mfma_f32_16x16x32_bf16 v[70:73], v[230:233], v[242:245], v[70:73]
	v_mfma_f32_16x16x32_bf16 v[74:77], v[230:233], v[246:249], v[74:77]
	v_mfma_f32_16x16x32_bf16 v[78:81], v[230:233], v[250:253], v[78:81]
	v_mfma_f32_16x16x32_bf16 v[82:85], v[234:237], v[238:241], v[82:85]
	v_mfma_f32_16x16x32_bf16 v[86:89], v[234:237], v[242:245], v[86:89]
	v_mfma_f32_16x16x32_bf16 v[90:93], v[234:237], v[246:249], v[90:93]
	v_mfma_f32_16x16x32_bf16 v[94:97], v[234:237], v[250:253], v[94:97]
	s_waitcnt lgkmcnt(0)
; DEV f32x4 mfma16(bf16x8 a, bf16x8 b, f32x4 c) { return __builtin_amdgcn_mfma_f32_16x16x32_bf16(a, b, c, 0, 0, 0); }
; template <int EPI, bool AF32>
; DEV void gemm_tile(const void* Ap, int lda, const u16* Bt, int ldb, int K, int m0, int n0, const Epi& ea, char* smem) {
;     ...
;   for (int kt = 0; kt < nk; kt++) {
;     const int buf = kt & 1;
;     if (kt + 1 < nk) swrite(buf ^ 1);
;     if (kt + 2 < nk) gload(kt + 2);
; #pragma unroll
;     for (int ks = 0; ks < 2; ks++) {
;       bf16x8 a[4], b[4];
; #pragma unroll
;       for (int m = 0; m < 4; m++) a[m] = *(const bf16x8*)(sA + buf * 9216 + (wr * 64 + m * 16 + fr) * 72 + ks * 32 + fq * 8);
; #pragma unroll
;       for (int n = 0; n < 4; n++) b[n] = *(const bf16x8*)(sB + buf * 9216 + (wc * 64 + n * 16 + fr) * 72 + ks * 32 + fq * 8);
;       __builtin_amdgcn_s_setprio(1);
; #pragma unroll
;       for (int m = 0; m < 4; m++)
; #pragma unroll
;         for (int n = 0; n < 4; n++) acc[m][n] = mfma16(a[m], b[n], acc[m][n]);
;       __builtin_amdgcn_s_setprio(0);
;     }
;     __syncthreads();
;   }
;     ...
;       u16* C = (u16*)ea.p0;
;       const u16* G = (const u16*)ea.p1 + (EPI == EP_MERGE2 ? 1024 : 0);
;       u16 gv[4][4][4], cv[4][4][4];
; #pragma unroll
;       for (int m = 0; m < 4; m++)
; #pragma unroll
;         for (int j = 0; j < 4; j++)
; #pragma unroll
;           for (int n = 0; n < 4; n++) {
;             gv[m][j][n] = G[(size_t)(rbase + m * 16 + j) * 2048 + cbase + n * 16];
;             if (EPI == EP_MERGE2) cv[m][j][n] = C[(size_t)(rbase + m * 16 + j) * 1024 + cbase + n * 16];
;           }
	ds_read_b128 v[222:225], v161 offset:18496
	ds_read_b128 v[226:229], v161 offset:20800
	ds_read_b128 v[230:233], v161 offset:23104
	ds_read_b128 v[234:237], v161 offset:25408
	ds_read_b128 v[238:241], v129 offset:55360
	ds_read_b128 v[242:245], v129 offset:57664
	ds_read_b128 v[246:249], v129 offset:59968
	ds_read_b128 v[250:253], v129 offset:62272
	v_mfma_f32_16x16x32_bf16 v[98:101], v[130:133], v[146:149], v[34:37]
	v_mfma_f32_16x16x32_bf16 v[102:105], v[130:133], v[150:153], v[38:41]
	v_mfma_f32_16x16x32_bf16 v[106:109], v[130:133], v[162:165], v[42:45]
	v_mfma_f32_16x16x32_bf16 v[110:113], v[130:133], v[166:169], v[46:49]
	v_mfma_f32_16x16x32_bf16 v[50:53], v[134:137], v[146:149], v[50:53]
	v_mfma_f32_16x16x32_bf16 v[54:57], v[134:137], v[150:153], v[54:57]
	v_mfma_f32_16x16x32_bf16 v[58:61], v[134:137], v[162:165], v[58:61]
	v_mfma_f32_16x16x32_bf16 v[62:65], v[134:137], v[166:169], v[62:65]
	v_mfma_f32_16x16x32_bf16 v[66:69], v[138:141], v[146:149], v[66:69]
	v_mfma_f32_16x16x32_bf16 v[70:73], v[138:141], v[150:153], v[70:73]
	v_mfma_f32_16x16x32_bf16 v[74:77], v[138:141], v[162:165], v[74:77]
	v_mfma_f32_16x16x32_bf16 v[78:81], v[138:141], v[166:169], v[78:81]
	v_mfma_f32_16x16x32_bf16 v[82:85], v[142:145], v[146:149], v[82:85]
	v_mfma_f32_16x16x32_bf16 v[86:89], v[142:145], v[150:153], v[86:89]
	v_mfma_f32_16x16x32_bf16 v[90:93], v[142:145], v[162:165], v[90:93]
	v_mfma_f32_16x16x32_bf16 v[94:97], v[142:145], v[166:169], v[94:97]
	s_waitcnt lgkmcnt(0)
	v_mfma_f32_16x16x32_bf16 v[30:33], v[230:233], v[238:241], v[66:69]
	v_mfma_f32_16x16x32_bf16 v[26:29], v[230:233], v[242:245], v[70:73]
	v_mfma_f32_16x16x32_bf16 v[22:25], v[230:233], v[246:249], v[74:77]
	v_mfma_f32_16x16x32_bf16 v[18:21], v[230:233], v[250:253], v[78:81]
	v_mfma_f32_16x16x32_bf16 v[14:17], v[234:237], v[238:241], v[82:85]
	v_mfma_f32_16x16x32_bf16 v[10:13], v[234:237], v[242:245], v[86:89]
	v_mfma_f32_16x16x32_bf16 v[6:9], v[234:237], v[246:249], v[90:93]
	v_mfma_f32_16x16x32_bf16 v[2:5], v[234:237], v[250:253], v[94:97]
	v_mfma_f32_16x16x32_bf16 v[34:37], v[226:229], v[250:253], v[62:65]
	v_mfma_f32_16x16x32_bf16 v[62:65], v[222:225], v[238:241], v[98:101]
	v_mfma_f32_16x16x32_bf16 v[38:41], v[226:229], v[246:249], v[58:61]
	v_mfma_f32_16x16x32_bf16 v[58:61], v[222:225], v[242:245], v[102:105]
	v_mfma_f32_16x16x32_bf16 v[42:45], v[226:229], v[242:245], v[54:57]
	v_mfma_f32_16x16x32_bf16 v[54:57], v[222:225], v[246:249], v[106:109]
	v_mfma_f32_16x16x32_bf16 v[46:49], v[226:229], v[238:241], v[50:53]
	v_mfma_f32_16x16x32_bf16 v[50:53], v[222:225], v[250:253], v[110:113]
	s_nop 7
	v_and_b32_e32 v114, 64, v114
	v_add_u32_e32 v0, s16, v117
	v_or3_b32 v68, v114, s15, v115
	v_lshl_or_b32 v66, v116, 2, v0
	v_ashrrev_i32_e32 v69, 31, v68
	v_lshlrev_b64 v[68:69], 1, v[68:69]
	v_ashrrev_i32_e32 v67, 31, v66
	v_lshl_add_u64 v[98:99], s[8:9], 0, v[68:69]
	v_lshl_add_u64 v[100:101], s[2:3], 0, v[68:69]
	v_lshlrev_b64 v[68:69], 12, v[66:67]
	v_lshl_add_u64 v[102:103], v[98:99], 0, v[68:69]
	v_lshlrev_b64 v[68:69], 11, v[66:67]
	v_lshl_add_u64 v[96:97], v[100:101], 0, v[68:69]
	v_or_b32_e32 v68, 1, v66
	v_ashrrev_i32_e32 v69, 31, v68
	v_lshlrev_b64 v[70:71], 12, v[68:69]
	v_lshlrev_b64 v[68:69], 11, v[68:69]
	v_lshl_add_u64 v[94:95], v[100:101], 0, v[68:69]
	v_or_b32_e32 v68, 2, v66
	v_ashrrev_i32_e32 v69, 31, v68
	v_lshl_add_u64 v[104:105], v[98:99], 0, v[70:71]
	v_lshlrev_b64 v[70:71], 12, v[68:69]
	v_lshlrev_b64 v[68:69], 11, v[68:69]
	v_lshl_add_u64 v[92:93], v[100:101], 0, v[68:69]
	v_or_b32_e32 v68, 3, v66
	v_ashrrev_i32_e32 v69, 31, v68
	v_lshl_add_u64 v[106:107], v[98:99], 0, v[70:71]
	v_lshlrev_b64 v[70:71], 12, v[68:69]
	v_lshlrev_b64 v[68:69], 11, v[68:69]
	v_lshl_add_u64 v[90:91], v[100:101], 0, v[68:69]
	v_or_b32_e32 v68, 16, v66
	v_ashrrev_i32_e32 v69, 31, v68
	v_lshl_add_u64 v[108:109], v[98:99], 0, v[70:71]
	v_lshlrev_b64 v[70:71], 12, v[68:69]
	v_lshlrev_b64 v[68:69], 11, v[68:69]
	v_lshl_add_u64 v[88:89], v[100:101], 0, v[68:69]
	v_or_b32_e32 v68, 17, v66
	v_ashrrev_i32_e32 v69, 31, v68
	v_lshl_add_u64 v[110:111], v[98:99], 0, v[70:71]
	v_lshlrev_b64 v[70:71], 12, v[68:69]
	v_lshlrev_b64 v[68:69], 11, v[68:69]
	v_lshl_add_u64 v[86:87], v[100:101], 0, v[68:69]
	v_or_b32_e32 v68, 18, v66
	v_ashrrev_i32_e32 v69, 31, v68
	v_lshl_add_u64 v[112:113], v[98:99], 0, v[70:71]
	v_lshlrev_b64 v[70:71], 12, v[68:69]
	v_lshlrev_b64 v[68:69], 11, v[68:69]
	v_lshl_add_u64 v[84:85], v[100:101], 0, v[68:69]
	v_or_b32_e32 v68, 19, v66
	v_ashrrev_i32_e32 v69, 31, v68
	v_lshl_add_u64 v[114:115], v[98:99], 0, v[70:71]
	v_lshlrev_b64 v[70:71], 12, v[68:69]
	v_lshlrev_b64 v[68:69], 11, v[68:69]
	v_lshl_add_u64 v[82:83], v[100:101], 0, v[68:69]
	v_or_b32_e32 v68, 32, v66
	v_ashrrev_i32_e32 v69, 31, v68
	v_lshl_add_u64 v[116:117], v[98:99], 0, v[70:71]
	v_lshlrev_b64 v[70:71], 12, v[68:69]
	v_lshlrev_b64 v[68:69], 11, v[68:69]
	v_lshl_add_u64 v[80:81], v[100:101], 0, v[68:69]
	v_or_b32_e32 v68, 33, v66
	v_ashrrev_i32_e32 v69, 31, v68
	v_lshl_add_u64 v[118:119], v[98:99], 0, v[70:71]
	v_lshlrev_b64 v[70:71], 12, v[68:69]
	v_lshlrev_b64 v[68:69], 11, v[68:69]
	v_lshl_add_u64 v[78:79], v[100:101], 0, v[68:69]
	v_or_b32_e32 v68, 34, v66
	v_ashrrev_i32_e32 v69, 31, v68
	v_lshl_add_u64 v[120:121], v[98:99], 0, v[70:71]
	v_lshlrev_b64 v[70:71], 12, v[68:69]
	v_lshlrev_b64 v[68:69], 11, v[68:69]
	v_lshl_add_u64 v[76:77], v[100:101], 0, v[68:69]
	v_or_b32_e32 v68, 35, v66
	v_ashrrev_i32_e32 v69, 31, v68
	v_lshl_add_u64 v[122:123], v[98:99], 0, v[70:71]
	v_lshlrev_b64 v[70:71], 12, v[68:69]
	v_lshlrev_b64 v[68:69], 11, v[68:69]
	v_lshl_add_u64 v[74:75], v[100:101], 0, v[68:69]
	v_or_b32_e32 v68, 48, v66
	v_ashrrev_i32_e32 v69, 31, v68
	v_lshl_add_u64 v[124:125], v[98:99], 0, v[70:71]
	v_lshlrev_b64 v[70:71], 12, v[68:69]
	v_lshlrev_b64 v[68:69], 11, v[68:69]
	v_lshl_add_u64 v[72:73], v[100:101], 0, v[68:69]
	v_or_b32_e32 v68, 49, v66
	v_ashrrev_i32_e32 v69, 31, v68
	v_lshl_add_u64 v[126:127], v[98:99], 0, v[70:71]
	v_lshlrev_b64 v[70:71], 12, v[68:69]
	v_lshlrev_b64 v[68:69], 11, v[68:69]
	v_lshl_add_u64 v[128:129], v[98:99], 0, v[70:71]
	v_lshl_add_u64 v[70:71], v[100:101], 0, v[68:69]
	v_or_b32_e32 v68, 50, v66
	v_or_b32_e32 v66, 51, v66
	v_ashrrev_i32_e32 v69, 31, v68
	v_ashrrev_i32_e32 v67, 31, v66
	v_lshlrev_b64 v[130:131], 12, v[68:69]
	v_lshlrev_b64 v[132:133], 12, v[66:67]
	v_lshl_add_u64 v[130:131], v[98:99], 0, v[130:131]
	v_lshlrev_b64 v[68:69], 11, v[68:69]
	v_lshl_add_u64 v[98:99], v[98:99], 0, v[132:133]
	v_lshlrev_b64 v[66:67], 11, v[66:67]
	s_barrier
; template <int EPI, bool AF32>
; DEV void gemm_tile(const void* Ap, int lda, const u16* Bt, int ldb, int K, int m0, int n0, const Epi& ea, char* smem) {
;     ...
;       u16 gv[4][4][4], cv[4][4][4];
; #pragma unroll
;       for (int m = 0; m < 4; m++)
; #pragma unroll
;         for (int j = 0; j < 4; j++)
; #pragma unroll
;           for (int n = 0; n < 4; n++) {
;             gv[m][j][n] = G[(size_t)(rbase + m * 16 + j) * 2048 + cbase + n * 16];
;             if (EPI == EP_MERGE2) cv[m][j][n] = C[(size_t)(rbase + m * 16 + j) * 1024 + cbase + n * 16];
;           }
	v_lshl_add_u64 v[68:69], v[100:101], 0, v[68:69]
	v_lshl_add_u64 v[66:67], v[100:101], 0, v[66:67]
	global_load_ushort v0, v[102:103], off
	global_load_ushort v100, v[102:103], off offset:32
	global_load_ushort v101, v[102:103], off offset:64
	s_nop 0
	global_load_ushort v102, v[102:103], off offset:96
	s_nop 0
	global_load_ushort v103, v[96:97], off
	global_load_ushort v132, v[96:97], off offset:32
	global_load_ushort v133, v[96:97], off offset:64
	global_load_ushort v134, v[96:97], off offset:96
	global_load_ushort v135, v[104:105], off
	global_load_ushort v136, v[104:105], off offset:32
	global_load_ushort v137, v[104:105], off offset:64
	s_nop 0
	global_load_ushort v104, v[104:105], off offset:96
	s_nop 0
	global_load_ushort v105, v[94:95], off
	global_load_ushort v138, v[94:95], off offset:32
	global_load_ushort v139, v[94:95], off offset:64
	global_load_ushort v140, v[94:95], off offset:96
	global_load_ushort v141, v[106:107], off
	global_load_ushort v142, v[106:107], off offset:32
	global_load_ushort v143, v[106:107], off offset:64
	s_nop 0
	global_load_ushort v106, v[106:107], off offset:96
	s_nop 0
	global_load_ushort v107, v[92:93], off
	global_load_ushort v144, v[92:93], off offset:32
	global_load_ushort v145, v[92:93], off offset:64
	global_load_ushort v146, v[92:93], off offset:96
	global_load_ushort v147, v[108:109], off
	global_load_ushort v148, v[108:109], off offset:32
	global_load_ushort v149, v[108:109], off offset:64
	s_nop 0
	global_load_ushort v108, v[108:109], off offset:96
	s_nop 0
	global_load_ushort v109, v[90:91], off
	global_load_ushort v150, v[90:91], off offset:32
	global_load_ushort v151, v[90:91], off offset:64
	global_load_ushort v152, v[90:91], off offset:96
	global_load_ushort v153, v[110:111], off
	global_load_ushort v161, v[110:111], off offset:32
	global_load_ushort v162, v[110:111], off offset:64
	s_nop 0
	global_load_ushort v110, v[110:111], off offset:96
	s_nop 0
	global_load_ushort v111, v[88:89], off
	global_load_ushort v163, v[88:89], off offset:32
	global_load_ushort v164, v[88:89], off offset:64
	global_load_ushort v165, v[88:89], off offset:96
	global_load_ushort v166, v[112:113], off
	global_load_ushort v167, v[112:113], off offset:32
	global_load_ushort v168, v[112:113], off offset:64
	s_nop 0
	global_load_ushort v112, v[112:113], off offset:96
	s_nop 0
	global_load_ushort v113, v[86:87], off
	global_load_ushort v169, v[86:87], off offset:32
	global_load_ushort v170, v[86:87], off offset:64
	global_load_ushort v171, v[86:87], off offset:96
	global_load_ushort v172, v[114:115], off
	global_load_ushort v173, v[114:115], off offset:32
	global_load_ushort v174, v[114:115], off offset:64
	s_nop 0
	global_load_ushort v114, v[114:115], off offset:96
	s_nop 0
	global_load_ushort v115, v[84:85], off
	global_load_ushort v175, v[84:85], off offset:32
	global_load_ushort v176, v[84:85], off offset:64
	global_load_ushort v177, v[84:85], off offset:96
	global_load_ushort v178, v[116:117], off
	global_load_ushort v179, v[116:117], off offset:32
	global_load_ushort v180, v[116:117], off offset:64
	s_nop 0
	global_load_ushort v116, v[116:117], off offset:96
	s_nop 0
	global_load_ushort v117, v[82:83], off
	global_load_ushort v181, v[82:83], off offset:32
	global_load_ushort v182, v[82:83], off offset:64
	global_load_ushort v183, v[82:83], off offset:96
	global_load_ushort v184, v[118:119], off
	global_load_ushort v185, v[118:119], off offset:32
	global_load_ushort v186, v[118:119], off offset:64
	s_nop 0
	global_load_ushort v118, v[118:119], off offset:96
	s_nop 0
	global_load_ushort v119, v[80:81], off
	global_load_ushort v187, v[80:81], off offset:32
	global_load_ushort v188, v[80:81], off offset:64
	global_load_ushort v189, v[80:81], off offset:96
	global_load_ushort v190, v[120:121], off
	global_load_ushort v191, v[120:121], off offset:32
	global_load_ushort v192, v[120:121], off offset:64
	s_nop 0
	global_load_ushort v120, v[120:121], off offset:96
	s_nop 0
	global_load_ushort v121, v[78:79], off
	global_load_ushort v193, v[78:79], off offset:32
	global_load_ushort v194, v[78:79], off offset:64
	global_load_ushort v195, v[78:79], off offset:96
	global_load_ushort v196, v[122:123], off
	global_load_ushort v197, v[122:123], off offset:32
	global_load_ushort v221, v[122:123], off offset:64
	s_nop 0
	global_load_ushort v122, v[122:123], off offset:96
	s_nop 0
	global_load_ushort v123, v[76:77], off
	global_load_ushort v222, v[76:77], off offset:32
	global_load_ushort v223, v[76:77], off offset:64
	global_load_ushort v224, v[76:77], off offset:96
	global_load_ushort v225, v[124:125], off
	global_load_ushort v226, v[124:125], off offset:32
	global_load_ushort v227, v[124:125], off offset:64
	s_nop 0
	global_load_ushort v124, v[124:125], off offset:96
	s_nop 0
	global_load_ushort v125, v[74:75], off
	global_load_ushort v228, v[74:75], off offset:32
	global_load_ushort v229, v[74:75], off offset:64
	global_load_ushort v230, v[74:75], off offset:96
	global_load_ushort v231, v[126:127], off
	global_load_ushort v232, v[126:127], off offset:32
	global_load_ushort v233, v[126:127], off offset:64
	s_nop 0
	global_load_ushort v126, v[126:127], off offset:96
	s_nop 0
	global_load_ushort v127, v[72:73], off
	global_load_ushort v234, v[72:73], off offset:32
	global_load_ushort v235, v[72:73], off offset:64
	global_load_ushort v236, v[72:73], off offset:96
	global_load_ushort v237, v[128:129], off
	global_load_ushort v238, v[128:129], off offset:32
	global_load_ushort v239, v[128:129], off offset:64
	s_nop 0
	global_load_ushort v128, v[128:129], off offset:96
	s_nop 0
	global_load_ushort v129, v[70:71], off
	global_load_ushort v240, v[70:71], off offset:32
	global_load_ushort v241, v[70:71], off offset:64
	global_load_ushort v242, v[70:71], off offset:96
	global_load_ushort v243, v[130:131], off
	global_load_ushort v244, v[130:131], off offset:32
	global_load_ushort v245, v[130:131], off offset:64
	s_nop 0
	global_load_ushort v130, v[130:131], off offset:96
	s_nop 0
	global_load_ushort v131, v[68:69], off
	global_load_ushort v246, v[68:69], off offset:32
	global_load_ushort v247, v[68:69], off offset:64
	global_load_ushort v248, v[68:69], off offset:96
	global_load_ushort v249, v[98:99], off
	global_load_ushort v250, v[98:99], off offset:32
	global_load_ushort v251, v[98:99], off offset:64
	s_nop 0
	global_load_ushort v98, v[98:99], off offset:96
	s_nop 0
	global_load_ushort v99, v[66:67], off
	global_load_ushort v252, v[66:67], off offset:32
	global_load_ushort v253, v[66:67], off offset:64
	global_load_ushort v201, v[66:67], off offset:96
	s_waitcnt vmcnt(62)
; DEV float bf2f(u16 h) { return __uint_as_float(((unsigned)h) << 16); }
; template <int EPI, bool AF32>
; DEV void gemm_tile(const void* Ap, int lda, const u16* Bt, int ldb, int K, int m0, int n0, const Epi& ea, char* smem) {
;     ...
; #pragma unroll
;       for (int m = 0; m < 4; m++)
; #pragma unroll
;         for (int j = 0; j < 4; j++)
; #pragma unroll
;           for (int n = 0; n < 4; n++) {
;             float v = bf2f(gv[m][j][n]) * acc[m][n][j];
;             if (EPI == EP_MERGE2) v += bf2f(cv[m][j][n]);
;             C[(size_t)(rbase + m * 16 + j) * 1024 + cbase + n * 16] = f2bf(v);
;           }
	v_lshlrev_b32_e32 v0, 16, v0
	v_lshlrev_b32_e32 v103, 16, v103
	v_fmac_f32_e32 v103, v62, v0
	v_cvt_pk_bf16_f32 v0, v103, s0
	global_store_short v[96:97], v0, off
	v_lshlrev_b32_e32 v0, 16, v100
	v_lshlrev_b32_e32 v62, 16, v132
	v_fmac_f32_e32 v62, v58, v0
	v_cvt_pk_bf16_f32 v0, v62, s0
	global_store_short v[96:97], v0, off offset:32
	v_lshlrev_b32_e32 v0, 16, v101
	v_lshlrev_b32_e32 v58, 16, v133
	v_fmac_f32_e32 v58, v54, v0
	v_cvt_pk_bf16_f32 v0, v58, s0
	global_store_short v[96:97], v0, off offset:64
	v_lshlrev_b32_e32 v0, 16, v102
	v_lshlrev_b32_e32 v54, 16, v134
	v_fmac_f32_e32 v54, v50, v0
	v_cvt_pk_bf16_f32 v0, v54, s0
	global_store_short v[96:97], v0, off offset:96
	v_lshlrev_b32_e32 v0, 16, v135
	v_lshlrev_b32_e32 v50, 16, v105
	v_fmac_f32_e32 v50, v63, v0
	v_cvt_pk_bf16_f32 v0, v50, s0
	global_store_short v[94:95], v0, off
	v_lshlrev_b32_e32 v0, 16, v136
	v_lshlrev_b32_e32 v50, 16, v138
	v_fmac_f32_e32 v50, v59, v0
	v_cvt_pk_bf16_f32 v0, v50, s0
	global_store_short v[94:95], v0, off offset:32
	v_lshlrev_b32_e32 v0, 16, v137
	v_lshlrev_b32_e32 v50, 16, v139
	v_fmac_f32_e32 v50, v55, v0
	v_cvt_pk_bf16_f32 v0, v50, s0
	global_store_short v[94:95], v0, off offset:64
	v_lshlrev_b32_e32 v0, 16, v104
	v_lshlrev_b32_e32 v50, 16, v140
	v_fmac_f32_e32 v50, v51, v0
	v_cvt_pk_bf16_f32 v0, v50, s0
	global_store_short v[94:95], v0, off offset:96
	v_lshlrev_b32_e32 v0, 16, v141
	v_lshlrev_b32_e32 v50, 16, v107
	v_fmac_f32_e32 v50, v64, v0
	v_cvt_pk_bf16_f32 v0, v50, s0
	global_store_short v[92:93], v0, off
	v_lshlrev_b32_e32 v0, 16, v142
	v_lshlrev_b32_e32 v50, 16, v144
	v_fmac_f32_e32 v50, v60, v0
	v_cvt_pk_bf16_f32 v0, v50, s0
	global_store_short v[92:93], v0, off offset:32
	v_lshlrev_b32_e32 v0, 16, v143
	v_lshlrev_b32_e32 v50, 16, v145
	v_fmac_f32_e32 v50, v56, v0
	v_cvt_pk_bf16_f32 v0, v50, s0
	global_store_short v[92:93], v0, off offset:64
	v_lshlrev_b32_e32 v0, 16, v106
	v_lshlrev_b32_e32 v50, 16, v146
	v_fmac_f32_e32 v50, v52, v0
	v_cvt_pk_bf16_f32 v0, v50, s0
	global_store_short v[92:93], v0, off offset:96
	v_lshlrev_b32_e32 v0, 16, v147
	v_lshlrev_b32_e32 v50, 16, v109
	v_fmac_f32_e32 v50, v65, v0
	v_cvt_pk_bf16_f32 v0, v50, s0
	global_store_short v[90:91], v0, off
	v_lshlrev_b32_e32 v0, 16, v148
	v_lshlrev_b32_e32 v50, 16, v150
	v_fmac_f32_e32 v50, v61, v0
	v_cvt_pk_bf16_f32 v0, v50, s0
	global_store_short v[90:91], v0, off offset:32
	v_lshlrev_b32_e32 v0, 16, v149
	v_lshlrev_b32_e32 v50, 16, v151
	v_fmac_f32_e32 v50, v57, v0
	v_cvt_pk_bf16_f32 v0, v50, s0
	global_store_short v[90:91], v0, off offset:64
	v_lshlrev_b32_e32 v0, 16, v108
	v_lshlrev_b32_e32 v50, 16, v152
	v_fmac_f32_e32 v50, v53, v0
	v_cvt_pk_bf16_f32 v0, v50, s0
	global_store_short v[90:91], v0, off offset:96
	v_lshlrev_b32_e32 v0, 16, v153
	v_lshlrev_b32_e32 v50, 16, v111
	v_fmac_f32_e32 v50, v46, v0
	v_cvt_pk_bf16_f32 v0, v50, s0
	global_store_short v[88:89], v0, off
	v_lshlrev_b32_e32 v0, 16, v161
	v_lshlrev_b32_e32 v46, 16, v163
	v_fmac_f32_e32 v46, v42, v0
	v_cvt_pk_bf16_f32 v0, v46, s0
	global_store_short v[88:89], v0, off offset:32
	v_lshlrev_b32_e32 v0, 16, v162
	v_lshlrev_b32_e32 v42, 16, v164
	v_fmac_f32_e32 v42, v38, v0
	v_cvt_pk_bf16_f32 v0, v42, s0
	global_store_short v[88:89], v0, off offset:64
	v_lshlrev_b32_e32 v0, 16, v110
	v_lshlrev_b32_e32 v38, 16, v165
	v_fmac_f32_e32 v38, v34, v0
	v_cvt_pk_bf16_f32 v0, v38, s0
	global_store_short v[88:89], v0, off offset:96
	v_lshlrev_b32_e32 v0, 16, v166
	v_lshlrev_b32_e32 v34, 16, v113
	v_fmac_f32_e32 v34, v47, v0
	v_cvt_pk_bf16_f32 v0, v34, s0
	global_store_short v[86:87], v0, off
	v_lshlrev_b32_e32 v0, 16, v167
	v_lshlrev_b32_e32 v34, 16, v169
	v_fmac_f32_e32 v34, v43, v0
	v_cvt_pk_bf16_f32 v0, v34, s0
	global_store_short v[86:87], v0, off offset:32
	v_lshlrev_b32_e32 v0, 16, v168
	v_lshlrev_b32_e32 v34, 16, v170
	v_fmac_f32_e32 v34, v39, v0
	v_cvt_pk_bf16_f32 v0, v34, s0
	global_store_short v[86:87], v0, off offset:64
	v_lshlrev_b32_e32 v0, 16, v112
	v_lshlrev_b32_e32 v34, 16, v171
	v_fmac_f32_e32 v34, v35, v0
	v_cvt_pk_bf16_f32 v0, v34, s0
	global_store_short v[86:87], v0, off offset:96
	v_lshlrev_b32_e32 v0, 16, v172
	v_lshlrev_b32_e32 v34, 16, v115
	v_fmac_f32_e32 v34, v48, v0
	v_cvt_pk_bf16_f32 v0, v34, s0
	global_store_short v[84:85], v0, off
	v_lshlrev_b32_e32 v0, 16, v173
	v_lshlrev_b32_e32 v34, 16, v175
	v_fmac_f32_e32 v34, v44, v0
	v_cvt_pk_bf16_f32 v0, v34, s0
	global_store_short v[84:85], v0, off offset:32
	v_lshlrev_b32_e32 v0, 16, v174
	v_lshlrev_b32_e32 v34, 16, v176
	v_fmac_f32_e32 v34, v40, v0
	v_cvt_pk_bf16_f32 v0, v34, s0
	global_store_short v[84:85], v0, off offset:64
	v_lshlrev_b32_e32 v0, 16, v114
	v_lshlrev_b32_e32 v34, 16, v177
	v_fmac_f32_e32 v34, v36, v0
	v_cvt_pk_bf16_f32 v0, v34, s0
	global_store_short v[84:85], v0, off offset:96
	v_lshlrev_b32_e32 v0, 16, v178
	v_lshlrev_b32_e32 v34, 16, v117
	v_fmac_f32_e32 v34, v49, v0
	v_cvt_pk_bf16_f32 v0, v34, s0
	global_store_short v[82:83], v0, off
	v_lshlrev_b32_e32 v0, 16, v179
	v_lshlrev_b32_e32 v34, 16, v181
	v_fmac_f32_e32 v34, v45, v0
	v_cvt_pk_bf16_f32 v0, v34, s0
	global_store_short v[82:83], v0, off offset:32
	v_lshlrev_b32_e32 v0, 16, v180
	v_lshlrev_b32_e32 v34, 16, v182
	v_fmac_f32_e32 v34, v41, v0
	v_cvt_pk_bf16_f32 v0, v34, s0
	global_store_short v[82:83], v0, off offset:64
	v_lshlrev_b32_e32 v0, 16, v116
	v_lshlrev_b32_e32 v34, 16, v183
	v_fmac_f32_e32 v34, v37, v0
	v_cvt_pk_bf16_f32 v0, v34, s0
	global_store_short v[82:83], v0, off offset:96
	v_lshlrev_b32_e32 v0, 16, v184
	s_waitcnt vmcnt(62)
; DEV int bidx() { int b = __builtin_amdgcn_readfirstlane(blockIdx.x); asm volatile("" : "+s"(b)); return b; }
; DEV int gdim() { int g = __builtin_amdgcn_readfirstlane(gridDim.x); asm volatile("" : "+s"(g)); return g; }
; DEV float bf2f(u16 h) { return __uint_as_float(((unsigned)h) << 16); }
; template <int EPI, bool AF32>
; DEV void gemm_tile(const void* Ap, int lda, const u16* Bt, int ldb, int K, int m0, int n0, const Epi& ea, char* smem) {
;     ...
; #pragma unroll
;       for (int m = 0; m < 4; m++)
; #pragma unroll
;         for (int j = 0; j < 4; j++)
; #pragma unroll
;           for (int n = 0; n < 4; n++) {
;             float v = bf2f(gv[m][j][n]) * acc[m][n][j];
;             if (EPI == EP_MERGE2) v += bf2f(cv[m][j][n]);
;             C[(size_t)(rbase + m * 16 + j) * 1024 + cbase + n * 16] = f2bf(v);
;           }
; template <int EPI, bool AF32>
; DEV void gemm_phase(const void* A, int lda, const u16* Bt, int ldb, int M, int N, int K, const Epi& ea, char* smem) {
;     ...
;   for (int tile = bidx(); tile < ntm * ntn; tile += gdim()) {
;     int m, n;
;     tile_mn(tile, ntm, ntn, m, n);
;     gemm_tile<EPI, AF32>(A, lda, Bt, ldb, K, m << 7, n << 7, ea, smem);
;   }
	v_lshlrev_b32_e32 v34, 16, v119
	v_fmac_f32_e32 v34, v30, v0
	v_cvt_pk_bf16_f32 v0, v34, s0
	global_store_short v[80:81], v0, off
	v_lshlrev_b32_e32 v0, 16, v185
	v_lshlrev_b32_e32 v30, 16, v187
	v_fmac_f32_e32 v30, v26, v0
	v_cvt_pk_bf16_f32 v0, v30, s0
	global_store_short v[80:81], v0, off offset:32
	v_lshlrev_b32_e32 v0, 16, v186
	v_lshlrev_b32_e32 v26, 16, v188
	v_fmac_f32_e32 v26, v22, v0
	v_cvt_pk_bf16_f32 v0, v26, s0
	global_store_short v[80:81], v0, off offset:64
	v_lshlrev_b32_e32 v0, 16, v118
	v_lshlrev_b32_e32 v22, 16, v189
	v_fmac_f32_e32 v22, v18, v0
	v_cvt_pk_bf16_f32 v0, v22, s0
	global_store_short v[80:81], v0, off offset:96
	v_lshlrev_b32_e32 v0, 16, v190
	v_lshlrev_b32_e32 v18, 16, v121
	v_fmac_f32_e32 v18, v31, v0
	v_cvt_pk_bf16_f32 v0, v18, s0
	global_store_short v[78:79], v0, off
	v_lshlrev_b32_e32 v0, 16, v191
	v_lshlrev_b32_e32 v18, 16, v193
	v_fmac_f32_e32 v18, v27, v0
	v_cvt_pk_bf16_f32 v0, v18, s0
	global_store_short v[78:79], v0, off offset:32
	v_lshlrev_b32_e32 v0, 16, v192
	v_lshlrev_b32_e32 v18, 16, v194
	v_fmac_f32_e32 v18, v23, v0
	v_cvt_pk_bf16_f32 v0, v18, s0
	global_store_short v[78:79], v0, off offset:64
	v_lshlrev_b32_e32 v0, 16, v120
	v_lshlrev_b32_e32 v18, 16, v195
	v_fmac_f32_e32 v18, v19, v0
	v_cvt_pk_bf16_f32 v0, v18, s0
	global_store_short v[78:79], v0, off offset:96
	v_lshlrev_b32_e32 v0, 16, v196
	v_lshlrev_b32_e32 v18, 16, v123
	v_fmac_f32_e32 v18, v32, v0
	v_cvt_pk_bf16_f32 v0, v18, s0
	global_store_short v[76:77], v0, off
	v_lshlrev_b32_e32 v0, 16, v197
	v_lshlrev_b32_e32 v18, 16, v222
	v_fmac_f32_e32 v18, v28, v0
	v_cvt_pk_bf16_f32 v0, v18, s0
	global_store_short v[76:77], v0, off offset:32
	v_lshlrev_b32_e32 v0, 16, v221
	v_lshlrev_b32_e32 v18, 16, v223
	v_fmac_f32_e32 v18, v24, v0
	v_cvt_pk_bf16_f32 v0, v18, s0
	global_store_short v[76:77], v0, off offset:64
	v_lshlrev_b32_e32 v0, 16, v122
	v_lshlrev_b32_e32 v18, 16, v224
	v_fmac_f32_e32 v18, v20, v0
	v_cvt_pk_bf16_f32 v0, v18, s0
	global_store_short v[76:77], v0, off offset:96
	v_lshlrev_b32_e32 v0, 16, v225
	v_lshlrev_b32_e32 v18, 16, v125
	v_fmac_f32_e32 v18, v33, v0
	v_cvt_pk_bf16_f32 v0, v18, s0
	global_store_short v[74:75], v0, off
	v_lshlrev_b32_e32 v0, 16, v226
	v_lshlrev_b32_e32 v18, 16, v228
	v_fmac_f32_e32 v18, v29, v0
	v_cvt_pk_bf16_f32 v0, v18, s0
	global_store_short v[74:75], v0, off offset:32
	v_lshlrev_b32_e32 v0, 16, v227
	v_lshlrev_b32_e32 v18, 16, v229
	v_fmac_f32_e32 v18, v25, v0
	v_cvt_pk_bf16_f32 v0, v18, s0
	global_store_short v[74:75], v0, off offset:64
	v_lshlrev_b32_e32 v0, 16, v124
	v_lshlrev_b32_e32 v18, 16, v230
	v_fmac_f32_e32 v18, v21, v0
	v_cvt_pk_bf16_f32 v0, v18, s0
	global_store_short v[74:75], v0, off offset:96
	v_lshlrev_b32_e32 v0, 16, v231
	s_waitcnt vmcnt(62)
	v_lshlrev_b32_e32 v18, 16, v127
	v_fmac_f32_e32 v18, v14, v0
	v_cvt_pk_bf16_f32 v0, v18, s0
	global_store_short v[72:73], v0, off
	v_lshlrev_b32_e32 v0, 16, v232
	v_lshlrev_b32_e32 v14, 16, v234
	v_fmac_f32_e32 v14, v10, v0
	v_cvt_pk_bf16_f32 v0, v14, s0
	global_store_short v[72:73], v0, off offset:32
	v_lshlrev_b32_e32 v0, 16, v233
	v_lshlrev_b32_e32 v10, 16, v235
	v_fmac_f32_e32 v10, v6, v0
	v_cvt_pk_bf16_f32 v0, v10, s0
	global_store_short v[72:73], v0, off offset:64
	v_lshlrev_b32_e32 v0, 16, v126
	v_lshlrev_b32_e32 v6, 16, v236
	v_fmac_f32_e32 v6, v2, v0
	v_cvt_pk_bf16_f32 v0, v6, s0
	global_store_short v[72:73], v0, off offset:96
	v_lshlrev_b32_e32 v0, 16, v237
	v_lshlrev_b32_e32 v2, 16, v129
	v_fmac_f32_e32 v2, v15, v0
	v_cvt_pk_bf16_f32 v0, v2, s0
	global_store_short v[70:71], v0, off
	v_lshlrev_b32_e32 v0, 16, v238
	v_lshlrev_b32_e32 v2, 16, v240
	v_fmac_f32_e32 v2, v11, v0
	v_cvt_pk_bf16_f32 v0, v2, s0
	global_store_short v[70:71], v0, off offset:32
	v_lshlrev_b32_e32 v0, 16, v239
	v_lshlrev_b32_e32 v2, 16, v241
	v_fmac_f32_e32 v2, v7, v0
	v_cvt_pk_bf16_f32 v0, v2, s0
	global_store_short v[70:71], v0, off offset:64
	v_lshlrev_b32_e32 v0, 16, v128
	v_lshlrev_b32_e32 v2, 16, v242
	v_fmac_f32_e32 v2, v3, v0
	v_cvt_pk_bf16_f32 v0, v2, s0
	global_store_short v[70:71], v0, off offset:96
	v_lshlrev_b32_e32 v0, 16, v243
	s_waitcnt vmcnt(62)
	v_lshlrev_b32_e32 v2, 16, v131
	v_fmac_f32_e32 v2, v16, v0
	v_cvt_pk_bf16_f32 v0, v2, s0
	global_store_short v[68:69], v0, off
	v_lshlrev_b32_e32 v0, 16, v244
	v_lshlrev_b32_e32 v2, 16, v246
	v_fmac_f32_e32 v2, v12, v0
	v_cvt_pk_bf16_f32 v0, v2, s0
	global_store_short v[68:69], v0, off offset:32
	v_lshlrev_b32_e32 v0, 16, v245
	v_lshlrev_b32_e32 v2, 16, v247
	v_fmac_f32_e32 v2, v8, v0
	v_cvt_pk_bf16_f32 v0, v2, s0
	global_store_short v[68:69], v0, off offset:64
	v_lshlrev_b32_e32 v0, 16, v130
	v_lshlrev_b32_e32 v2, 16, v248
	v_fmac_f32_e32 v2, v4, v0
	v_cvt_pk_bf16_f32 v0, v2, s0
	global_store_short v[68:69], v0, off offset:96
	v_lshlrev_b32_e32 v0, 16, v249
	s_waitcnt vmcnt(62)
	v_lshlrev_b32_e32 v2, 16, v99
	v_fmac_f32_e32 v2, v17, v0
	v_cvt_pk_bf16_f32 v0, v2, s0
	global_store_short v[66:67], v0, off
	v_lshlrev_b32_e32 v0, 16, v250
	v_lshlrev_b32_e32 v2, 16, v252
	v_fmac_f32_e32 v2, v13, v0
	v_cvt_pk_bf16_f32 v0, v2, s0
	global_store_short v[66:67], v0, off offset:32
	v_lshlrev_b32_e32 v0, 16, v251
	s_waitcnt vmcnt(62)
	v_lshlrev_b32_e32 v2, 16, v253
	v_fmac_f32_e32 v2, v9, v0
	v_cvt_pk_bf16_f32 v0, v2, s0
	global_store_short v[66:67], v0, off offset:64
	v_lshlrev_b32_e32 v0, 16, v98
	v_lshlrev_b32_e32 v2, 16, v201
	v_fmac_f32_e32 v2, v5, v0
	v_cvt_pk_bf16_f32 v0, v2, s0
	v_readfirstlane_b32 s0, v198
	global_store_short v[66:67], v0, off offset:96
	s_add_i32 s14, s0, s14
	s_cmpk_lt_i32 s14, 0x820
	s_cbranch_scc1 .LBB0_1309
	v_mov_b32_e32 v201, 0x2723000

; DEV int tidx() { int t = threadIdx.x; asm volatile("" : "+v"(t)); return t; }
; template <int EPI, bool AF32>
; DEV void gemm_tile(const void* Ap, int lda, const u16* Bt, int ldb, int K, int m0, int n0, const Epi& ea, char* smem) {
;   u16* sA = (u16*)smem;
;   u16* sB = sA + 2 * 128 * 72;
;   const int tid = tidx(), lane = tid & 63, wv = tid >> 6;
;   const int wr = wv >> 1, wc = wv & 1, fr = lane & 15, fq = lane >> 4;
;   f32x4 acc[4][4];
; #pragma unroll
;   for (int m = 0; m < 4; m++)
; #pragma unroll
;     for (int n = 0; n < 4; n++) acc[m][n] = (f32x4){0.f, 0.f, 0.f, 0.f};
;   u32x4 ra[4], rb[4];
;   f32x4 rfa[8];
;   const int nk = K >> 6;
;   auto gload = [&](int kt) {
;     const int k0 = kt << 6;
; #pragma unroll
;     for (int i = 0; i < 4; i++) {
;       const int c = tid + i * 256, row = c >> 3, kc = c & 7;
;       if (AF32) {
;         const float* pa = (const float*)Ap + (size_t)(m0 + row) * lda + k0 + kc * 8;
;         rfa[2 * i] = *(const f32x4*)pa;
;         rfa[2 * i + 1] = *(const f32x4*)(pa + 4);
;       } else {
;         ra[i] = *(const u32x4*)((const u16*)Ap + (size_t)(m0 + row) * lda + k0 + kc * 8);
;       }
;       rb[i] = *(const u32x4*)(Bt + (size_t)(n0 + row) * ldb + k0 + kc * 8);
;     }
;   };
;   auto swrite = [&](int buf) {
; #pragma unroll
;     for (int i = 0; i < 4; i++) {
;       const int c = tid + i * 256, row = c >> 3, kc = c & 7;
;       u32x4 va;
;       if (AF32) {
;         va = (u32x4){pack2(rfa[2 * i][0], rfa[2 * i][1]), pack2(rfa[2 * i][2], rfa[2 * i][3]),
;                      pack2(rfa[2 * i + 1][0], rfa[2 * i + 1][1]), pack2(rfa[2 * i + 1][2], rfa[2 * i + 1][3])};
;       } else {
;         va = ra[i];
;       }
;       *(u32x4*)(sA + buf * 9216 + row * 72 + kc * 8) = va;
;       *(u32x4*)(sB + buf * 9216 + row * 72 + kc * 8) = rb[i];
;     }
;   };
;   gload(0);
;   swrite(0);
;   if (nk > 1) gload(1);
;   __syncthreads();
.LBB0_1352:
	s_ashr_i32 s10, s12, 31
	s_lshr_b32 s10, s10, 24
	s_add_i32 s10, s12, s10
	s_ashr_i32 s11, s10, 8
	s_and_b32 s10, s10, 0xffffff00
	s_lshl_b32 s14, s11, 5
	s_sub_i32 s13, s12, s10
	s_sub_i32 s10, 0x104, s14
	s_min_u32 s15, s10, 32
	v_cvt_f32_ubyte0_e32 v2, s15
	v_cvt_f32_i32_e32 v0, s13
	v_rcp_iflag_f32_e32 v3, v2
	s_ashr_i32 s10, s13, 30
	s_or_b32 s16, s10, 1
	s_waitcnt vmcnt(12)
	v_mov_b32_e32 v114, v157
	v_mul_f32_e32 v3, v0, v3
	v_trunc_f32_e32 v3, v3
	v_fma_f32 v0, -v3, v2, v0
	v_cvt_i32_f32_e32 v3, v3
	v_cmp_ge_f32_e64 s[10:11], |v0|, v2
	s_and_b64 s[10:11], s[10:11], exec
	s_cselect_b32 s10, s16, 0
	v_readfirstlane_b32 s11, v3
	s_add_i32 s10, s11, s10
	s_sext_i32_i16 s11, s10
	s_mul_i32 s10, s10, s15
	s_sub_i32 s10, s13, s10
	s_sext_i32_i16 s10, s10
	s_add_i32 s14, s14, s10
	s_lshl_b32 s14, s14, 7
	s_lshl_b32 s13, s11, 7
	v_ashrrev_i32_e32 v8, 3, v114
	v_add_u32_e32 v2, s14, v8
	v_ashrrev_i32_e32 v3, 31, v2
	v_lshlrev_b32_e32 v0, 3, v114
	v_add_u32_e32 v4, 0x100, v114
	v_lshlrev_b64 v[58:59], 11, v[2:3]
	v_and_b32_e32 v0, 56, v0
	v_ashrrev_i32_e32 v9, 3, v4
	v_lshl_add_u64 v[2:3], s[0:1], 0, v[58:59]
	v_lshlrev_b32_e32 v0, 1, v0
	v_add_u32_e32 v4, s14, v9
	v_add_u32_e32 v6, 0x200, v114
	v_lshl_add_u64 v[14:15], v[2:3], 0, v[0:1]
	v_add_u32_e32 v2, s13, v8
	v_ashrrev_i32_e32 v5, 31, v4
	v_ashrrev_i32_e32 v10, 3, v6
	v_ashrrev_i32_e32 v3, 31, v2
	v_lshlrev_b64 v[62:63], 11, v[4:5]
	v_add_u32_e32 v6, s14, v10
	v_lshlrev_b64 v[60:61], 11, v[2:3]
	v_lshl_add_u64 v[4:5], s[0:1], 0, v[62:63]
	v_ashrrev_i32_e32 v7, 31, v6
	v_lshl_add_u64 v[2:3], s[4:5], 0, v[60:61]
	v_lshl_add_u64 v[16:17], v[4:5], 0, v[0:1]
	v_add_u32_e32 v4, s13, v9
	v_lshlrev_b64 v[66:67], 11, v[6:7]
	v_lshl_add_u64 v[2:3], v[2:3], 0, v[0:1]
	v_ashrrev_i32_e32 v5, 31, v4
	v_lshl_add_u64 v[6:7], s[0:1], 0, v[66:67]
	global_load_dwordx4 v[30:33], v[2:3], off
	v_lshlrev_b64 v[64:65], 11, v[4:5]
	v_lshl_add_u64 v[68:69], v[6:7], 0, v[0:1]
	v_add_u32_e32 v6, s13, v10
	global_load_dwordx4 v[26:29], v[14:15], off
	global_load_dwordx4 v[34:37], v[16:17], off
	v_lshl_add_u64 v[4:5], s[4:5], 0, v[64:65]
	v_ashrrev_i32_e32 v7, 31, v6
	v_lshl_add_u64 v[4:5], v[4:5], 0, v[0:1]
	v_lshlrev_b64 v[70:71], 11, v[6:7]
	global_load_dwordx4 v[38:41], v[4:5], off
	v_lshl_add_u64 v[6:7], s[4:5], 0, v[70:71]
	global_load_dwordx4 v[42:45], v[68:69], off
	v_lshl_add_u64 v[18:19], v[6:7], 0, v[0:1]
	global_load_dwordx4 v[46:49], v[18:19], off
	v_add_u32_e32 v6, 0x300, v114
	v_ashrrev_i32_e32 v80, 3, v6
	v_add_u32_e32 v6, s14, v80
	v_ashrrev_i32_e32 v7, 31, v6
	v_lshlrev_b64 v[72:73], 11, v[6:7]
	v_lshl_add_u64 v[6:7], s[0:1], 0, v[72:73]
	v_lshl_add_u64 v[74:75], v[6:7], 0, v[0:1]
	v_add_u32_e32 v6, s13, v80
	v_ashrrev_i32_e32 v7, 31, v6
	v_lshlrev_b64 v[76:77], 11, v[6:7]
	v_lshl_add_u64 v[6:7], s[4:5], 0, v[76:77]
	v_lshl_add_u64 v[78:79], v[6:7], 0, v[0:1]
	global_load_dwordx4 v[50:53], v[74:75], off
	global_load_dwordx4 v[54:57], v[78:79], off
	s_waitcnt vmcnt(19)
	v_mul_lo_u32 v118, v8, s71
	v_mul_lo_u32 v119, v9, s71
	s_waitcnt vmcnt(18)
	v_mul_lo_u32 v123, v10, s71
	global_load_dwordx4 v[6:9], v[2:3], off offset:128
	global_load_dwordx4 v[10:13], v[4:5], off offset:128
	s_nop 0
	global_load_dwordx4 v[2:5], v[18:19], off offset:128
	global_load_dwordx4 v[22:25], v[14:15], off offset:128
	s_nop 0
	global_load_dwordx4 v[18:21], v[16:17], off offset:128
	s_nop 0
	global_load_dwordx4 v[14:17], v[68:69], off offset:128
	v_bfe_u32 v161, v157, 3, 4
	v_add_u32_e32 v161, 4, v161
	v_lshlrev_b32_e32 v161, 1, v161
	v_and_b32_e32 v161, 16, v161
	v_xor_b32_e32 v129, v0, v161
	v_lshl_add_u32 v122, v118, 1, v129
	v_lshl_add_u32 v121, v119, 1, v129
	v_lshl_add_u32 v120, v123, 1, v129
	v_and_b32_e32 v115, 15, v114
	s_waitcnt vmcnt(23)
	v_mul_lo_u32 v126, v80, s71
	v_bfe_u32 v116, v114, 4, 2
	v_lshl_add_u32 v124, v126, 1, v129
	s_mov_b32 s15, 0
	v_lshlrev_b32_e32 v125, 4, v116
	v_and_b32_e32 v161, 15, v157
	v_add_u32_e32 v161, 4, v161
	v_lshlrev_b32_e32 v161, 1, v161
	v_and_b32_e32 v161, 16, v161
	v_xor_b32_e32 v125, v125, v161
	s_mov_b64 s[10:11], 0
	s_waitcnt vmcnt(13)
	ds_write_b128 v122, v[30:33] offset:36864
	s_waitcnt vmcnt(12)
	ds_write_b128 v122, v[26:29]
	s_waitcnt vmcnt(11)
	ds_write_b128 v121, v[34:37]
	s_waitcnt vmcnt(10)
	ds_write_b128 v121, v[38:41] offset:36864
	s_waitcnt vmcnt(9)
	ds_write_b128 v120, v[42:45]
	s_waitcnt vmcnt(8)
	ds_write_b128 v120, v[46:49] offset:36864
	global_load_dwordx4 v[26:29], v[74:75], off offset:128
	global_load_dwordx4 v[30:33], v[78:79], off offset:128
	v_ashrrev_i32_e32 v34, 1, v114
	v_and_b32_e32 v117, 0xffffffc0, v34
	v_or_b32_e32 v34, v117, v115
	v_mul_lo_u32 v128, v34, s71
	v_lshlrev_b32_e32 v34, 4, v114
	v_and_b32_e32 v34, 0x70, v34
	v_and_b32_e32 v35, 0x4f, v114
	v_or_b32_e32 v76, v76, v34
	v_or_b32_e32 v72, v72, v34
	v_or_b32_e32 v70, v70, v34
	v_or_b32_e32 v66, v66, v34
	v_or_b32_e32 v64, v64, v34
	v_or_b32_e32 v62, v62, v34
	v_or_b32_e32 v60, v60, v34
	v_or_b32_e32 v58, v58, v34
	v_mov_b32_e32 v34, 0
	s_waitcnt vmcnt(9)
	ds_write_b128 v124, v[50:53]
	s_waitcnt vmcnt(8)
	ds_write_b128 v124, v[54:57] offset:36864
	v_mul_u32_u24_e32 v127, 0x48, v35
	v_mov_b32_e32 v98, v76
	v_mov_b32_e32 v100, v72
	v_mov_b32_e32 v102, v70
	v_mov_b32_e32 v104, v66
	v_mov_b32_e32 v106, v64
	v_mov_b32_e32 v108, v62
	v_mov_b32_e32 v110, v60
	v_mov_b32_e32 v112, v58
	v_mov_b32_e32 v35, v34
	v_mov_b32_e32 v36, v34
	v_mov_b32_e32 v37, v34
	v_mov_b32_e32 v38, v34
	v_mov_b32_e32 v39, v34
	v_mov_b32_e32 v40, v34
	v_mov_b32_e32 v41, v34
	v_mov_b32_e32 v42, v34
	v_mov_b32_e32 v43, v34
	v_mov_b32_e32 v44, v34
	v_mov_b32_e32 v45, v34
	v_mov_b32_e32 v46, v34
	v_mov_b32_e32 v47, v34
	v_mov_b32_e32 v48, v34
	v_mov_b32_e32 v49, v34
	v_mov_b32_e32 v50, v34
	v_mov_b32_e32 v51, v34
	v_mov_b32_e32 v52, v34
	v_mov_b32_e32 v53, v34
	v_mov_b32_e32 v54, v34
	v_mov_b32_e32 v55, v34
	v_mov_b32_e32 v56, v34
	v_mov_b32_e32 v57, v34
	v_mov_b32_e32 v58, v34
	v_mov_b32_e32 v59, v34
	v_mov_b32_e32 v60, v34
	v_mov_b32_e32 v61, v34
	v_mov_b32_e32 v62, v34
	v_mov_b32_e32 v63, v34
	v_mov_b32_e32 v64, v34
	v_mov_b32_e32 v65, v34
	v_mov_b32_e32 v66, v34
	v_mov_b32_e32 v67, v34
	v_mov_b32_e32 v68, v34
	v_mov_b32_e32 v69, v34
	v_mov_b32_e32 v70, v34
	v_mov_b32_e32 v71, v34
	v_mov_b32_e32 v72, v34
	v_mov_b32_e32 v73, v34
	v_mov_b32_e32 v74, v34
	v_mov_b32_e32 v75, v34
	v_mov_b32_e32 v76, v34
	v_mov_b32_e32 v77, v34
	v_mov_b32_e32 v78, v34
	v_mov_b32_e32 v79, v34
	v_mov_b32_e32 v80, v34
	v_mov_b32_e32 v81, v34
	v_mov_b32_e32 v82, v34
	v_mov_b32_e32 v83, v34
	v_mov_b32_e32 v84, v34
	v_mov_b32_e32 v85, v34
	v_mov_b32_e32 v86, v34
	v_mov_b32_e32 v87, v34
	v_mov_b32_e32 v88, v34
	v_mov_b32_e32 v89, v34
	v_mov_b32_e32 v90, v34
	v_mov_b32_e32 v91, v34
	v_mov_b32_e32 v92, v34
	v_mov_b32_e32 v93, v34
	v_mov_b32_e32 v94, v34
	v_mov_b32_e32 v95, v34
	v_mov_b32_e32 v96, v34
	v_mov_b32_e32 v97, v34
	s_waitcnt lgkmcnt(0)
	s_barrier
; DEV f32x4 mfma16(bf16x8 a, bf16x8 b, f32x4 c) { return __builtin_amdgcn_mfma_f32_16x16x32_bf16(a, b, c, 0, 0, 0); }
; template <int EPI, bool AF32>
; DEV void gemm_tile(const void* Ap, int lda, const u16* Bt, int ldb, int K, int m0, int n0, const Epi& ea, char* smem) {
;     ...
;   auto gload = [&](int kt) {
;     const int k0 = kt << 6;
; #pragma unroll
;     for (int i = 0; i < 4; i++) {
;       const int c = tid + i * 256, row = c >> 3, kc = c & 7;
;       if (AF32) {
;         const float* pa = (const float*)Ap + (size_t)(m0 + row) * lda + k0 + kc * 8;
;         rfa[2 * i] = *(const f32x4*)pa;
;         rfa[2 * i + 1] = *(const f32x4*)(pa + 4);
;       } else {
;         ra[i] = *(const u32x4*)((const u16*)Ap + (size_t)(m0 + row) * lda + k0 + kc * 8);
;       }
;       rb[i] = *(const u32x4*)(Bt + (size_t)(n0 + row) * ldb + k0 + kc * 8);
;     }
;   };
;   auto swrite = [&](int buf) {
; #pragma unroll
;     for (int i = 0; i < 4; i++) {
;       const int c = tid + i * 256, row = c >> 3, kc = c & 7;
;       u32x4 va;
;       if (AF32) {
;         va = (u32x4){pack2(rfa[2 * i][0], rfa[2 * i][1]), pack2(rfa[2 * i][2], rfa[2 * i][3]),
;                      pack2(rfa[2 * i + 1][0], rfa[2 * i + 1][1]), pack2(rfa[2 * i + 1][2], rfa[2 * i + 1][3])};
;       } else {
;         va = ra[i];
;       }
;       *(u32x4*)(sA + buf * 9216 + row * 72 + kc * 8) = va;
;       *(u32x4*)(sB + buf * 9216 + row * 72 + kc * 8) = rb[i];
;     }
;   };
;   gload(0);
;   swrite(0);
;   if (nk > 1) gload(1);
;   __syncthreads();
;   for (int kt = 0; kt < nk; kt++) {
;     const int buf = kt & 1;
;     if (kt + 1 < nk) swrite(buf ^ 1);
;     if (kt + 2 < nk) gload(kt + 2);
; #pragma unroll
;     for (int ks = 0; ks < 2; ks++) {
;       bf16x8 a[4], b[4];
; #pragma unroll
;       for (int m = 0; m < 4; m++) a[m] = *(const bf16x8*)(sA + buf * 9216 + (wr * 64 + m * 16 + fr) * 72 + ks * 32 + fq * 8);
; #pragma unroll
;       for (int n = 0; n < 4; n++) b[n] = *(const bf16x8*)(sB + buf * 9216 + (wc * 64 + n * 16 + fr) * 72 + ks * 32 + fq * 8);
;       __builtin_amdgcn_s_setprio(1);
; #pragma unroll
;       for (int m = 0; m < 4; m++)
; #pragma unroll
;         for (int n = 0; n < 4; n++) acc[m][n] = mfma16(a[m], b[n], acc[m][n]);
;       __builtin_amdgcn_s_setprio(0);
;     }
;     __syncthreads();
	v_lshl_add_u32 v161, v128, 1, v125
	v_lshl_add_u32 v129, v127, 1, v125
	s_mov_b32 s15, 0
	s_mov_b64 s[10:11], 0x100
	ds_read_b128 v[130:133], v161
	ds_read_b128 v[134:137], v161 offset:2304
	ds_read_b128 v[138:141], v161 offset:4608
	ds_read_b128 v[142:145], v161 offset:6912
	ds_read_b128 v[146:149], v129 offset:36864
	ds_read_b128 v[150:153], v129 offset:39168
	ds_read_b128 v[162:165], v129 offset:41472
	ds_read_b128 v[166:169], v129 offset:43776
.Lgk5_loop:
	s_waitcnt lgkmcnt(0)
	ds_read_b128 v[222:225], v161 offset:64
	ds_read_b128 v[226:229], v161 offset:2368
	ds_read_b128 v[230:233], v161 offset:4672
	ds_read_b128 v[234:237], v161 offset:6976
	ds_read_b128 v[238:241], v129 offset:36928
	ds_read_b128 v[242:245], v129 offset:39232
	ds_read_b128 v[246:249], v129 offset:41536
	ds_read_b128 v[250:253], v129 offset:43840
	v_mfma_f32_16x16x32_bf16 v[34:37], v[130:133], v[146:149], v[34:37]
	v_mfma_f32_16x16x32_bf16 v[38:41], v[130:133], v[150:153], v[38:41]
	v_mfma_f32_16x16x32_bf16 v[42:45], v[130:133], v[162:165], v[42:45]
	v_mfma_f32_16x16x32_bf16 v[46:49], v[130:133], v[166:169], v[46:49]
	s_waitcnt vmcnt(0)
	ds_write_b128 v122, v[22:25] offset:18432
	ds_write_b128 v122, v[6:9] offset:55296
	v_mfma_f32_16x16x32_bf16 v[50:53], v[134:137], v[146:149], v[50:53]
	ds_write_b128 v121, v[18:21] offset:18432
	ds_write_b128 v121, v[10:13] offset:55296
	v_mfma_f32_16x16x32_bf16 v[54:57], v[134:137], v[150:153], v[54:57]
	ds_write_b128 v120, v[14:17] offset:18432
	ds_write_b128 v120, v[2:5] offset:55296
	v_mfma_f32_16x16x32_bf16 v[58:61], v[134:137], v[162:165], v[58:61]
	ds_write_b128 v124, v[26:29] offset:18432
	ds_write_b128 v124, v[30:33] offset:55296
	v_mfma_f32_16x16x32_bf16 v[62:65], v[134:137], v[166:169], v[62:65]
	global_load_dwordx4 v[22:25], v112, s[8:9]
	v_mfma_f32_16x16x32_bf16 v[66:69], v[138:141], v[146:149], v[66:69]
	global_load_dwordx4 v[6:9], v110, s[6:7]
	v_mfma_f32_16x16x32_bf16 v[70:73], v[138:141], v[150:153], v[70:73]
	global_load_dwordx4 v[18:21], v108, s[8:9]
	v_mfma_f32_16x16x32_bf16 v[74:77], v[138:141], v[162:165], v[74:77]
	global_load_dwordx4 v[10:13], v106, s[6:7]
	v_mfma_f32_16x16x32_bf16 v[78:81], v[138:141], v[166:169], v[78:81]
	global_load_dwordx4 v[14:17], v104, s[8:9]
	v_mfma_f32_16x16x32_bf16 v[82:85], v[142:145], v[146:149], v[82:85]
	global_load_dwordx4 v[2:5], v102, s[6:7]
	v_mfma_f32_16x16x32_bf16 v[86:89], v[142:145], v[150:153], v[86:89]
	global_load_dwordx4 v[26:29], v100, s[8:9]
	v_mfma_f32_16x16x32_bf16 v[90:93], v[142:145], v[162:165], v[90:93]
	global_load_dwordx4 v[30:33], v98, s[6:7]
	v_mfma_f32_16x16x32_bf16 v[94:97], v[142:145], v[166:169], v[94:97]
	s_waitcnt lgkmcnt(0)
	s_barrier
	ds_read_b128 v[130:133], v161 offset:18432
	v_mfma_f32_16x16x32_bf16 v[34:37], v[222:225], v[238:241], v[34:37]
	ds_read_b128 v[134:137], v161 offset:20736
	v_mfma_f32_16x16x32_bf16 v[38:41], v[222:225], v[242:245], v[38:41]
	ds_read_b128 v[138:141], v161 offset:23040
	v_mfma_f32_16x16x32_bf16 v[42:45], v[222:225], v[246:249], v[42:45]
	ds_read_b128 v[142:145], v161 offset:25344
	v_mfma_f32_16x16x32_bf16 v[46:49], v[222:225], v[250:253], v[46:49]
	ds_read_b128 v[146:149], v129 offset:55296
	v_mfma_f32_16x16x32_bf16 v[50:53], v[226:229], v[238:241], v[50:53]
	ds_read_b128 v[150:153], v129 offset:57600
	v_mfma_f32_16x16x32_bf16 v[54:57], v[226:229], v[242:245], v[54:57]
	ds_read_b128 v[162:165], v129 offset:59904
	v_mfma_f32_16x16x32_bf16 v[58:61], v[226:229], v[246:249], v[58:61]
	ds_read_b128 v[166:169], v129 offset:62208
	v_mfma_f32_16x16x32_bf16 v[62:65], v[226:229], v[250:253], v[62:65]
	v_mfma_f32_16x16x32_bf16 v[66:69], v[230:233], v[238:241], v[66:69]
	v_mfma_f32_16x16x32_bf16 v[70:73], v[230:233], v[242:245], v[70:73]
	v_mfma_f32_16x16x32_bf16 v[74:77], v[230:233], v[246:249], v[74:77]
	v_mfma_f32_16x16x32_bf16 v[78:81], v[230:233], v[250:253], v[78:81]
	v_mfma_f32_16x16x32_bf16 v[82:85], v[234:237], v[238:241], v[82:85]
	v_mfma_f32_16x16x32_bf16 v[86:89], v[234:237], v[242:245], v[86:89]
	v_mfma_f32_16x16x32_bf16 v[90:93], v[234:237], v[246:249], v[90:93]
	v_mfma_f32_16x16x32_bf16 v[94:97], v[234:237], v[250:253], v[94:97]
	s_waitcnt lgkmcnt(0)
	ds_read_b128 v[222:225], v161 offset:18496
	ds_read_b128 v[226:229], v161 offset:20800
	ds_read_b128 v[230:233], v161 offset:23104
	ds_read_b128 v[234:237], v161 offset:25408
	ds_read_b128 v[238:241], v129 offset:55360
	ds_read_b128 v[242:245], v129 offset:57664
	ds_read_b128 v[246:249], v129 offset:59968
	ds_read_b128 v[250:253], v129 offset:62272
	v_mfma_f32_16x16x32_bf16 v[34:37], v[130:133], v[146:149], v[34:37]
	v_mfma_f32_16x16x32_bf16 v[38:41], v[130:133], v[150:153], v[38:41]
	v_mfma_f32_16x16x32_bf16 v[42:45], v[130:133], v[162:165], v[42:45]
	v_mfma_f32_16x16x32_bf16 v[46:49], v[130:133], v[166:169], v[46:49]
	s_waitcnt vmcnt(0)
	ds_write_b128 v122, v[22:25]
	ds_write_b128 v122, v[6:9] offset:36864
	v_mfma_f32_16x16x32_bf16 v[50:53], v[134:137], v[146:149], v[50:53]
	ds_write_b128 v121, v[18:21]
	ds_write_b128 v121, v[10:13] offset:36864
	v_mfma_f32_16x16x32_bf16 v[54:57], v[134:137], v[150:153], v[54:57]
	ds_write_b128 v120, v[14:17]
	ds_write_b128 v120, v[2:5] offset:36864
	v_mfma_f32_16x16x32_bf16 v[58:61], v[134:137], v[162:165], v[58:61]
	ds_write_b128 v124, v[26:29]
	ds_write_b128 v124, v[30:33] offset:36864
	v_mfma_f32_16x16x32_bf16 v[62:65], v[134:137], v[166:169], v[62:65]
	global_load_dwordx4 v[22:25], v112, s[8:9] offset:128
	v_mfma_f32_16x16x32_bf16 v[66:69], v[138:141], v[146:149], v[66:69]
	global_load_dwordx4 v[6:9], v110, s[6:7] offset:128
	v_mfma_f32_16x16x32_bf16 v[70:73], v[138:141], v[150:153], v[70:73]
	global_load_dwordx4 v[18:21], v108, s[8:9] offset:128
	v_mfma_f32_16x16x32_bf16 v[74:77], v[138:141], v[162:165], v[74:77]
	global_load_dwordx4 v[10:13], v106, s[6:7] offset:128
	v_mfma_f32_16x16x32_bf16 v[78:81], v[138:141], v[166:169], v[78:81]
	global_load_dwordx4 v[14:17], v104, s[8:9] offset:128
	v_mfma_f32_16x16x32_bf16 v[82:85], v[142:145], v[146:149], v[82:85]
	global_load_dwordx4 v[2:5], v102, s[6:7] offset:128
	v_mfma_f32_16x16x32_bf16 v[86:89], v[142:145], v[150:153], v[86:89]
	global_load_dwordx4 v[26:29], v100, s[8:9] offset:128
	v_mfma_f32_16x16x32_bf16 v[90:93], v[142:145], v[162:165], v[90:93]
	global_load_dwordx4 v[30:33], v98, s[6:7] offset:128
	v_mfma_f32_16x16x32_bf16 v[94:97], v[142:145], v[166:169], v[94:97]
	s_waitcnt lgkmcnt(0)
	s_barrier
; DEV f32x4 mfma16(bf16x8 a, bf16x8 b, f32x4 c) { return __builtin_amdgcn_mfma_f32_16x16x32_bf16(a, b, c, 0, 0, 0); }
; template <int EPI, bool AF32>
; DEV void gemm_tile(const void* Ap, int lda, const u16* Bt, int ldb, int K, int m0, int n0, const Epi& ea, char* smem) {
;     ...
;   auto gload = [&](int kt) {
;     const int k0 = kt << 6;
; #pragma unroll
;     for (int i = 0; i < 4; i++) {
;       const int c = tid + i * 256, row = c >> 3, kc = c & 7;
;       if (AF32) {
;         const float* pa = (const float*)Ap + (size_t)(m0 + row) * lda + k0 + kc * 8;
;         rfa[2 * i] = *(const f32x4*)pa;
;         rfa[2 * i + 1] = *(const f32x4*)(pa + 4);
;       } else {
;         ra[i] = *(const u32x4*)((const u16*)Ap + (size_t)(m0 + row) * lda + k0 + kc * 8);
;       }
;       rb[i] = *(const u32x4*)(Bt + (size_t)(n0 + row) * ldb + k0 + kc * 8);
;     }
;   };
;   auto swrite = [&](int buf) {
; #pragma unroll
;     for (int i = 0; i < 4; i++) {
;       const int c = tid + i * 256, row = c >> 3, kc = c & 7;
;       u32x4 va;
;       if (AF32) {
;         va = (u32x4){pack2(rfa[2 * i][0], rfa[2 * i][1]), pack2(rfa[2 * i][2], rfa[2 * i][3]),
;                      pack2(rfa[2 * i + 1][0], rfa[2 * i + 1][1]), pack2(rfa[2 * i + 1][2], rfa[2 * i + 1][3])};
;       } else {
;         va = ra[i];
;       }
;       *(u32x4*)(sA + buf * 9216 + row * 72 + kc * 8) = va;
;       *(u32x4*)(sB + buf * 9216 + row * 72 + kc * 8) = rb[i];
;     }
;   };
;   gload(0);
;   swrite(0);
;   if (nk > 1) gload(1);
;   __syncthreads();
;   for (int kt = 0; kt < nk; kt++) {
;     const int buf = kt & 1;
;     if (kt + 1 < nk) swrite(buf ^ 1);
;     if (kt + 2 < nk) gload(kt + 2);
; #pragma unroll
;     for (int ks = 0; ks < 2; ks++) {
;       bf16x8 a[4], b[4];
; #pragma unroll
;       for (int m = 0; m < 4; m++) a[m] = *(const bf16x8*)(sA + buf * 9216 + (wr * 64 + m * 16 + fr) * 72 + ks * 32 + fq * 8);
; #pragma unroll
;       for (int n = 0; n < 4; n++) b[n] = *(const bf16x8*)(sB + buf * 9216 + (wc * 64 + n * 16 + fr) * 72 + ks * 32 + fq * 8);
;       __builtin_amdgcn_s_setprio(1);
; #pragma unroll
;       for (int m = 0; m < 4; m++)
; #pragma unroll
;         for (int n = 0; n < 4; n++) acc[m][n] = mfma16(a[m], b[n], acc[m][n]);
;       __builtin_amdgcn_s_setprio(0);
;     }
;     __syncthreads();
	ds_read_b128 v[130:133], v161
	v_mfma_f32_16x16x32_bf16 v[34:37], v[222:225], v[238:241], v[34:37]
	ds_read_b128 v[134:137], v161 offset:2304
	v_mfma_f32_16x16x32_bf16 v[38:41], v[222:225], v[242:245], v[38:41]
	ds_read_b128 v[138:141], v161 offset:4608
	v_mfma_f32_16x16x32_bf16 v[42:45], v[222:225], v[246:249], v[42:45]
	ds_read_b128 v[142:145], v161 offset:6912
	v_mfma_f32_16x16x32_bf16 v[46:49], v[222:225], v[250:253], v[46:49]
	ds_read_b128 v[146:149], v129 offset:36864
	v_mfma_f32_16x16x32_bf16 v[50:53], v[226:229], v[238:241], v[50:53]
	ds_read_b128 v[150:153], v129 offset:39168
	v_mfma_f32_16x16x32_bf16 v[54:57], v[226:229], v[242:245], v[54:57]
	ds_read_b128 v[162:165], v129 offset:41472
	v_mfma_f32_16x16x32_bf16 v[58:61], v[226:229], v[246:249], v[58:61]
	ds_read_b128 v[166:169], v129 offset:43776
	v_mfma_f32_16x16x32_bf16 v[62:65], v[226:229], v[250:253], v[62:65]
	v_mfma_f32_16x16x32_bf16 v[66:69], v[230:233], v[238:241], v[66:69]
	v_add_u32_e32 v112, 0x100, v112
	v_mfma_f32_16x16x32_bf16 v[70:73], v[230:233], v[242:245], v[70:73]
	v_add_u32_e32 v110, 0x100, v110
	v_mfma_f32_16x16x32_bf16 v[74:77], v[230:233], v[246:249], v[74:77]
	v_add_u32_e32 v108, 0x100, v108
	v_mfma_f32_16x16x32_bf16 v[78:81], v[230:233], v[250:253], v[78:81]
	v_add_u32_e32 v106, 0x100, v106
	v_mfma_f32_16x16x32_bf16 v[82:85], v[234:237], v[238:241], v[82:85]
	v_add_u32_e32 v104, 0x100, v104
	v_mfma_f32_16x16x32_bf16 v[86:89], v[234:237], v[242:245], v[86:89]
	v_add_u32_e32 v102, 0x100, v102
	v_mfma_f32_16x16x32_bf16 v[90:93], v[234:237], v[246:249], v[90:93]
	v_add_u32_e32 v100, 0x100, v100
	v_mfma_f32_16x16x32_bf16 v[94:97], v[234:237], v[250:253], v[94:97]
	v_add_u32_e32 v98, 0x100, v98
	s_add_i32 s15, s15, 1
	s_cmp_lg_u32 s15, 7
	s_cbranch_scc1 .Lgk5_loop
	s_waitcnt lgkmcnt(0)
	ds_read_b128 v[222:225], v161 offset:64
	ds_read_b128 v[226:229], v161 offset:2368
	ds_read_b128 v[230:233], v161 offset:4672
	ds_read_b128 v[234:237], v161 offset:6976
	ds_read_b128 v[238:241], v129 offset:36928
	ds_read_b128 v[242:245], v129 offset:39232
	ds_read_b128 v[246:249], v129 offset:41536
	ds_read_b128 v[250:253], v129 offset:43840
	v_mfma_f32_16x16x32_bf16 v[34:37], v[130:133], v[146:149], v[34:37]
	v_mfma_f32_16x16x32_bf16 v[38:41], v[130:133], v[150:153], v[38:41]
	v_mfma_f32_16x16x32_bf16 v[42:45], v[130:133], v[162:165], v[42:45]
	v_mfma_f32_16x16x32_bf16 v[46:49], v[130:133], v[166:169], v[46:49]
	s_waitcnt vmcnt(0)
	ds_write_b128 v122, v[22:25] offset:18432
	ds_write_b128 v122, v[6:9] offset:55296
	v_mfma_f32_16x16x32_bf16 v[50:53], v[134:137], v[146:149], v[50:53]
	ds_write_b128 v121, v[18:21] offset:18432
	ds_write_b128 v121, v[10:13] offset:55296
	v_mfma_f32_16x16x32_bf16 v[54:57], v[134:137], v[150:153], v[54:57]
	ds_write_b128 v120, v[14:17] offset:18432
	ds_write_b128 v120, v[2:5] offset:55296
	v_mfma_f32_16x16x32_bf16 v[58:61], v[134:137], v[162:165], v[58:61]
	ds_write_b128 v124, v[26:29] offset:18432
	ds_write_b128 v124, v[30:33] offset:55296
	v_mfma_f32_16x16x32_bf16 v[62:65], v[134:137], v[166:169], v[62:65]
	v_mfma_f32_16x16x32_bf16 v[66:69], v[138:141], v[146:149], v[66:69]
	v_mfma_f32_16x16x32_bf16 v[70:73], v[138:141], v[150:153], v[70:73]
	v_mfma_f32_16x16x32_bf16 v[74:77], v[138:141], v[162:165], v[74:77]
	v_mfma_f32_16x16x32_bf16 v[78:81], v[138:141], v[166:169], v[78:81]
	v_mfma_f32_16x16x32_bf16 v[82:85], v[142:145], v[146:149], v[82:85]
	v_mfma_f32_16x16x32_bf16 v[86:89], v[142:145], v[150:153], v[86:89]
	v_mfma_f32_16x16x32_bf16 v[90:93], v[142:145], v[162:165], v[90:93]
	v_mfma_f32_16x16x32_bf16 v[94:97], v[142:145], v[166:169], v[94:97]
	s_waitcnt lgkmcnt(0)
	s_barrier
	ds_read_b128 v[130:133], v161 offset:18432
	v_mfma_f32_16x16x32_bf16 v[34:37], v[222:225], v[238:241], v[34:37]
	ds_read_b128 v[134:137], v161 offset:20736
	v_mfma_f32_16x16x32_bf16 v[38:41], v[222:225], v[242:245], v[38:41]
	ds_read_b128 v[138:141], v161 offset:23040
	v_mfma_f32_16x16x32_bf16 v[42:45], v[222:225], v[246:249], v[42:45]
	ds_read_b128 v[142:145], v161 offset:25344
	v_mfma_f32_16x16x32_bf16 v[46:49], v[222:225], v[250:253], v[46:49]
	ds_read_b128 v[146:149], v129 offset:55296
	v_mfma_f32_16x16x32_bf16 v[50:53], v[226:229], v[238:241], v[50:53]
	ds_read_b128 v[150:153], v129 offset:57600
	v_mfma_f32_16x16x32_bf16 v[54:57], v[226:229], v[242:245], v[54:57]
	ds_read_b128 v[162:165], v129 offset:59904
	v_mfma_f32_16x16x32_bf16 v[58:61], v[226:229], v[246:249], v[58:61]
	ds_read_b128 v[166:169], v129 offset:62208
	v_mfma_f32_16x16x32_bf16 v[62:65], v[226:229], v[250:253], v[62:65]
	v_mfma_f32_16x16x32_bf16 v[66:69], v[230:233], v[238:241], v[66:69]
	v_mfma_f32_16x16x32_bf16 v[70:73], v[230:233], v[242:245], v[70:73]
	v_mfma_f32_16x16x32_bf16 v[74:77], v[230:233], v[246:249], v[74:77]
	v_mfma_f32_16x16x32_bf16 v[78:81], v[230:233], v[250:253], v[78:81]
	v_mfma_f32_16x16x32_bf16 v[82:85], v[234:237], v[238:241], v[82:85]
	v_mfma_f32_16x16x32_bf16 v[86:89], v[234:237], v[242:245], v[86:89]
	v_mfma_f32_16x16x32_bf16 v[90:93], v[234:237], v[246:249], v[90:93]
	v_mfma_f32_16x16x32_bf16 v[94:97], v[234:237], v[250:253], v[94:97]
	s_waitcnt lgkmcnt(0)
; DEV f32x4 mfma16(bf16x8 a, bf16x8 b, f32x4 c) { return __builtin_amdgcn_mfma_f32_16x16x32_bf16(a, b, c, 0, 0, 0); }
; template <int EPI, bool AF32>
; DEV void gemm_tile(const void* Ap, int lda, const u16* Bt, int ldb, int K, int m0, int n0, const Epi& ea, char* smem) {
;     ...
;   for (int kt = 0; kt < nk; kt++) {
;     const int buf = kt & 1;
;     if (kt + 1 < nk) swrite(buf ^ 1);
;     if (kt + 2 < nk) gload(kt + 2);
; #pragma unroll
;     for (int ks = 0; ks < 2; ks++) {
;       bf16x8 a[4], b[4];
; #pragma unroll
;       for (int m = 0; m < 4; m++) a[m] = *(const bf16x8*)(sA + buf * 9216 + (wr * 64 + m * 16 + fr) * 72 + ks * 32 + fq * 8);
; #pragma unroll
;       for (int n = 0; n < 4; n++) b[n] = *(const bf16x8*)(sB + buf * 9216 + (wc * 64 + n * 16 + fr) * 72 + ks * 32 + fq * 8);
;       __builtin_amdgcn_s_setprio(1);
; #pragma unroll
;       for (int m = 0; m < 4; m++)
; #pragma unroll
;         for (int n = 0; n < 4; n++) acc[m][n] = mfma16(a[m], b[n], acc[m][n]);
;       __builtin_amdgcn_s_setprio(0);
;     }
;     __syncthreads();
;   }
;   const int cb = n0 + wc * 64;
;   if (EPI == EP_RESB) {
;     const int rbase = m0 + wr * 64 + fq * 4, cbase = cb + fr;
;     float* C = (float*)ea.p0;
;     const u16* R = (const u16*)ea.p1;
;     u16 rv[4][4][4];
; #pragma unroll
;     for (int m = 0; m < 4; m++)
; #pragma unroll
;       for (int j = 0; j < 4; j++)
; #pragma unroll
;         for (int n = 0; n < 4; n++) rv[m][j][n] = R[(size_t)(rbase + m * 16 + j) * 1024 + cbase + n * 16];
	ds_read_b128 v[222:225], v161 offset:18496
	ds_read_b128 v[226:229], v161 offset:20800
	ds_read_b128 v[230:233], v161 offset:23104
	ds_read_b128 v[234:237], v161 offset:25408
	ds_read_b128 v[238:241], v129 offset:55360
	ds_read_b128 v[242:245], v129 offset:57664
	ds_read_b128 v[246:249], v129 offset:59968
	ds_read_b128 v[250:253], v129 offset:62272
	v_mfma_f32_16x16x32_bf16 v[34:37], v[130:133], v[146:149], v[34:37]
	v_mfma_f32_16x16x32_bf16 v[38:41], v[130:133], v[150:153], v[38:41]
	v_mfma_f32_16x16x32_bf16 v[42:45], v[130:133], v[162:165], v[42:45]
	v_mfma_f32_16x16x32_bf16 v[46:49], v[130:133], v[166:169], v[46:49]
	v_mfma_f32_16x16x32_bf16 v[50:53], v[134:137], v[146:149], v[50:53]
	v_mfma_f32_16x16x32_bf16 v[54:57], v[134:137], v[150:153], v[54:57]
	v_mfma_f32_16x16x32_bf16 v[58:61], v[134:137], v[162:165], v[58:61]
	v_mfma_f32_16x16x32_bf16 v[62:65], v[134:137], v[166:169], v[62:65]
	v_mfma_f32_16x16x32_bf16 v[66:69], v[138:141], v[146:149], v[66:69]
	v_mfma_f32_16x16x32_bf16 v[70:73], v[138:141], v[150:153], v[70:73]
	v_mfma_f32_16x16x32_bf16 v[74:77], v[138:141], v[162:165], v[74:77]
	v_mfma_f32_16x16x32_bf16 v[78:81], v[138:141], v[166:169], v[78:81]
	v_mfma_f32_16x16x32_bf16 v[82:85], v[142:145], v[146:149], v[82:85]
	v_mfma_f32_16x16x32_bf16 v[86:89], v[142:145], v[150:153], v[86:89]
	v_mfma_f32_16x16x32_bf16 v[90:93], v[142:145], v[162:165], v[90:93]
	v_mfma_f32_16x16x32_bf16 v[94:97], v[142:145], v[166:169], v[94:97]
	s_waitcnt lgkmcnt(0)
	v_mfma_f32_16x16x32_bf16 v[110:113], v[222:225], v[238:241], v[34:37]
	v_mfma_f32_16x16x32_bf16 v[118:121], v[222:225], v[242:245], v[38:41]
	v_mfma_f32_16x16x32_bf16 v[122:125], v[222:225], v[246:249], v[42:45]
	v_mfma_f32_16x16x32_bf16 v[126:129], v[222:225], v[250:253], v[46:49]
	v_mfma_f32_16x16x32_bf16 v[46:49], v[226:229], v[238:241], v[50:53]
	v_mfma_f32_16x16x32_bf16 v[42:45], v[226:229], v[242:245], v[54:57]
	v_mfma_f32_16x16x32_bf16 v[38:41], v[226:229], v[246:249], v[58:61]
	v_mfma_f32_16x16x32_bf16 v[34:37], v[226:229], v[250:253], v[62:65]
	v_mfma_f32_16x16x32_bf16 v[30:33], v[230:233], v[238:241], v[66:69]
	v_mfma_f32_16x16x32_bf16 v[26:29], v[230:233], v[242:245], v[70:73]
	v_mfma_f32_16x16x32_bf16 v[22:25], v[230:233], v[246:249], v[74:77]
	v_mfma_f32_16x16x32_bf16 v[18:21], v[230:233], v[250:253], v[78:81]
	v_mfma_f32_16x16x32_bf16 v[14:17], v[234:237], v[238:241], v[82:85]
	v_mfma_f32_16x16x32_bf16 v[10:13], v[234:237], v[242:245], v[86:89]
	v_mfma_f32_16x16x32_bf16 v[6:9], v[234:237], v[246:249], v[90:93]
	v_mfma_f32_16x16x32_bf16 v[2:5], v[234:237], v[250:253], v[94:97]
	s_nop 7
	v_and_b32_e32 v114, 64, v114
	v_add_u32_e32 v0, s14, v117
	v_lshl_or_b32 v60, v116, 2, v0
	v_or3_b32 v62, v114, s13, v115
	v_ashrrev_i32_e32 v63, 31, v62
	v_ashrrev_i32_e32 v61, 31, v60
	v_or_b32_e32 v68, 1, v60
	v_lshl_add_u64 v[64:65], v[62:63], 1, s[60:61]
	v_lshlrev_b64 v[50:51], 11, v[60:61]
	v_ashrrev_i32_e32 v69, 31, v68
	v_or_b32_e32 v72, 2, v60
	v_lshl_add_u64 v[66:67], v[64:65], 0, v[50:51]
	v_lshlrev_b64 v[50:51], 11, v[68:69]
	v_ashrrev_i32_e32 v73, 31, v72
	v_or_b32_e32 v76, 3, v60
	v_lshl_add_u64 v[70:71], v[64:65], 0, v[50:51]
	v_lshlrev_b64 v[50:51], 11, v[72:73]
	v_ashrrev_i32_e32 v77, 31, v76
	v_or_b32_e32 v80, 16, v60
	v_lshl_add_u64 v[74:75], v[64:65], 0, v[50:51]
	v_lshlrev_b64 v[50:51], 11, v[76:77]
	v_ashrrev_i32_e32 v81, 31, v80
	v_or_b32_e32 v84, 17, v60
	v_lshl_add_u64 v[78:79], v[64:65], 0, v[50:51]
	v_lshlrev_b64 v[50:51], 11, v[80:81]
	v_ashrrev_i32_e32 v85, 31, v84
	v_or_b32_e32 v88, 18, v60
	v_lshl_add_u64 v[82:83], v[64:65], 0, v[50:51]
	v_lshlrev_b64 v[50:51], 11, v[84:85]
	v_ashrrev_i32_e32 v89, 31, v88
	v_or_b32_e32 v92, 19, v60
	v_lshl_add_u64 v[86:87], v[64:65], 0, v[50:51]
	v_lshlrev_b64 v[50:51], 11, v[88:89]
	v_ashrrev_i32_e32 v93, 31, v92
	v_or_b32_e32 v96, 32, v60
	v_lshl_add_u64 v[90:91], v[64:65], 0, v[50:51]
	v_lshlrev_b64 v[50:51], 11, v[92:93]
	v_ashrrev_i32_e32 v97, 31, v96
	v_or_b32_e32 v100, 33, v60
	v_lshl_add_u64 v[94:95], v[64:65], 0, v[50:51]
	v_lshlrev_b64 v[50:51], 11, v[96:97]
	v_ashrrev_i32_e32 v101, 31, v100
	v_or_b32_e32 v104, 34, v60
	v_lshl_add_u64 v[98:99], v[64:65], 0, v[50:51]
	v_lshlrev_b64 v[50:51], 11, v[100:101]
	v_ashrrev_i32_e32 v105, 31, v104
	v_or_b32_e32 v58, 35, v60
	v_lshl_add_u64 v[102:103], v[64:65], 0, v[50:51]
	v_lshlrev_b64 v[50:51], 11, v[104:105]
	v_ashrrev_i32_e32 v59, 31, v58
	v_or_b32_e32 v56, 48, v60
	v_lshl_add_u64 v[106:107], v[64:65], 0, v[50:51]
	v_lshlrev_b64 v[50:51], 11, v[58:59]
	v_ashrrev_i32_e32 v57, 31, v56
	v_or_b32_e32 v54, 49, v60
	v_lshl_add_u64 v[108:109], v[64:65], 0, v[50:51]
	v_lshlrev_b64 v[50:51], 11, v[56:57]
	v_ashrrev_i32_e32 v55, 31, v54
	v_or_b32_e32 v52, 50, v60
	v_lshl_add_u64 v[114:115], v[64:65], 0, v[50:51]
	v_lshlrev_b64 v[50:51], 11, v[54:55]
	v_ashrrev_i32_e32 v53, 31, v52
	v_lshl_add_u64 v[116:117], v[64:65], 0, v[50:51]
	v_lshlrev_b64 v[50:51], 11, v[52:53]
	v_lshl_add_u64 v[130:131], v[64:65], 0, v[50:51]
	v_or_b32_e32 v50, 51, v60
	v_ashrrev_i32_e32 v51, 31, v50
	v_lshlrev_b64 v[132:133], 11, v[50:51]
	v_lshl_add_u64 v[64:65], v[64:65], 0, v[132:133]
	s_barrier
; DEV float bf2f(u16 h) { return __uint_as_float(((unsigned)h) << 16); }
; template <int EPI, bool AF32>
; DEV void gemm_tile(const void* Ap, int lda, const u16* Bt, int ldb, int K, int m0, int n0, const Epi& ea, char* smem) {
;     ...
;   if (EPI == EP_RESB) {
;     const int rbase = m0 + wr * 64 + fq * 4, cbase = cb + fr;
;     float* C = (float*)ea.p0;
;     const u16* R = (const u16*)ea.p1;
;     u16 rv[4][4][4];
; #pragma unroll
;     for (int m = 0; m < 4; m++)
; #pragma unroll
;       for (int j = 0; j < 4; j++)
; #pragma unroll
;         for (int n = 0; n < 4; n++) rv[m][j][n] = R[(size_t)(rbase + m * 16 + j) * 1024 + cbase + n * 16];
;     __builtin_amdgcn_sched_barrier(0);
; #pragma unroll
;     for (int m = 0; m < 4; m++)
; #pragma unroll
;       for (int j = 0; j < 4; j++)
; #pragma unroll
;         for (int n = 0; n < 4; n++)
;           C[(size_t)(rbase + m * 16 + j) * 1024 + cbase + n * 16] = ALPHA_ * bf2f(rv[m][j][n]) + acc[m][n][j];
;     return;
	global_load_ushort v0, v[66:67], off
	global_load_ushort v132, v[66:67], off offset:32
	global_load_ushort v133, v[66:67], off offset:64
	s_nop 0
	global_load_ushort v66, v[66:67], off offset:96
	s_nop 0
	global_load_ushort v67, v[70:71], off
	global_load_ushort v134, v[70:71], off offset:32
	global_load_ushort v135, v[70:71], off offset:64
	s_nop 0
	global_load_ushort v70, v[70:71], off offset:96
	s_nop 0
	global_load_ushort v71, v[74:75], off
	global_load_ushort v136, v[74:75], off offset:32
	global_load_ushort v137, v[74:75], off offset:64
	s_nop 0
	global_load_ushort v74, v[74:75], off offset:96
	s_nop 0
	global_load_ushort v75, v[78:79], off
	global_load_ushort v138, v[78:79], off offset:32
	global_load_ushort v139, v[78:79], off offset:64
	s_nop 0
	global_load_ushort v78, v[78:79], off offset:96
	s_nop 0
	global_load_ushort v79, v[82:83], off
	global_load_ushort v140, v[82:83], off offset:32
	global_load_ushort v141, v[82:83], off offset:64
	s_nop 0
	global_load_ushort v82, v[82:83], off offset:96
	s_nop 0
	global_load_ushort v83, v[86:87], off
	global_load_ushort v142, v[86:87], off offset:32
	global_load_ushort v143, v[86:87], off offset:64
	s_nop 0
	global_load_ushort v86, v[86:87], off offset:96
	s_nop 0
	global_load_ushort v87, v[90:91], off
	global_load_ushort v144, v[90:91], off offset:32
	global_load_ushort v145, v[90:91], off offset:64
	s_nop 0
	global_load_ushort v90, v[90:91], off offset:96
	s_nop 0
	global_load_ushort v91, v[94:95], off
	global_load_ushort v146, v[94:95], off offset:32
	global_load_ushort v147, v[94:95], off offset:64
	s_nop 0
	global_load_ushort v94, v[94:95], off offset:96
	s_nop 0
	global_load_ushort v95, v[98:99], off
	global_load_ushort v148, v[98:99], off offset:32
	global_load_ushort v149, v[98:99], off offset:64
	s_nop 0
	global_load_ushort v98, v[98:99], off offset:96
	s_nop 0
	global_load_ushort v99, v[102:103], off
	global_load_ushort v150, v[102:103], off offset:32
	global_load_ushort v151, v[102:103], off offset:64
	s_nop 0
	global_load_ushort v102, v[102:103], off offset:96
	s_nop 0
	global_load_ushort v103, v[106:107], off
	global_load_ushort v152, v[106:107], off offset:32
	global_load_ushort v153, v[106:107], off offset:64
	s_nop 0
	global_load_ushort v106, v[106:107], off offset:96
	s_nop 0
	global_load_ushort v107, v[108:109], off
	global_load_ushort v161, v[108:109], off offset:32
	global_load_ushort v162, v[108:109], off offset:64
	s_nop 0
	global_load_ushort v108, v[108:109], off offset:96
	s_nop 0
	global_load_ushort v109, v[114:115], off
	global_load_ushort v163, v[114:115], off offset:32
	global_load_ushort v164, v[114:115], off offset:64
	s_nop 0
	global_load_ushort v114, v[114:115], off offset:96
	s_nop 0
	global_load_ushort v115, v[116:117], off
	global_load_ushort v165, v[116:117], off offset:32
	global_load_ushort v166, v[116:117], off offset:64
	s_nop 0
	global_load_ushort v116, v[116:117], off offset:96
	s_nop 0
	global_load_ushort v117, v[130:131], off
	global_load_ushort v167, v[130:131], off offset:32
	global_load_ushort v168, v[130:131], off offset:64
	s_nop 0
	global_load_ushort v130, v[130:131], off offset:96
	s_nop 0
	global_load_ushort v131, v[64:65], off
	global_load_ushort v169, v[64:65], off offset:32
	global_load_ushort v170, v[64:65], off offset:64
	s_nop 0
	global_load_ushort v64, v[64:65], off offset:96
	v_lshl_add_u64 v[62:63], v[62:63], 2, s[2:3]
	v_lshlrev_b64 v[60:61], 12, v[60:61]
	s_waitcnt vmcnt(62)
	v_lshlrev_b32_e32 v0, 16, v0
	v_lshl_add_u64 v[60:61], v[62:63], 0, v[60:61]
	v_fmamk_f32 v0, v0, 0x3fb504f3, v110
	global_store_dword v[60:61], v0, off
	v_lshlrev_b32_e32 v0, 16, v132
	v_fmamk_f32 v0, v0, 0x3fb504f3, v118
	global_store_dword v[60:61], v0, off offset:64
	s_waitcnt vmcnt(62)
	v_lshlrev_b32_e32 v0, 16, v133
	v_fmamk_f32 v0, v0, 0x3fb504f3, v122
	global_store_dword v[60:61], v0, off offset:128
	v_lshlrev_b32_e32 v0, 16, v66
	v_fmamk_f32 v0, v0, 0x3fb504f3, v126
	global_store_dword v[60:61], v0, off offset:192
	v_lshlrev_b64 v[60:61], 12, v[68:69]
	s_waitcnt vmcnt(62)
	v_lshlrev_b32_e32 v0, 16, v67
	v_lshl_add_u64 v[60:61], v[62:63], 0, v[60:61]
	v_fmamk_f32 v0, v0, 0x3fb504f3, v111
	global_store_dword v[60:61], v0, off
	v_lshlrev_b32_e32 v0, 16, v134
	v_fmamk_f32 v0, v0, 0x3fb504f3, v119
	global_store_dword v[60:61], v0, off offset:64
	s_waitcnt vmcnt(62)
	v_lshlrev_b32_e32 v0, 16, v135
	v_fmamk_f32 v0, v0, 0x3fb504f3, v123
	global_store_dword v[60:61], v0, off offset:128
	v_lshlrev_b32_e32 v0, 16, v70
	v_fmamk_f32 v0, v0, 0x3fb504f3, v127
	global_store_dword v[60:61], v0, off offset:192
	v_lshlrev_b64 v[60:61], 12, v[72:73]
	s_waitcnt vmcnt(62)
	v_lshlrev_b32_e32 v0, 16, v71
	v_lshl_add_u64 v[60:61], v[62:63], 0, v[60:61]
	v_fmamk_f32 v0, v0, 0x3fb504f3, v112
	global_store_dword v[60:61], v0, off
	v_lshlrev_b32_e32 v0, 16, v136
	v_fmamk_f32 v0, v0, 0x3fb504f3, v120
	global_store_dword v[60:61], v0, off offset:64
	s_waitcnt vmcnt(62)
	v_lshlrev_b32_e32 v0, 16, v137
	v_fmamk_f32 v0, v0, 0x3fb504f3, v124
	global_store_dword v[60:61], v0, off offset:128
	v_lshlrev_b32_e32 v0, 16, v74
	v_fmamk_f32 v0, v0, 0x3fb504f3, v128
	global_store_dword v[60:61], v0, off offset:192
	s_waitcnt vmcnt(62)
	v_lshlrev_b32_e32 v0, 16, v75
	v_fmac_f32_e32 v113, 0x3fb504f3, v0
	v_lshlrev_b32_e32 v0, 16, v138
	v_fmac_f32_e32 v121, 0x3fb504f3, v0
	s_waitcnt vmcnt(61)
	v_lshlrev_b32_e32 v0, 16, v139
	v_lshlrev_b64 v[60:61], 12, v[76:77]
	v_fmac_f32_e32 v125, 0x3fb504f3, v0
	s_waitcnt vmcnt(60)
; DEV float bf2f(u16 h) { return __uint_as_float(((unsigned)h) << 16); }
; template <int EPI, bool AF32>
; DEV void gemm_tile(const void* Ap, int lda, const u16* Bt, int ldb, int K, int m0, int n0, const Epi& ea, char* smem) {
;     ...
; #pragma unroll
;     for (int m = 0; m < 4; m++)
; #pragma unroll
;       for (int j = 0; j < 4; j++)
; #pragma unroll
;         for (int n = 0; n < 4; n++)
;           C[(size_t)(rbase + m * 16 + j) * 1024 + cbase + n * 16] = ALPHA_ * bf2f(rv[m][j][n]) + acc[m][n][j];
;     return;
	v_lshlrev_b32_e32 v0, 16, v78
	v_lshl_add_u64 v[60:61], v[62:63], 0, v[60:61]
	v_fmac_f32_e32 v129, 0x3fb504f3, v0
	global_store_dword v[60:61], v113, off
	global_store_dword v[60:61], v121, off offset:64
	global_store_dword v[60:61], v125, off offset:128
	global_store_dword v[60:61], v129, off offset:192
	v_lshlrev_b64 v[60:61], 12, v[80:81]
	s_waitcnt vmcnt(62)
	v_lshlrev_b32_e32 v0, 16, v79
	v_lshl_add_u64 v[60:61], v[62:63], 0, v[60:61]
	v_fmamk_f32 v0, v0, 0x3fb504f3, v46
	global_store_dword v[60:61], v0, off
	v_lshlrev_b32_e32 v0, 16, v140
	v_fmamk_f32 v0, v0, 0x3fb504f3, v42
	global_store_dword v[60:61], v0, off offset:64
	s_waitcnt vmcnt(62)
	v_lshlrev_b32_e32 v0, 16, v141
	v_fmamk_f32 v0, v0, 0x3fb504f3, v38
	global_store_dword v[60:61], v0, off offset:128
	v_lshlrev_b32_e32 v0, 16, v82
	v_fmamk_f32 v0, v0, 0x3fb504f3, v34
	global_store_dword v[60:61], v0, off offset:192
	v_lshlrev_b64 v[60:61], 12, v[84:85]
	s_waitcnt vmcnt(62)
	v_lshlrev_b32_e32 v0, 16, v83
	v_lshl_add_u64 v[60:61], v[62:63], 0, v[60:61]
	v_fmamk_f32 v0, v0, 0x3fb504f3, v47
	global_store_dword v[60:61], v0, off
	v_lshlrev_b32_e32 v0, 16, v142
	v_fmamk_f32 v0, v0, 0x3fb504f3, v43
	global_store_dword v[60:61], v0, off offset:64
	s_waitcnt vmcnt(62)
	v_lshlrev_b32_e32 v0, 16, v143
	v_fmamk_f32 v0, v0, 0x3fb504f3, v39
	global_store_dword v[60:61], v0, off offset:128
	v_lshlrev_b32_e32 v0, 16, v86
	v_fmamk_f32 v0, v0, 0x3fb504f3, v35
	global_store_dword v[60:61], v0, off offset:192
	v_lshlrev_b64 v[34:35], 12, v[88:89]
	s_waitcnt vmcnt(62)
	v_lshlrev_b32_e32 v0, 16, v87
	v_lshl_add_u64 v[34:35], v[62:63], 0, v[34:35]
	v_fmamk_f32 v0, v0, 0x3fb504f3, v48
	global_store_dword v[34:35], v0, off
	v_lshlrev_b32_e32 v0, 16, v144
	v_fmamk_f32 v0, v0, 0x3fb504f3, v44
	global_store_dword v[34:35], v0, off offset:64
	s_waitcnt vmcnt(62)
	v_lshlrev_b32_e32 v0, 16, v145
	v_fmamk_f32 v0, v0, 0x3fb504f3, v40
	global_store_dword v[34:35], v0, off offset:128
	v_lshlrev_b32_e32 v0, 16, v90
	v_fmamk_f32 v0, v0, 0x3fb504f3, v36
	global_store_dword v[34:35], v0, off offset:192
	s_waitcnt vmcnt(62)
	v_lshlrev_b32_e32 v0, 16, v91
	v_fmac_f32_e32 v49, 0x3fb504f3, v0
	v_lshlrev_b32_e32 v0, 16, v146
	v_fmac_f32_e32 v45, 0x3fb504f3, v0
	s_waitcnt vmcnt(61)
	v_lshlrev_b32_e32 v0, 16, v147
	v_lshlrev_b64 v[34:35], 12, v[92:93]
	v_fmac_f32_e32 v41, 0x3fb504f3, v0
	s_waitcnt vmcnt(60)
	v_lshlrev_b32_e32 v0, 16, v94
	v_lshl_add_u64 v[34:35], v[62:63], 0, v[34:35]
	v_fmac_f32_e32 v37, 0x3fb504f3, v0
	global_store_dword v[34:35], v49, off
	global_store_dword v[34:35], v45, off offset:64
	global_store_dword v[34:35], v41, off offset:128
	global_store_dword v[34:35], v37, off offset:192
	v_lshlrev_b64 v[34:35], 12, v[96:97]
	s_waitcnt vmcnt(62)
	v_lshlrev_b32_e32 v0, 16, v95
	v_lshl_add_u64 v[34:35], v[62:63], 0, v[34:35]
	v_fmamk_f32 v0, v0, 0x3fb504f3, v30
	global_store_dword v[34:35], v0, off
	v_lshlrev_b32_e32 v0, 16, v148
	v_fmamk_f32 v0, v0, 0x3fb504f3, v26
	global_store_dword v[34:35], v0, off offset:64
	s_waitcnt vmcnt(62)
	v_lshlrev_b32_e32 v0, 16, v149
	v_fmamk_f32 v0, v0, 0x3fb504f3, v22
	global_store_dword v[34:35], v0, off offset:128
	v_lshlrev_b32_e32 v0, 16, v98
	v_fmamk_f32 v0, v0, 0x3fb504f3, v18
	global_store_dword v[34:35], v0, off offset:192
	v_lshlrev_b64 v[34:35], 12, v[100:101]
	s_waitcnt vmcnt(62)
	v_lshlrev_b32_e32 v0, 16, v99
	v_lshl_add_u64 v[34:35], v[62:63], 0, v[34:35]
	v_fmamk_f32 v0, v0, 0x3fb504f3, v31
	global_store_dword v[34:35], v0, off
	v_lshlrev_b32_e32 v0, 16, v150
	v_fmamk_f32 v0, v0, 0x3fb504f3, v27
	global_store_dword v[34:35], v0, off offset:64
	s_waitcnt vmcnt(62)
; DEV int bidx() { int b = __builtin_amdgcn_readfirstlane(blockIdx.x); asm volatile("" : "+s"(b)); return b; }
; DEV int gdim() { int g = __builtin_amdgcn_readfirstlane(gridDim.x); asm volatile("" : "+s"(g)); return g; }
; DEV float bf2f(u16 h) { return __uint_as_float(((unsigned)h) << 16); }
; template <int EPI, bool AF32>
; DEV void gemm_tile(const void* Ap, int lda, const u16* Bt, int ldb, int K, int m0, int n0, const Epi& ea, char* smem) {
;     ...
; #pragma unroll
;     for (int m = 0; m < 4; m++)
; #pragma unroll
;       for (int j = 0; j < 4; j++)
; #pragma unroll
;         for (int n = 0; n < 4; n++)
;           C[(size_t)(rbase + m * 16 + j) * 1024 + cbase + n * 16] = ALPHA_ * bf2f(rv[m][j][n]) + acc[m][n][j];
;     return;
; template <int EPI, bool AF32>
; DEV void gemm_phase(const void* A, int lda, const u16* Bt, int ldb, int M, int N, int K, const Epi& ea, char* smem) {
;     ...
;   for (int tile = bidx(); tile < ntm * ntn; tile += gdim()) {
;     int m, n;
;     tile_mn(tile, ntm, ntn, m, n);
;     gemm_tile<EPI, AF32>(A, lda, Bt, ldb, K, m << 7, n << 7, ea, smem);
;   }
	v_lshlrev_b32_e32 v0, 16, v151
	v_fmamk_f32 v0, v0, 0x3fb504f3, v23
	global_store_dword v[34:35], v0, off offset:128
	v_lshlrev_b32_e32 v0, 16, v102
	v_fmamk_f32 v0, v0, 0x3fb504f3, v19
	global_store_dword v[34:35], v0, off offset:192
	v_lshlrev_b64 v[18:19], 12, v[104:105]
	s_waitcnt vmcnt(62)
	v_lshlrev_b32_e32 v0, 16, v103
	v_lshl_add_u64 v[18:19], v[62:63], 0, v[18:19]
	v_fmamk_f32 v0, v0, 0x3fb504f3, v32
	global_store_dword v[18:19], v0, off
	v_lshlrev_b32_e32 v0, 16, v152
	v_fmamk_f32 v0, v0, 0x3fb504f3, v28
	global_store_dword v[18:19], v0, off offset:64
	s_waitcnt vmcnt(62)
	v_lshlrev_b32_e32 v0, 16, v153
	v_fmamk_f32 v0, v0, 0x3fb504f3, v24
	global_store_dword v[18:19], v0, off offset:128
	v_lshlrev_b32_e32 v0, 16, v106
	v_fmamk_f32 v0, v0, 0x3fb504f3, v20
	global_store_dword v[18:19], v0, off offset:192
	s_waitcnt vmcnt(62)
	v_lshlrev_b32_e32 v0, 16, v107
	v_fmac_f32_e32 v33, 0x3fb504f3, v0
	v_lshlrev_b32_e32 v0, 16, v161
	v_fmac_f32_e32 v29, 0x3fb504f3, v0
	s_waitcnt vmcnt(61)
	v_lshlrev_b32_e32 v0, 16, v162
	v_lshlrev_b64 v[18:19], 12, v[58:59]
	v_fmac_f32_e32 v25, 0x3fb504f3, v0
	s_waitcnt vmcnt(60)
	v_lshlrev_b32_e32 v0, 16, v108
	v_lshl_add_u64 v[18:19], v[62:63], 0, v[18:19]
	v_fmac_f32_e32 v21, 0x3fb504f3, v0
	global_store_dword v[18:19], v33, off
	global_store_dword v[18:19], v29, off offset:64
	global_store_dword v[18:19], v25, off offset:128
	global_store_dword v[18:19], v21, off offset:192
	v_lshlrev_b64 v[18:19], 12, v[56:57]
	s_waitcnt vmcnt(62)
	v_lshlrev_b32_e32 v0, 16, v109
	v_lshl_add_u64 v[18:19], v[62:63], 0, v[18:19]
	v_fmamk_f32 v0, v0, 0x3fb504f3, v14
	global_store_dword v[18:19], v0, off
	v_lshlrev_b32_e32 v0, 16, v163
	v_fmamk_f32 v0, v0, 0x3fb504f3, v10
	global_store_dword v[18:19], v0, off offset:64
	s_waitcnt vmcnt(62)
	v_lshlrev_b32_e32 v0, 16, v164
	v_fmamk_f32 v0, v0, 0x3fb504f3, v6
	global_store_dword v[18:19], v0, off offset:128
	v_lshlrev_b32_e32 v0, 16, v114
	v_fmamk_f32 v0, v0, 0x3fb504f3, v2
	global_store_dword v[18:19], v0, off offset:192
	v_lshlrev_b64 v[18:19], 12, v[54:55]
	s_waitcnt vmcnt(62)
	v_lshlrev_b32_e32 v0, 16, v115
	v_lshl_add_u64 v[18:19], v[62:63], 0, v[18:19]
	v_fmamk_f32 v0, v0, 0x3fb504f3, v15
	global_store_dword v[18:19], v0, off
	v_lshlrev_b32_e32 v0, 16, v165
	v_fmamk_f32 v0, v0, 0x3fb504f3, v11
	global_store_dword v[18:19], v0, off offset:64
	s_waitcnt vmcnt(62)
	v_lshlrev_b32_e32 v0, 16, v166
	v_fmamk_f32 v0, v0, 0x3fb504f3, v7
	global_store_dword v[18:19], v0, off offset:128
	v_lshlrev_b32_e32 v0, 16, v116
	v_fmamk_f32 v0, v0, 0x3fb504f3, v3
	global_store_dword v[18:19], v0, off offset:192
	v_lshlrev_b64 v[2:3], 12, v[52:53]
	s_waitcnt vmcnt(62)
	v_lshlrev_b32_e32 v0, 16, v117
	v_lshl_add_u64 v[2:3], v[62:63], 0, v[2:3]
	v_fmamk_f32 v0, v0, 0x3fb504f3, v16
	global_store_dword v[2:3], v0, off
	v_lshlrev_b32_e32 v0, 16, v167
	v_fmamk_f32 v0, v0, 0x3fb504f3, v12
	global_store_dword v[2:3], v0, off offset:64
	s_waitcnt vmcnt(62)
	v_lshlrev_b32_e32 v0, 16, v168
	v_fmamk_f32 v0, v0, 0x3fb504f3, v8
	global_store_dword v[2:3], v0, off offset:128
	v_lshlrev_b32_e32 v0, 16, v130
	v_fmamk_f32 v0, v0, 0x3fb504f3, v4
	global_store_dword v[2:3], v0, off offset:192
	s_waitcnt vmcnt(62)
	v_lshlrev_b32_e32 v0, 16, v131
	v_fmac_f32_e32 v17, 0x3fb504f3, v0
	v_lshlrev_b32_e32 v0, 16, v169
	v_fmac_f32_e32 v13, 0x3fb504f3, v0
	s_waitcnt vmcnt(61)
	v_lshlrev_b32_e32 v0, 16, v170
	v_lshlrev_b64 v[2:3], 12, v[50:51]
	v_fmac_f32_e32 v9, 0x3fb504f3, v0
	s_waitcnt vmcnt(60)
	v_lshlrev_b32_e32 v0, 16, v64
	v_lshl_add_u64 v[2:3], v[62:63], 0, v[2:3]
	v_fmac_f32_e32 v5, 0x3fb504f3, v0
	v_readfirstlane_b32 s10, v198
	global_store_dword v[2:3], v17, off
	global_store_dword v[2:3], v13, off offset:64
	global_store_dword v[2:3], v9, off offset:128
	global_store_dword v[2:3], v5, off offset:192
	s_add_i32 s12, s10, s12
	s_cmpk_lt_i32 s12, 0x820
	s_cbranch_scc1 .LBB0_1352

; DEV int tidx() { int t = threadIdx.x; asm volatile("" : "+v"(t)); return t; }
; template <int EPI, bool AF32>
; DEV void gemm_tile(const void* Ap, int lda, const u16* Bt, int ldb, int K, int m0, int n0, const Epi& ea, char* smem) {
;   u16* sA = (u16*)smem;
;   u16* sB = sA + 2 * 128 * 72;
;   const int tid = tidx(), lane = tid & 63, wv = tid >> 6;
;   const int wr = wv >> 1, wc = wv & 1, fr = lane & 15, fq = lane >> 4;
;   f32x4 acc[4][4];
; #pragma unroll
;   for (int m = 0; m < 4; m++)
; #pragma unroll
;     for (int n = 0; n < 4; n++) acc[m][n] = (f32x4){0.f, 0.f, 0.f, 0.f};
;   u32x4 ra[4], rb[4];
;   f32x4 rfa[8];
;   const int nk = K >> 6;
;   auto gload = [&](int kt) {
;     const int k0 = kt << 6;
; #pragma unroll
;     for (int i = 0; i < 4; i++) {
;       const int c = tid + i * 256, row = c >> 3, kc = c & 7;
;       if (AF32) {
;         const float* pa = (const float*)Ap + (size_t)(m0 + row) * lda + k0 + kc * 8;
;         rfa[2 * i] = *(const f32x4*)pa;
;         rfa[2 * i + 1] = *(const f32x4*)(pa + 4);
;       } else {
;         ra[i] = *(const u32x4*)((const u16*)Ap + (size_t)(m0 + row) * lda + k0 + kc * 8);
;       }
;       rb[i] = *(const u32x4*)(Bt + (size_t)(n0 + row) * ldb + k0 + kc * 8);
;     }
;   };
;   auto swrite = [&](int buf) {
; #pragma unroll
;     for (int i = 0; i < 4; i++) {
;       const int c = tid + i * 256, row = c >> 3, kc = c & 7;
;       u32x4 va;
;       if (AF32) {
;         va = (u32x4){pack2(rfa[2 * i][0], rfa[2 * i][1]), pack2(rfa[2 * i][2], rfa[2 * i][3]),
;                      pack2(rfa[2 * i + 1][0], rfa[2 * i + 1][1]), pack2(rfa[2 * i + 1][2], rfa[2 * i + 1][3])};
;       } else {
;         va = ra[i];
;       }
;       *(u32x4*)(sA + buf * 9216 + row * 72 + kc * 8) = va;
;       *(u32x4*)(sB + buf * 9216 + row * 72 + kc * 8) = rb[i];
;     }
;   };
;   gload(0);
;   swrite(0);
;   if (nk > 1) gload(1);
;   __syncthreads();
.LBB0_1436:
	s_mul_hi_i32 s0, s12, 0x2e8ba2e9
	s_lshr_b32 s1, s0, 31
	s_ashr_i32 s0, s0, 8
	s_add_i32 s0, s0, s1
	s_lshl_b32 s14, s0, 5
	s_mul_i32 s1, s0, 0x580
	s_sub_i32 s0, 0x104, s14
	s_min_u32 s15, s0, 32
	s_sub_i32 s13, s12, s1
	v_cvt_f32_ubyte0_e32 v2, s15
	v_cvt_f32_i32_e32 v0, s13
	v_rcp_iflag_f32_e32 v3, v2
	s_ashr_i32 s0, s13, 30
	s_or_b32 s16, s0, 1
	s_waitcnt vmcnt(12)
	v_mov_b32_e32 v114, v157
	v_mul_f32_e32 v3, v0, v3
	v_trunc_f32_e32 v3, v3
	v_fma_f32 v0, -v3, v2, v0
	v_cvt_i32_f32_e32 v3, v3
	v_cmp_ge_f32_e64 s[0:1], |v0|, v2
	s_and_b64 s[0:1], s[0:1], exec
	s_cselect_b32 s0, s16, 0
	v_readfirstlane_b32 s1, v3
	s_add_i32 s0, s1, s0
	s_sext_i32_i16 s1, s0
	s_mul_i32 s0, s0, s15
	s_sub_i32 s0, s13, s0
	s_sext_i32_i16 s0, s0
	s_add_i32 s14, s14, s0
	s_lshl_b32 s13, s14, 7
	s_lshl_b32 s14, s1, 7
	v_ashrrev_i32_e32 v8, 3, v114
	v_add_u32_e32 v2, s13, v8
	v_ashrrev_i32_e32 v3, 31, v2
	v_lshlrev_b32_e32 v0, 3, v114
	v_add_u32_e32 v4, 0x100, v114
	v_lshlrev_b64 v[58:59], 11, v[2:3]
	v_and_b32_e32 v0, 56, v0
	v_ashrrev_i32_e32 v9, 3, v4
	v_lshl_add_u64 v[2:3], s[4:5], 0, v[58:59]
	v_lshlrev_b32_e32 v0, 1, v0
	v_add_u32_e32 v4, s13, v9
	v_add_u32_e32 v6, 0x200, v114
	v_lshl_add_u64 v[14:15], v[2:3], 0, v[0:1]
	v_add_u32_e32 v2, s14, v8
	v_ashrrev_i32_e32 v5, 31, v4
	v_ashrrev_i32_e32 v10, 3, v6
	v_ashrrev_i32_e32 v3, 31, v2
	v_lshlrev_b64 v[62:63], 11, v[4:5]
	v_add_u32_e32 v6, s13, v10
	v_lshlrev_b64 v[60:61], 11, v[2:3]
	v_lshl_add_u64 v[4:5], s[4:5], 0, v[62:63]
	v_ashrrev_i32_e32 v7, 31, v6
	v_lshl_add_u64 v[2:3], s[6:7], 0, v[60:61]
	v_lshl_add_u64 v[16:17], v[4:5], 0, v[0:1]
	v_add_u32_e32 v4, s14, v9
	v_lshlrev_b64 v[66:67], 11, v[6:7]
	v_lshl_add_u64 v[2:3], v[2:3], 0, v[0:1]
	v_ashrrev_i32_e32 v5, 31, v4
	v_lshl_add_u64 v[6:7], s[4:5], 0, v[66:67]
	global_load_dwordx4 v[30:33], v[2:3], off
	v_lshlrev_b64 v[64:65], 11, v[4:5]
	v_lshl_add_u64 v[68:69], v[6:7], 0, v[0:1]
	v_add_u32_e32 v6, s14, v10
	global_load_dwordx4 v[26:29], v[14:15], off
	global_load_dwordx4 v[34:37], v[16:17], off
	v_lshl_add_u64 v[4:5], s[6:7], 0, v[64:65]
	v_ashrrev_i32_e32 v7, 31, v6
	v_lshl_add_u64 v[4:5], v[4:5], 0, v[0:1]
	v_lshlrev_b64 v[70:71], 11, v[6:7]
	global_load_dwordx4 v[38:41], v[4:5], off
	v_lshl_add_u64 v[6:7], s[6:7], 0, v[70:71]
	global_load_dwordx4 v[42:45], v[68:69], off
	v_lshl_add_u64 v[18:19], v[6:7], 0, v[0:1]
	global_load_dwordx4 v[46:49], v[18:19], off
	v_add_u32_e32 v6, 0x300, v114
	v_ashrrev_i32_e32 v80, 3, v6
	v_add_u32_e32 v6, s13, v80
	v_ashrrev_i32_e32 v7, 31, v6
	v_lshlrev_b64 v[72:73], 11, v[6:7]
	v_lshl_add_u64 v[6:7], s[4:5], 0, v[72:73]
	v_lshl_add_u64 v[74:75], v[6:7], 0, v[0:1]
	v_add_u32_e32 v6, s14, v80
	v_ashrrev_i32_e32 v7, 31, v6
	v_lshlrev_b64 v[76:77], 11, v[6:7]
	v_lshl_add_u64 v[6:7], s[6:7], 0, v[76:77]
	v_lshl_add_u64 v[78:79], v[6:7], 0, v[0:1]
	global_load_dwordx4 v[50:53], v[74:75], off
	global_load_dwordx4 v[54:57], v[78:79], off
	s_waitcnt vmcnt(19)
	v_mul_lo_u32 v118, v8, s71
	v_mul_lo_u32 v119, v9, s71
	s_waitcnt vmcnt(18)
	v_mul_lo_u32 v123, v10, s71
	global_load_dwordx4 v[6:9], v[2:3], off offset:128
	global_load_dwordx4 v[10:13], v[4:5], off offset:128
	s_nop 0
	global_load_dwordx4 v[2:5], v[18:19], off offset:128
	global_load_dwordx4 v[22:25], v[14:15], off offset:128
	s_nop 0
	global_load_dwordx4 v[18:21], v[16:17], off offset:128
	s_nop 0
	global_load_dwordx4 v[14:17], v[68:69], off offset:128
	v_bfe_u32 v161, v157, 3, 4
	v_add_u32_e32 v161, 4, v161
	v_lshlrev_b32_e32 v161, 1, v161
	v_and_b32_e32 v161, 16, v161
	v_xor_b32_e32 v129, v0, v161
	v_lshl_add_u32 v122, v118, 1, v129
	v_lshl_add_u32 v121, v119, 1, v129
	v_lshl_add_u32 v120, v123, 1, v129
	v_and_b32_e32 v115, 15, v114
	s_waitcnt vmcnt(23)
	v_mul_lo_u32 v126, v80, s71
	v_bfe_u32 v116, v114, 4, 2
	v_lshl_add_u32 v124, v126, 1, v129
	s_mov_b32 s15, 0
	v_lshlrev_b32_e32 v125, 4, v116
	v_and_b32_e32 v161, 15, v157
	v_add_u32_e32 v161, 4, v161
	v_lshlrev_b32_e32 v161, 1, v161
	v_and_b32_e32 v161, 16, v161
	v_xor_b32_e32 v125, v125, v161
	s_mov_b64 s[0:1], 0
	s_waitcnt vmcnt(13)
	ds_write_b128 v122, v[30:33] offset:36864
	s_waitcnt vmcnt(12)
	ds_write_b128 v122, v[26:29]
	s_waitcnt vmcnt(11)
	ds_write_b128 v121, v[34:37]
	s_waitcnt vmcnt(10)
	ds_write_b128 v121, v[38:41] offset:36864
	s_waitcnt vmcnt(9)
	ds_write_b128 v120, v[42:45]
	s_waitcnt vmcnt(8)
	ds_write_b128 v120, v[46:49] offset:36864
	global_load_dwordx4 v[26:29], v[74:75], off offset:128
	global_load_dwordx4 v[30:33], v[78:79], off offset:128
	v_ashrrev_i32_e32 v34, 1, v114
	v_and_b32_e32 v117, 0xffffffc0, v34
	v_or_b32_e32 v34, v117, v115
	v_mul_lo_u32 v128, v34, s71
	v_lshlrev_b32_e32 v34, 4, v114
	v_and_b32_e32 v34, 0x70, v34
	v_and_b32_e32 v35, 0x4f, v114
	v_or_b32_e32 v76, v76, v34
	v_or_b32_e32 v72, v72, v34
	v_or_b32_e32 v70, v70, v34
	v_or_b32_e32 v66, v66, v34
	v_or_b32_e32 v64, v64, v34
	v_or_b32_e32 v62, v62, v34
	v_or_b32_e32 v60, v60, v34
	v_or_b32_e32 v58, v58, v34
	v_mov_b32_e32 v34, 0
	s_waitcnt vmcnt(9)
	ds_write_b128 v124, v[50:53]
	s_waitcnt vmcnt(8)
	ds_write_b128 v124, v[54:57] offset:36864
	v_mul_u32_u24_e32 v127, 0x48, v35
	v_mov_b32_e32 v98, v76
	v_mov_b32_e32 v100, v72
	v_mov_b32_e32 v102, v70
	v_mov_b32_e32 v104, v66
	v_mov_b32_e32 v106, v64
	v_mov_b32_e32 v108, v62
	v_mov_b32_e32 v110, v60
	v_mov_b32_e32 v112, v58
	v_mov_b32_e32 v35, v34
	v_mov_b32_e32 v36, v34
	v_mov_b32_e32 v37, v34
	v_mov_b32_e32 v38, v34
	v_mov_b32_e32 v39, v34
	v_mov_b32_e32 v40, v34
	v_mov_b32_e32 v41, v34
	v_mov_b32_e32 v42, v34
	v_mov_b32_e32 v43, v34
	v_mov_b32_e32 v44, v34
	v_mov_b32_e32 v45, v34
	v_mov_b32_e32 v46, v34
	v_mov_b32_e32 v47, v34
	v_mov_b32_e32 v48, v34
	v_mov_b32_e32 v49, v34
	v_mov_b32_e32 v50, v34
	v_mov_b32_e32 v51, v34
	v_mov_b32_e32 v52, v34
	v_mov_b32_e32 v53, v34
	v_mov_b32_e32 v54, v34
	v_mov_b32_e32 v55, v34
	v_mov_b32_e32 v56, v34
	v_mov_b32_e32 v57, v34
	v_mov_b32_e32 v58, v34
	v_mov_b32_e32 v59, v34
	v_mov_b32_e32 v60, v34
	v_mov_b32_e32 v61, v34
	v_mov_b32_e32 v62, v34
	v_mov_b32_e32 v63, v34
	v_mov_b32_e32 v64, v34
	v_mov_b32_e32 v65, v34
	v_mov_b32_e32 v66, v34
	v_mov_b32_e32 v67, v34
	v_mov_b32_e32 v68, v34
	v_mov_b32_e32 v69, v34
	v_mov_b32_e32 v70, v34
	v_mov_b32_e32 v71, v34
	v_mov_b32_e32 v72, v34
	v_mov_b32_e32 v73, v34
	v_mov_b32_e32 v74, v34
	v_mov_b32_e32 v75, v34
	v_mov_b32_e32 v76, v34
	v_mov_b32_e32 v77, v34
	v_mov_b32_e32 v78, v34
	v_mov_b32_e32 v79, v34
	v_mov_b32_e32 v80, v34
	v_mov_b32_e32 v81, v34
	v_mov_b32_e32 v82, v34
	v_mov_b32_e32 v83, v34
	v_mov_b32_e32 v84, v34
	v_mov_b32_e32 v85, v34
	v_mov_b32_e32 v86, v34
	v_mov_b32_e32 v87, v34
	v_mov_b32_e32 v88, v34
	v_mov_b32_e32 v89, v34
	v_mov_b32_e32 v90, v34
	v_mov_b32_e32 v91, v34
	v_mov_b32_e32 v92, v34
	v_mov_b32_e32 v93, v34
	v_mov_b32_e32 v94, v34
	v_mov_b32_e32 v95, v34
	v_mov_b32_e32 v96, v34
	v_mov_b32_e32 v97, v34
	s_waitcnt lgkmcnt(0)
	s_barrier
; DEV f32x4 mfma16(bf16x8 a, bf16x8 b, f32x4 c) { return __builtin_amdgcn_mfma_f32_16x16x32_bf16(a, b, c, 0, 0, 0); }
; template <int EPI, bool AF32>
; DEV void gemm_tile(const void* Ap, int lda, const u16* Bt, int ldb, int K, int m0, int n0, const Epi& ea, char* smem) {
;     ...
;   auto gload = [&](int kt) {
;     const int k0 = kt << 6;
; #pragma unroll
;     for (int i = 0; i < 4; i++) {
;       const int c = tid + i * 256, row = c >> 3, kc = c & 7;
;       if (AF32) {
;         const float* pa = (const float*)Ap + (size_t)(m0 + row) * lda + k0 + kc * 8;
;         rfa[2 * i] = *(const f32x4*)pa;
;         rfa[2 * i + 1] = *(const f32x4*)(pa + 4);
;       } else {
;         ra[i] = *(const u32x4*)((const u16*)Ap + (size_t)(m0 + row) * lda + k0 + kc * 8);
;       }
;       rb[i] = *(const u32x4*)(Bt + (size_t)(n0 + row) * ldb + k0 + kc * 8);
;     }
;   };
;   auto swrite = [&](int buf) {
; #pragma unroll
;     for (int i = 0; i < 4; i++) {
;       const int c = tid + i * 256, row = c >> 3, kc = c & 7;
;       u32x4 va;
;       if (AF32) {
;         va = (u32x4){pack2(rfa[2 * i][0], rfa[2 * i][1]), pack2(rfa[2 * i][2], rfa[2 * i][3]),
;                      pack2(rfa[2 * i + 1][0], rfa[2 * i + 1][1]), pack2(rfa[2 * i + 1][2], rfa[2 * i + 1][3])};
;       } else {
;         va = ra[i];
;       }
;       *(u32x4*)(sA + buf * 9216 + row * 72 + kc * 8) = va;
;       *(u32x4*)(sB + buf * 9216 + row * 72 + kc * 8) = rb[i];
;     }
;   };
;   gload(0);
;   swrite(0);
;   if (nk > 1) gload(1);
;   __syncthreads();
;   for (int kt = 0; kt < nk; kt++) {
;     const int buf = kt & 1;
;     if (kt + 1 < nk) swrite(buf ^ 1);
;     if (kt + 2 < nk) gload(kt + 2);
; #pragma unroll
;     for (int ks = 0; ks < 2; ks++) {
;       bf16x8 a[4], b[4];
; #pragma unroll
;       for (int m = 0; m < 4; m++) a[m] = *(const bf16x8*)(sA + buf * 9216 + (wr * 64 + m * 16 + fr) * 72 + ks * 32 + fq * 8);
; #pragma unroll
;       for (int n = 0; n < 4; n++) b[n] = *(const bf16x8*)(sB + buf * 9216 + (wc * 64 + n * 16 + fr) * 72 + ks * 32 + fq * 8);
;       __builtin_amdgcn_s_setprio(1);
; #pragma unroll
;       for (int m = 0; m < 4; m++)
; #pragma unroll
;         for (int n = 0; n < 4; n++) acc[m][n] = mfma16(a[m], b[n], acc[m][n]);
;       __builtin_amdgcn_s_setprio(0);
;     }
;     __syncthreads();
	v_lshl_add_u32 v161, v128, 1, v125
	v_lshl_add_u32 v129, v127, 1, v125
	s_mov_b32 s15, 0
	s_mov_b64 s[0:1], 0x100
	ds_read_b128 v[130:133], v161
	ds_read_b128 v[134:137], v161 offset:2304
	ds_read_b128 v[138:141], v161 offset:4608
	ds_read_b128 v[142:145], v161 offset:6912
	ds_read_b128 v[146:149], v129 offset:36864
	ds_read_b128 v[150:153], v129 offset:39168
	ds_read_b128 v[162:165], v129 offset:41472
	ds_read_b128 v[166:169], v129 offset:43776
.Lgk6_loop:
	s_waitcnt lgkmcnt(0)
	ds_read_b128 v[222:225], v161 offset:64
	ds_read_b128 v[226:229], v161 offset:2368
	ds_read_b128 v[230:233], v161 offset:4672
	ds_read_b128 v[234:237], v161 offset:6976
	ds_read_b128 v[238:241], v129 offset:36928
	ds_read_b128 v[242:245], v129 offset:39232
	ds_read_b128 v[246:249], v129 offset:41536
	ds_read_b128 v[250:253], v129 offset:43840
	v_mfma_f32_16x16x32_bf16 v[94:97], v[130:133], v[146:149], v[94:97]
	v_mfma_f32_16x16x32_bf16 v[90:93], v[130:133], v[150:153], v[90:93]
	v_mfma_f32_16x16x32_bf16 v[86:89], v[130:133], v[162:165], v[86:89]
	v_mfma_f32_16x16x32_bf16 v[82:85], v[130:133], v[166:169], v[82:85]
	s_waitcnt vmcnt(0)
	ds_write_b128 v122, v[22:25] offset:18432
	ds_write_b128 v122, v[6:9] offset:55296
	v_mfma_f32_16x16x32_bf16 v[78:81], v[134:137], v[146:149], v[78:81]
	ds_write_b128 v121, v[18:21] offset:18432
	ds_write_b128 v121, v[10:13] offset:55296
	v_mfma_f32_16x16x32_bf16 v[74:77], v[134:137], v[150:153], v[74:77]
	ds_write_b128 v120, v[14:17] offset:18432
	ds_write_b128 v120, v[2:5] offset:55296
	v_mfma_f32_16x16x32_bf16 v[70:73], v[134:137], v[162:165], v[70:73]
	ds_write_b128 v124, v[26:29] offset:18432
	ds_write_b128 v124, v[30:33] offset:55296
	v_mfma_f32_16x16x32_bf16 v[66:69], v[134:137], v[166:169], v[66:69]
	global_load_dwordx4 v[22:25], v112, s[10:11]
	v_mfma_f32_16x16x32_bf16 v[62:65], v[138:141], v[146:149], v[62:65]
	global_load_dwordx4 v[6:9], v110, s[8:9]
	v_mfma_f32_16x16x32_bf16 v[58:61], v[138:141], v[150:153], v[58:61]
	global_load_dwordx4 v[18:21], v108, s[10:11]
	v_mfma_f32_16x16x32_bf16 v[54:57], v[138:141], v[162:165], v[54:57]
	global_load_dwordx4 v[10:13], v106, s[8:9]
	v_mfma_f32_16x16x32_bf16 v[50:53], v[138:141], v[166:169], v[50:53]
	global_load_dwordx4 v[14:17], v104, s[10:11]
	v_mfma_f32_16x16x32_bf16 v[46:49], v[142:145], v[146:149], v[46:49]
	global_load_dwordx4 v[2:5], v102, s[8:9]
	v_mfma_f32_16x16x32_bf16 v[42:45], v[142:145], v[150:153], v[42:45]
	global_load_dwordx4 v[26:29], v100, s[10:11]
	v_mfma_f32_16x16x32_bf16 v[38:41], v[142:145], v[162:165], v[38:41]
	global_load_dwordx4 v[30:33], v98, s[8:9]
	v_mfma_f32_16x16x32_bf16 v[34:37], v[142:145], v[166:169], v[34:37]
	s_waitcnt lgkmcnt(0)
	s_barrier
	ds_read_b128 v[130:133], v161 offset:18432
	v_mfma_f32_16x16x32_bf16 v[94:97], v[222:225], v[238:241], v[94:97]
	ds_read_b128 v[134:137], v161 offset:20736
	v_mfma_f32_16x16x32_bf16 v[90:93], v[222:225], v[242:245], v[90:93]
	ds_read_b128 v[138:141], v161 offset:23040
	v_mfma_f32_16x16x32_bf16 v[86:89], v[222:225], v[246:249], v[86:89]
	ds_read_b128 v[142:145], v161 offset:25344
	v_mfma_f32_16x16x32_bf16 v[82:85], v[222:225], v[250:253], v[82:85]
	ds_read_b128 v[146:149], v129 offset:55296
	v_mfma_f32_16x16x32_bf16 v[78:81], v[226:229], v[238:241], v[78:81]
	ds_read_b128 v[150:153], v129 offset:57600
	v_mfma_f32_16x16x32_bf16 v[74:77], v[226:229], v[242:245], v[74:77]
	ds_read_b128 v[162:165], v129 offset:59904
	v_mfma_f32_16x16x32_bf16 v[70:73], v[226:229], v[246:249], v[70:73]
	ds_read_b128 v[166:169], v129 offset:62208
	v_mfma_f32_16x16x32_bf16 v[66:69], v[226:229], v[250:253], v[66:69]
	v_mfma_f32_16x16x32_bf16 v[62:65], v[230:233], v[238:241], v[62:65]
	v_mfma_f32_16x16x32_bf16 v[58:61], v[230:233], v[242:245], v[58:61]
	v_mfma_f32_16x16x32_bf16 v[54:57], v[230:233], v[246:249], v[54:57]
	v_mfma_f32_16x16x32_bf16 v[50:53], v[230:233], v[250:253], v[50:53]
	v_mfma_f32_16x16x32_bf16 v[46:49], v[234:237], v[238:241], v[46:49]
	v_mfma_f32_16x16x32_bf16 v[42:45], v[234:237], v[242:245], v[42:45]
	v_mfma_f32_16x16x32_bf16 v[38:41], v[234:237], v[246:249], v[38:41]
	v_mfma_f32_16x16x32_bf16 v[34:37], v[234:237], v[250:253], v[34:37]
	s_waitcnt lgkmcnt(0)
	ds_read_b128 v[222:225], v161 offset:18496
	ds_read_b128 v[226:229], v161 offset:20800
	ds_read_b128 v[230:233], v161 offset:23104
	ds_read_b128 v[234:237], v161 offset:25408
	ds_read_b128 v[238:241], v129 offset:55360
	ds_read_b128 v[242:245], v129 offset:57664
	ds_read_b128 v[246:249], v129 offset:59968
	ds_read_b128 v[250:253], v129 offset:62272
	v_mfma_f32_16x16x32_bf16 v[94:97], v[130:133], v[146:149], v[94:97]
	v_mfma_f32_16x16x32_bf16 v[90:93], v[130:133], v[150:153], v[90:93]
	v_mfma_f32_16x16x32_bf16 v[86:89], v[130:133], v[162:165], v[86:89]
	v_mfma_f32_16x16x32_bf16 v[82:85], v[130:133], v[166:169], v[82:85]
	s_waitcnt vmcnt(0)
	ds_write_b128 v122, v[22:25]
	ds_write_b128 v122, v[6:9] offset:36864
	v_mfma_f32_16x16x32_bf16 v[78:81], v[134:137], v[146:149], v[78:81]
	ds_write_b128 v121, v[18:21]
	ds_write_b128 v121, v[10:13] offset:36864
	v_mfma_f32_16x16x32_bf16 v[74:77], v[134:137], v[150:153], v[74:77]
	ds_write_b128 v120, v[14:17]
	ds_write_b128 v120, v[2:5] offset:36864
	v_mfma_f32_16x16x32_bf16 v[70:73], v[134:137], v[162:165], v[70:73]
	ds_write_b128 v124, v[26:29]
	ds_write_b128 v124, v[30:33] offset:36864
	v_mfma_f32_16x16x32_bf16 v[66:69], v[134:137], v[166:169], v[66:69]
	global_load_dwordx4 v[22:25], v112, s[10:11] offset:128
	v_mfma_f32_16x16x32_bf16 v[62:65], v[138:141], v[146:149], v[62:65]
	global_load_dwordx4 v[6:9], v110, s[8:9] offset:128
	v_mfma_f32_16x16x32_bf16 v[58:61], v[138:141], v[150:153], v[58:61]
	global_load_dwordx4 v[18:21], v108, s[10:11] offset:128
	v_mfma_f32_16x16x32_bf16 v[54:57], v[138:141], v[162:165], v[54:57]
	global_load_dwordx4 v[10:13], v106, s[8:9] offset:128
	v_mfma_f32_16x16x32_bf16 v[50:53], v[138:141], v[166:169], v[50:53]
	global_load_dwordx4 v[14:17], v104, s[10:11] offset:128
	v_mfma_f32_16x16x32_bf16 v[46:49], v[142:145], v[146:149], v[46:49]
	global_load_dwordx4 v[2:5], v102, s[8:9] offset:128
	v_mfma_f32_16x16x32_bf16 v[42:45], v[142:145], v[150:153], v[42:45]
	global_load_dwordx4 v[26:29], v100, s[10:11] offset:128
	v_mfma_f32_16x16x32_bf16 v[38:41], v[142:145], v[162:165], v[38:41]
	global_load_dwordx4 v[30:33], v98, s[8:9] offset:128
	v_mfma_f32_16x16x32_bf16 v[34:37], v[142:145], v[166:169], v[34:37]
	s_waitcnt lgkmcnt(0)
	s_barrier
; DEV f32x4 mfma16(bf16x8 a, bf16x8 b, f32x4 c) { return __builtin_amdgcn_mfma_f32_16x16x32_bf16(a, b, c, 0, 0, 0); }
; template <int EPI, bool AF32>
; DEV void gemm_tile(const void* Ap, int lda, const u16* Bt, int ldb, int K, int m0, int n0, const Epi& ea, char* smem) {
;     ...
;   auto gload = [&](int kt) {
;     const int k0 = kt << 6;
; #pragma unroll
;     for (int i = 0; i < 4; i++) {
;       const int c = tid + i * 256, row = c >> 3, kc = c & 7;
;       if (AF32) {
;         const float* pa = (const float*)Ap + (size_t)(m0 + row) * lda + k0 + kc * 8;
;         rfa[2 * i] = *(const f32x4*)pa;
;         rfa[2 * i + 1] = *(const f32x4*)(pa + 4);
;       } else {
;         ra[i] = *(const u32x4*)((const u16*)Ap + (size_t)(m0 + row) * lda + k0 + kc * 8);
;       }
;       rb[i] = *(const u32x4*)(Bt + (size_t)(n0 + row) * ldb + k0 + kc * 8);
;     }
;   };
;   auto swrite = [&](int buf) {
; #pragma unroll
;     for (int i = 0; i < 4; i++) {
;       const int c = tid + i * 256, row = c >> 3, kc = c & 7;
;       u32x4 va;
;       if (AF32) {
;         va = (u32x4){pack2(rfa[2 * i][0], rfa[2 * i][1]), pack2(rfa[2 * i][2], rfa[2 * i][3]),
;                      pack2(rfa[2 * i + 1][0], rfa[2 * i + 1][1]), pack2(rfa[2 * i + 1][2], rfa[2 * i + 1][3])};
;       } else {
;         va = ra[i];
;       }
;       *(u32x4*)(sA + buf * 9216 + row * 72 + kc * 8) = va;
;       *(u32x4*)(sB + buf * 9216 + row * 72 + kc * 8) = rb[i];
;     }
;   };
;   gload(0);
;   swrite(0);
;   if (nk > 1) gload(1);
;   __syncthreads();
;   for (int kt = 0; kt < nk; kt++) {
;     const int buf = kt & 1;
;     if (kt + 1 < nk) swrite(buf ^ 1);
;     if (kt + 2 < nk) gload(kt + 2);
; #pragma unroll
;     for (int ks = 0; ks < 2; ks++) {
;       bf16x8 a[4], b[4];
; #pragma unroll
;       for (int m = 0; m < 4; m++) a[m] = *(const bf16x8*)(sA + buf * 9216 + (wr * 64 + m * 16 + fr) * 72 + ks * 32 + fq * 8);
; #pragma unroll
;       for (int n = 0; n < 4; n++) b[n] = *(const bf16x8*)(sB + buf * 9216 + (wc * 64 + n * 16 + fr) * 72 + ks * 32 + fq * 8);
;       __builtin_amdgcn_s_setprio(1);
; #pragma unroll
;       for (int m = 0; m < 4; m++)
; #pragma unroll
;         for (int n = 0; n < 4; n++) acc[m][n] = mfma16(a[m], b[n], acc[m][n]);
;       __builtin_amdgcn_s_setprio(0);
;     }
;     __syncthreads();
	ds_read_b128 v[130:133], v161
	v_mfma_f32_16x16x32_bf16 v[94:97], v[222:225], v[238:241], v[94:97]
	ds_read_b128 v[134:137], v161 offset:2304
	v_mfma_f32_16x16x32_bf16 v[90:93], v[222:225], v[242:245], v[90:93]
	ds_read_b128 v[138:141], v161 offset:4608
	v_mfma_f32_16x16x32_bf16 v[86:89], v[222:225], v[246:249], v[86:89]
	ds_read_b128 v[142:145], v161 offset:6912
	v_mfma_f32_16x16x32_bf16 v[82:85], v[222:225], v[250:253], v[82:85]
	ds_read_b128 v[146:149], v129 offset:36864
	v_mfma_f32_16x16x32_bf16 v[78:81], v[226:229], v[238:241], v[78:81]
	ds_read_b128 v[150:153], v129 offset:39168
	v_mfma_f32_16x16x32_bf16 v[74:77], v[226:229], v[242:245], v[74:77]
	ds_read_b128 v[162:165], v129 offset:41472
	v_mfma_f32_16x16x32_bf16 v[70:73], v[226:229], v[246:249], v[70:73]
	ds_read_b128 v[166:169], v129 offset:43776
	v_mfma_f32_16x16x32_bf16 v[66:69], v[226:229], v[250:253], v[66:69]
	v_mfma_f32_16x16x32_bf16 v[62:65], v[230:233], v[238:241], v[62:65]
	v_add_u32_e32 v112, 0x100, v112
	v_mfma_f32_16x16x32_bf16 v[58:61], v[230:233], v[242:245], v[58:61]
	v_add_u32_e32 v110, 0x100, v110
	v_mfma_f32_16x16x32_bf16 v[54:57], v[230:233], v[246:249], v[54:57]
	v_add_u32_e32 v108, 0x100, v108
	v_mfma_f32_16x16x32_bf16 v[50:53], v[230:233], v[250:253], v[50:53]
	v_add_u32_e32 v106, 0x100, v106
	v_mfma_f32_16x16x32_bf16 v[46:49], v[234:237], v[238:241], v[46:49]
	v_add_u32_e32 v104, 0x100, v104
	v_mfma_f32_16x16x32_bf16 v[42:45], v[234:237], v[242:245], v[42:45]
	v_add_u32_e32 v102, 0x100, v102
	v_mfma_f32_16x16x32_bf16 v[38:41], v[234:237], v[246:249], v[38:41]
	v_add_u32_e32 v100, 0x100, v100
	v_mfma_f32_16x16x32_bf16 v[34:37], v[234:237], v[250:253], v[34:37]
	v_add_u32_e32 v98, 0x100, v98
	s_add_i32 s15, s15, 1
	s_cmp_lg_u32 s15, 7
	s_cbranch_scc1 .Lgk6_loop
	s_waitcnt lgkmcnt(0)
	ds_read_b128 v[222:225], v161 offset:64
	ds_read_b128 v[226:229], v161 offset:2368
	ds_read_b128 v[230:233], v161 offset:4672
	ds_read_b128 v[234:237], v161 offset:6976
	ds_read_b128 v[238:241], v129 offset:36928
	ds_read_b128 v[242:245], v129 offset:39232
	ds_read_b128 v[246:249], v129 offset:41536
	ds_read_b128 v[250:253], v129 offset:43840
	v_mfma_f32_16x16x32_bf16 v[94:97], v[130:133], v[146:149], v[94:97]
	v_mfma_f32_16x16x32_bf16 v[90:93], v[130:133], v[150:153], v[90:93]
	v_mfma_f32_16x16x32_bf16 v[86:89], v[130:133], v[162:165], v[86:89]
	v_mfma_f32_16x16x32_bf16 v[82:85], v[130:133], v[166:169], v[82:85]
	s_waitcnt vmcnt(0)
	ds_write_b128 v122, v[22:25] offset:18432
	ds_write_b128 v122, v[6:9] offset:55296
	v_mfma_f32_16x16x32_bf16 v[78:81], v[134:137], v[146:149], v[78:81]
	ds_write_b128 v121, v[18:21] offset:18432
	ds_write_b128 v121, v[10:13] offset:55296
	v_mfma_f32_16x16x32_bf16 v[74:77], v[134:137], v[150:153], v[74:77]
	ds_write_b128 v120, v[14:17] offset:18432
	ds_write_b128 v120, v[2:5] offset:55296
	v_mfma_f32_16x16x32_bf16 v[70:73], v[134:137], v[162:165], v[70:73]
	ds_write_b128 v124, v[26:29] offset:18432
	ds_write_b128 v124, v[30:33] offset:55296
	v_mfma_f32_16x16x32_bf16 v[66:69], v[134:137], v[166:169], v[66:69]
	v_mfma_f32_16x16x32_bf16 v[62:65], v[138:141], v[146:149], v[62:65]
	v_mfma_f32_16x16x32_bf16 v[58:61], v[138:141], v[150:153], v[58:61]
	v_mfma_f32_16x16x32_bf16 v[54:57], v[138:141], v[162:165], v[54:57]
	v_mfma_f32_16x16x32_bf16 v[50:53], v[138:141], v[166:169], v[50:53]
	v_mfma_f32_16x16x32_bf16 v[46:49], v[142:145], v[146:149], v[46:49]
	v_mfma_f32_16x16x32_bf16 v[42:45], v[142:145], v[150:153], v[42:45]
	v_mfma_f32_16x16x32_bf16 v[38:41], v[142:145], v[162:165], v[38:41]
	v_mfma_f32_16x16x32_bf16 v[34:37], v[142:145], v[166:169], v[34:37]
	s_waitcnt lgkmcnt(0)
	s_barrier
	ds_read_b128 v[130:133], v161 offset:18432
	v_mfma_f32_16x16x32_bf16 v[94:97], v[222:225], v[238:241], v[94:97]
	ds_read_b128 v[134:137], v161 offset:20736
	v_mfma_f32_16x16x32_bf16 v[90:93], v[222:225], v[242:245], v[90:93]
	ds_read_b128 v[138:141], v161 offset:23040
	v_mfma_f32_16x16x32_bf16 v[86:89], v[222:225], v[246:249], v[86:89]
	ds_read_b128 v[142:145], v161 offset:25344
	v_mfma_f32_16x16x32_bf16 v[82:85], v[222:225], v[250:253], v[82:85]
	ds_read_b128 v[146:149], v129 offset:55296
	v_mfma_f32_16x16x32_bf16 v[78:81], v[226:229], v[238:241], v[78:81]
	ds_read_b128 v[150:153], v129 offset:57600
	v_mfma_f32_16x16x32_bf16 v[74:77], v[226:229], v[242:245], v[74:77]
	ds_read_b128 v[162:165], v129 offset:59904
	v_mfma_f32_16x16x32_bf16 v[70:73], v[226:229], v[246:249], v[70:73]
	ds_read_b128 v[166:169], v129 offset:62208
	v_mfma_f32_16x16x32_bf16 v[66:69], v[226:229], v[250:253], v[66:69]
	v_mfma_f32_16x16x32_bf16 v[62:65], v[230:233], v[238:241], v[62:65]
	v_mfma_f32_16x16x32_bf16 v[58:61], v[230:233], v[242:245], v[58:61]
	v_mfma_f32_16x16x32_bf16 v[54:57], v[230:233], v[246:249], v[54:57]
	v_mfma_f32_16x16x32_bf16 v[50:53], v[230:233], v[250:253], v[50:53]
	v_mfma_f32_16x16x32_bf16 v[46:49], v[234:237], v[238:241], v[46:49]
	v_mfma_f32_16x16x32_bf16 v[42:45], v[234:237], v[242:245], v[42:45]
	v_mfma_f32_16x16x32_bf16 v[38:41], v[234:237], v[246:249], v[38:41]
	v_mfma_f32_16x16x32_bf16 v[34:37], v[234:237], v[250:253], v[34:37]
	s_waitcnt lgkmcnt(0)
; DEV float siluf(float x) { return x * __builtin_amdgcn_rcpf(1.f + __expf(-x)); }
; DEV f32x4 mfma16(bf16x8 a, bf16x8 b, f32x4 c) { return __builtin_amdgcn_mfma_f32_16x16x32_bf16(a, b, c, 0, 0, 0); }
; template <int EPI, bool AF32>
; DEV void gemm_tile(const void* Ap, int lda, const u16* Bt, int ldb, int K, int m0, int n0, const Epi& ea, char* smem) {
;     ...
;   for (int kt = 0; kt < nk; kt++) {
;     const int buf = kt & 1;
;     if (kt + 1 < nk) swrite(buf ^ 1);
;     if (kt + 2 < nk) gload(kt + 2);
; #pragma unroll
;     for (int ks = 0; ks < 2; ks++) {
;       bf16x8 a[4], b[4];
; #pragma unroll
;       for (int m = 0; m < 4; m++) a[m] = *(const bf16x8*)(sA + buf * 9216 + (wr * 64 + m * 16 + fr) * 72 + ks * 32 + fq * 8);
; #pragma unroll
;       for (int n = 0; n < 4; n++) b[n] = *(const bf16x8*)(sB + buf * 9216 + (wc * 64 + n * 16 + fr) * 72 + ks * 32 + fq * 8);
;       __builtin_amdgcn_s_setprio(1);
; #pragma unroll
;       for (int m = 0; m < 4; m++)
; #pragma unroll
;         for (int n = 0; n < 4; n++) acc[m][n] = mfma16(a[m], b[n], acc[m][n]);
;       __builtin_amdgcn_s_setprio(0);
;     }
;     __syncthreads();
;     ...
;       } else if (EPI == EP_SWIGLU) {
;         u16* C = (u16*)ea.p0;
;         const int jb = (cb >> 6) * 32;
; #pragma unroll
;         for (int n = 0; n < 2; n++)
;           __builtin_nontemporal_store(f2bf(siluf(acc[m][n][j]) * acc[m][n + 2][j]), &C[(size_t)row * 2816 + jb + n * 16 + fr]);
	ds_read_b128 v[222:225], v161 offset:18496
	ds_read_b128 v[226:229], v161 offset:20800
	ds_read_b128 v[230:233], v161 offset:23104
	ds_read_b128 v[234:237], v161 offset:25408
	ds_read_b128 v[238:241], v129 offset:55360
	ds_read_b128 v[242:245], v129 offset:57664
	ds_read_b128 v[246:249], v129 offset:59968
	ds_read_b128 v[250:253], v129 offset:62272
	v_mfma_f32_16x16x32_bf16 v[94:97], v[130:133], v[146:149], v[94:97]
	v_mfma_f32_16x16x32_bf16 v[90:93], v[130:133], v[150:153], v[90:93]
	v_mfma_f32_16x16x32_bf16 v[86:89], v[130:133], v[162:165], v[86:89]
	v_mfma_f32_16x16x32_bf16 v[82:85], v[130:133], v[166:169], v[82:85]
	v_mfma_f32_16x16x32_bf16 v[78:81], v[134:137], v[146:149], v[78:81]
	v_mfma_f32_16x16x32_bf16 v[74:77], v[134:137], v[150:153], v[74:77]
	v_mfma_f32_16x16x32_bf16 v[70:73], v[134:137], v[162:165], v[70:73]
	v_mfma_f32_16x16x32_bf16 v[66:69], v[134:137], v[166:169], v[66:69]
	v_mfma_f32_16x16x32_bf16 v[62:65], v[138:141], v[146:149], v[62:65]
	v_mfma_f32_16x16x32_bf16 v[58:61], v[138:141], v[150:153], v[58:61]
	v_mfma_f32_16x16x32_bf16 v[54:57], v[138:141], v[162:165], v[54:57]
	v_mfma_f32_16x16x32_bf16 v[50:53], v[138:141], v[166:169], v[50:53]
	v_mfma_f32_16x16x32_bf16 v[46:49], v[142:145], v[146:149], v[46:49]
	v_mfma_f32_16x16x32_bf16 v[42:45], v[142:145], v[150:153], v[42:45]
	v_mfma_f32_16x16x32_bf16 v[38:41], v[142:145], v[162:165], v[38:41]
	v_mfma_f32_16x16x32_bf16 v[34:37], v[142:145], v[166:169], v[34:37]
	s_waitcnt lgkmcnt(0)
	v_mfma_f32_16x16x32_bf16 v[26:29], v[230:233], v[238:241], v[62:65]
	v_mfma_f32_16x16x32_bf16 v[18:21], v[230:233], v[242:245], v[58:61]
	v_mfma_f32_16x16x32_bf16 v[30:33], v[230:233], v[246:249], v[54:57]
	v_mfma_f32_16x16x32_bf16 v[22:25], v[230:233], v[250:253], v[50:53]
	v_mfma_f32_16x16x32_bf16 v[10:13], v[234:237], v[238:241], v[46:49]
	v_mfma_f32_16x16x32_bf16 v[2:5], v[234:237], v[242:245], v[42:45]
	v_mfma_f32_16x16x32_bf16 v[14:17], v[234:237], v[246:249], v[38:41]
	v_mfma_f32_16x16x32_bf16 v[6:9], v[234:237], v[250:253], v[34:37]
	v_mfma_f32_16x16x32_bf16 v[58:61], v[222:225], v[238:241], v[94:97]
	v_mfma_f32_16x16x32_bf16 v[50:53], v[222:225], v[242:245], v[90:93]
	v_mfma_f32_16x16x32_bf16 v[62:65], v[222:225], v[246:249], v[86:89]
	v_mfma_f32_16x16x32_bf16 v[54:57], v[222:225], v[250:253], v[82:85]
	v_mfma_f32_16x16x32_bf16 v[42:45], v[226:229], v[238:241], v[78:81]
	v_mfma_f32_16x16x32_bf16 v[34:37], v[226:229], v[242:245], v[74:77]
	v_mfma_f32_16x16x32_bf16 v[46:49], v[226:229], v[246:249], v[70:73]
	v_mfma_f32_16x16x32_bf16 v[38:41], v[226:229], v[250:253], v[66:69]
	s_nop 7
	v_and_or_b32 v0, v114, 64, s14
	v_add_u32_e32 v66, s13, v117
	v_lshl_or_b32 v68, v116, 2, v66
	v_ashrrev_i32_e32 v66, 1, v0
	v_ashrrev_i32_e32 v67, 31, v66
	v_lshl_add_u64 v[66:67], v[66:67], 1, s[2:3]
	v_lshlrev_b32_e32 v0, 1, v115
	v_lshl_add_u64 v[66:67], v[66:67], 0, v[0:1]
	v_mul_f32_e32 v0, 0xbfb8aa3b, v58
	v_exp_f32_e32 v0, v0
	v_mad_i64_i32 v[70:71], s[0:1], v68, s54, v[66:67]
	v_add_f32_e32 v0, 1.0, v0
	v_rcp_f32_e32 v0, v0
	s_barrier
	v_mul_f32_e32 v0, v58, v0
	v_mul_f32_e32 v0, v62, v0
	v_cvt_pk_bf16_f32 v0, v0, s0
	global_store_short v[70:71], v0, off nt
	v_mul_f32_e32 v0, 0xbfb8aa3b, v50
	v_exp_f32_e32 v0, v0
	s_nop 0
	v_add_f32_e32 v0, 1.0, v0
	v_rcp_f32_e32 v0, v0
	s_nop 0
	v_mul_f32_e32 v0, v50, v0
	v_mul_f32_e32 v0, v54, v0
	v_cvt_pk_bf16_f32 v0, v0, s0
	global_store_short v[70:71], v0, off offset:32 nt
	v_or_b32_e32 v0, 1, v68
	v_mad_i64_i32 v[70:71], s[0:1], v0, s54, v[66:67]
	v_mul_f32_e32 v0, 0xbfb8aa3b, v59
	v_exp_f32_e32 v0, v0
	s_nop 0
	v_add_f32_e32 v0, 1.0, v0
	v_rcp_f32_e32 v0, v0
	s_nop 0
	v_mul_f32_e32 v0, v59, v0
	v_mul_f32_e32 v0, v63, v0
	v_cvt_pk_bf16_f32 v0, v0, s0
	global_store_short v[70:71], v0, off nt
	v_mul_f32_e32 v0, 0xbfb8aa3b, v51
	v_exp_f32_e32 v0, v0
	s_nop 0
	v_add_f32_e32 v0, 1.0, v0
	v_rcp_f32_e32 v0, v0
	s_nop 0
	v_mul_f32_e32 v0, v51, v0
	v_mul_f32_e32 v0, v55, v0
	v_cvt_pk_bf16_f32 v0, v0, s0
	global_store_short v[70:71], v0, off offset:32 nt
	v_or_b32_e32 v0, 2, v68
	v_mad_i64_i32 v[50:51], s[0:1], v0, s54, v[66:67]
	v_mul_f32_e32 v0, 0xbfb8aa3b, v60
	v_exp_f32_e32 v0, v0
	s_nop 0
	v_add_f32_e32 v0, 1.0, v0
	v_rcp_f32_e32 v0, v0
	s_nop 0
	v_mul_f32_e32 v0, v60, v0
	v_mul_f32_e32 v0, v64, v0
	v_cvt_pk_bf16_f32 v0, v0, s0
	global_store_short v[50:51], v0, off nt
	v_mul_f32_e32 v0, 0xbfb8aa3b, v52
	v_exp_f32_e32 v0, v0
	s_nop 0
	v_add_f32_e32 v0, 1.0, v0
	v_rcp_f32_e32 v0, v0
	s_nop 0
	v_mul_f32_e32 v0, v52, v0
	v_mul_f32_e32 v0, v56, v0
	v_cvt_pk_bf16_f32 v0, v0, s0
	global_store_short v[50:51], v0, off offset:32 nt
	v_or_b32_e32 v0, 3, v68
	v_mad_i64_i32 v[50:51], s[0:1], v0, s54, v[66:67]
	v_mul_f32_e32 v0, 0xbfb8aa3b, v61
	v_exp_f32_e32 v0, v0
	s_nop 0
	v_add_f32_e32 v0, 1.0, v0
	v_rcp_f32_e32 v0, v0
	s_nop 0
	v_mul_f32_e32 v0, v61, v0
	v_mul_f32_e32 v0, v65, v0
	v_cvt_pk_bf16_f32 v0, v0, s0
	global_store_short v[50:51], v0, off nt
	v_mul_f32_e32 v0, 0xbfb8aa3b, v53
	v_exp_f32_e32 v0, v0
	s_nop 0
	v_add_f32_e32 v0, 1.0, v0
	v_rcp_f32_e32 v0, v0
	s_nop 0
	v_mul_f32_e32 v0, v53, v0
	v_mul_f32_e32 v0, v57, v0
	v_cvt_pk_bf16_f32 v0, v0, s0
	global_store_short v[50:51], v0, off offset:32 nt
	v_or_b32_e32 v0, 16, v68
	v_mad_i64_i32 v[50:51], s[0:1], v0, s54, v[66:67]
	v_mul_f32_e32 v0, 0xbfb8aa3b, v42
	v_exp_f32_e32 v0, v0
	s_nop 0
	v_add_f32_e32 v0, 1.0, v0
	v_rcp_f32_e32 v0, v0
	s_nop 0
	v_mul_f32_e32 v0, v42, v0
	v_mul_f32_e32 v0, v46, v0
	v_cvt_pk_bf16_f32 v0, v0, s0
	global_store_short v[50:51], v0, off nt
	v_mul_f32_e32 v0, 0xbfb8aa3b, v34
	v_exp_f32_e32 v0, v0
	s_nop 0
	v_add_f32_e32 v0, 1.0, v0
	v_rcp_f32_e32 v0, v0
	s_nop 0
	v_mul_f32_e32 v0, v34, v0
; DEV int bidx() { int b = __builtin_amdgcn_readfirstlane(blockIdx.x); asm volatile("" : "+s"(b)); return b; }
; DEV int gdim() { int g = __builtin_amdgcn_readfirstlane(gridDim.x); asm volatile("" : "+s"(g)); return g; }
; DEV float siluf(float x) { return x * __builtin_amdgcn_rcpf(1.f + __expf(-x)); }
; template <int EPI, bool AF32>
; DEV void gemm_tile(const void* Ap, int lda, const u16* Bt, int ldb, int K, int m0, int n0, const Epi& ea, char* smem) {
;     ...
;       } else if (EPI == EP_SWIGLU) {
;         u16* C = (u16*)ea.p0;
;         const int jb = (cb >> 6) * 32;
; #pragma unroll
;         for (int n = 0; n < 2; n++)
;           __builtin_nontemporal_store(f2bf(siluf(acc[m][n][j]) * acc[m][n + 2][j]), &C[(size_t)row * 2816 + jb + n * 16 + fr]);
; template <int EPI, bool AF32>
; DEV void gemm_phase(const void* A, int lda, const u16* Bt, int ldb, int M, int N, int K, const Epi& ea, char* smem) {
;     ...
;   for (int tile = bidx(); tile < ntm * ntn; tile += gdim()) {
;     int m, n;
;     tile_mn(tile, ntm, ntn, m, n);
;     gemm_tile<EPI, AF32>(A, lda, Bt, ldb, K, m << 7, n << 7, ea, smem);
;   }
	v_mul_f32_e32 v0, v38, v0
	v_cvt_pk_bf16_f32 v0, v0, s0
	global_store_short v[50:51], v0, off offset:32 nt
	v_or_b32_e32 v0, 17, v68
	v_mad_i64_i32 v[50:51], s[0:1], v0, s54, v[66:67]
	v_mul_f32_e32 v0, 0xbfb8aa3b, v43
	v_exp_f32_e32 v0, v0
	s_nop 0
	v_add_f32_e32 v0, 1.0, v0
	v_rcp_f32_e32 v0, v0
	s_nop 0
	v_mul_f32_e32 v0, v43, v0
	v_mul_f32_e32 v0, v47, v0
	v_cvt_pk_bf16_f32 v0, v0, s0
	global_store_short v[50:51], v0, off nt
	v_mul_f32_e32 v0, 0xbfb8aa3b, v35
	v_exp_f32_e32 v0, v0
	s_nop 0
	v_add_f32_e32 v0, 1.0, v0
	v_rcp_f32_e32 v0, v0
	s_nop 0
	v_mul_f32_e32 v0, v35, v0
	v_mul_f32_e32 v0, v39, v0
	v_cvt_pk_bf16_f32 v0, v0, s0
	global_store_short v[50:51], v0, off offset:32 nt
	v_or_b32_e32 v0, 18, v68
	v_mad_i64_i32 v[34:35], s[0:1], v0, s54, v[66:67]
	v_mul_f32_e32 v0, 0xbfb8aa3b, v44
	v_exp_f32_e32 v0, v0
	s_nop 0
	v_add_f32_e32 v0, 1.0, v0
	v_rcp_f32_e32 v0, v0
	s_nop 0
	v_mul_f32_e32 v0, v44, v0
	v_mul_f32_e32 v0, v48, v0
	v_cvt_pk_bf16_f32 v0, v0, s0
	global_store_short v[34:35], v0, off nt
	v_mul_f32_e32 v0, 0xbfb8aa3b, v36
	v_exp_f32_e32 v0, v0
	s_nop 0
	v_add_f32_e32 v0, 1.0, v0
	v_rcp_f32_e32 v0, v0
	s_nop 0
	v_mul_f32_e32 v0, v36, v0
	v_mul_f32_e32 v0, v40, v0
	v_cvt_pk_bf16_f32 v0, v0, s0
	global_store_short v[34:35], v0, off offset:32 nt
	v_or_b32_e32 v0, 19, v68
	v_mad_i64_i32 v[34:35], s[0:1], v0, s54, v[66:67]
	v_mul_f32_e32 v0, 0xbfb8aa3b, v45
	v_exp_f32_e32 v0, v0
	s_nop 0
	v_add_f32_e32 v0, 1.0, v0
	v_rcp_f32_e32 v0, v0
	s_nop 0
	v_mul_f32_e32 v0, v45, v0
	v_mul_f32_e32 v0, v49, v0
	v_cvt_pk_bf16_f32 v0, v0, s0
	global_store_short v[34:35], v0, off nt
	v_mul_f32_e32 v0, 0xbfb8aa3b, v37
	v_exp_f32_e32 v0, v0
	s_nop 0
	v_add_f32_e32 v0, 1.0, v0
	v_rcp_f32_e32 v0, v0
	s_nop 0
	v_mul_f32_e32 v0, v37, v0
	v_mul_f32_e32 v0, v41, v0
	v_cvt_pk_bf16_f32 v0, v0, s0
	global_store_short v[34:35], v0, off offset:32 nt
	v_or_b32_e32 v0, 32, v68
	v_mad_i64_i32 v[34:35], s[0:1], v0, s54, v[66:67]
	v_mul_f32_e32 v0, 0xbfb8aa3b, v26
	v_exp_f32_e32 v0, v0
	s_nop 0
	v_add_f32_e32 v0, 1.0, v0
	v_rcp_f32_e32 v0, v0
	s_nop 0
	v_mul_f32_e32 v0, v26, v0
	v_mul_f32_e32 v0, v30, v0
	v_cvt_pk_bf16_f32 v0, v0, s0
	global_store_short v[34:35], v0, off nt
	v_mul_f32_e32 v0, 0xbfb8aa3b, v18
	v_exp_f32_e32 v0, v0
	s_nop 0
	v_add_f32_e32 v0, 1.0, v0
	v_rcp_f32_e32 v0, v0
	s_nop 0
	v_mul_f32_e32 v0, v18, v0
	v_mul_f32_e32 v0, v22, v0
	v_cvt_pk_bf16_f32 v0, v0, s0
	global_store_short v[34:35], v0, off offset:32 nt
	v_or_b32_e32 v0, 33, v68
	v_mad_i64_i32 v[34:35], s[0:1], v0, s54, v[66:67]
	v_mul_f32_e32 v0, 0xbfb8aa3b, v27
	v_exp_f32_e32 v0, v0
	s_nop 0
	v_add_f32_e32 v0, 1.0, v0
	v_rcp_f32_e32 v0, v0
	s_nop 0
	v_mul_f32_e32 v0, v27, v0
	v_mul_f32_e32 v0, v31, v0
	v_cvt_pk_bf16_f32 v0, v0, s0
	global_store_short v[34:35], v0, off nt
	v_mul_f32_e32 v0, 0xbfb8aa3b, v19
	v_exp_f32_e32 v0, v0
	s_nop 0
	v_add_f32_e32 v0, 1.0, v0
	v_rcp_f32_e32 v0, v0
	s_nop 0
	v_mul_f32_e32 v0, v19, v0
	v_mul_f32_e32 v0, v23, v0
	v_cvt_pk_bf16_f32 v0, v0, s0
	global_store_short v[34:35], v0, off offset:32 nt
	v_or_b32_e32 v0, 34, v68
	v_mad_i64_i32 v[18:19], s[0:1], v0, s54, v[66:67]
	v_mul_f32_e32 v0, 0xbfb8aa3b, v28
	v_exp_f32_e32 v0, v0
	s_nop 0
	v_add_f32_e32 v0, 1.0, v0
	v_rcp_f32_e32 v0, v0
	s_nop 0
	v_mul_f32_e32 v0, v28, v0
	v_mul_f32_e32 v0, v32, v0
	v_cvt_pk_bf16_f32 v0, v0, s0
	global_store_short v[18:19], v0, off nt
	v_mul_f32_e32 v0, 0xbfb8aa3b, v20
	v_exp_f32_e32 v0, v0
	s_nop 0
	v_add_f32_e32 v0, 1.0, v0
	v_rcp_f32_e32 v0, v0
	s_nop 0
	v_mul_f32_e32 v0, v20, v0
	v_mul_f32_e32 v0, v24, v0
	v_cvt_pk_bf16_f32 v0, v0, s0
	global_store_short v[18:19], v0, off offset:32 nt
	v_or_b32_e32 v0, 35, v68
	v_mad_i64_i32 v[18:19], s[0:1], v0, s54, v[66:67]
	v_mul_f32_e32 v0, 0xbfb8aa3b, v29
	v_exp_f32_e32 v0, v0
	s_nop 0
	v_add_f32_e32 v0, 1.0, v0
	v_rcp_f32_e32 v0, v0
	s_nop 0
	v_mul_f32_e32 v0, v29, v0
	v_mul_f32_e32 v0, v33, v0
	v_cvt_pk_bf16_f32 v0, v0, s0
	global_store_short v[18:19], v0, off nt
	v_mul_f32_e32 v0, 0xbfb8aa3b, v21
	v_exp_f32_e32 v0, v0
	s_nop 0
	v_add_f32_e32 v0, 1.0, v0
	v_rcp_f32_e32 v0, v0
	s_nop 0
	v_mul_f32_e32 v0, v21, v0
	v_mul_f32_e32 v0, v25, v0
	v_cvt_pk_bf16_f32 v0, v0, s0
	global_store_short v[18:19], v0, off offset:32 nt
	v_or_b32_e32 v0, 48, v68
	v_mad_i64_i32 v[18:19], s[0:1], v0, s54, v[66:67]
	v_mul_f32_e32 v0, 0xbfb8aa3b, v10
	v_exp_f32_e32 v0, v0
	s_nop 0
	v_add_f32_e32 v0, 1.0, v0
	v_rcp_f32_e32 v0, v0
	s_nop 0
	v_mul_f32_e32 v0, v10, v0
	v_mul_f32_e32 v0, v14, v0
	v_cvt_pk_bf16_f32 v0, v0, s0
	global_store_short v[18:19], v0, off nt
	v_mul_f32_e32 v0, 0xbfb8aa3b, v2
	v_exp_f32_e32 v0, v0
	s_nop 0
	v_add_f32_e32 v0, 1.0, v0
	v_rcp_f32_e32 v0, v0
	s_nop 0
	v_mul_f32_e32 v0, v2, v0
	v_mul_f32_e32 v0, v6, v0
	v_cvt_pk_bf16_f32 v0, v0, s0
	global_store_short v[18:19], v0, off offset:32 nt
	v_or_b32_e32 v0, 49, v68
	v_mad_i64_i32 v[18:19], s[0:1], v0, s54, v[66:67]
	v_mul_f32_e32 v0, 0xbfb8aa3b, v11
	v_exp_f32_e32 v0, v0
	s_nop 0
	v_add_f32_e32 v0, 1.0, v0
	v_rcp_f32_e32 v0, v0
	s_nop 0
	v_mul_f32_e32 v0, v11, v0
	v_mul_f32_e32 v0, v15, v0
	v_cvt_pk_bf16_f32 v0, v0, s0
	global_store_short v[18:19], v0, off nt
	v_mul_f32_e32 v0, 0xbfb8aa3b, v3
	v_exp_f32_e32 v0, v0
	s_nop 0
	v_add_f32_e32 v0, 1.0, v0
	v_rcp_f32_e32 v0, v0
	s_nop 0
	v_mul_f32_e32 v0, v3, v0
	v_mul_f32_e32 v0, v7, v0
	v_cvt_pk_bf16_f32 v0, v0, s0
	global_store_short v[18:19], v0, off offset:32 nt
	v_or_b32_e32 v0, 50, v68
	v_mad_i64_i32 v[2:3], s[0:1], v0, s54, v[66:67]
	v_mul_f32_e32 v0, 0xbfb8aa3b, v12
	v_exp_f32_e32 v0, v0
	s_nop 0
	v_add_f32_e32 v0, 1.0, v0
	v_rcp_f32_e32 v0, v0
	s_nop 0
	v_mul_f32_e32 v0, v12, v0
	v_mul_f32_e32 v0, v16, v0
	v_cvt_pk_bf16_f32 v0, v0, s0
	global_store_short v[2:3], v0, off nt
	v_mul_f32_e32 v0, 0xbfb8aa3b, v4
	v_exp_f32_e32 v0, v0
	s_nop 0
	v_add_f32_e32 v0, 1.0, v0
	v_rcp_f32_e32 v0, v0
	s_nop 0
	v_mul_f32_e32 v0, v4, v0
	v_mul_f32_e32 v0, v8, v0
	v_cvt_pk_bf16_f32 v0, v0, s0
	global_store_short v[2:3], v0, off offset:32 nt
	v_or_b32_e32 v0, 51, v68
	v_mad_i64_i32 v[2:3], s[0:1], v0, s54, v[66:67]
	v_mul_f32_e32 v0, 0xbfb8aa3b, v13
	v_exp_f32_e32 v0, v0
	s_nop 0
	v_add_f32_e32 v0, 1.0, v0
	v_rcp_f32_e32 v0, v0
	s_nop 0
	v_mul_f32_e32 v0, v13, v0
	v_mul_f32_e32 v0, v17, v0
	v_cvt_pk_bf16_f32 v0, v0, s0
	global_store_short v[2:3], v0, off nt
	v_mul_f32_e32 v0, 0xbfb8aa3b, v5
	v_exp_f32_e32 v0, v0
	s_nop 0
	v_add_f32_e32 v0, 1.0, v0
	v_rcp_f32_e32 v0, v0
	s_nop 0
	v_mul_f32_e32 v0, v5, v0
	v_mul_f32_e32 v0, v9, v0
	v_cvt_pk_bf16_f32 v0, v0, s0
	v_readfirstlane_b32 s0, v198
	global_store_short v[2:3], v0, off offset:32 nt
	s_add_i32 s12, s0, s12
	s_cmpk_lt_i32 s12, 0x2cb0
	s_cbranch_scc1 .LBB0_1436

; DEV int tidx() { int t = threadIdx.x; asm volatile("" : "+v"(t)); return t; }
; template <int EPI, bool AF32>
; DEV void gemm_tile(const void* Ap, int lda, const u16* Bt, int ldb, int K, int m0, int n0, const Epi& ea, char* smem) {
;   u16* sA = (u16*)smem;
;   u16* sB = sA + 2 * 128 * 72;
;   const int tid = tidx(), lane = tid & 63, wv = tid >> 6;
;   const int wr = wv >> 1, wc = wv & 1, fr = lane & 15, fq = lane >> 4;
;   f32x4 acc[4][4];
; #pragma unroll
;   for (int m = 0; m < 4; m++)
; #pragma unroll
;     for (int n = 0; n < 4; n++) acc[m][n] = (f32x4){0.f, 0.f, 0.f, 0.f};
;   u32x4 ra[4], rb[4];
;   f32x4 rfa[8];
;   const int nk = K >> 6;
;   auto gload = [&](int kt) {
;     const int k0 = kt << 6;
; #pragma unroll
;     for (int i = 0; i < 4; i++) {
;       const int c = tid + i * 256, row = c >> 3, kc = c & 7;
;       if (AF32) {
;         const float* pa = (const float*)Ap + (size_t)(m0 + row) * lda + k0 + kc * 8;
;         rfa[2 * i] = *(const f32x4*)pa;
;         rfa[2 * i + 1] = *(const f32x4*)(pa + 4);
;       } else {
;         ra[i] = *(const u32x4*)((const u16*)Ap + (size_t)(m0 + row) * lda + k0 + kc * 8);
;       }
;       rb[i] = *(const u32x4*)(Bt + (size_t)(n0 + row) * ldb + k0 + kc * 8);
;     }
;   };
;   auto swrite = [&](int buf) {
; #pragma unroll
;     for (int i = 0; i < 4; i++) {
;       const int c = tid + i * 256, row = c >> 3, kc = c & 7;
;       u32x4 va;
;       if (AF32) {
;         va = (u32x4){pack2(rfa[2 * i][0], rfa[2 * i][1]), pack2(rfa[2 * i][2], rfa[2 * i][3]),
;                      pack2(rfa[2 * i + 1][0], rfa[2 * i + 1][1]), pack2(rfa[2 * i + 1][2], rfa[2 * i + 1][3])};
;       } else {
;         va = ra[i];
;       }
;       *(u32x4*)(sA + buf * 9216 + row * 72 + kc * 8) = va;
;       *(u32x4*)(sB + buf * 9216 + row * 72 + kc * 8) = rb[i];
;     }
;   };
;   gload(0);
;   swrite(0);
;   if (nk > 1) gload(1);
;   __syncthreads();
.LBB0_1478:
	s_ashr_i32 s0, s14, 31
	s_lshr_b32 s0, s0, 24
	s_add_i32 s0, s14, s0
	s_ashr_i32 s1, s0, 8
	s_and_b32 s0, s0, 0xffffff00
	s_lshl_b32 s16, s1, 5
	s_sub_i32 s15, s14, s0
	s_sub_i32 s0, 0x104, s16
	s_min_u32 s17, s0, 32
	v_cvt_f32_ubyte0_e32 v2, s17
	v_cvt_f32_i32_e32 v0, s15
	v_rcp_iflag_f32_e32 v3, v2
	s_ashr_i32 s0, s15, 30
	s_or_b32 s18, s0, 1
	s_waitcnt vmcnt(12)
	v_mov_b32_e32 v116, v157
	v_mul_f32_e32 v3, v0, v3
	v_trunc_f32_e32 v3, v3
	v_fma_f32 v0, -v3, v2, v0
	v_cvt_i32_f32_e32 v3, v3
	v_cmp_ge_f32_e64 s[0:1], |v0|, v2
	s_and_b64 s[0:1], s[0:1], exec
	s_cselect_b32 s0, s18, 0
	v_readfirstlane_b32 s1, v3
	s_add_i32 s0, s1, s0
	s_sext_i32_i16 s1, s0
	s_mul_i32 s0, s0, s17
	s_sub_i32 s0, s15, s0
	s_sext_i32_i16 s0, s0
	s_add_i32 s16, s16, s0
	s_lshl_b32 s16, s16, 7
	v_mov_b64_e32 v[2:3], s[6:7]
	v_ashrrev_i32_e32 v54, 3, v116
	v_lshlrev_b32_e32 v0, 3, v116
	v_add_u32_e32 v62, s16, v54
	v_and_b32_e32 v0, 56, v0
	s_lshl_b32 s15, s1, 7
	v_mad_i64_i32 v[4:5], s[0:1], v62, s54, v[2:3]
	v_lshlrev_b32_e32 v0, 1, v0
	v_add_u32_e32 v18, 0x100, v116
	v_add_u32_e32 v26, 0x200, v116
	v_lshl_add_u64 v[6:7], v[4:5], 0, v[0:1]
	v_add_u32_e32 v55, s15, v54
	v_mov_b64_e32 v[4:5], s[8:9]
	v_ashrrev_i32_e32 v70, 3, v18
	v_ashrrev_i32_e32 v71, 3, v26
	v_mad_i64_i32 v[8:9], s[0:1], v55, s54, v[4:5]
	v_add_u32_e32 v64, s16, v70
	v_add_u32_e32 v56, s15, v70
	v_add_u32_e32 v66, s16, v71
	v_add_u32_e32 v58, s15, v71
	v_lshl_add_u64 v[8:9], v[8:9], 0, v[0:1]
	v_mad_i64_i32 v[18:19], s[0:1], v64, s54, v[2:3]
	v_mad_i64_i32 v[22:23], s[0:1], v56, s54, v[4:5]
	v_mad_i64_i32 v[26:27], s[0:1], v66, s54, v[2:3]
	v_mad_i64_i32 v[30:31], s[0:1], v58, s54, v[4:5]
	global_load_dwordx4 v[14:17], v[8:9], off
	v_lshl_add_u64 v[42:43], v[18:19], 0, v[0:1]
	v_lshl_add_u64 v[44:45], v[22:23], 0, v[0:1]
	v_lshl_add_u64 v[46:47], v[26:27], 0, v[0:1]
	v_lshl_add_u64 v[48:49], v[30:31], 0, v[0:1]
	global_load_dwordx4 v[10:13], v[6:7], off
	global_load_dwordx4 v[18:21], v[42:43], off
	global_load_dwordx4 v[22:25], v[44:45], off
	global_load_dwordx4 v[26:29], v[46:47], off
	global_load_dwordx4 v[30:33], v[48:49], off
	v_add_u32_e32 v34, 0x300, v116
	v_ashrrev_i32_e32 v72, 3, v34
	v_add_u32_e32 v68, s16, v72
	v_mad_i64_i32 v[2:3], s[0:1], v68, s54, v[2:3]
	v_lshl_add_u64 v[50:51], v[2:3], 0, v[0:1]
	global_load_dwordx4 v[34:37], v[50:51], off
	v_add_u32_e32 v60, s15, v72
	v_mad_i64_i32 v[2:3], s[0:1], v60, s54, v[4:5]
	s_waitcnt vmcnt(18)
	v_mul_lo_u32 v119, v54, s71
	v_lshl_add_u64 v[52:53], v[2:3], 0, v[0:1]
	v_bfe_u32 v161, v157, 3, 4
	v_add_u32_e32 v161, 4, v161
	v_lshlrev_b32_e32 v161, 1, v161
	v_and_b32_e32 v161, 16, v161
	v_xor_b32_e32 v129, v0, v161
	v_lshl_add_u32 v118, v119, 1, v129
	v_mul_lo_u32 v121, v70, s71
	s_waitcnt vmcnt(17)
	v_mul_lo_u32 v124, v71, s71
	global_load_dwordx4 v[38:41], v[52:53], off
	global_load_dwordx4 v[2:5], v[8:9], off offset:128
	v_lshl_add_u32 v120, v121, 1, v129
	global_load_dwordx4 v[6:9], v[6:7], off offset:128
	v_lshl_add_u32 v122, v124, 1, v129
	s_waitcnt vmcnt(19)
	v_mul_lo_u32 v126, v72, s71
	v_lshl_add_u32 v123, v126, 1, v129
	v_and_b32_e32 v114, 15, v116
	v_mad_i64_i32 v[54:55], s[0:1], v55, s54, 0
	v_mad_i64_i32 v[56:57], s[0:1], v56, s54, 0
	v_mad_i64_i32 v[58:59], s[0:1], v58, s54, 0
	v_mad_i64_i32 v[60:61], s[0:1], v60, s54, 0
	v_mad_i64_i32 v[62:63], s[0:1], v62, s54, 0
	v_mad_i64_i32 v[64:65], s[0:1], v64, s54, 0
	v_mad_i64_i32 v[66:67], s[0:1], v66, s54, 0
	v_mad_i64_i32 v[68:69], s[0:1], v68, s54, 0
	s_waitcnt vmcnt(9)
	ds_write_b128 v118, v[14:17] offset:36864
	s_waitcnt vmcnt(8)
	ds_write_b128 v118, v[10:13]
	global_load_dwordx4 v[10:13], v[42:43], off offset:128
	s_waitcnt vmcnt(8)
	ds_write_b128 v120, v[18:21]
	global_load_dwordx4 v[14:17], v[44:45], off offset:128
	s_waitcnt vmcnt(8)
	ds_write_b128 v120, v[22:25] offset:36864
	global_load_dwordx4 v[18:21], v[46:47], off offset:128
	s_waitcnt vmcnt(8)
	ds_write_b128 v122, v[26:29]
	global_load_dwordx4 v[22:25], v[48:49], off offset:128
	s_waitcnt vmcnt(8)
	ds_write_b128 v122, v[30:33] offset:36864
	global_load_dwordx4 v[26:29], v[50:51], off offset:128
	global_load_dwordx4 v[30:33], v[52:53], off offset:128
	v_bfe_u32 v115, v116, 4, 2
	s_waitcnt vmcnt(9)
	ds_write_b128 v123, v[34:37]
	v_ashrrev_i32_e32 v34, 1, v116
	v_and_b32_e32 v117, 0xffffffc0, v34
	v_or_b32_e32 v34, v117, v114
	v_mul_lo_u32 v128, v34, s71
	v_lshlrev_b32_e32 v34, 4, v116
	v_and_b32_e32 v34, 0x70, v34
	v_and_b32_e32 v35, 0x4f, v116
	v_or_b32_e32 v60, v60, v34
	v_or_b32_e32 v68, v68, v34
	v_or_b32_e32 v58, v58, v34
	v_or_b32_e32 v66, v66, v34
	v_or_b32_e32 v56, v56, v34
	v_or_b32_e32 v64, v64, v34
	v_or_b32_e32 v54, v54, v34
	v_or_b32_e32 v62, v62, v34
	v_mov_b32_e32 v34, 0
	s_mov_b32 s17, 0
	s_waitcnt vmcnt(8)
	ds_write_b128 v123, v[38:41] offset:36864
	v_lshlrev_b32_e32 v125, 4, v115
	v_and_b32_e32 v161, 15, v157
	v_add_u32_e32 v161, 4, v161
	v_lshlrev_b32_e32 v161, 1, v161
	v_and_b32_e32 v161, 16, v161
	v_xor_b32_e32 v125, v125, v161
	v_mul_u32_u24_e32 v127, 0x48, v35
	v_mov_b32_e32 v98, v60
	v_mov_b32_e32 v100, v68
	v_mov_b32_e32 v102, v58
	v_mov_b32_e32 v104, v66
	v_mov_b32_e32 v106, v56
	v_mov_b32_e32 v108, v64
	v_mov_b32_e32 v110, v54
	v_mov_b32_e32 v112, v62
	s_mov_b64 s[0:1], 0
	v_mov_b32_e32 v35, v34
	v_mov_b32_e32 v36, v34
	v_mov_b32_e32 v37, v34
	v_mov_b32_e32 v38, v34
	v_mov_b32_e32 v39, v34
	v_mov_b32_e32 v40, v34
	v_mov_b32_e32 v41, v34
	v_mov_b32_e32 v42, v34
	v_mov_b32_e32 v43, v34
	v_mov_b32_e32 v44, v34
	v_mov_b32_e32 v45, v34
	v_mov_b32_e32 v46, v34
	v_mov_b32_e32 v47, v34
	v_mov_b32_e32 v48, v34
	v_mov_b32_e32 v49, v34
	v_mov_b32_e32 v50, v34
	v_mov_b32_e32 v51, v34
	v_mov_b32_e32 v52, v34
	v_mov_b32_e32 v53, v34
	v_mov_b32_e32 v54, v34
	v_mov_b32_e32 v55, v34
	v_mov_b32_e32 v56, v34
	v_mov_b32_e32 v57, v34
	v_mov_b32_e32 v58, v34
	v_mov_b32_e32 v59, v34
	v_mov_b32_e32 v60, v34
	v_mov_b32_e32 v61, v34
	v_mov_b32_e32 v62, v34
	v_mov_b32_e32 v63, v34
	v_mov_b32_e32 v64, v34
	v_mov_b32_e32 v65, v34
	v_mov_b32_e32 v66, v34
	v_mov_b32_e32 v67, v34
	v_mov_b32_e32 v68, v34
	v_mov_b32_e32 v69, v34
	v_mov_b32_e32 v70, v34
	v_mov_b32_e32 v71, v34
	v_mov_b32_e32 v72, v34
	v_mov_b32_e32 v73, v34
	v_mov_b32_e32 v74, v34
	v_mov_b32_e32 v75, v34
	v_mov_b32_e32 v76, v34
	v_mov_b32_e32 v77, v34
	v_mov_b32_e32 v78, v34
	v_mov_b32_e32 v79, v34
	v_mov_b32_e32 v80, v34
	v_mov_b32_e32 v81, v34
	v_mov_b32_e32 v82, v34
	v_mov_b32_e32 v83, v34
	v_mov_b32_e32 v84, v34
	v_mov_b32_e32 v85, v34
	v_mov_b32_e32 v86, v34
	v_mov_b32_e32 v87, v34
	v_mov_b32_e32 v88, v34
	v_mov_b32_e32 v89, v34
	v_mov_b32_e32 v90, v34
	v_mov_b32_e32 v91, v34
	v_mov_b32_e32 v92, v34
	v_mov_b32_e32 v93, v34
	v_mov_b32_e32 v94, v34
	v_mov_b32_e32 v95, v34
	v_mov_b32_e32 v96, v34
	v_mov_b32_e32 v97, v34
	s_waitcnt lgkmcnt(0)
	s_barrier
; DEV f32x4 mfma16(bf16x8 a, bf16x8 b, f32x4 c) { return __builtin_amdgcn_mfma_f32_16x16x32_bf16(a, b, c, 0, 0, 0); }
; template <int EPI, bool AF32>
; DEV void gemm_tile(const void* Ap, int lda, const u16* Bt, int ldb, int K, int m0, int n0, const Epi& ea, char* smem) {
;     ...
;   auto gload = [&](int kt) {
;     const int k0 = kt << 6;
; #pragma unroll
;     for (int i = 0; i < 4; i++) {
;       const int c = tid + i * 256, row = c >> 3, kc = c & 7;
;       if (AF32) {
;         const float* pa = (const float*)Ap + (size_t)(m0 + row) * lda + k0 + kc * 8;
;         rfa[2 * i] = *(const f32x4*)pa;
;         rfa[2 * i + 1] = *(const f32x4*)(pa + 4);
;       } else {
;         ra[i] = *(const u32x4*)((const u16*)Ap + (size_t)(m0 + row) * lda + k0 + kc * 8);
;       }
;       rb[i] = *(const u32x4*)(Bt + (size_t)(n0 + row) * ldb + k0 + kc * 8);
;     }
;   };
;   auto swrite = [&](int buf) {
; #pragma unroll
;     for (int i = 0; i < 4; i++) {
;       const int c = tid + i * 256, row = c >> 3, kc = c & 7;
;       u32x4 va;
;       if (AF32) {
;         va = (u32x4){pack2(rfa[2 * i][0], rfa[2 * i][1]), pack2(rfa[2 * i][2], rfa[2 * i][3]),
;                      pack2(rfa[2 * i + 1][0], rfa[2 * i + 1][1]), pack2(rfa[2 * i + 1][2], rfa[2 * i + 1][3])};
;       } else {
;         va = ra[i];
;       }
;       *(u32x4*)(sA + buf * 9216 + row * 72 + kc * 8) = va;
;       *(u32x4*)(sB + buf * 9216 + row * 72 + kc * 8) = rb[i];
;     }
;   };
;   gload(0);
;   swrite(0);
;   if (nk > 1) gload(1);
;   __syncthreads();
;   for (int kt = 0; kt < nk; kt++) {
;     const int buf = kt & 1;
;     if (kt + 1 < nk) swrite(buf ^ 1);
;     if (kt + 2 < nk) gload(kt + 2);
; #pragma unroll
;     for (int ks = 0; ks < 2; ks++) {
;       bf16x8 a[4], b[4];
; #pragma unroll
;       for (int m = 0; m < 4; m++) a[m] = *(const bf16x8*)(sA + buf * 9216 + (wr * 64 + m * 16 + fr) * 72 + ks * 32 + fq * 8);
; #pragma unroll
;       for (int n = 0; n < 4; n++) b[n] = *(const bf16x8*)(sB + buf * 9216 + (wc * 64 + n * 16 + fr) * 72 + ks * 32 + fq * 8);
;       __builtin_amdgcn_s_setprio(1);
; #pragma unroll
;       for (int m = 0; m < 4; m++)
; #pragma unroll
;         for (int n = 0; n < 4; n++) acc[m][n] = mfma16(a[m], b[n], acc[m][n]);
;       __builtin_amdgcn_s_setprio(0);
;     }
;     __syncthreads();
	v_lshl_add_u32 v161, v128, 1, v125
	v_lshl_add_u32 v129, v127, 1, v125
	s_mov_b32 s17, 0
	s_mov_b64 s[0:1], 0x100
	ds_read_b128 v[130:133], v161
	ds_read_b128 v[134:137], v161 offset:2304
	ds_read_b128 v[138:141], v161 offset:4608
	ds_read_b128 v[142:145], v161 offset:6912
	ds_read_b128 v[146:149], v129 offset:36864
	ds_read_b128 v[150:153], v129 offset:39168
	ds_read_b128 v[162:165], v129 offset:41472
	ds_read_b128 v[166:169], v129 offset:43776
.Lgk7_loop:
	s_waitcnt lgkmcnt(0)
	ds_read_b128 v[222:225], v161 offset:64
	ds_read_b128 v[226:229], v161 offset:2368
	ds_read_b128 v[230:233], v161 offset:4672
	ds_read_b128 v[234:237], v161 offset:6976
	ds_read_b128 v[238:241], v129 offset:36928
	ds_read_b128 v[242:245], v129 offset:39232
	ds_read_b128 v[246:249], v129 offset:41536
	ds_read_b128 v[250:253], v129 offset:43840
	v_mfma_f32_16x16x32_bf16 v[34:37], v[130:133], v[146:149], v[34:37]
	v_mfma_f32_16x16x32_bf16 v[38:41], v[130:133], v[150:153], v[38:41]
	v_mfma_f32_16x16x32_bf16 v[42:45], v[130:133], v[162:165], v[42:45]
	v_mfma_f32_16x16x32_bf16 v[46:49], v[130:133], v[166:169], v[46:49]
	s_waitcnt vmcnt(0)
	ds_write_b128 v118, v[6:9] offset:18432
	ds_write_b128 v118, v[2:5] offset:55296
	v_mfma_f32_16x16x32_bf16 v[50:53], v[134:137], v[146:149], v[50:53]
	ds_write_b128 v120, v[10:13] offset:18432
	ds_write_b128 v120, v[14:17] offset:55296
	v_mfma_f32_16x16x32_bf16 v[54:57], v[134:137], v[150:153], v[54:57]
	ds_write_b128 v122, v[18:21] offset:18432
	ds_write_b128 v122, v[22:25] offset:55296
	v_mfma_f32_16x16x32_bf16 v[58:61], v[134:137], v[162:165], v[58:61]
	ds_write_b128 v123, v[26:29] offset:18432
	ds_write_b128 v123, v[30:33] offset:55296
	v_mfma_f32_16x16x32_bf16 v[62:65], v[134:137], v[166:169], v[62:65]
	global_load_dwordx4 v[6:9], v112, s[12:13]
	v_mfma_f32_16x16x32_bf16 v[66:69], v[138:141], v[146:149], v[66:69]
	global_load_dwordx4 v[2:5], v110, s[10:11]
	v_mfma_f32_16x16x32_bf16 v[70:73], v[138:141], v[150:153], v[70:73]
	global_load_dwordx4 v[10:13], v108, s[12:13]
	v_mfma_f32_16x16x32_bf16 v[74:77], v[138:141], v[162:165], v[74:77]
	global_load_dwordx4 v[14:17], v106, s[10:11]
	v_mfma_f32_16x16x32_bf16 v[78:81], v[138:141], v[166:169], v[78:81]
	global_load_dwordx4 v[18:21], v104, s[12:13]
	v_mfma_f32_16x16x32_bf16 v[82:85], v[142:145], v[146:149], v[82:85]
	global_load_dwordx4 v[22:25], v102, s[10:11]
	v_mfma_f32_16x16x32_bf16 v[86:89], v[142:145], v[150:153], v[86:89]
	global_load_dwordx4 v[26:29], v100, s[12:13]
	v_mfma_f32_16x16x32_bf16 v[90:93], v[142:145], v[162:165], v[90:93]
	global_load_dwordx4 v[30:33], v98, s[10:11]
	v_mfma_f32_16x16x32_bf16 v[94:97], v[142:145], v[166:169], v[94:97]
	s_waitcnt lgkmcnt(0)
	s_barrier
	ds_read_b128 v[130:133], v161 offset:18432
	v_mfma_f32_16x16x32_bf16 v[34:37], v[222:225], v[238:241], v[34:37]
	ds_read_b128 v[134:137], v161 offset:20736
	v_mfma_f32_16x16x32_bf16 v[38:41], v[222:225], v[242:245], v[38:41]
	ds_read_b128 v[138:141], v161 offset:23040
	v_mfma_f32_16x16x32_bf16 v[42:45], v[222:225], v[246:249], v[42:45]
	ds_read_b128 v[142:145], v161 offset:25344
	v_mfma_f32_16x16x32_bf16 v[46:49], v[222:225], v[250:253], v[46:49]
	ds_read_b128 v[146:149], v129 offset:55296
	v_mfma_f32_16x16x32_bf16 v[50:53], v[226:229], v[238:241], v[50:53]
	ds_read_b128 v[150:153], v129 offset:57600
	v_mfma_f32_16x16x32_bf16 v[54:57], v[226:229], v[242:245], v[54:57]
	ds_read_b128 v[162:165], v129 offset:59904
	v_mfma_f32_16x16x32_bf16 v[58:61], v[226:229], v[246:249], v[58:61]
	ds_read_b128 v[166:169], v129 offset:62208
	v_mfma_f32_16x16x32_bf16 v[62:65], v[226:229], v[250:253], v[62:65]
	v_mfma_f32_16x16x32_bf16 v[66:69], v[230:233], v[238:241], v[66:69]
	v_mfma_f32_16x16x32_bf16 v[70:73], v[230:233], v[242:245], v[70:73]
	v_mfma_f32_16x16x32_bf16 v[74:77], v[230:233], v[246:249], v[74:77]
	v_mfma_f32_16x16x32_bf16 v[78:81], v[230:233], v[250:253], v[78:81]
	v_mfma_f32_16x16x32_bf16 v[82:85], v[234:237], v[238:241], v[82:85]
	v_mfma_f32_16x16x32_bf16 v[86:89], v[234:237], v[242:245], v[86:89]
	v_mfma_f32_16x16x32_bf16 v[90:93], v[234:237], v[246:249], v[90:93]
	v_mfma_f32_16x16x32_bf16 v[94:97], v[234:237], v[250:253], v[94:97]
	s_waitcnt lgkmcnt(0)
	ds_read_b128 v[222:225], v161 offset:18496
	ds_read_b128 v[226:229], v161 offset:20800
	ds_read_b128 v[230:233], v161 offset:23104
	ds_read_b128 v[234:237], v161 offset:25408
	ds_read_b128 v[238:241], v129 offset:55360
	ds_read_b128 v[242:245], v129 offset:57664
	ds_read_b128 v[246:249], v129 offset:59968
	ds_read_b128 v[250:253], v129 offset:62272
	v_mfma_f32_16x16x32_bf16 v[34:37], v[130:133], v[146:149], v[34:37]
	v_mfma_f32_16x16x32_bf16 v[38:41], v[130:133], v[150:153], v[38:41]
	v_mfma_f32_16x16x32_bf16 v[42:45], v[130:133], v[162:165], v[42:45]
	v_mfma_f32_16x16x32_bf16 v[46:49], v[130:133], v[166:169], v[46:49]
	s_waitcnt vmcnt(0)
	ds_write_b128 v118, v[6:9]
	ds_write_b128 v118, v[2:5] offset:36864
	v_mfma_f32_16x16x32_bf16 v[50:53], v[134:137], v[146:149], v[50:53]
	ds_write_b128 v120, v[10:13]
	ds_write_b128 v120, v[14:17] offset:36864
	v_mfma_f32_16x16x32_bf16 v[54:57], v[134:137], v[150:153], v[54:57]
	ds_write_b128 v122, v[18:21]
	ds_write_b128 v122, v[22:25] offset:36864
	v_mfma_f32_16x16x32_bf16 v[58:61], v[134:137], v[162:165], v[58:61]
	ds_write_b128 v123, v[26:29]
	ds_write_b128 v123, v[30:33] offset:36864
	v_mfma_f32_16x16x32_bf16 v[62:65], v[134:137], v[166:169], v[62:65]
	global_load_dwordx4 v[6:9], v112, s[12:13] offset:128
	v_mfma_f32_16x16x32_bf16 v[66:69], v[138:141], v[146:149], v[66:69]
	global_load_dwordx4 v[2:5], v110, s[10:11] offset:128
	v_mfma_f32_16x16x32_bf16 v[70:73], v[138:141], v[150:153], v[70:73]
	global_load_dwordx4 v[10:13], v108, s[12:13] offset:128
	v_mfma_f32_16x16x32_bf16 v[74:77], v[138:141], v[162:165], v[74:77]
	global_load_dwordx4 v[14:17], v106, s[10:11] offset:128
	v_mfma_f32_16x16x32_bf16 v[78:81], v[138:141], v[166:169], v[78:81]
	global_load_dwordx4 v[18:21], v104, s[12:13] offset:128
	v_mfma_f32_16x16x32_bf16 v[82:85], v[142:145], v[146:149], v[82:85]
	global_load_dwordx4 v[22:25], v102, s[10:11] offset:128
	v_mfma_f32_16x16x32_bf16 v[86:89], v[142:145], v[150:153], v[86:89]
	global_load_dwordx4 v[26:29], v100, s[12:13] offset:128
	v_mfma_f32_16x16x32_bf16 v[90:93], v[142:145], v[162:165], v[90:93]
	global_load_dwordx4 v[30:33], v98, s[10:11] offset:128
	v_mfma_f32_16x16x32_bf16 v[94:97], v[142:145], v[166:169], v[94:97]
	s_waitcnt lgkmcnt(0)
	s_barrier
; DEV f32x4 mfma16(bf16x8 a, bf16x8 b, f32x4 c) { return __builtin_amdgcn_mfma_f32_16x16x32_bf16(a, b, c, 0, 0, 0); }
; template <int EPI, bool AF32>
; DEV void gemm_tile(const void* Ap, int lda, const u16* Bt, int ldb, int K, int m0, int n0, const Epi& ea, char* smem) {
;     ...
;   auto gload = [&](int kt) {
;     const int k0 = kt << 6;
; #pragma unroll
;     for (int i = 0; i < 4; i++) {
;       const int c = tid + i * 256, row = c >> 3, kc = c & 7;
;       if (AF32) {
;         const float* pa = (const float*)Ap + (size_t)(m0 + row) * lda + k0 + kc * 8;
;         rfa[2 * i] = *(const f32x4*)pa;
;         rfa[2 * i + 1] = *(const f32x4*)(pa + 4);
;       } else {
;         ra[i] = *(const u32x4*)((const u16*)Ap + (size_t)(m0 + row) * lda + k0 + kc * 8);
;       }
;       rb[i] = *(const u32x4*)(Bt + (size_t)(n0 + row) * ldb + k0 + kc * 8);
;     }
;   };
;   auto swrite = [&](int buf) {
; #pragma unroll
;     for (int i = 0; i < 4; i++) {
;       const int c = tid + i * 256, row = c >> 3, kc = c & 7;
;       u32x4 va;
;       if (AF32) {
;         va = (u32x4){pack2(rfa[2 * i][0], rfa[2 * i][1]), pack2(rfa[2 * i][2], rfa[2 * i][3]),
;                      pack2(rfa[2 * i + 1][0], rfa[2 * i + 1][1]), pack2(rfa[2 * i + 1][2], rfa[2 * i + 1][3])};
;       } else {
;         va = ra[i];
;       }
;       *(u32x4*)(sA + buf * 9216 + row * 72 + kc * 8) = va;
;       *(u32x4*)(sB + buf * 9216 + row * 72 + kc * 8) = rb[i];
;     }
;   };
;   gload(0);
;   swrite(0);
;   if (nk > 1) gload(1);
;   __syncthreads();
;   for (int kt = 0; kt < nk; kt++) {
;     const int buf = kt & 1;
;     if (kt + 1 < nk) swrite(buf ^ 1);
;     if (kt + 2 < nk) gload(kt + 2);
; #pragma unroll
;     for (int ks = 0; ks < 2; ks++) {
;       bf16x8 a[4], b[4];
; #pragma unroll
;       for (int m = 0; m < 4; m++) a[m] = *(const bf16x8*)(sA + buf * 9216 + (wr * 64 + m * 16 + fr) * 72 + ks * 32 + fq * 8);
; #pragma unroll
;       for (int n = 0; n < 4; n++) b[n] = *(const bf16x8*)(sB + buf * 9216 + (wc * 64 + n * 16 + fr) * 72 + ks * 32 + fq * 8);
;       __builtin_amdgcn_s_setprio(1);
; #pragma unroll
;       for (int m = 0; m < 4; m++)
; #pragma unroll
;         for (int n = 0; n < 4; n++) acc[m][n] = mfma16(a[m], b[n], acc[m][n]);
;       __builtin_amdgcn_s_setprio(0);
;     }
;     __syncthreads();
	ds_read_b128 v[130:133], v161
	v_mfma_f32_16x16x32_bf16 v[34:37], v[222:225], v[238:241], v[34:37]
	ds_read_b128 v[134:137], v161 offset:2304
	v_mfma_f32_16x16x32_bf16 v[38:41], v[222:225], v[242:245], v[38:41]
	ds_read_b128 v[138:141], v161 offset:4608
	v_mfma_f32_16x16x32_bf16 v[42:45], v[222:225], v[246:249], v[42:45]
	ds_read_b128 v[142:145], v161 offset:6912
	v_mfma_f32_16x16x32_bf16 v[46:49], v[222:225], v[250:253], v[46:49]
	ds_read_b128 v[146:149], v129 offset:36864
	v_mfma_f32_16x16x32_bf16 v[50:53], v[226:229], v[238:241], v[50:53]
	ds_read_b128 v[150:153], v129 offset:39168
	v_mfma_f32_16x16x32_bf16 v[54:57], v[226:229], v[242:245], v[54:57]
	ds_read_b128 v[162:165], v129 offset:41472
	v_mfma_f32_16x16x32_bf16 v[58:61], v[226:229], v[246:249], v[58:61]
	ds_read_b128 v[166:169], v129 offset:43776
	v_mfma_f32_16x16x32_bf16 v[62:65], v[226:229], v[250:253], v[62:65]
	v_mfma_f32_16x16x32_bf16 v[66:69], v[230:233], v[238:241], v[66:69]
	v_add_u32_e32 v112, 0x100, v112
	v_mfma_f32_16x16x32_bf16 v[70:73], v[230:233], v[242:245], v[70:73]
	v_add_u32_e32 v110, 0x100, v110
	v_mfma_f32_16x16x32_bf16 v[74:77], v[230:233], v[246:249], v[74:77]
	v_add_u32_e32 v108, 0x100, v108
	v_mfma_f32_16x16x32_bf16 v[78:81], v[230:233], v[250:253], v[78:81]
	v_add_u32_e32 v106, 0x100, v106
	v_mfma_f32_16x16x32_bf16 v[82:85], v[234:237], v[238:241], v[82:85]
	v_add_u32_e32 v104, 0x100, v104
	v_mfma_f32_16x16x32_bf16 v[86:89], v[234:237], v[242:245], v[86:89]
	v_add_u32_e32 v102, 0x100, v102
	v_mfma_f32_16x16x32_bf16 v[90:93], v[234:237], v[246:249], v[90:93]
	v_add_u32_e32 v100, 0x100, v100
	v_mfma_f32_16x16x32_bf16 v[94:97], v[234:237], v[250:253], v[94:97]
	v_add_u32_e32 v98, 0x100, v98
	s_add_i32 s17, s17, 1
	s_cmp_lg_u32 s17, 21
	s_cbranch_scc1 .Lgk7_loop
	s_waitcnt lgkmcnt(0)
	ds_read_b128 v[222:225], v161 offset:64
	ds_read_b128 v[226:229], v161 offset:2368
	ds_read_b128 v[230:233], v161 offset:4672
	ds_read_b128 v[234:237], v161 offset:6976
	ds_read_b128 v[238:241], v129 offset:36928
	ds_read_b128 v[242:245], v129 offset:39232
	ds_read_b128 v[246:249], v129 offset:41536
	ds_read_b128 v[250:253], v129 offset:43840
	v_mfma_f32_16x16x32_bf16 v[34:37], v[130:133], v[146:149], v[34:37]
	v_mfma_f32_16x16x32_bf16 v[38:41], v[130:133], v[150:153], v[38:41]
	v_mfma_f32_16x16x32_bf16 v[42:45], v[130:133], v[162:165], v[42:45]
	v_mfma_f32_16x16x32_bf16 v[46:49], v[130:133], v[166:169], v[46:49]
	s_waitcnt vmcnt(0)
	ds_write_b128 v118, v[6:9] offset:18432
	ds_write_b128 v118, v[2:5] offset:55296
	v_mfma_f32_16x16x32_bf16 v[50:53], v[134:137], v[146:149], v[50:53]
	ds_write_b128 v120, v[10:13] offset:18432
	ds_write_b128 v120, v[14:17] offset:55296
	v_mfma_f32_16x16x32_bf16 v[54:57], v[134:137], v[150:153], v[54:57]
	ds_write_b128 v122, v[18:21] offset:18432
	ds_write_b128 v122, v[22:25] offset:55296
	v_mfma_f32_16x16x32_bf16 v[58:61], v[134:137], v[162:165], v[58:61]
	ds_write_b128 v123, v[26:29] offset:18432
	ds_write_b128 v123, v[30:33] offset:55296
	v_mfma_f32_16x16x32_bf16 v[62:65], v[134:137], v[166:169], v[62:65]
	v_mfma_f32_16x16x32_bf16 v[66:69], v[138:141], v[146:149], v[66:69]
	v_mfma_f32_16x16x32_bf16 v[70:73], v[138:141], v[150:153], v[70:73]
	v_mfma_f32_16x16x32_bf16 v[74:77], v[138:141], v[162:165], v[74:77]
	v_mfma_f32_16x16x32_bf16 v[78:81], v[138:141], v[166:169], v[78:81]
	v_mfma_f32_16x16x32_bf16 v[82:85], v[142:145], v[146:149], v[82:85]
	v_mfma_f32_16x16x32_bf16 v[86:89], v[142:145], v[150:153], v[86:89]
	v_mfma_f32_16x16x32_bf16 v[90:93], v[142:145], v[162:165], v[90:93]
	v_mfma_f32_16x16x32_bf16 v[94:97], v[142:145], v[166:169], v[94:97]
	s_waitcnt lgkmcnt(0)
	s_barrier
	ds_read_b128 v[130:133], v161 offset:18432
	v_mfma_f32_16x16x32_bf16 v[34:37], v[222:225], v[238:241], v[34:37]
	ds_read_b128 v[134:137], v161 offset:20736
	v_mfma_f32_16x16x32_bf16 v[38:41], v[222:225], v[242:245], v[38:41]
	ds_read_b128 v[138:141], v161 offset:23040
	v_mfma_f32_16x16x32_bf16 v[42:45], v[222:225], v[246:249], v[42:45]
	ds_read_b128 v[142:145], v161 offset:25344
	v_mfma_f32_16x16x32_bf16 v[46:49], v[222:225], v[250:253], v[46:49]
	ds_read_b128 v[146:149], v129 offset:55296
	v_mfma_f32_16x16x32_bf16 v[50:53], v[226:229], v[238:241], v[50:53]
	ds_read_b128 v[150:153], v129 offset:57600
	v_mfma_f32_16x16x32_bf16 v[54:57], v[226:229], v[242:245], v[54:57]
	ds_read_b128 v[162:165], v129 offset:59904
	v_mfma_f32_16x16x32_bf16 v[58:61], v[226:229], v[246:249], v[58:61]
	ds_read_b128 v[166:169], v129 offset:62208
	v_mfma_f32_16x16x32_bf16 v[62:65], v[226:229], v[250:253], v[62:65]
	v_mfma_f32_16x16x32_bf16 v[66:69], v[230:233], v[238:241], v[66:69]
	v_mfma_f32_16x16x32_bf16 v[70:73], v[230:233], v[242:245], v[70:73]
	v_mfma_f32_16x16x32_bf16 v[74:77], v[230:233], v[246:249], v[74:77]
	v_mfma_f32_16x16x32_bf16 v[78:81], v[230:233], v[250:253], v[78:81]
	v_mfma_f32_16x16x32_bf16 v[82:85], v[234:237], v[238:241], v[82:85]
	v_mfma_f32_16x16x32_bf16 v[86:89], v[234:237], v[242:245], v[86:89]
	v_mfma_f32_16x16x32_bf16 v[90:93], v[234:237], v[246:249], v[90:93]
	v_mfma_f32_16x16x32_bf16 v[94:97], v[234:237], v[250:253], v[94:97]
	s_waitcnt lgkmcnt(0)
; DEV f32x4 mfma16(bf16x8 a, bf16x8 b, f32x4 c) { return __builtin_amdgcn_mfma_f32_16x16x32_bf16(a, b, c, 0, 0, 0); }
; template <int EPI, bool AF32>
; DEV void gemm_tile(const void* Ap, int lda, const u16* Bt, int ldb, int K, int m0, int n0, const Epi& ea, char* smem) {
;     ...
;   for (int kt = 0; kt < nk; kt++) {
;     const int buf = kt & 1;
;     if (kt + 1 < nk) swrite(buf ^ 1);
;     if (kt + 2 < nk) gload(kt + 2);
; #pragma unroll
;     for (int ks = 0; ks < 2; ks++) {
;       bf16x8 a[4], b[4];
; #pragma unroll
;       for (int m = 0; m < 4; m++) a[m] = *(const bf16x8*)(sA + buf * 9216 + (wr * 64 + m * 16 + fr) * 72 + ks * 32 + fq * 8);
; #pragma unroll
;       for (int n = 0; n < 4; n++) b[n] = *(const bf16x8*)(sB + buf * 9216 + (wc * 64 + n * 16 + fr) * 72 + ks * 32 + fq * 8);
;       __builtin_amdgcn_s_setprio(1);
; #pragma unroll
;       for (int m = 0; m < 4; m++)
; #pragma unroll
;         for (int n = 0; n < 4; n++) acc[m][n] = mfma16(a[m], b[n], acc[m][n]);
;       __builtin_amdgcn_s_setprio(0);
;     }
;     __syncthreads();
;     ...
;   if (EPI == EP_RES || EPI == EP_MERGE1 || EPI == EP_MERGE2) {
;     const int rbase = m0 + wr * 64 + fq * 4, cbase = cb + fr;
;     if (EPI == EP_RES) {
;       float* C = (float*)ea.p0;
;       const float* R = (const float*)ea.p1;
;       float rv[4][4][4];
; #pragma unroll
;       for (int m = 0; m < 4; m++)
; #pragma unroll
;         for (int j = 0; j < 4; j++)
; #pragma unroll
;           for (int n = 0; n < 4; n++) rv[m][j][n] = R[(size_t)(rbase + m * 16 + j) * 1024 + cbase + n * 16];
	ds_read_b128 v[222:225], v161 offset:18496
	ds_read_b128 v[226:229], v161 offset:20800
	ds_read_b128 v[230:233], v161 offset:23104
	ds_read_b128 v[234:237], v161 offset:25408
	ds_read_b128 v[238:241], v129 offset:55360
	ds_read_b128 v[242:245], v129 offset:57664
	ds_read_b128 v[246:249], v129 offset:59968
	ds_read_b128 v[250:253], v129 offset:62272
	v_mfma_f32_16x16x32_bf16 v[98:101], v[130:133], v[146:149], v[34:37]
	v_mfma_f32_16x16x32_bf16 v[102:105], v[130:133], v[150:153], v[38:41]
	v_mfma_f32_16x16x32_bf16 v[106:109], v[130:133], v[162:165], v[42:45]
	v_mfma_f32_16x16x32_bf16 v[110:113], v[130:133], v[166:169], v[46:49]
	v_mfma_f32_16x16x32_bf16 v[50:53], v[134:137], v[146:149], v[50:53]
	v_mfma_f32_16x16x32_bf16 v[54:57], v[134:137], v[150:153], v[54:57]
	v_mfma_f32_16x16x32_bf16 v[58:61], v[134:137], v[162:165], v[58:61]
	v_mfma_f32_16x16x32_bf16 v[62:65], v[134:137], v[166:169], v[62:65]
	v_mfma_f32_16x16x32_bf16 v[66:69], v[138:141], v[146:149], v[66:69]
	v_mfma_f32_16x16x32_bf16 v[70:73], v[138:141], v[150:153], v[70:73]
	v_mfma_f32_16x16x32_bf16 v[74:77], v[138:141], v[162:165], v[74:77]
	v_mfma_f32_16x16x32_bf16 v[78:81], v[138:141], v[166:169], v[78:81]
	v_mfma_f32_16x16x32_bf16 v[82:85], v[142:145], v[146:149], v[82:85]
	v_mfma_f32_16x16x32_bf16 v[86:89], v[142:145], v[150:153], v[86:89]
	v_mfma_f32_16x16x32_bf16 v[90:93], v[142:145], v[162:165], v[90:93]
	v_mfma_f32_16x16x32_bf16 v[94:97], v[142:145], v[166:169], v[94:97]
	s_waitcnt lgkmcnt(0)
	v_mfma_f32_16x16x32_bf16 v[30:33], v[230:233], v[238:241], v[66:69]
	v_mfma_f32_16x16x32_bf16 v[26:29], v[230:233], v[242:245], v[70:73]
	v_mfma_f32_16x16x32_bf16 v[22:25], v[230:233], v[246:249], v[74:77]
	v_mfma_f32_16x16x32_bf16 v[18:21], v[230:233], v[250:253], v[78:81]
	v_mfma_f32_16x16x32_bf16 v[14:17], v[234:237], v[238:241], v[82:85]
	v_mfma_f32_16x16x32_bf16 v[10:13], v[234:237], v[242:245], v[86:89]
	v_mfma_f32_16x16x32_bf16 v[6:9], v[234:237], v[246:249], v[90:93]
	v_mfma_f32_16x16x32_bf16 v[2:5], v[234:237], v[250:253], v[94:97]
	v_mfma_f32_16x16x32_bf16 v[34:37], v[226:229], v[250:253], v[62:65]
	v_mfma_f32_16x16x32_bf16 v[62:65], v[222:225], v[238:241], v[98:101]
	v_mfma_f32_16x16x32_bf16 v[38:41], v[226:229], v[246:249], v[58:61]
	v_mfma_f32_16x16x32_bf16 v[58:61], v[222:225], v[242:245], v[102:105]
	v_mfma_f32_16x16x32_bf16 v[42:45], v[226:229], v[242:245], v[54:57]
	v_mfma_f32_16x16x32_bf16 v[54:57], v[222:225], v[246:249], v[106:109]
	v_mfma_f32_16x16x32_bf16 v[46:49], v[226:229], v[238:241], v[50:53]
	v_mfma_f32_16x16x32_bf16 v[50:53], v[222:225], v[250:253], v[110:113]
	s_nop 7
	v_and_b32_e32 v116, 64, v116
	v_add_u32_e32 v0, s16, v117
	v_or3_b32 v66, v116, s15, v114
	v_lshl_or_b32 v72, v115, 2, v0
	v_ashrrev_i32_e32 v67, 31, v66
	v_lshlrev_b64 v[66:67], 2, v[66:67]
	v_ashrrev_i32_e32 v73, 31, v72
	v_lshl_add_u64 v[74:75], s[4:5], 0, v[66:67]
	v_lshlrev_b64 v[68:69], 12, v[72:73]
	v_lshl_add_u64 v[70:71], v[74:75], 0, v[68:69]
	s_barrier
	global_load_dword v0, v[70:71], off
	global_load_dword v104, v[70:71], off offset:64
	global_load_dword v105, v[70:71], off offset:128
	global_load_dword v106, v[70:71], off offset:192
	v_or_b32_e32 v70, 1, v72
	v_ashrrev_i32_e32 v71, 31, v70
	v_lshlrev_b64 v[70:71], 12, v[70:71]
	v_lshl_add_u64 v[76:77], v[74:75], 0, v[70:71]
	global_load_dword v107, v[76:77], off
	global_load_dword v108, v[76:77], off offset:64
	global_load_dword v109, v[76:77], off offset:128
	global_load_dword v110, v[76:77], off offset:192
	v_or_b32_e32 v76, 2, v72
	v_ashrrev_i32_e32 v77, 31, v76
	v_lshlrev_b64 v[76:77], 12, v[76:77]
	v_lshl_add_u64 v[78:79], v[74:75], 0, v[76:77]
	global_load_dword v111, v[78:79], off
	global_load_dword v112, v[78:79], off offset:64
	global_load_dword v113, v[78:79], off offset:128
	global_load_dword v114, v[78:79], off offset:192
	v_or_b32_e32 v78, 3, v72
	v_ashrrev_i32_e32 v79, 31, v78
	v_lshlrev_b64 v[78:79], 12, v[78:79]
	v_lshl_add_u64 v[80:81], v[74:75], 0, v[78:79]
	global_load_dword v115, v[80:81], off
	global_load_dword v116, v[80:81], off offset:64
	global_load_dword v117, v[80:81], off offset:128
	global_load_dword v118, v[80:81], off offset:192
	v_or_b32_e32 v80, 16, v72
	v_ashrrev_i32_e32 v81, 31, v80
	v_lshlrev_b64 v[80:81], 12, v[80:81]
	v_lshl_add_u64 v[82:83], v[74:75], 0, v[80:81]
	global_load_dword v119, v[82:83], off
	global_load_dword v120, v[82:83], off offset:64
	global_load_dword v121, v[82:83], off offset:128
	global_load_dword v122, v[82:83], off offset:192
	v_or_b32_e32 v82, 17, v72
	v_ashrrev_i32_e32 v83, 31, v82
	v_lshlrev_b64 v[82:83], 12, v[82:83]
	v_lshl_add_u64 v[84:85], v[74:75], 0, v[82:83]
	global_load_dword v123, v[84:85], off
	global_load_dword v124, v[84:85], off offset:64
	global_load_dword v125, v[84:85], off offset:128
	global_load_dword v126, v[84:85], off offset:192
	v_or_b32_e32 v84, 18, v72
	v_ashrrev_i32_e32 v85, 31, v84
	v_lshlrev_b64 v[84:85], 12, v[84:85]
	v_lshl_add_u64 v[86:87], v[74:75], 0, v[84:85]
	global_load_dword v127, v[86:87], off
	global_load_dword v128, v[86:87], off offset:64
	global_load_dword v129, v[86:87], off offset:128
	global_load_dword v130, v[86:87], off offset:192
	v_or_b32_e32 v86, 19, v72
	v_ashrrev_i32_e32 v87, 31, v86
	v_lshlrev_b64 v[86:87], 12, v[86:87]
	v_lshl_add_u64 v[88:89], v[74:75], 0, v[86:87]
	global_load_dword v131, v[88:89], off
	global_load_dword v132, v[88:89], off offset:64
	global_load_dword v133, v[88:89], off offset:128
	global_load_dword v134, v[88:89], off offset:192
	v_or_b32_e32 v88, 32, v72
	v_ashrrev_i32_e32 v89, 31, v88
	v_lshlrev_b64 v[88:89], 12, v[88:89]
	v_lshl_add_u64 v[90:91], v[74:75], 0, v[88:89]
; template <int EPI, bool AF32>
; DEV void gemm_tile(const void* Ap, int lda, const u16* Bt, int ldb, int K, int m0, int n0, const Epi& ea, char* smem) {
;     ...
; #pragma unroll
;       for (int m = 0; m < 4; m++)
; #pragma unroll
;         for (int j = 0; j < 4; j++)
; #pragma unroll
;           for (int n = 0; n < 4; n++) rv[m][j][n] = R[(size_t)(rbase + m * 16 + j) * 1024 + cbase + n * 16];
;       __builtin_amdgcn_sched_barrier(0);
; #pragma unroll
;       for (int m = 0; m < 4; m++)
; #pragma unroll
;         for (int j = 0; j < 4; j++)
; #pragma unroll
;           for (int n = 0; n < 4; n++)
;             C[(size_t)(rbase + m * 16 + j) * 1024 + cbase + n * 16] = ALPHA_ * rv[m][j][n] + acc[m][n][j];
	global_load_dword v135, v[90:91], off
	global_load_dword v136, v[90:91], off offset:64
	global_load_dword v137, v[90:91], off offset:128
	global_load_dword v138, v[90:91], off offset:192
	v_or_b32_e32 v90, 33, v72
	v_ashrrev_i32_e32 v91, 31, v90
	v_lshlrev_b64 v[90:91], 12, v[90:91]
	v_lshl_add_u64 v[92:93], v[74:75], 0, v[90:91]
	global_load_dword v139, v[92:93], off
	global_load_dword v140, v[92:93], off offset:64
	global_load_dword v141, v[92:93], off offset:128
	global_load_dword v142, v[92:93], off offset:192
	v_or_b32_e32 v92, 34, v72
	v_ashrrev_i32_e32 v93, 31, v92
	v_lshlrev_b64 v[92:93], 12, v[92:93]
	v_lshl_add_u64 v[94:95], v[74:75], 0, v[92:93]
	global_load_dword v143, v[94:95], off
	global_load_dword v144, v[94:95], off offset:64
	global_load_dword v145, v[94:95], off offset:128
	global_load_dword v146, v[94:95], off offset:192
	v_or_b32_e32 v94, 35, v72
	v_ashrrev_i32_e32 v95, 31, v94
	v_lshlrev_b64 v[94:95], 12, v[94:95]
	v_lshl_add_u64 v[96:97], v[74:75], 0, v[94:95]
	global_load_dword v147, v[96:97], off
	global_load_dword v148, v[96:97], off offset:64
	global_load_dword v149, v[96:97], off offset:128
	global_load_dword v150, v[96:97], off offset:192
	v_or_b32_e32 v96, 48, v72
	v_ashrrev_i32_e32 v97, 31, v96
	v_lshlrev_b64 v[96:97], 12, v[96:97]
	v_lshl_add_u64 v[98:99], v[74:75], 0, v[96:97]
	global_load_dword v151, v[98:99], off
	global_load_dword v152, v[98:99], off offset:64
	global_load_dword v153, v[98:99], off offset:128
	global_load_dword v161, v[98:99], off offset:192
	v_or_b32_e32 v98, 49, v72
	v_ashrrev_i32_e32 v99, 31, v98
	v_lshlrev_b64 v[98:99], 12, v[98:99]
	v_lshl_add_u64 v[100:101], v[74:75], 0, v[98:99]
	global_load_dword v162, v[100:101], off
	global_load_dword v163, v[100:101], off offset:64
	global_load_dword v164, v[100:101], off offset:128
	global_load_dword v165, v[100:101], off offset:192
	v_or_b32_e32 v100, 50, v72
	v_or_b32_e32 v72, 51, v72
	v_ashrrev_i32_e32 v101, 31, v100
	v_ashrrev_i32_e32 v73, 31, v72
	v_lshlrev_b64 v[100:101], 12, v[100:101]
	v_lshlrev_b64 v[72:73], 12, v[72:73]
	v_lshl_add_u64 v[102:103], v[74:75], 0, v[100:101]
	v_lshl_add_u64 v[74:75], v[74:75], 0, v[72:73]
	global_load_dword v166, v[102:103], off
	global_load_dword v167, v[102:103], off offset:64
	global_load_dword v168, v[102:103], off offset:128
	s_nop 0
	global_load_dword v102, v[102:103], off offset:192
	s_nop 0
	global_load_dword v103, v[74:75], off
	global_load_dword v169, v[74:75], off offset:64
	global_load_dword v170, v[74:75], off offset:128
	s_nop 0
	global_load_dword v74, v[74:75], off offset:192
	v_lshl_add_u64 v[66:67], s[2:3], 0, v[66:67]
	v_lshl_add_u64 v[68:69], v[66:67], 0, v[68:69]
	s_waitcnt vmcnt(62)
	v_fmamk_f32 v0, v0, 0x3fb504f3, v62
	global_store_dword v[68:69], v0, off
	v_fmamk_f32 v0, v104, 0x3fb504f3, v58
	global_store_dword v[68:69], v0, off offset:64
	s_waitcnt vmcnt(62)
	v_fmamk_f32 v0, v105, 0x3fb504f3, v54
	global_store_dword v[68:69], v0, off offset:128
	v_fmamk_f32 v0, v106, 0x3fb504f3, v50
	global_store_dword v[68:69], v0, off offset:192
	v_lshl_add_u64 v[68:69], v[66:67], 0, v[70:71]
	s_waitcnt vmcnt(62)
	v_fmamk_f32 v0, v107, 0x3fb504f3, v63
	global_store_dword v[68:69], v0, off
	v_fmamk_f32 v0, v108, 0x3fb504f3, v59
	global_store_dword v[68:69], v0, off offset:64
	s_waitcnt vmcnt(62)
	v_fmamk_f32 v0, v109, 0x3fb504f3, v55
	global_store_dword v[68:69], v0, off offset:128
	v_fmamk_f32 v0, v110, 0x3fb504f3, v51
	global_store_dword v[68:69], v0, off offset:192
	v_lshl_add_u64 v[50:51], v[66:67], 0, v[76:77]
	s_waitcnt vmcnt(62)
	v_fmamk_f32 v0, v111, 0x3fb504f3, v64
	global_store_dword v[50:51], v0, off
	v_fmamk_f32 v0, v112, 0x3fb504f3, v60
	global_store_dword v[50:51], v0, off offset:64
	s_waitcnt vmcnt(62)
	v_fmamk_f32 v0, v113, 0x3fb504f3, v56
	global_store_dword v[50:51], v0, off offset:128
	v_fmamk_f32 v0, v114, 0x3fb504f3, v52
	global_store_dword v[50:51], v0, off offset:192
	v_lshl_add_u64 v[50:51], v[66:67], 0, v[78:79]
	s_waitcnt vmcnt(62)
	v_fmac_f32_e32 v65, 0x3fb504f3, v115
	v_fmac_f32_e32 v61, 0x3fb504f3, v116
	s_waitcnt vmcnt(61)
	v_fmac_f32_e32 v57, 0x3fb504f3, v117
	s_waitcnt vmcnt(60)
	v_fmac_f32_e32 v53, 0x3fb504f3, v118
	global_store_dword v[50:51], v65, off
	global_store_dword v[50:51], v61, off offset:64
	global_store_dword v[50:51], v57, off offset:128
	global_store_dword v[50:51], v53, off offset:192
	v_lshl_add_u64 v[50:51], v[66:67], 0, v[80:81]
	s_waitcnt vmcnt(62)
	v_fmamk_f32 v0, v119, 0x3fb504f3, v46
	global_store_dword v[50:51], v0, off
	v_fmamk_f32 v0, v120, 0x3fb504f3, v42
	global_store_dword v[50:51], v0, off offset:64
	s_waitcnt vmcnt(62)
	v_fmamk_f32 v0, v121, 0x3fb504f3, v38
	global_store_dword v[50:51], v0, off offset:128
	v_fmamk_f32 v0, v122, 0x3fb504f3, v34
	global_store_dword v[50:51], v0, off offset:192
	v_lshl_add_u64 v[50:51], v[66:67], 0, v[82:83]
	s_waitcnt vmcnt(62)
; DEV int bidx() { int b = __builtin_amdgcn_readfirstlane(blockIdx.x); asm volatile("" : "+s"(b)); return b; }
; DEV int gdim() { int g = __builtin_amdgcn_readfirstlane(gridDim.x); asm volatile("" : "+s"(g)); return g; }
; template <int EPI, bool AF32>
; DEV void gemm_tile(const void* Ap, int lda, const u16* Bt, int ldb, int K, int m0, int n0, const Epi& ea, char* smem) {
;     ...
;       __builtin_amdgcn_sched_barrier(0);
; #pragma unroll
;       for (int m = 0; m < 4; m++)
; #pragma unroll
;         for (int j = 0; j < 4; j++)
; #pragma unroll
;           for (int n = 0; n < 4; n++)
;             C[(size_t)(rbase + m * 16 + j) * 1024 + cbase + n * 16] = ALPHA_ * rv[m][j][n] + acc[m][n][j];
; template <int EPI, bool AF32>
; DEV void gemm_phase(const void* A, int lda, const u16* Bt, int ldb, int M, int N, int K, const Epi& ea, char* smem) {
;     ...
;   for (int tile = bidx(); tile < ntm * ntn; tile += gdim()) {
;     int m, n;
;     tile_mn(tile, ntm, ntn, m, n);
;     gemm_tile<EPI, AF32>(A, lda, Bt, ldb, K, m << 7, n << 7, ea, smem);
;   }
	v_fmamk_f32 v0, v123, 0x3fb504f3, v47
	global_store_dword v[50:51], v0, off
	v_fmamk_f32 v0, v124, 0x3fb504f3, v43
	global_store_dword v[50:51], v0, off offset:64
	s_waitcnt vmcnt(62)
	v_fmamk_f32 v0, v125, 0x3fb504f3, v39
	global_store_dword v[50:51], v0, off offset:128
	v_fmamk_f32 v0, v126, 0x3fb504f3, v35
	global_store_dword v[50:51], v0, off offset:192
	v_lshl_add_u64 v[34:35], v[66:67], 0, v[84:85]
	s_waitcnt vmcnt(62)
	v_fmamk_f32 v0, v127, 0x3fb504f3, v48
	global_store_dword v[34:35], v0, off
	v_fmamk_f32 v0, v128, 0x3fb504f3, v44
	global_store_dword v[34:35], v0, off offset:64
	s_waitcnt vmcnt(62)
	v_fmamk_f32 v0, v129, 0x3fb504f3, v40
	global_store_dword v[34:35], v0, off offset:128
	v_fmamk_f32 v0, v130, 0x3fb504f3, v36
	global_store_dword v[34:35], v0, off offset:192
	v_lshl_add_u64 v[34:35], v[66:67], 0, v[86:87]
	s_waitcnt vmcnt(62)
	v_fmac_f32_e32 v49, 0x3fb504f3, v131
	v_fmac_f32_e32 v45, 0x3fb504f3, v132
	s_waitcnt vmcnt(61)
	v_fmac_f32_e32 v41, 0x3fb504f3, v133
	s_waitcnt vmcnt(60)
	v_fmac_f32_e32 v37, 0x3fb504f3, v134
	global_store_dword v[34:35], v49, off
	global_store_dword v[34:35], v45, off offset:64
	global_store_dword v[34:35], v41, off offset:128
	global_store_dword v[34:35], v37, off offset:192
	v_lshl_add_u64 v[34:35], v[66:67], 0, v[88:89]
	s_waitcnt vmcnt(62)
	v_fmamk_f32 v0, v135, 0x3fb504f3, v30
	global_store_dword v[34:35], v0, off
	v_fmamk_f32 v0, v136, 0x3fb504f3, v26
	global_store_dword v[34:35], v0, off offset:64
	s_waitcnt vmcnt(62)
	v_fmamk_f32 v0, v137, 0x3fb504f3, v22
	global_store_dword v[34:35], v0, off offset:128
	v_fmamk_f32 v0, v138, 0x3fb504f3, v18
	global_store_dword v[34:35], v0, off offset:192
	v_lshl_add_u64 v[34:35], v[66:67], 0, v[90:91]
	s_waitcnt vmcnt(62)
	v_fmamk_f32 v0, v139, 0x3fb504f3, v31
	global_store_dword v[34:35], v0, off
	v_fmamk_f32 v0, v140, 0x3fb504f3, v27
	global_store_dword v[34:35], v0, off offset:64
	s_waitcnt vmcnt(62)
	v_fmamk_f32 v0, v141, 0x3fb504f3, v23
	global_store_dword v[34:35], v0, off offset:128
	v_fmamk_f32 v0, v142, 0x3fb504f3, v19
	global_store_dword v[34:35], v0, off offset:192
	v_lshl_add_u64 v[18:19], v[66:67], 0, v[92:93]
	s_waitcnt vmcnt(62)
	v_fmamk_f32 v0, v143, 0x3fb504f3, v32
	global_store_dword v[18:19], v0, off
	v_fmamk_f32 v0, v144, 0x3fb504f3, v28
	global_store_dword v[18:19], v0, off offset:64
	s_waitcnt vmcnt(62)
	v_fmamk_f32 v0, v145, 0x3fb504f3, v24
	global_store_dword v[18:19], v0, off offset:128
	v_fmamk_f32 v0, v146, 0x3fb504f3, v20
	global_store_dword v[18:19], v0, off offset:192
	v_lshl_add_u64 v[18:19], v[66:67], 0, v[94:95]
	s_waitcnt vmcnt(62)
	v_fmac_f32_e32 v33, 0x3fb504f3, v147
	v_fmac_f32_e32 v29, 0x3fb504f3, v148
	s_waitcnt vmcnt(61)
	v_fmac_f32_e32 v25, 0x3fb504f3, v149
	s_waitcnt vmcnt(60)
	v_fmac_f32_e32 v21, 0x3fb504f3, v150
	global_store_dword v[18:19], v33, off
	global_store_dword v[18:19], v29, off offset:64
	global_store_dword v[18:19], v25, off offset:128
	global_store_dword v[18:19], v21, off offset:192
	v_lshl_add_u64 v[18:19], v[66:67], 0, v[96:97]
	s_waitcnt vmcnt(62)
	v_fmamk_f32 v0, v151, 0x3fb504f3, v14
	global_store_dword v[18:19], v0, off
	v_fmamk_f32 v0, v152, 0x3fb504f3, v10
	global_store_dword v[18:19], v0, off offset:64
	s_waitcnt vmcnt(62)
	v_fmamk_f32 v0, v153, 0x3fb504f3, v6
	global_store_dword v[18:19], v0, off offset:128
	v_fmamk_f32 v0, v161, 0x3fb504f3, v2
	global_store_dword v[18:19], v0, off offset:192
	v_lshl_add_u64 v[18:19], v[66:67], 0, v[98:99]
	s_waitcnt vmcnt(62)
	v_fmamk_f32 v0, v162, 0x3fb504f3, v15
	global_store_dword v[18:19], v0, off
	v_fmamk_f32 v0, v163, 0x3fb504f3, v11
	global_store_dword v[18:19], v0, off offset:64
	s_waitcnt vmcnt(62)
	v_fmamk_f32 v0, v164, 0x3fb504f3, v7
	global_store_dword v[18:19], v0, off offset:128
	v_fmamk_f32 v0, v165, 0x3fb504f3, v3
	global_store_dword v[18:19], v0, off offset:192
	v_lshl_add_u64 v[2:3], v[66:67], 0, v[100:101]
	s_waitcnt vmcnt(62)
	v_fmamk_f32 v0, v166, 0x3fb504f3, v16
	global_store_dword v[2:3], v0, off
	v_fmamk_f32 v0, v167, 0x3fb504f3, v12
	global_store_dword v[2:3], v0, off offset:64
	s_waitcnt vmcnt(62)
	v_fmamk_f32 v0, v168, 0x3fb504f3, v8
	global_store_dword v[2:3], v0, off offset:128
	v_fmamk_f32 v0, v102, 0x3fb504f3, v4
	global_store_dword v[2:3], v0, off offset:192
	v_lshl_add_u64 v[2:3], v[66:67], 0, v[72:73]
	s_waitcnt vmcnt(62)
	v_fmac_f32_e32 v17, 0x3fb504f3, v103
	v_fmac_f32_e32 v13, 0x3fb504f3, v169
	s_waitcnt vmcnt(61)
	v_fmac_f32_e32 v9, 0x3fb504f3, v170
	s_waitcnt vmcnt(60)
	v_fmac_f32_e32 v5, 0x3fb504f3, v74
	v_readfirstlane_b32 s0, v198
	global_store_dword v[2:3], v17, off
	global_store_dword v[2:3], v13, off offset:64
	global_store_dword v[2:3], v9, off offset:128
	global_store_dword v[2:3], v5, off offset:192
	s_add_i32 s14, s0, s14
	s_cmpk_lt_i32 s14, 0x820
	s_cbranch_scc1 .LBB0_1478
